# v_cvt_pk_bf16_f32 packing everywhere it is provably local + s_nop padding restored for every MFMA/SGPR software distance the deletions shortened (static check clean)
# speedup vs baseline: 1.0183x; 1.0183x over previous
.Ltail84:
	s_add_i32 s3, s24, 2
	v_add_u32_e32 v181, v144, v145
	ds_read_b128 v[80:83], v181 offset:16384
	ds_read_b128 v[84:87], v181 offset:18432
	ds_read_b128 v[88:91], v181 offset:20480
	ds_read_b128 v[92:95], v181 offset:22528
	v_add_u32_e32 v180, v143, v145
	ds_read_b128 v[64:67], v180
	s_add_i32 s24, s24, 4
	ds_read_b128 v[68:71], v180 offset:2048
	s_min_u32 s24, s24, 15
	s_lshl_b32 s92, s24, 7
	ds_read_b128 v[72:75], v180 offset:4096
	ds_read_b128 v[76:79], v180 offset:6144
	v_add_u32_e32 v182, v143, v146
	v_add_u32_e32 v186, v144, v146
	v_lshl_add_u64 v[224:225], v[138:139], 0, s[92:93]
	ds_read_b128 v[192:195], v182
	ds_read_b128 v[196:199], v182 offset:2048
	ds_read_b128 v[200:203], v182 offset:4096
	ds_read_b128 v[204:207], v182 offset:6144
	ds_read_b128 v[208:211], v186 offset:16384
	ds_read_b128 v[212:215], v186 offset:18432
	ds_read_b128 v[216:219], v186 offset:20480
	ds_read_b128 v[220:223], v186 offset:22528
	s_waitcnt lgkmcnt(11)
	v_mfma_f32_16x16x32_bf16 v[60:63], v[80:83], v[64:67], v[60:63]
	v_mfma_f32_16x16x32_bf16 v[56:59], v[84:87], v[64:67], v[56:59]
	v_mfma_f32_16x16x32_bf16 v[52:55], v[88:91], v[64:67], v[52:55]
	v_mfma_f32_16x16x32_bf16 v[48:51], v[92:95], v[64:67], v[48:51]
	s_waitcnt vmcnt(7)
	ds_write_b128 v156, v[96:99] offset:32768
	v_add_co_u32_e32 v96, vcc, s11, v224
	s_waitcnt lgkmcnt(11)
	v_mfma_f32_16x16x32_bf16 v[44:47], v[80:83], v[68:71], v[44:47]
	v_addc_co_u32_e32 v97, vcc, 0, v225, vcc
	v_mfma_f32_16x16x32_bf16 v[40:43], v[84:87], v[68:71], v[40:43]
	v_mfma_f32_16x16x32_bf16 v[36:39], v[88:91], v[68:71], v[36:39]
	v_mfma_f32_16x16x32_bf16 v[32:35], v[92:95], v[68:71], v[32:35]
	v_add_co_u32_e32 v96, vcc, s33, v224
	s_waitcnt vmcnt(6)
	ds_write_b128 v156, v[100:103] offset:36864
	s_nop 0
	v_addc_co_u32_e32 v97, vcc, 0, v225, vcc
	s_waitcnt lgkmcnt(11)
	v_mfma_f32_16x16x32_bf16 v[28:31], v[80:83], v[72:75], v[28:31]
	v_mfma_f32_16x16x32_bf16 v[24:27], v[84:87], v[72:75], v[24:27]
	v_mfma_f32_16x16x32_bf16 v[20:23], v[88:91], v[72:75], v[20:23]
	v_mfma_f32_16x16x32_bf16 v[16:19], v[92:95], v[72:75], v[16:19]
	s_waitcnt vmcnt(5)
	ds_write_b128 v156, v[104:107] offset:40960
	s_waitcnt lgkmcnt(11)
	v_mfma_f32_16x16x32_bf16 v[12:15], v[80:83], v[76:79], v[12:15]
	v_add_co_u32_e32 v80, vcc, s59, v224
	v_mfma_f32_16x16x32_bf16 v[0:3], v[92:95], v[76:79], v[0:3]
	s_nop 0
	v_addc_co_u32_e32 v81, vcc, 0, v225, vcc
	v_lshl_add_u64 v[92:93], v[140:141], 0, s[92:93]
	v_mfma_f32_16x16x32_bf16 v[8:11], v[84:87], v[76:79], v[8:11]
	v_add_co_u32_e32 v84, vcc, s11, v92
	s_nop 1
	v_addc_co_u32_e32 v85, vcc, 0, v93, vcc
	v_mfma_f32_16x16x32_bf16 v[4:7], v[88:91], v[76:79], v[4:7]
	v_add_co_u32_e32 v88, vcc, s33, v92
	s_nop 0
	s_nop 0
	v_addc_co_u32_e32 v89, vcc, 0, v93, vcc
	s_waitcnt vmcnt(4)
	ds_write_b128 v156, v[112:115] offset:45056
	s_waitcnt lgkmcnt(7)
	v_mfma_f32_16x16x32_bf16 v[60:63], v[208:211], v[192:195], v[60:63]
	s_waitcnt lgkmcnt(6)
	v_mfma_f32_16x16x32_bf16 v[56:59], v[212:215], v[192:195], v[56:59]
	s_waitcnt lgkmcnt(5)
	v_mfma_f32_16x16x32_bf16 v[52:55], v[216:219], v[192:195], v[52:55]
	s_waitcnt lgkmcnt(4)
	v_mfma_f32_16x16x32_bf16 v[48:51], v[220:223], v[192:195], v[48:51]
	v_add_co_u32_e32 v92, vcc, s59, v92
	s_waitcnt vmcnt(3)
	ds_write_b128 v156, v[108:111] offset:49152
	s_nop 0
	v_addc_co_u32_e32 v93, vcc, 0, v93, vcc
	v_mfma_f32_16x16x32_bf16 v[44:47], v[208:211], v[196:199], v[44:47]
	v_mfma_f32_16x16x32_bf16 v[40:43], v[212:215], v[196:199], v[40:43]
	v_mfma_f32_16x16x32_bf16 v[36:39], v[216:219], v[196:199], v[36:39]
	v_mfma_f32_16x16x32_bf16 v[32:35], v[220:223], v[196:199], v[32:35]
	s_waitcnt vmcnt(2)
	ds_write_b128 v156, v[116:119] offset:53248
	v_mfma_f32_16x16x32_bf16 v[28:31], v[208:211], v[200:203], v[28:31]
	v_mfma_f32_16x16x32_bf16 v[24:27], v[212:215], v[200:203], v[24:27]
	v_mfma_f32_16x16x32_bf16 v[20:23], v[216:219], v[200:203], v[20:23]
	v_mfma_f32_16x16x32_bf16 v[16:19], v[220:223], v[200:203], v[16:19]
	s_waitcnt vmcnt(1)
	ds_write_b128 v156, v[120:123] offset:57344
	v_mfma_f32_16x16x32_bf16 v[12:15], v[208:211], v[204:207], v[12:15]
	v_mfma_f32_16x16x32_bf16 v[8:11], v[212:215], v[204:207], v[8:11]
	v_mfma_f32_16x16x32_bf16 v[4:7], v[216:219], v[204:207], v[4:7]
	v_mfma_f32_16x16x32_bf16 v[0:3], v[220:223], v[204:207], v[0:3]
	s_waitcnt vmcnt(0)
	ds_write_b128 v156, v[124:127] offset:61440
	s_waitcnt lgkmcnt(0)
	s_barrier
	ds_read_b128 v[112:115], v181 offset:49152
	ds_read_b128 v[116:119], v181 offset:51200
	ds_read_b128 v[120:123], v181 offset:53248
	ds_read_b128 v[124:127], v181 offset:55296
	ds_read_b128 v[96:99], v180 offset:32768
	ds_read_b128 v[100:103], v180 offset:34816
	s_min_u32 s24, s3, 12
	s_lshl_b32 s92, s24, 7
	ds_read_b128 v[104:107], v180 offset:36864
	v_lshl_add_u64 v[224:225], v[138:139], 0, s[92:93]
	ds_read_b128 v[108:111], v180 offset:38912
	ds_read_b128 v[192:195], v182 offset:32768
	ds_read_b128 v[196:199], v182 offset:34816
	ds_read_b128 v[200:203], v182 offset:36864
	ds_read_b128 v[204:207], v182 offset:38912
	ds_read_b128 v[208:211], v186 offset:49152
	ds_read_b128 v[212:215], v186 offset:51200
	ds_read_b128 v[216:219], v186 offset:53248
	ds_read_b128 v[220:223], v186 offset:55296
	s_waitcnt lgkmcnt(11)
	v_mfma_f32_16x16x32_bf16 v[60:63], v[112:115], v[96:99], v[60:63]
	v_mfma_f32_16x16x32_bf16 v[56:59], v[116:119], v[96:99], v[56:59]
	v_mfma_f32_16x16x32_bf16 v[52:55], v[120:123], v[96:99], v[52:55]
	v_mfma_f32_16x16x32_bf16 v[48:51], v[124:127], v[96:99], v[48:51]
	v_add_co_u32_e32 v64, vcc, s11, v224
	s_waitcnt lgkmcnt(10)
	v_mfma_f32_16x16x32_bf16 v[44:47], v[112:115], v[100:103], v[44:47]
	v_addc_co_u32_e32 v65, vcc, 0, v225, vcc
	v_mfma_f32_16x16x32_bf16 v[40:43], v[116:119], v[100:103], v[40:43]
	v_mfma_f32_16x16x32_bf16 v[36:39], v[120:123], v[100:103], v[36:39]
	v_mfma_f32_16x16x32_bf16 v[32:35], v[124:127], v[100:103], v[32:35]
	v_add_co_u32_e32 v64, vcc, s33, v224
	s_nop 1
	v_addc_co_u32_e32 v65, vcc, 0, v225, vcc
	s_waitcnt lgkmcnt(9)
	v_mfma_f32_16x16x32_bf16 v[28:31], v[112:115], v[104:107], v[28:31]
	v_mfma_f32_16x16x32_bf16 v[24:27], v[116:119], v[104:107], v[24:27]
	v_mfma_f32_16x16x32_bf16 v[20:23], v[120:123], v[104:107], v[20:23]
	v_mfma_f32_16x16x32_bf16 v[16:19], v[124:127], v[104:107], v[16:19]
	v_add_co_u32_e32 v64, vcc, s59, v224
	s_nop 1
	v_addc_co_u32_e32 v65, vcc, 0, v225, vcc
	s_waitcnt lgkmcnt(8)
	v_mfma_f32_16x16x32_bf16 v[12:15], v[112:115], v[108:111], v[12:15]
	v_mfma_f32_16x16x32_bf16 v[8:11], v[116:119], v[108:111], v[8:11]
	v_mfma_f32_16x16x32_bf16 v[4:7], v[120:123], v[108:111], v[4:7]
	v_mfma_f32_16x16x32_bf16 v[0:3], v[124:127], v[108:111], v[0:3]
	v_lshl_add_u64 v[64:65], v[140:141], 0, s[92:93]
	v_add_co_u32_e32 v66, vcc, s11, v64
	s_nop 1
	v_addc_co_u32_e32 v67, vcc, 0, v65, vcc
	s_waitcnt lgkmcnt(3)
	v_mfma_f32_16x16x32_bf16 v[60:63], v[208:211], v[192:195], v[60:63]
	s_waitcnt lgkmcnt(2)
	v_mfma_f32_16x16x32_bf16 v[56:59], v[212:215], v[192:195], v[56:59]
	s_waitcnt lgkmcnt(1)
	v_mfma_f32_16x16x32_bf16 v[52:55], v[216:219], v[192:195], v[52:55]
	s_waitcnt lgkmcnt(0)
	v_mfma_f32_16x16x32_bf16 v[48:51], v[220:223], v[192:195], v[48:51]
	v_mfma_f32_16x16x32_bf16 v[44:47], v[208:211], v[196:199], v[44:47]
	v_mfma_f32_16x16x32_bf16 v[40:43], v[212:215], v[196:199], v[40:43]
	v_mfma_f32_16x16x32_bf16 v[36:39], v[216:219], v[196:199], v[36:39]
	v_mfma_f32_16x16x32_bf16 v[32:35], v[220:223], v[196:199], v[32:35]
	v_add_co_u32_e32 v66, vcc, s33, v64
	s_nop 1
	v_addc_co_u32_e32 v67, vcc, 0, v65, vcc
	v_add_co_u32_e32 v64, vcc, s59, v64
	v_mfma_f32_16x16x32_bf16 v[28:31], v[208:211], v[200:203], v[28:31]
	s_nop 0
	v_addc_co_u32_e32 v65, vcc, 0, v65, vcc
	v_mfma_f32_16x16x32_bf16 v[24:27], v[212:215], v[200:203], v[24:27]
	v_mfma_f32_16x16x32_bf16 v[20:23], v[216:219], v[200:203], v[20:23]
	v_mfma_f32_16x16x32_bf16 v[16:19], v[220:223], v[200:203], v[16:19]
	v_mfma_f32_16x16x32_bf16 v[12:15], v[208:211], v[204:207], v[12:15]
	v_mfma_f32_16x16x32_bf16 v[8:11], v[212:215], v[204:207], v[8:11]
	v_mfma_f32_16x16x32_bf16 v[4:7], v[216:219], v[204:207], v[4:7]
	v_mfma_f32_16x16x32_bf16 v[0:3], v[220:223], v[204:207], v[0:3]
	s_mov_b32 s24, s3
	s_waitcnt lgkmcnt(0)
	s_barrier
	s_and_saveexec_b64 s[24:25], s[36:37]
	s_cbranch_execz .LBB0_82
	v_add_f32_e32 v64, 0, v128
	v_add_f32_e32 v64, v64, v157
	v_add_f32_e32 v64, v64, v158
	v_add_f32_e32 v64, v64, v159
	v_add_f32_e32 v64, v64, v160
	v_add_f32_e32 v64, v64, v161
	v_add_f32_e32 v64, v64, v162
	v_add_f32_e32 v64, v64, v163
	v_add_f32_e32 v64, v64, v164
	v_add_f32_e32 v64, v64, v165
	v_add_f32_e32 v64, v64, v168
	v_add_f32_e32 v64, v64, v175
	v_add_f32_e32 v64, v64, v179
	v_add_f32_e32 v64, v64, v183
	v_add_f32_e32 v64, v64, v190
	v_add_f32_e32 v64, v64, v191
	v_fmamk_f32 v64, v64, 0x3a800000, v167
	s_mov_b32 s3, 0x800000
	v_mul_f32_e32 v65, 0x4b800000, v64
	v_cmp_gt_f32_e32 vcc, s3, v64
	s_nop 1
	v_cndmask_b32_e32 v64, v64, v65, vcc
	v_rsq_f32_e32 v64, v64
	s_nop 0
	v_mul_f32_e32 v65, 0x45800000, v64
	v_cndmask_b32_e32 v64, v64, v65, vcc
	ds_write_b32 v155, v64
	s_branch .LBB0_82

.Ltail92:
	s_add_i32 s0, s1, 2
	v_add_u32_e32 v111, v104, v105
	ds_read_b128 v[136:139], v111 offset:16384
	ds_read_b128 v[140:143], v111 offset:18432
	ds_read_b128 v[144:147], v111 offset:20480
	ds_read_b128 v[148:151], v111 offset:22528
	v_add_u32_e32 v110, v103, v105
	ds_read_b128 v[116:119], v110
	s_add_i32 s1, s1, 4
	ds_read_b128 v[120:123], v110 offset:2048
	s_min_u32 s1, s1, 15
	v_add_u32_e32 v113, v104, v114
	s_lshl_b32 s92, s1, 7
	ds_read_b128 v[124:127], v110 offset:4096
	v_add_u32_e32 v112, v103, v114
	ds_read_b128 v[194:197], v113 offset:16384
	ds_read_b128 v[198:201], v113 offset:18432
	ds_read_b128 v[202:205], v113 offset:20480
	ds_read_b128 v[206:209], v113 offset:22528
	v_lshl_add_u64 v[164:165], v[98:99], 0, s[92:93]
	ds_read_b128 v[132:135], v110 offset:6144
	ds_read_b128 v[152:155], v112
	ds_read_b128 v[156:159], v112 offset:2048
	ds_read_b128 v[160:163], v112 offset:4096
	ds_read_b128 v[190:193], v112 offset:6144
	s_waitcnt lgkmcnt(11)
	v_mfma_f32_16x16x32_bf16 v[92:95], v[136:139], v[116:119], v[92:95]
	v_mfma_f32_16x16x32_bf16 v[88:91], v[140:143], v[116:119], v[88:91]
	v_mfma_f32_16x16x32_bf16 v[52:55], v[144:147], v[116:119], v[52:55]
	v_mfma_f32_16x16x32_bf16 v[48:51], v[148:151], v[116:119], v[48:51]
	s_waitcnt vmcnt(7)
	ds_write_b128 v109, v[56:59] offset:32768
	v_add_co_u32_e32 v56, vcc, s11, v164
	s_waitcnt lgkmcnt(11)
	v_mfma_f32_16x16x32_bf16 v[44:47], v[136:139], v[120:123], v[44:47]
	v_addc_co_u32_e32 v57, vcc, 0, v165, vcc
	v_mfma_f32_16x16x32_bf16 v[40:43], v[140:143], v[120:123], v[40:43]
	v_mfma_f32_16x16x32_bf16 v[36:39], v[144:147], v[120:123], v[36:39]
	v_mfma_f32_16x16x32_bf16 v[32:35], v[148:151], v[120:123], v[32:35]
	v_add_co_u32_e32 v56, vcc, s33, v164
	s_waitcnt vmcnt(6)
	ds_write_b128 v109, v[60:63] offset:36864
	s_nop 0
	v_addc_co_u32_e32 v57, vcc, 0, v165, vcc
	s_waitcnt lgkmcnt(11)
	v_mfma_f32_16x16x32_bf16 v[28:31], v[136:139], v[124:127], v[28:31]
	v_mfma_f32_16x16x32_bf16 v[24:27], v[140:143], v[124:127], v[24:27]
	v_mfma_f32_16x16x32_bf16 v[20:23], v[144:147], v[124:127], v[20:23]
	v_mfma_f32_16x16x32_bf16 v[16:19], v[148:151], v[124:127], v[16:19]
	v_add_co_u32_e32 v56, vcc, s59, v164
	s_waitcnt vmcnt(5)
	ds_write_b128 v109, v[64:67] offset:40960
	s_nop 0
	v_addc_co_u32_e32 v57, vcc, 0, v165, vcc
	v_lshl_add_u64 v[64:65], v[100:101], 0, s[92:93]
	v_add_co_u32_e32 v66, vcc, s11, v64
	s_waitcnt lgkmcnt(7)
	v_mfma_f32_16x16x32_bf16 v[12:15], v[136:139], v[132:135], v[12:15]
	v_addc_co_u32_e32 v67, vcc, 0, v65, vcc
	v_mfma_f32_16x16x32_bf16 v[8:11], v[140:143], v[132:135], v[8:11]
	v_mfma_f32_16x16x32_bf16 v[4:7], v[144:147], v[132:135], v[4:7]
	v_mfma_f32_16x16x32_bf16 v[0:3], v[148:151], v[132:135], v[0:3]
	s_waitcnt vmcnt(4)
	ds_write_b128 v109, v[72:75] offset:45056
	s_waitcnt lgkmcnt(7)
	v_mfma_f32_16x16x32_bf16 v[56:59], v[194:197], v[152:155], v[92:95]
	v_mfma_f32_16x16x32_bf16 v[60:63], v[198:201], v[152:155], v[88:91]
	v_mfma_f32_16x16x32_bf16 v[52:55], v[202:205], v[152:155], v[52:55]
	v_mfma_f32_16x16x32_bf16 v[48:51], v[206:209], v[152:155], v[48:51]
	s_waitcnt vmcnt(3)
	ds_write_b128 v109, v[68:71] offset:49152
	s_waitcnt lgkmcnt(7)
	v_mfma_f32_16x16x32_bf16 v[44:47], v[194:197], v[156:159], v[44:47]
	v_mfma_f32_16x16x32_bf16 v[40:43], v[198:201], v[156:159], v[40:43]
	v_mfma_f32_16x16x32_bf16 v[36:39], v[202:205], v[156:159], v[36:39]
	v_mfma_f32_16x16x32_bf16 v[32:35], v[206:209], v[156:159], v[32:35]
	v_add_co_u32_e32 v66, vcc, s33, v64
	s_waitcnt vmcnt(2)
	ds_write_b128 v109, v[76:79] offset:53248
	v_addc_co_u32_e32 v67, vcc, 0, v65, vcc
	v_add_co_u32_e32 v64, vcc, s59, v64
	s_waitcnt lgkmcnt(7)
	v_mfma_f32_16x16x32_bf16 v[28:31], v[194:197], v[160:163], v[28:31]
	v_addc_co_u32_e32 v65, vcc, 0, v65, vcc
	v_mfma_f32_16x16x32_bf16 v[24:27], v[198:201], v[160:163], v[24:27]
	v_mfma_f32_16x16x32_bf16 v[20:23], v[202:205], v[160:163], v[20:23]
	v_mfma_f32_16x16x32_bf16 v[16:19], v[206:209], v[160:163], v[16:19]
	s_waitcnt vmcnt(1)
	ds_write_b128 v109, v[80:83] offset:57344
	s_waitcnt lgkmcnt(7)
	v_mfma_f32_16x16x32_bf16 v[12:15], v[194:197], v[190:193], v[12:15]
	v_mfma_f32_16x16x32_bf16 v[8:11], v[198:201], v[190:193], v[8:11]
	v_mfma_f32_16x16x32_bf16 v[4:7], v[202:205], v[190:193], v[4:7]
	v_mfma_f32_16x16x32_bf16 v[0:3], v[206:209], v[190:193], v[0:3]
	s_waitcnt vmcnt(0)
	ds_write_b128 v109, v[84:87] offset:61440
	s_waitcnt lgkmcnt(0)
	s_barrier
	ds_read_b128 v[84:87], v111 offset:51200
	ds_read_b128 v[80:83], v111 offset:49152
	ds_read_b128 v[88:91], v111 offset:53248
	ds_read_b128 v[92:95], v111 offset:55296
	ds_read_b128 v[64:67], v110 offset:32768
	s_min_u32 s1, s0, 12
	s_lshl_b32 s92, s1, 7
	ds_read_b128 v[68:71], v110 offset:34816
	v_lshl_add_u64 v[164:165], v[98:99], 0, s[92:93]
	ds_read_b128 v[72:75], v110 offset:36864
	ds_read_b128 v[76:79], v110 offset:38912
	ds_read_b128 v[152:155], v112 offset:32768
	ds_read_b128 v[156:159], v112 offset:34816
	ds_read_b128 v[160:163], v112 offset:36864
	ds_read_b128 v[190:193], v112 offset:38912
	ds_read_b128 v[194:197], v113 offset:49152
	ds_read_b128 v[198:201], v113 offset:51200
	ds_read_b128 v[202:205], v113 offset:53248
	ds_read_b128 v[206:209], v113 offset:55296
	s_waitcnt lgkmcnt(11)
	v_mfma_f32_16x16x32_bf16 v[214:217], v[84:87], v[64:67], v[60:63]
	v_mfma_f32_16x16x32_bf16 v[210:213], v[80:83], v[64:67], v[56:59]
	s_nop 1
	v_add_co_u32_e32 v60, vcc, s11, v164
	s_nop 1
	v_addc_co_u32_e32 v61, vcc, 0, v165, vcc
	v_mfma_f32_16x16x32_bf16 v[52:55], v[88:91], v[64:67], v[52:55]
	v_mfma_f32_16x16x32_bf16 v[48:51], v[92:95], v[64:67], v[48:51]
	v_add_co_u32_e32 v64, vcc, s33, v164
	s_nop 0
	s_nop 0
	v_addc_co_u32_e32 v65, vcc, 0, v165, vcc
	s_waitcnt lgkmcnt(10)
	v_mfma_f32_16x16x32_bf16 v[44:47], v[80:83], v[68:71], v[44:47]
	v_mfma_f32_16x16x32_bf16 v[40:43], v[84:87], v[68:71], v[40:43]
	v_mfma_f32_16x16x32_bf16 v[36:39], v[88:91], v[68:71], v[36:39]
	v_mfma_f32_16x16x32_bf16 v[32:35], v[92:95], v[68:71], v[32:35]
	v_add_co_u32_e32 v68, vcc, s59, v164
	s_waitcnt lgkmcnt(9)
	v_mfma_f32_16x16x32_bf16 v[28:31], v[80:83], v[72:75], v[28:31]
	v_addc_co_u32_e32 v69, vcc, 0, v165, vcc
	v_mfma_f32_16x16x32_bf16 v[24:27], v[84:87], v[72:75], v[24:27]
	v_mfma_f32_16x16x32_bf16 v[20:23], v[88:91], v[72:75], v[20:23]
	v_mfma_f32_16x16x32_bf16 v[16:19], v[92:95], v[72:75], v[16:19]
	s_waitcnt lgkmcnt(8)
	v_mfma_f32_16x16x32_bf16 v[8:11], v[84:87], v[76:79], v[8:11]
	v_lshl_add_u64 v[84:85], v[100:101], 0, s[92:93]
	v_mfma_f32_16x16x32_bf16 v[12:15], v[80:83], v[76:79], v[12:15]
	v_mfma_f32_16x16x32_bf16 v[4:7], v[88:91], v[76:79], v[4:7]
	v_mfma_f32_16x16x32_bf16 v[0:3], v[92:95], v[76:79], v[0:3]
	v_add_co_u32_e32 v76, vcc, s11, v84
	s_nop 0
	s_nop 0
	v_addc_co_u32_e32 v77, vcc, 0, v85, vcc
	v_add_co_u32_e32 v80, vcc, s33, v84
	s_nop 1
	v_addc_co_u32_e32 v81, vcc, 0, v85, vcc
	s_waitcnt lgkmcnt(3)
	v_mfma_f32_16x16x32_bf16 v[92:95], v[194:197], v[152:155], v[210:213]
	s_waitcnt lgkmcnt(2)
	v_mfma_f32_16x16x32_bf16 v[88:91], v[198:201], v[152:155], v[214:217]
	s_waitcnt lgkmcnt(1)
	v_mfma_f32_16x16x32_bf16 v[52:55], v[202:205], v[152:155], v[52:55]
	s_waitcnt lgkmcnt(0)
	v_mfma_f32_16x16x32_bf16 v[48:51], v[206:209], v[152:155], v[48:51]
	v_add_co_u32_e32 v84, vcc, s59, v84
	s_nop 1
	v_addc_co_u32_e32 v85, vcc, 0, v85, vcc
	v_mfma_f32_16x16x32_bf16 v[44:47], v[194:197], v[156:159], v[44:47]
	v_mfma_f32_16x16x32_bf16 v[40:43], v[198:201], v[156:159], v[40:43]
	v_mfma_f32_16x16x32_bf16 v[36:39], v[202:205], v[156:159], v[36:39]
	v_mfma_f32_16x16x32_bf16 v[32:35], v[206:209], v[156:159], v[32:35]
	v_mfma_f32_16x16x32_bf16 v[28:31], v[194:197], v[160:163], v[28:31]
	v_mfma_f32_16x16x32_bf16 v[24:27], v[198:201], v[160:163], v[24:27]
	v_mfma_f32_16x16x32_bf16 v[20:23], v[202:205], v[160:163], v[20:23]
	v_mfma_f32_16x16x32_bf16 v[16:19], v[206:209], v[160:163], v[16:19]
	v_mfma_f32_16x16x32_bf16 v[12:15], v[194:197], v[190:193], v[12:15]
	v_mfma_f32_16x16x32_bf16 v[8:11], v[198:201], v[190:193], v[8:11]
	v_mfma_f32_16x16x32_bf16 v[4:7], v[202:205], v[190:193], v[4:7]
	v_mfma_f32_16x16x32_bf16 v[0:3], v[206:209], v[190:193], v[0:3]
	s_mov_b32 s1, s0
	s_waitcnt lgkmcnt(0)
	s_barrier
	s_mul_i32 s0, s69, 0x12000
	v_readlane_b32 s16, v250, 25
	s_add_u32 s24, s16, s0
	v_readlane_b32 s0, v251, 5
	v_lshlrev_b32_e32 v114, 6, v102
	v_readlane_b32 s17, v250, 26
	s_waitcnt vmcnt(5)
	v_add_u32_e32 v64, s0, v108
	v_readlane_b32 s0, v251, 6
	v_add_u32_e32 v56, 0xffffe000, v64
	v_or_b32_e32 v62, v64, v107
	v_or_b32_e32 v65, s0, v114
	v_lshrrev_b32_e32 v56, 10, v56
	s_movk_i32 s0, 0x1800
	v_mad_u32_u24 v56, v56, s0, s0
	v_cmp_lt_i32_e32 vcc, s13, v62
	s_addc_u32 s25, s17, 0
	v_lshlrev_b32_e32 v115, 2, v97
	v_cndmask_b32_e32 v56, 0, v56, vcc
	s_add_u32 s40, s24, 0x2000
	v_or_b32_e32 v58, v65, v115
	v_ashrrev_i32_e32 v57, 31, v56
	s_addc_u32 s41, s25, 0
	s_waitcnt vmcnt(4)
	v_lshlrev_b64 v[74:75], 2, v[56:57]
	v_ashrrev_i32_e32 v59, 31, v58
	v_ashrrev_i32_e32 v63, 31, v62
	v_lshl_add_u64 v[56:57], s[40:41], 0, v[74:75]
	v_lshlrev_b64 v[60:61], 2, v[58:59]
	v_readlane_b32 s0, v250, 15
	s_waitcnt vmcnt(1)
	v_lshl_add_u64 v[82:83], v[56:57], 0, v[60:61]
	v_lshlrev_b64 v[56:57], 12, v[62:63]
	v_readlane_b32 s1, v250, 16
	v_readlane_b32 s16, v250, 21
	v_lshlrev_b64 v[78:79], 11, v[62:63]
	v_lshl_add_u64 v[56:57], s[0:1], 0, v[56:57]
	s_waitcnt vmcnt(0)
	v_lshl_add_u64 v[84:85], v[56:57], 0, v[60:61]
	global_load_dwordx4 v[116:119], v[82:83], off
	global_load_dwordx4 v[120:123], v[82:83], off offset:64
	global_load_dwordx4 v[124:127], v[82:83], off offset:128
	global_load_dwordx4 v[132:135], v[82:83], off offset:192
	global_load_dwordx4 v[190:193], v[84:85], off
	global_load_dwordx4 v[194:197], v[84:85], off offset:64
	global_load_dwordx4 v[198:201], v[84:85], off offset:128
	global_load_dwordx4 v[202:205], v[84:85], off offset:192
	v_add_co_u32_e32 v164, vcc, 0x10000, v84
	s_nop 1
	v_addc_co_u32_e32 v165, vcc, 0, v85, vcc
	v_add_co_u32_e32 v222, vcc, 0x20000, v84
	s_nop 1
	v_addc_co_u32_e32 v223, vcc, 0, v85, vcc
	v_add_co_u32_e32 v224, vcc, 0x30000, v84
	s_nop 1
	v_addc_co_u32_e32 v225, vcc, 0, v85, vcc
	global_load_dwordx4 v[206:209], v[164:165], off
	global_load_dwordx4 v[210:213], v[164:165], off offset:64
	global_load_dwordx4 v[214:217], v[164:165], off offset:128
	global_load_dwordx4 v[218:221], v[164:165], off offset:192
	s_lshl_b32 s0, s69, 12
	v_readlane_b32 s68, v250, 41
	v_readlane_b32 s72, v250, 45
	v_readlane_b32 s73, v250, 46
	s_add_u32 s0, s72, s0
	s_addc_u32 s1, s73, 0
	s_add_u32 s42, s24, 0x4000
	s_addc_u32 s43, s25, 0
	v_lshl_add_u64 v[74:75], s[42:43], 0, v[74:75]
	v_lshl_add_u64 v[56:57], s[0:1], 0, v[60:61]
	v_lshl_add_u64 v[86:87], v[74:75], 0, v[60:61]
	v_readlane_b32 s17, v250, 22
	v_readlane_b32 s69, v250, 42
	v_readlane_b32 s69, v254, 49
	v_lshl_add_u64 v[78:79], s[16:17], 0, v[78:79]
	s_mul_i32 s24, s69, 0x140000
	s_add_u32 s24, s86, s24
	v_lshrrev_b32_e32 v65, 6, v65
	s_mov_b32 s16, 0xa000
	s_addc_u32 s25, s87, 0
	s_add_u32 s26, s24, 0xaf1a000
	s_addc_u32 s27, s25, 0
	v_cmp_eq_u32_e64 s[36:37], 0, v97
	v_readlane_b32 s70, v250, 43
	v_readlane_b32 s71, v250, 44
	v_readlane_b32 s74, v250, 47
	v_readlane_b32 s75, v250, 48
	v_readlane_b32 s76, v250, 49
	v_readlane_b32 s77, v250, 50
	v_readlane_b32 s78, v250, 51
	v_readlane_b32 s79, v250, 52
	v_readlane_b32 s80, v250, 53
	v_readlane_b32 s81, v250, 54
	v_readlane_b32 s82, v250, 55
	v_readlane_b32 s83, v250, 56
	s_waitcnt vmcnt(4)
	v_pk_fma_f32 v[68:69], v[94:95], v[118:119], v[192:193]
	v_pk_fma_f32 v[66:67], v[92:93], v[116:117], v[190:191]
	global_store_dwordx4 v[84:85], v[66:69], off
	global_load_dwordx4 v[136:139], v[56:57], off
	global_load_dwordx4 v[140:143], v[56:57], off offset:64
	global_load_dwordx4 v[144:147], v[56:57], off offset:128
	global_load_dwordx4 v[148:151], v[56:57], off offset:192
	global_load_dwordx4 v[152:155], v[86:87], off
	global_load_dwordx4 v[156:159], v[86:87], off offset:64
	global_load_dwordx4 v[160:163], v[86:87], off offset:128
	global_load_dwordx4 v[180:183], v[86:87], off offset:192
	v_lshl_add_u64 v[92:93], v[58:59], 1, v[78:79]
	s_waitcnt vmcnt(0)
	v_pk_mul_f32 v[72:73], v[68:69], v[138:139]
	v_pk_mul_f32 v[70:71], v[66:67], v[136:137]
	s_waitcnt vmcnt(0)
	v_pk_add_f32 v[76:77], v[154:155], 1.0 op_sel_hi:[1,0]
	v_pk_add_f32 v[74:75], v[152:153], 1.0 op_sel_hi:[1,0]
	v_pk_mul_f32 v[72:73], v[72:73], v[76:77]
	v_pk_mul_f32 v[70:71], v[70:71], v[74:75]
	v_and_b32_sdwa v77, v71, v170 dst_sel:DWORD dst_unused:UNUSED_PAD src0_sel:WORD_1 src1_sel:DWORD
	v_and_b32_sdwa v75, v70, v170 dst_sel:DWORD dst_unused:UNUSED_PAD src0_sel:WORD_1 src1_sel:DWORD
	v_add3_u32 v71, v71, v77, s56
	v_add3_u32 v70, v70, v75, s56
	v_and_b32_e32 v74, 0xffff0000, v71
	v_cvt_pk_bf16_f32 v71, v72, v73
	v_or_b32_sdwa v70, v74, v70 dst_sel:DWORD dst_unused:UNUSED_PAD src0_sel:DWORD src1_sel:WORD_1
	global_store_dwordx2 v[92:93], v[70:71], off
	s_nop 0
	s_waitcnt vmcnt(0)
	v_pk_fma_f32 v[72:73], v[90:91], v[122:123], v[196:197]
	v_pk_fma_f32 v[70:71], v[88:89], v[120:121], v[194:195]
	global_store_dwordx4 v[84:85], v[70:73], off offset:64
	v_pk_mul_f32 v[76:77], v[72:73], v[142:143]
	v_pk_mul_f32 v[74:75], v[70:71], v[140:141]
	v_pk_add_f32 v[80:81], v[158:159], 1.0 op_sel_hi:[1,0]
	v_pk_add_f32 v[78:79], v[156:157], 1.0 op_sel_hi:[1,0]
	v_pk_mul_f32 v[76:77], v[76:77], v[80:81]
	v_pk_mul_f32 v[74:75], v[74:75], v[78:79]
	v_and_b32_sdwa v81, v75, v170 dst_sel:DWORD dst_unused:UNUSED_PAD src0_sel:WORD_1 src1_sel:DWORD
	v_and_b32_sdwa v79, v74, v170 dst_sel:DWORD dst_unused:UNUSED_PAD src0_sel:WORD_1 src1_sel:DWORD
	v_add3_u32 v75, v75, v81, s56
	v_add3_u32 v74, v74, v79, s56
	v_and_b32_e32 v78, 0xffff0000, v75
	v_cvt_pk_bf16_f32 v75, v76, v77
	v_or_b32_sdwa v74, v78, v74 dst_sel:DWORD dst_unused:UNUSED_PAD src0_sel:DWORD src1_sel:WORD_1
	global_store_dwordx2 v[92:93], v[74:75], off offset:32
	s_nop 0
	v_pk_fma_f32 v[54:55], v[54:55], v[126:127], v[200:201]
	v_pk_fma_f32 v[52:53], v[52:53], v[124:125], v[198:199]
	global_store_dwordx4 v[84:85], v[52:55], off offset:128
	v_pk_mul_f32 v[76:77], v[54:55], v[146:147]
	v_pk_mul_f32 v[74:75], v[52:53], v[144:145]
	v_pk_add_f32 v[80:81], v[162:163], 1.0 op_sel_hi:[1,0]
	v_pk_add_f32 v[78:79], v[160:161], 1.0 op_sel_hi:[1,0]
	v_pk_mul_f32 v[76:77], v[76:77], v[80:81]
	v_pk_mul_f32 v[74:75], v[74:75], v[78:79]
	v_and_b32_sdwa v81, v75, v170 dst_sel:DWORD dst_unused:UNUSED_PAD src0_sel:WORD_1 src1_sel:DWORD
	v_and_b32_sdwa v79, v74, v170 dst_sel:DWORD dst_unused:UNUSED_PAD src0_sel:WORD_1 src1_sel:DWORD
	v_add3_u32 v75, v75, v81, s56
	v_add3_u32 v74, v74, v79, s56
	v_and_b32_e32 v78, 0xffff0000, v75
	v_cvt_pk_bf16_f32 v75, v76, v77
	v_or_b32_sdwa v74, v78, v74 dst_sel:DWORD dst_unused:UNUSED_PAD src0_sel:DWORD src1_sel:WORD_1
	global_store_dwordx2 v[92:93], v[74:75], off offset:64
	s_nop 0
	v_pk_fma_f32 v[76:77], v[50:51], v[134:135], v[204:205]
	v_pk_fma_f32 v[74:75], v[48:49], v[132:133], v[202:203]
	global_store_dwordx4 v[84:85], v[74:77], off offset:192
	s_nop 0
	v_mbcnt_lo_u32_b32 v48, -1, 0
	v_mbcnt_hi_u32_b32 v48, -1, v48
	v_and_b32_e32 v50, 64, v48
	v_xor_b32_e32 v49, 16, v48
	v_add_u32_e32 v50, 64, v50
	v_xor_b32_e32 v51, 32, v48
	v_cmp_lt_i32_e32 vcc, v49, v50
	s_nop 1
	v_cndmask_b32_e32 v49, v48, v49, vcc
	v_cmp_lt_i32_e32 vcc, v51, v50
	v_lshlrev_b32_e32 v105, 2, v49
	s_nop 0
	v_cndmask_b32_e32 v50, v48, v51, vcc
	v_lshlrev_b32_e32 v104, 2, v50
	v_mul_f32_e32 v50, v67, v67
	v_mul_f32_e32 v51, v71, v71
	v_fmac_f32_e32 v50, v66, v66
	v_fmac_f32_e32 v51, v70, v70
	v_fmac_f32_e32 v50, v68, v68
	v_fmac_f32_e32 v51, v72, v72
	v_fmac_f32_e32 v50, v69, v69
	v_fmac_f32_e32 v51, v73, v73
	v_add_f32_e32 v50, v50, v51
	v_mul_f32_e32 v51, v53, v53
	v_fmac_f32_e32 v51, v52, v52
	v_fmac_f32_e32 v51, v54, v54
	v_fmac_f32_e32 v51, v55, v55
	v_add_f32_e32 v50, v50, v51
	v_mul_f32_e32 v51, v75, v75
	v_fmac_f32_e32 v51, v74, v74
	v_fmac_f32_e32 v51, v76, v76
	v_fmac_f32_e32 v51, v77, v77
	v_add_f32_e32 v50, v50, v51
	ds_bpermute_b32 v51, v105, v50
	v_mul_lo_u32 v48, v65, s16
	v_ashrrev_i32_e32 v49, 31, v48
	v_lshl_add_u64 v[48:49], s[26:27], 0, v[48:49]
	v_lshl_add_u64 v[48:49], v[62:63], 2, v[48:49]
	s_waitcnt lgkmcnt(0)
	v_add_f32_e32 v50, v50, v51
	ds_bpermute_b32 v51, v104, v50
	v_pk_mul_f32 v[52:53], v[76:77], v[150:151]
	v_pk_mul_f32 v[54:55], v[74:75], v[148:149]
	v_pk_add_f32 v[66:67], v[182:183], 1.0 op_sel_hi:[1,0]
	v_pk_add_f32 v[68:69], v[180:181], 1.0 op_sel_hi:[1,0]
	v_pk_mul_f32 v[52:53], v[52:53], v[66:67]
	v_pk_mul_f32 v[54:55], v[54:55], v[68:69]
	v_cvt_pk_bf16_f32 v53, v52, v53
	v_cvt_pk_bf16_f32 v52, v54, v55
	global_store_dwordx2 v[92:93], v[52:53], off offset:96
	s_and_saveexec_b64 s[24:25], s[36:37]
	s_cbranch_execz .LBB0_95
	s_waitcnt lgkmcnt(0)
	v_add_f32_e32 v50, v50, v51
	global_store_dword v[48:49], v50, off

.Ltail106:
	s_add_i32 s29, s44, 2
	ds_read_b128 v[136:139], v111 offset:16384
	ds_read_b128 v[140:143], v111 offset:18432
	ds_read_b128 v[144:147], v111 offset:20480
	ds_read_b128 v[148:151], v111 offset:22528
	ds_read_b128 v[116:119], v110
	s_add_i32 s44, s44, 4
	ds_read_b128 v[120:123], v110 offset:2048
	s_min_u32 s44, s44, 15
	s_lshl_b32 s92, s44, 7
	ds_read_b128 v[124:127], v110 offset:4096
	ds_read_b128 v[194:197], v113 offset:16384
	ds_read_b128 v[198:201], v113 offset:18432
	ds_read_b128 v[202:205], v113 offset:20480
	ds_read_b128 v[206:209], v113 offset:22528
	v_lshl_add_u64 v[164:165], v[100:101], 0, s[92:93]
	ds_read_b128 v[132:135], v110 offset:6144
	ds_read_b128 v[152:155], v112
	ds_read_b128 v[156:159], v112 offset:2048
	ds_read_b128 v[160:163], v112 offset:4096
	ds_read_b128 v[190:193], v112 offset:6144
	s_waitcnt lgkmcnt(11)
	v_mfma_f32_16x16x32_bf16 v[92:95], v[136:139], v[116:119], v[92:95]
	v_mfma_f32_16x16x32_bf16 v[88:91], v[140:143], v[116:119], v[88:91]
	v_mfma_f32_16x16x32_bf16 v[56:59], v[144:147], v[116:119], v[56:59]
	v_mfma_f32_16x16x32_bf16 v[48:51], v[148:151], v[116:119], v[48:51]
	s_waitcnt vmcnt(7)
	ds_write_b128 v109, v[52:55] offset:32768
	v_add_co_u32_e32 v52, vcc, s11, v164
	s_waitcnt lgkmcnt(11)
	v_mfma_f32_16x16x32_bf16 v[44:47], v[136:139], v[120:123], v[44:47]
	v_addc_co_u32_e32 v53, vcc, 0, v165, vcc
	v_mfma_f32_16x16x32_bf16 v[40:43], v[140:143], v[120:123], v[40:43]
	v_mfma_f32_16x16x32_bf16 v[36:39], v[144:147], v[120:123], v[36:39]
	v_mfma_f32_16x16x32_bf16 v[32:35], v[148:151], v[120:123], v[32:35]
	v_add_co_u32_e32 v52, vcc, s33, v164
	s_waitcnt vmcnt(6)
	ds_write_b128 v109, v[60:63] offset:36864
	s_nop 0
	v_addc_co_u32_e32 v53, vcc, 0, v165, vcc
	s_waitcnt lgkmcnt(11)
	v_mfma_f32_16x16x32_bf16 v[28:31], v[136:139], v[124:127], v[28:31]
	v_mfma_f32_16x16x32_bf16 v[24:27], v[140:143], v[124:127], v[24:27]
	v_mfma_f32_16x16x32_bf16 v[20:23], v[144:147], v[124:127], v[20:23]
	v_mfma_f32_16x16x32_bf16 v[16:19], v[148:151], v[124:127], v[16:19]
	v_add_co_u32_e32 v52, vcc, s59, v164
	s_waitcnt vmcnt(5)
	ds_write_b128 v109, v[64:67] offset:40960
	s_nop 0
	v_addc_co_u32_e32 v53, vcc, 0, v165, vcc
	v_lshl_add_u64 v[64:65], v[102:103], 0, s[92:93]
	v_add_co_u32_e32 v66, vcc, s11, v64
	s_waitcnt lgkmcnt(7)
	v_mfma_f32_16x16x32_bf16 v[12:15], v[136:139], v[132:135], v[12:15]
	v_addc_co_u32_e32 v67, vcc, 0, v65, vcc
	v_mfma_f32_16x16x32_bf16 v[8:11], v[140:143], v[132:135], v[8:11]
	v_mfma_f32_16x16x32_bf16 v[4:7], v[144:147], v[132:135], v[4:7]
	v_mfma_f32_16x16x32_bf16 v[0:3], v[148:151], v[132:135], v[0:3]
	s_waitcnt vmcnt(4)
	ds_write_b128 v109, v[72:75] offset:45056
	s_waitcnt lgkmcnt(7)
	v_mfma_f32_16x16x32_bf16 v[52:55], v[194:197], v[152:155], v[92:95]
	v_mfma_f32_16x16x32_bf16 v[60:63], v[198:201], v[152:155], v[88:91]
	v_mfma_f32_16x16x32_bf16 v[56:59], v[202:205], v[152:155], v[56:59]
	v_mfma_f32_16x16x32_bf16 v[48:51], v[206:209], v[152:155], v[48:51]
	s_waitcnt vmcnt(3)
	ds_write_b128 v109, v[68:71] offset:49152
	s_waitcnt lgkmcnt(7)
	v_mfma_f32_16x16x32_bf16 v[44:47], v[194:197], v[156:159], v[44:47]
	v_mfma_f32_16x16x32_bf16 v[40:43], v[198:201], v[156:159], v[40:43]
	v_mfma_f32_16x16x32_bf16 v[36:39], v[202:205], v[156:159], v[36:39]
	v_mfma_f32_16x16x32_bf16 v[32:35], v[206:209], v[156:159], v[32:35]
	v_add_co_u32_e32 v66, vcc, s33, v64
	s_waitcnt vmcnt(2)
	ds_write_b128 v109, v[76:79] offset:53248
	v_addc_co_u32_e32 v67, vcc, 0, v65, vcc
	v_add_co_u32_e32 v64, vcc, s59, v64
	s_waitcnt lgkmcnt(7)
	v_mfma_f32_16x16x32_bf16 v[28:31], v[194:197], v[160:163], v[28:31]
	v_addc_co_u32_e32 v65, vcc, 0, v65, vcc
	v_mfma_f32_16x16x32_bf16 v[24:27], v[198:201], v[160:163], v[24:27]
	v_mfma_f32_16x16x32_bf16 v[20:23], v[202:205], v[160:163], v[20:23]
	v_mfma_f32_16x16x32_bf16 v[16:19], v[206:209], v[160:163], v[16:19]
	s_waitcnt vmcnt(1)
	ds_write_b128 v109, v[80:83] offset:57344
	s_waitcnt lgkmcnt(7)
	v_mfma_f32_16x16x32_bf16 v[12:15], v[194:197], v[190:193], v[12:15]
	v_mfma_f32_16x16x32_bf16 v[8:11], v[198:201], v[190:193], v[8:11]
	v_mfma_f32_16x16x32_bf16 v[4:7], v[202:205], v[190:193], v[4:7]
	v_mfma_f32_16x16x32_bf16 v[0:3], v[206:209], v[190:193], v[0:3]
	s_waitcnt vmcnt(0)
	ds_write_b128 v109, v[84:87] offset:61440
	s_waitcnt lgkmcnt(0)
	s_barrier
	ds_read_b128 v[84:87], v111 offset:51200
	ds_read_b128 v[80:83], v111 offset:49152
	ds_read_b128 v[88:91], v111 offset:53248
	ds_read_b128 v[92:95], v111 offset:55296
	ds_read_b128 v[64:67], v110 offset:32768
	s_min_u32 s44, s29, 12
	s_lshl_b32 s92, s44, 7
	ds_read_b128 v[68:71], v110 offset:34816
	v_lshl_add_u64 v[164:165], v[100:101], 0, s[92:93]
	ds_read_b128 v[72:75], v110 offset:36864
	ds_read_b128 v[76:79], v110 offset:38912
	ds_read_b128 v[152:155], v112 offset:32768
	ds_read_b128 v[156:159], v112 offset:34816
	ds_read_b128 v[160:163], v112 offset:36864
	ds_read_b128 v[190:193], v112 offset:38912
	ds_read_b128 v[194:197], v113 offset:49152
	ds_read_b128 v[198:201], v113 offset:51200
	ds_read_b128 v[202:205], v113 offset:53248
	ds_read_b128 v[206:209], v113 offset:55296
	s_waitcnt lgkmcnt(11)
	v_mfma_f32_16x16x32_bf16 v[214:217], v[84:87], v[64:67], v[60:63]
	v_mfma_f32_16x16x32_bf16 v[210:213], v[80:83], v[64:67], v[52:55]
	s_nop 1
	v_add_co_u32_e32 v60, vcc, s11, v164
	s_nop 1
	v_addc_co_u32_e32 v61, vcc, 0, v165, vcc
	v_mfma_f32_16x16x32_bf16 v[56:59], v[88:91], v[64:67], v[56:59]
	v_mfma_f32_16x16x32_bf16 v[48:51], v[92:95], v[64:67], v[48:51]
	v_add_co_u32_e32 v64, vcc, s33, v164
	s_nop 0
	s_nop 0
	v_addc_co_u32_e32 v65, vcc, 0, v165, vcc
	s_waitcnt lgkmcnt(10)
	v_mfma_f32_16x16x32_bf16 v[44:47], v[80:83], v[68:71], v[44:47]
	v_mfma_f32_16x16x32_bf16 v[40:43], v[84:87], v[68:71], v[40:43]
	v_mfma_f32_16x16x32_bf16 v[36:39], v[88:91], v[68:71], v[36:39]
	v_mfma_f32_16x16x32_bf16 v[32:35], v[92:95], v[68:71], v[32:35]
	v_add_co_u32_e32 v68, vcc, s59, v164
	s_waitcnt lgkmcnt(9)
	v_mfma_f32_16x16x32_bf16 v[28:31], v[80:83], v[72:75], v[28:31]
	v_addc_co_u32_e32 v69, vcc, 0, v165, vcc
	v_mfma_f32_16x16x32_bf16 v[24:27], v[84:87], v[72:75], v[24:27]
	v_mfma_f32_16x16x32_bf16 v[20:23], v[88:91], v[72:75], v[20:23]
	v_mfma_f32_16x16x32_bf16 v[16:19], v[92:95], v[72:75], v[16:19]
	s_waitcnt lgkmcnt(8)
	v_mfma_f32_16x16x32_bf16 v[8:11], v[84:87], v[76:79], v[8:11]
	v_lshl_add_u64 v[84:85], v[102:103], 0, s[92:93]
	v_mfma_f32_16x16x32_bf16 v[12:15], v[80:83], v[76:79], v[12:15]
	v_mfma_f32_16x16x32_bf16 v[4:7], v[88:91], v[76:79], v[4:7]
	v_mfma_f32_16x16x32_bf16 v[0:3], v[92:95], v[76:79], v[0:3]
	v_add_co_u32_e32 v76, vcc, s11, v84
	s_nop 0
	s_nop 0
	v_addc_co_u32_e32 v77, vcc, 0, v85, vcc
	v_add_co_u32_e32 v80, vcc, s33, v84
	s_nop 1
	v_addc_co_u32_e32 v81, vcc, 0, v85, vcc
	s_waitcnt lgkmcnt(3)
	v_mfma_f32_16x16x32_bf16 v[92:95], v[194:197], v[152:155], v[210:213]
	s_waitcnt lgkmcnt(2)
	v_mfma_f32_16x16x32_bf16 v[88:91], v[198:201], v[152:155], v[214:217]
	s_waitcnt lgkmcnt(1)
	v_mfma_f32_16x16x32_bf16 v[56:59], v[202:205], v[152:155], v[56:59]
	s_waitcnt lgkmcnt(0)
	v_mfma_f32_16x16x32_bf16 v[48:51], v[206:209], v[152:155], v[48:51]
	v_add_co_u32_e32 v84, vcc, s59, v84
	s_nop 1
	v_addc_co_u32_e32 v85, vcc, 0, v85, vcc
	v_mfma_f32_16x16x32_bf16 v[44:47], v[194:197], v[156:159], v[44:47]
	v_mfma_f32_16x16x32_bf16 v[40:43], v[198:201], v[156:159], v[40:43]
	v_mfma_f32_16x16x32_bf16 v[36:39], v[202:205], v[156:159], v[36:39]
	v_mfma_f32_16x16x32_bf16 v[32:35], v[206:209], v[156:159], v[32:35]
	v_mfma_f32_16x16x32_bf16 v[28:31], v[194:197], v[160:163], v[28:31]
	v_mfma_f32_16x16x32_bf16 v[24:27], v[198:201], v[160:163], v[24:27]
	v_mfma_f32_16x16x32_bf16 v[20:23], v[202:205], v[160:163], v[20:23]
	v_mfma_f32_16x16x32_bf16 v[16:19], v[206:209], v[160:163], v[16:19]
	v_mfma_f32_16x16x32_bf16 v[12:15], v[194:197], v[190:193], v[12:15]
	v_mfma_f32_16x16x32_bf16 v[8:11], v[198:201], v[190:193], v[8:11]
	v_mfma_f32_16x16x32_bf16 v[4:7], v[202:205], v[190:193], v[4:7]
	v_mfma_f32_16x16x32_bf16 v[0:3], v[206:209], v[190:193], v[0:3]
	s_mov_b32 s44, s29
	s_waitcnt lgkmcnt(0)
	s_barrier
	s_waitcnt vmcnt(5)
	v_add_u32_e32 v64, s24, v108
	v_add_u32_e32 v52, 0xffffe000, v64
	v_or_b32_e32 v62, v64, v107
	v_lshrrev_b32_e32 v52, 10, v52
	s_movk_i32 s16, 0x1800
	v_mad_u32_u24 v52, v52, s16, s16
	v_cmp_lt_i32_e32 vcc, s13, v62
	v_or_b32_e32 v65, s25, v114
	v_or_b32_e32 v54, v65, v115
	v_cndmask_b32_e32 v52, 0, v52, vcc
	v_ashrrev_i32_e32 v53, 31, v52
	s_waitcnt vmcnt(4)
	v_lshlrev_b64 v[74:75], 2, v[52:53]
	v_ashrrev_i32_e32 v55, 31, v54
	v_ashrrev_i32_e32 v63, 31, v62
	v_lshl_add_u64 v[52:53], s[40:41], 0, v[74:75]
	v_lshlrev_b64 v[60:61], 2, v[54:55]
	v_readlane_b32 s16, v250, 15
	s_waitcnt vmcnt(1)
	v_lshl_add_u64 v[82:83], v[52:53], 0, v[60:61]
	v_lshlrev_b64 v[52:53], 12, v[62:63]
	v_readlane_b32 s17, v250, 16
	v_lshl_add_u64 v[74:75], s[42:43], 0, v[74:75]
	s_waitcnt vmcnt(0)
	v_lshl_add_u64 v[86:87], v[74:75], 0, v[60:61]
	v_lshl_add_u64 v[52:53], s[16:17], 0, v[52:53]
	v_lshl_add_u64 v[84:85], v[52:53], 0, v[60:61]
	global_load_dwordx4 v[66:69], v[82:83], off
	global_load_dwordx4 v[70:73], v[84:85], off
	v_lshl_add_u64 v[52:53], s[0:1], 0, v[60:61]
	v_readlane_b32 s16, v250, 21
	v_lshlrev_b64 v[78:79], 11, v[62:63]
	v_readlane_b32 s17, v250, 22
	s_waitcnt vmcnt(0)
	v_pk_fma_f32 v[68:69], v[94:95], v[68:69], v[72:73]
	v_pk_fma_f32 v[66:67], v[92:93], v[66:67], v[70:71]
	global_store_dwordx4 v[84:85], v[66:69], off
	global_load_dwordx4 v[70:73], v[52:53], off
	global_load_dwordx4 v[74:77], v[86:87], off
	v_lshl_add_u64 v[78:79], s[16:17], 0, v[78:79]
	v_lshl_add_u64 v[92:93], v[54:55], 1, v[78:79]
	s_mov_b32 s16, 0xa000
	s_waitcnt vmcnt(1)
	v_pk_mul_f32 v[72:73], v[68:69], v[72:73]
	v_pk_mul_f32 v[70:71], v[66:67], v[70:71]
	s_waitcnt vmcnt(0)
	v_pk_add_f32 v[76:77], v[76:77], 1.0 op_sel_hi:[1,0]
	v_pk_add_f32 v[74:75], v[74:75], 1.0 op_sel_hi:[1,0]
	v_pk_mul_f32 v[72:73], v[72:73], v[76:77]
	v_pk_mul_f32 v[70:71], v[70:71], v[74:75]
	v_and_b32_sdwa v77, v71, v170 dst_sel:DWORD dst_unused:UNUSED_PAD src0_sel:WORD_1 src1_sel:DWORD
	v_and_b32_sdwa v75, v70, v170 dst_sel:DWORD dst_unused:UNUSED_PAD src0_sel:WORD_1 src1_sel:DWORD
	v_add3_u32 v71, v71, v77, s56
	v_add3_u32 v70, v70, v75, s56
	v_and_b32_e32 v74, 0xffff0000, v71
	v_cvt_pk_bf16_f32 v71, v72, v73
	v_or_b32_sdwa v70, v74, v70 dst_sel:DWORD dst_unused:UNUSED_PAD src0_sel:DWORD src1_sel:WORD_1
	global_store_dwordx2 v[92:93], v[70:71], off
	global_load_dwordx4 v[70:73], v[82:83], off offset:64
	s_nop 0
	global_load_dwordx4 v[74:77], v[84:85], off offset:64
	s_waitcnt vmcnt(0)
	v_pk_fma_f32 v[72:73], v[90:91], v[72:73], v[76:77]
	v_pk_fma_f32 v[70:71], v[88:89], v[70:71], v[74:75]
	global_store_dwordx4 v[84:85], v[70:73], off offset:64
	global_load_dwordx4 v[74:77], v[52:53], off offset:64
	global_load_dwordx4 v[78:81], v[86:87], off offset:64
	s_waitcnt vmcnt(1)
	v_pk_mul_f32 v[76:77], v[72:73], v[76:77]
	v_pk_mul_f32 v[74:75], v[70:71], v[74:75]
	s_waitcnt vmcnt(0)
	v_pk_add_f32 v[80:81], v[80:81], 1.0 op_sel_hi:[1,0]
	v_pk_add_f32 v[78:79], v[78:79], 1.0 op_sel_hi:[1,0]
	v_pk_mul_f32 v[76:77], v[76:77], v[80:81]
	v_pk_mul_f32 v[74:75], v[74:75], v[78:79]
	v_and_b32_sdwa v81, v75, v170 dst_sel:DWORD dst_unused:UNUSED_PAD src0_sel:WORD_1 src1_sel:DWORD
	v_and_b32_sdwa v79, v74, v170 dst_sel:DWORD dst_unused:UNUSED_PAD src0_sel:WORD_1 src1_sel:DWORD
	v_add3_u32 v75, v75, v81, s56
	v_add3_u32 v74, v74, v79, s56
	v_and_b32_e32 v78, 0xffff0000, v75
	v_cvt_pk_bf16_f32 v75, v76, v77
	v_or_b32_sdwa v74, v78, v74 dst_sel:DWORD dst_unused:UNUSED_PAD src0_sel:DWORD src1_sel:WORD_1
	global_store_dwordx2 v[92:93], v[74:75], off offset:32
	global_load_dwordx4 v[74:77], v[82:83], off offset:128
	s_nop 0
	global_load_dwordx4 v[78:81], v[84:85], off offset:128
	s_waitcnt vmcnt(0)
	v_pk_fma_f32 v[58:59], v[58:59], v[76:77], v[80:81]
	v_pk_fma_f32 v[56:57], v[56:57], v[74:75], v[78:79]
	global_store_dwordx4 v[84:85], v[56:59], off offset:128
	global_load_dwordx4 v[74:77], v[52:53], off offset:128
	global_load_dwordx4 v[78:81], v[86:87], off offset:128
	s_waitcnt vmcnt(1)
	v_pk_mul_f32 v[76:77], v[58:59], v[76:77]
	v_pk_mul_f32 v[74:75], v[56:57], v[74:75]
	s_waitcnt vmcnt(0)
	v_pk_add_f32 v[80:81], v[80:81], 1.0 op_sel_hi:[1,0]
	v_pk_add_f32 v[78:79], v[78:79], 1.0 op_sel_hi:[1,0]
	v_pk_mul_f32 v[76:77], v[76:77], v[80:81]
	v_pk_mul_f32 v[74:75], v[74:75], v[78:79]
	v_and_b32_sdwa v81, v75, v170 dst_sel:DWORD dst_unused:UNUSED_PAD src0_sel:WORD_1 src1_sel:DWORD
	v_and_b32_sdwa v79, v74, v170 dst_sel:DWORD dst_unused:UNUSED_PAD src0_sel:WORD_1 src1_sel:DWORD
	v_add3_u32 v75, v75, v81, s56
	v_add3_u32 v74, v74, v79, s56
	v_and_b32_e32 v78, 0xffff0000, v75
	v_cvt_pk_bf16_f32 v75, v76, v77
	v_or_b32_sdwa v74, v78, v74 dst_sel:DWORD dst_unused:UNUSED_PAD src0_sel:DWORD src1_sel:WORD_1
	global_store_dwordx2 v[92:93], v[74:75], off offset:64
	global_load_dwordx4 v[74:77], v[82:83], off offset:192
	s_nop 0
	global_load_dwordx4 v[78:81], v[84:85], off offset:192
	s_waitcnt vmcnt(0)
	v_pk_fma_f32 v[76:77], v[50:51], v[76:77], v[80:81]
	v_pk_fma_f32 v[74:75], v[48:49], v[74:75], v[78:79]
	global_store_dwordx4 v[84:85], v[74:77], off offset:192
	global_load_dwordx4 v[78:81], v[52:53], off offset:192
	s_nop 0
	global_load_dwordx4 v[82:85], v[86:87], off offset:192
	v_mul_f32_e32 v48, v67, v67
	v_mul_f32_e32 v49, v71, v71
	v_fmac_f32_e32 v48, v66, v66
	v_fmac_f32_e32 v49, v70, v70
	v_fmac_f32_e32 v48, v68, v68
	v_fmac_f32_e32 v49, v72, v72
	v_fmac_f32_e32 v48, v69, v69
	v_fmac_f32_e32 v49, v73, v73
	v_add_f32_e32 v48, v48, v49
	v_mul_f32_e32 v49, v57, v57
	v_fmac_f32_e32 v49, v56, v56
	v_fmac_f32_e32 v49, v58, v58
	v_fmac_f32_e32 v49, v59, v59
	v_add_f32_e32 v48, v48, v49
	v_mul_f32_e32 v49, v75, v75
	v_fmac_f32_e32 v49, v74, v74
	v_fmac_f32_e32 v49, v76, v76
	v_fmac_f32_e32 v49, v77, v77
	v_add_f32_e32 v50, v48, v49
	ds_bpermute_b32 v51, v105, v50
	v_lshrrev_b32_e32 v48, 6, v65
	v_mul_lo_u32 v48, v48, s16
	v_ashrrev_i32_e32 v49, 31, v48
	v_lshl_add_u64 v[48:49], s[26:27], 0, v[48:49]
	s_waitcnt lgkmcnt(0)
	v_add_f32_e32 v50, v50, v51
	ds_bpermute_b32 v51, v104, v50
	v_lshl_add_u64 v[48:49], v[62:63], 2, v[48:49]
	s_waitcnt vmcnt(1)
	v_pk_mul_f32 v[56:57], v[76:77], v[80:81]
	v_pk_mul_f32 v[58:59], v[74:75], v[78:79]
	s_waitcnt vmcnt(0)
	v_pk_add_f32 v[66:67], v[84:85], 1.0 op_sel_hi:[1,0]
	v_pk_add_f32 v[68:69], v[82:83], 1.0 op_sel_hi:[1,0]
	v_pk_mul_f32 v[56:57], v[56:57], v[66:67]
	v_pk_mul_f32 v[58:59], v[58:59], v[68:69]
	v_cvt_pk_bf16_f32 v57, v56, v57
	v_cvt_pk_bf16_f32 v56, v58, v59
	global_store_dwordx2 v[92:93], v[56:57], off offset:96
	s_and_saveexec_b64 s[24:25], s[36:37]
	s_cbranch_execz .LBB0_109
	s_waitcnt lgkmcnt(0)
	v_add_f32_e32 v50, v50, v51
	global_store_dword v[48:49], v50, off

.Ltail119:
	s_add_i32 s2, s3, 2
	v_add_u32_e32 v127, v89, v90
	ds_read_b128 v[100:103], v127 offset:16384
	ds_read_b128 v[106:109], v127 offset:18432
	ds_read_b128 v[110:113], v127 offset:20480
	ds_read_b128 v[114:117], v127 offset:22528
	v_add_u32_e32 v126, v88, v90
	ds_read_b128 v[92:95], v126
	ds_read_b128 v[96:99], v126 offset:2048
	s_add_i32 s3, s3, 4
	s_min_u32 s3, s3, 15
	v_add_u32_e32 v128, v88, v91
	v_add_u32_e32 v130, v89, v91
	s_lshl_b32 s92, s3, 7
	ds_read_b128 v[118:121], v130 offset:18432
	ds_read_b128 v[122:125], v130 offset:20480
	ds_read_b128 v[132:135], v130 offset:22528
	s_waitcnt lgkmcnt(4)
	v_mfma_f32_16x16x32_bf16 v[76:79], v[100:103], v[92:95], v[76:79]
	v_lshl_add_u64 v[44:45], v[80:81], 0, s[92:93]
	v_add_co_u32_e32 v46, vcc, s11, v44
	v_mfma_f32_16x16x32_bf16 v[68:71], v[106:109], v[92:95], v[68:71]
	s_nop 0
	v_addc_co_u32_e32 v47, vcc, 0, v45, vcc
	v_mfma_f32_16x16x32_bf16 v[52:55], v[110:113], v[92:95], v[52:55]
	v_mfma_f32_16x16x32_bf16 v[40:43], v[114:117], v[92:95], v[40:43]
	s_waitcnt lgkmcnt(3)
	v_mfma_f32_16x16x32_bf16 v[92:95], v[100:103], v[96:99], v[36:39]
	s_nop 2
	ds_read_b128 v[36:39], v128
	v_mfma_f32_16x16x32_bf16 v[100:103], v[106:109], v[96:99], v[8:11]
	v_mfma_f32_16x16x32_bf16 v[106:109], v[110:113], v[96:99], v[4:7]
	ds_read_b128 v[110:113], v128 offset:2048
	v_mfma_f32_16x16x32_bf16 v[96:99], v[114:117], v[96:99], v[0:3]
	ds_read_b128 v[114:117], v130 offset:16384
	s_waitcnt vmcnt(0)
	ds_write_b128 v87, v[12:15] offset:53248
	v_add_co_u32_e32 v46, vcc, s33, v44
	s_waitcnt vmcnt(1)
	ds_write_b128 v87, v[16:19] offset:49152
	s_nop 0
	v_addc_co_u32_e32 v47, vcc, 0, v45, vcc
	v_add_co_u32_e32 v44, vcc, s59, v44
	s_nop 0
	s_nop 0
	v_addc_co_u32_e32 v45, vcc, 0, v45, vcc
	s_waitcnt vmcnt(2)
	ds_write_b128 v87, v[20:23] offset:45056
	v_lshl_add_u64 v[44:45], v[82:83], 0, s[92:93]
	s_waitcnt vmcnt(5)
	ds_write_b128 v87, v[28:31] offset:32768
	s_waitcnt lgkmcnt(4)
	v_mfma_f32_16x16x32_bf16 v[0:3], v[114:117], v[36:39], v[76:79]
	v_mfma_f32_16x16x32_bf16 v[4:7], v[118:121], v[36:39], v[68:71]
	v_add_co_u32_e32 v44, vcc, s11, v44
	s_waitcnt vmcnt(4)
	ds_write_b128 v87, v[32:35] offset:36864
	s_nop 0
	v_addc_co_u32_e32 v45, vcc, 0, v45, vcc
	v_mfma_f32_16x16x32_bf16 v[8:11], v[122:125], v[36:39], v[52:55]
	v_mfma_f32_16x16x32_bf16 v[36:39], v[132:135], v[36:39], v[40:43]
	s_waitcnt vmcnt(3)
	ds_write_b128 v87, v[24:27] offset:40960
	v_mfma_f32_16x16x32_bf16 v[40:43], v[114:117], v[110:113], v[92:95]
	v_mfma_f32_16x16x32_bf16 v[52:55], v[118:121], v[110:113], v[100:103]
	v_mfma_f32_16x16x32_bf16 v[68:71], v[122:125], v[110:113], v[106:109]
	v_mfma_f32_16x16x32_bf16 v[76:79], v[132:135], v[110:113], v[96:99]
	s_waitcnt lgkmcnt(0)
	s_barrier
	ds_read_b128 v[100:103], v127 offset:49152
	ds_read_b128 v[106:109], v127 offset:51200
	ds_read_b128 v[110:113], v127 offset:53248
	ds_read_b128 v[114:117], v127 offset:55296
	ds_read_b128 v[92:95], v126 offset:32768
	ds_read_b128 v[96:99], v126 offset:34816
	s_min_u32 s3, s2, 12
	s_lshl_b32 s92, s3, 7
	ds_read_b128 v[118:121], v130 offset:51200
	ds_read_b128 v[122:125], v130 offset:53248
	ds_read_b128 v[132:135], v130 offset:55296
	s_waitcnt lgkmcnt(4)
	v_mfma_f32_16x16x32_bf16 v[0:3], v[100:103], v[92:95], v[0:3]
	v_lshl_add_u64 v[12:13], v[80:81], 0, s[92:93]
	v_add_co_u32_e32 v14, vcc, s11, v12
	v_mfma_f32_16x16x32_bf16 v[4:7], v[106:109], v[92:95], v[4:7]
	s_nop 0
	v_addc_co_u32_e32 v15, vcc, 0, v13, vcc
	v_mfma_f32_16x16x32_bf16 v[8:11], v[110:113], v[92:95], v[8:11]
	v_mfma_f32_16x16x32_bf16 v[36:39], v[114:117], v[92:95], v[36:39]
	s_waitcnt lgkmcnt(3)
	v_mfma_f32_16x16x32_bf16 v[92:95], v[100:103], v[96:99], v[40:43]
	s_nop 2
	ds_read_b128 v[40:43], v128 offset:32768
	v_mfma_f32_16x16x32_bf16 v[100:103], v[106:109], v[96:99], v[52:55]
	v_mfma_f32_16x16x32_bf16 v[106:109], v[110:113], v[96:99], v[68:71]
	ds_read_b128 v[110:113], v128 offset:34816
	v_mfma_f32_16x16x32_bf16 v[96:99], v[114:117], v[96:99], v[76:79]
	ds_read_b128 v[114:117], v130 offset:49152
	v_add_co_u32_e32 v14, vcc, s33, v12
	s_nop 0
	s_nop 0
	v_addc_co_u32_e32 v15, vcc, 0, v13, vcc
	v_add_co_u32_e32 v12, vcc, s59, v12
	s_nop 0
	s_nop 0
	v_addc_co_u32_e32 v13, vcc, 0, v13, vcc
	v_lshl_add_u64 v[12:13], v[82:83], 0, s[92:93]
	s_waitcnt lgkmcnt(0)
	v_mfma_f32_16x16x32_bf16 v[76:79], v[114:117], v[40:43], v[0:3]
	v_mfma_f32_16x16x32_bf16 v[68:71], v[118:121], v[40:43], v[4:7]
	v_add_co_u32_e32 v12, vcc, s11, v12
	s_nop 0
	s_nop 0
	v_addc_co_u32_e32 v13, vcc, 0, v13, vcc
	v_mfma_f32_16x16x32_bf16 v[52:55], v[122:125], v[40:43], v[8:11]
	v_mfma_f32_16x16x32_bf16 v[40:43], v[132:135], v[40:43], v[36:39]
	v_mfma_f32_16x16x32_bf16 v[36:39], v[114:117], v[110:113], v[92:95]
	v_mfma_f32_16x16x32_bf16 v[8:11], v[118:121], v[110:113], v[100:103]
	v_mfma_f32_16x16x32_bf16 v[4:7], v[122:125], v[110:113], v[106:109]
	v_mfma_f32_16x16x32_bf16 v[0:3], v[132:135], v[110:113], v[96:99]
	s_mov_b32 s3, s2
	s_waitcnt lgkmcnt(0)
	s_barrier
	v_readlane_b32 s2, v251, 18
	s_waitcnt vmcnt(1)
	s_nop 0
	v_add_u32_e32 v18, s2, v86
	v_readlane_b32 s2, v251, 19
	s_waitcnt vmcnt(0)
	v_add_u32_e32 v13, 0xffffe000, v18
	v_or_b32_e32 v12, v18, v85
	v_lshl_or_b32 v19, v84, 2, s2
	v_lshrrev_b32_e32 v13, 10, v13
	s_movk_i32 s2, 0x1800
	v_mad_u32_u24 v13, v13, s2, s2
	v_cmp_lt_i32_e32 vcc, s13, v12
	v_lshlrev_b32_e32 v128, 2, v19
	v_readlane_b32 s2, v250, 15
	v_cndmask_b32_e32 v14, 0, v13, vcc
	v_ashrrev_i32_e32 v15, 31, v14
	v_lshlrev_b64 v[24:25], 2, v[14:15]
	v_ashrrev_i32_e32 v13, 31, v12
	v_lshl_add_u64 v[14:15], s[40:41], 0, v[24:25]
	v_lshl_add_u64 v[48:49], v[14:15], 0, v[128:129]
	v_lshlrev_b64 v[14:15], 12, v[12:13]
	v_readlane_b32 s3, v250, 16
	v_lshl_add_u64 v[28:29], s[42:43], 0, v[24:25]
	v_lshlrev_b64 v[32:33], 11, v[12:13]
	v_lshl_add_u64 v[14:15], s[2:3], 0, v[14:15]
	v_lshl_add_u64 v[50:51], v[14:15], 0, v[128:129]
	global_load_dwordx4 v[72:75], v[48:49], off
	global_load_dwordx4 v[80:83], v[48:49], off offset:64
	global_load_dwordx4 v[88:91], v[48:49], off offset:128
	global_load_dwordx4 v[136:139], v[48:49], off offset:192
	global_load_dwordx4 v[194:197], v[50:51], off
	global_load_dwordx4 v[198:201], v[50:51], off offset:64
	global_load_dwordx4 v[202:205], v[50:51], off offset:128
	global_load_dwordx4 v[206:209], v[50:51], off offset:192
	v_add_co_u32_e32 v58, vcc, 0x10000, v50
	s_nop 1
	v_addc_co_u32_e32 v59, vcc, 0, v51, vcc
	global_load_dwordx4 v[210:213], v[58:59], off
	global_load_dwordx4 v[214:217], v[58:59], off offset:64
	global_load_dwordx4 v[218:221], v[58:59], off offset:128
	global_load_dwordx4 v[222:225], v[58:59], off offset:192
	v_readlane_b32 s2, v250, 21
	v_readlane_b32 s3, v250, 22
	v_cmp_eq_u32_e32 vcc, 0, v84
	s_waitcnt vmcnt(4)
	v_pk_fma_f32 v[22:23], v[78:79], v[74:75], v[196:197]
	v_pk_fma_f32 v[20:21], v[76:77], v[72:73], v[194:195]
	global_store_dwordx4 v[50:51], v[20:23], off
	v_lshl_add_u64 v[14:15], v[28:29], 0, v[128:129]
	global_load_dwordx4 v[140:143], v128, s[0:1]
	global_load_dwordx4 v[144:147], v128, s[0:1] offset:64
	global_load_dwordx4 v[148:151], v128, s[0:1] offset:128
	global_load_dwordx4 v[152:155], v128, s[0:1] offset:192
	global_load_dwordx4 v[156:159], v[14:15], off
	global_load_dwordx4 v[160:163], v[14:15], off offset:64
	global_load_dwordx4 v[180:183], v[14:15], off offset:128
	global_load_dwordx4 v[190:193], v[14:15], off offset:192
	v_lshlrev_b32_e32 v16, 1, v19
	v_mov_b32_e32 v17, v129
	v_lshl_add_u64 v[32:33], s[2:3], 0, v[32:33]
	v_lshl_add_u64 v[56:57], v[32:33], 0, v[16:17]
	s_waitcnt vmcnt(0)
	v_pk_mul_f32 v[26:27], v[22:23], v[142:143]
	v_pk_mul_f32 v[24:25], v[20:21], v[140:141]
	s_waitcnt vmcnt(0)
	v_pk_add_f32 v[30:31], v[158:159], 1.0 op_sel_hi:[1,0]
	v_pk_add_f32 v[28:29], v[156:157], 1.0 op_sel_hi:[1,0]
	v_pk_mul_f32 v[26:27], v[26:27], v[30:31]
	v_pk_mul_f32 v[24:25], v[24:25], v[28:29]
	v_and_b32_sdwa v19, v26, v170 dst_sel:DWORD dst_unused:UNUSED_PAD src0_sel:WORD_1 src1_sel:DWORD
	v_and_b32_sdwa v29, v27, v170 dst_sel:DWORD dst_unused:UNUSED_PAD src0_sel:WORD_1 src1_sel:DWORD
	v_and_b32_sdwa v30, v25, v170 dst_sel:DWORD dst_unused:UNUSED_PAD src0_sel:WORD_1 src1_sel:DWORD
	v_and_b32_sdwa v28, v24, v170 dst_sel:DWORD dst_unused:UNUSED_PAD src0_sel:WORD_1 src1_sel:DWORD
	v_add3_u32 v19, v26, v19, s56
	v_add3_u32 v26, v27, v29, s56
	v_add3_u32 v25, v25, v30, s56
	v_add3_u32 v24, v24, v28, s56
	v_and_b32_e32 v26, 0xffff0000, v26
	v_and_b32_e32 v27, 0xffff0000, v25
	v_or_b32_sdwa v25, v26, v19 dst_sel:DWORD dst_unused:UNUSED_PAD src0_sel:DWORD src1_sel:WORD_1
	v_or_b32_sdwa v24, v27, v24 dst_sel:DWORD dst_unused:UNUSED_PAD src0_sel:DWORD src1_sel:WORD_1
	global_store_dwordx2 v[56:57], v[24:25], off
	s_nop 0
	s_waitcnt vmcnt(0)
	v_pk_fma_f32 v[26:27], v[70:71], v[82:83], v[200:201]
	v_pk_fma_f32 v[24:25], v[68:69], v[80:81], v[198:199]
	global_store_dwordx4 v[50:51], v[24:27], off offset:64
	v_pk_mul_f32 v[30:31], v[26:27], v[146:147]
	v_pk_mul_f32 v[28:29], v[24:25], v[144:145]
	v_pk_add_f32 v[34:35], v[162:163], 1.0 op_sel_hi:[1,0]
	v_pk_add_f32 v[32:33], v[160:161], 1.0 op_sel_hi:[1,0]
	v_pk_mul_f32 v[30:31], v[30:31], v[34:35]
	v_pk_mul_f32 v[28:29], v[28:29], v[32:33]
	v_and_b32_sdwa v19, v30, v170 dst_sel:DWORD dst_unused:UNUSED_PAD src0_sel:WORD_1 src1_sel:DWORD
	v_and_b32_sdwa v33, v31, v170 dst_sel:DWORD dst_unused:UNUSED_PAD src0_sel:WORD_1 src1_sel:DWORD
	v_and_b32_sdwa v34, v29, v170 dst_sel:DWORD dst_unused:UNUSED_PAD src0_sel:WORD_1 src1_sel:DWORD
	v_and_b32_sdwa v32, v28, v170 dst_sel:DWORD dst_unused:UNUSED_PAD src0_sel:WORD_1 src1_sel:DWORD
	v_add3_u32 v19, v30, v19, s56
	v_add3_u32 v30, v31, v33, s56
	v_add3_u32 v29, v29, v34, s56
	v_add3_u32 v28, v28, v32, s56
	v_and_b32_e32 v30, 0xffff0000, v30
	v_and_b32_e32 v31, 0xffff0000, v29
	v_or_b32_sdwa v29, v30, v19 dst_sel:DWORD dst_unused:UNUSED_PAD src0_sel:DWORD src1_sel:WORD_1
	v_or_b32_sdwa v28, v31, v28 dst_sel:DWORD dst_unused:UNUSED_PAD src0_sel:DWORD src1_sel:WORD_1
	global_store_dwordx2 v[56:57], v[28:29], off offset:32
	s_nop 0
	v_pk_fma_f32 v[30:31], v[54:55], v[90:91], v[204:205]
	v_pk_fma_f32 v[28:29], v[52:53], v[88:89], v[202:203]
	global_store_dwordx4 v[50:51], v[28:31], off offset:128
	v_pk_mul_f32 v[34:35], v[30:31], v[150:151]
	v_pk_mul_f32 v[32:33], v[28:29], v[148:149]
	v_pk_add_f32 v[46:47], v[182:183], 1.0 op_sel_hi:[1,0]
	v_pk_add_f32 v[44:45], v[180:181], 1.0 op_sel_hi:[1,0]
	v_pk_mul_f32 v[34:35], v[34:35], v[46:47]
	v_pk_mul_f32 v[32:33], v[32:33], v[44:45]
	v_and_b32_sdwa v19, v34, v170 dst_sel:DWORD dst_unused:UNUSED_PAD src0_sel:WORD_1 src1_sel:DWORD
	v_and_b32_sdwa v45, v35, v170 dst_sel:DWORD dst_unused:UNUSED_PAD src0_sel:WORD_1 src1_sel:DWORD
	v_and_b32_sdwa v46, v33, v170 dst_sel:DWORD dst_unused:UNUSED_PAD src0_sel:WORD_1 src1_sel:DWORD
	v_and_b32_sdwa v44, v32, v170 dst_sel:DWORD dst_unused:UNUSED_PAD src0_sel:WORD_1 src1_sel:DWORD
	v_add3_u32 v19, v34, v19, s56
	v_add3_u32 v34, v35, v45, s56
	v_add3_u32 v33, v33, v46, s56
	v_add3_u32 v32, v32, v44, s56
	v_and_b32_e32 v34, 0xffff0000, v34
	v_and_b32_e32 v35, 0xffff0000, v33
	v_or_b32_sdwa v33, v34, v19 dst_sel:DWORD dst_unused:UNUSED_PAD src0_sel:DWORD src1_sel:WORD_1
	v_or_b32_sdwa v32, v35, v32 dst_sel:DWORD dst_unused:UNUSED_PAD src0_sel:DWORD src1_sel:WORD_1
	global_store_dwordx2 v[56:57], v[32:33], off offset:64
	s_nop 0
	v_pk_fma_f32 v[34:35], v[42:43], v[138:139], v[208:209]
	v_pk_fma_f32 v[32:33], v[40:41], v[136:137], v[206:207]
	global_store_dwordx4 v[50:51], v[32:35], off offset:192
	v_mul_f32_e32 v14, v21, v21
	v_mul_f32_e32 v15, v25, v25
	v_fmac_f32_e32 v14, v20, v20
	v_fmac_f32_e32 v15, v24, v24
	v_fmac_f32_e32 v14, v22, v22
	v_fmac_f32_e32 v15, v26, v26
	v_fmac_f32_e32 v14, v23, v23
	v_fmac_f32_e32 v15, v27, v27
	v_add_f32_e32 v14, v14, v15
	v_mul_f32_e32 v15, v29, v29
	v_fmac_f32_e32 v15, v28, v28
	v_fmac_f32_e32 v15, v30, v30
	v_fmac_f32_e32 v15, v31, v31
	v_add_f32_e32 v14, v14, v15
	v_mul_f32_e32 v15, v33, v33
	v_fmac_f32_e32 v15, v32, v32
	v_fmac_f32_e32 v15, v34, v34
	v_fmac_f32_e32 v15, v35, v35
	v_add_f32_e32 v14, v14, v15
	ds_bpermute_b32 v15, v105, v14
	s_waitcnt lgkmcnt(0)
	v_add_f32_e32 v14, v14, v15
	ds_bpermute_b32 v15, v104, v14
	v_pk_mul_f32 v[20:21], v[34:35], v[154:155]
	v_pk_mul_f32 v[22:23], v[32:33], v[152:153]
	v_pk_add_f32 v[24:25], v[192:193], 1.0 op_sel_hi:[1,0]
	v_pk_add_f32 v[26:27], v[190:191], 1.0 op_sel_hi:[1,0]
	v_pk_mul_f32 v[20:21], v[20:21], v[24:25]
	v_pk_mul_f32 v[22:23], v[22:23], v[26:27]
	v_and_b32_sdwa v19, v20, v170 dst_sel:DWORD dst_unused:UNUSED_PAD src0_sel:WORD_1 src1_sel:DWORD
	v_and_b32_sdwa v25, v21, v170 dst_sel:DWORD dst_unused:UNUSED_PAD src0_sel:WORD_1 src1_sel:DWORD
	v_and_b32_sdwa v26, v23, v170 dst_sel:DWORD dst_unused:UNUSED_PAD src0_sel:WORD_1 src1_sel:DWORD
	v_and_b32_sdwa v24, v22, v170 dst_sel:DWORD dst_unused:UNUSED_PAD src0_sel:WORD_1 src1_sel:DWORD
	v_add3_u32 v19, v20, v19, s56
	v_add3_u32 v20, v21, v25, s56
	v_add3_u32 v21, v23, v26, s56
	v_add3_u32 v22, v22, v24, s56
	v_and_b32_e32 v20, 0xffff0000, v20
	v_and_b32_e32 v23, 0xffff0000, v21
	v_or_b32_sdwa v21, v20, v19 dst_sel:DWORD dst_unused:UNUSED_PAD src0_sel:DWORD src1_sel:WORD_1
	v_or_b32_sdwa v20, v23, v22 dst_sel:DWORD dst_unused:UNUSED_PAD src0_sel:DWORD src1_sel:WORD_1
	global_store_dwordx2 v[56:57], v[20:21], off offset:96
	s_and_saveexec_b64 s[2:3], vcc
	s_cbranch_execz .LBB0_122
	v_readlane_b32 s16, v253, 20
	s_add_u32 s24, s26, s16
	s_addc_u32 s25, s27, 0
	v_lshl_add_u64 v[20:21], v[12:13], 2, s[24:25]
	s_waitcnt lgkmcnt(0)
	v_add_f32_e32 v13, v14, v15
	global_store_dword v[20:21], v13, off
.LBB0_122:
	s_or_b64 exec, exec, s[2:3]
	v_add_u32_e32 v13, 0xffffe010, v18
	s_waitcnt lgkmcnt(0)
	v_lshl_add_u64 v[14:15], s[0:1], 0, v[128:129]
	v_or_b32_e32 v12, 16, v12
	v_lshrrev_b32_e32 v13, 10, v13
	s_movk_i32 s0, 0x1800
	v_mad_u32_u24 v13, v13, s0, s0
	v_cmp_lt_i32_e64 s[0:1], s13, v12
	s_nop 1
	v_cndmask_b32_e64 v18, 0, v13, s[0:1]
	v_ashrrev_i32_e32 v19, 31, v18
	v_lshlrev_b64 v[34:35], 2, v[18:19]
	v_ashrrev_i32_e32 v13, 31, v12
	v_lshl_add_u64 v[18:19], s[40:41], 0, v[34:35]
	v_readlane_b32 s0, v250, 15
	v_lshl_add_u64 v[20:21], v[18:19], 0, v[128:129]
	v_lshlrev_b64 v[18:19], 12, v[12:13]
	v_readlane_b32 s1, v250, 16
	s_nop 0
	s_nop 0
	v_lshl_add_u64 v[18:19], s[0:1], 0, v[18:19]
	v_lshl_add_u64 v[18:19], v[18:19], 0, v[128:129]
	v_readlane_b32 s0, v250, 21
	v_readlane_b32 s1, v250, 22
	s_waitcnt vmcnt(16)
	v_pk_fma_f32 v[28:29], v[38:39], v[74:75], v[212:213]
	v_pk_fma_f32 v[26:27], v[36:37], v[72:73], v[210:211]
	v_lshl_add_u64 v[22:23], s[42:43], 0, v[34:35]
	global_store_dwordx4 v[18:19], v[26:29], off
	v_lshl_add_u64 v[22:23], v[22:23], 0, v[128:129]
	v_mul_f32_e32 v38, v27, v27
	v_fmac_f32_e32 v38, v26, v26
	v_fmac_f32_e32 v38, v28, v28
	v_fmac_f32_e32 v38, v29, v29
	v_pk_mul_f32 v[24:25], v[28:29], v[142:143]
	v_pk_add_f32 v[28:29], v[158:159], 1.0 op_sel_hi:[1,0]
	v_pk_mul_f32 v[26:27], v[26:27], v[140:141]
	v_pk_add_f32 v[30:31], v[156:157], 1.0 op_sel_hi:[1,0]
	v_pk_mul_f32 v[24:25], v[24:25], v[28:29]
	v_lshlrev_b64 v[28:29], 11, v[12:13]
	v_pk_mul_f32 v[26:27], v[26:27], v[30:31]
	v_lshl_add_u64 v[28:29], s[0:1], 0, v[28:29]
	v_lshl_add_u64 v[16:17], v[28:29], 0, v[16:17]
	v_cvt_pk_bf16_f32 v25, v24, v25
	v_cvt_pk_bf16_f32 v24, v26, v27
	global_store_dwordx2 v[16:17], v[24:25], off
	s_nop 0
	v_pk_fma_f32 v[8:9], v[8:9], v[80:81], v[214:215]
	s_nop 0
	v_mul_f32_e32 v24, v9, v9
	v_pk_fma_f32 v[10:11], v[10:11], v[82:83], v[216:217]
	v_fmac_f32_e32 v24, v8, v8
	v_fmac_f32_e32 v24, v10, v10
	global_store_dwordx4 v[18:19], v[8:11], off offset:64
	v_fmac_f32_e32 v24, v11, v11
	v_add_f32_e32 v32, v38, v24
	v_pk_mul_f32 v[10:11], v[10:11], v[146:147]
	v_pk_mul_f32 v[8:9], v[8:9], v[144:145]
	v_pk_add_f32 v[24:25], v[162:163], 1.0 op_sel_hi:[1,0]
	v_pk_add_f32 v[26:27], v[160:161], 1.0 op_sel_hi:[1,0]
	v_pk_mul_f32 v[10:11], v[10:11], v[24:25]
	v_pk_mul_f32 v[8:9], v[8:9], v[26:27]
	v_and_b32_sdwa v25, v8, v170 dst_sel:DWORD dst_unused:UNUSED_PAD src0_sel:WORD_1 src1_sel:DWORD
	v_add3_u32 v8, v8, v25, s56
	v_and_b32_sdwa v25, v9, v170 dst_sel:DWORD dst_unused:UNUSED_PAD src0_sel:WORD_1 src1_sel:DWORD
	v_add3_u32 v9, v9, v25, s56
	v_and_b32_e32 v24, 0xffff0000, v9
	v_cvt_pk_bf16_f32 v9, v10, v11
	v_or_b32_sdwa v8, v24, v8 dst_sel:DWORD dst_unused:UNUSED_PAD src0_sel:DWORD src1_sel:WORD_1
	global_store_dwordx2 v[16:17], v[8:9], off offset:32
	s_nop 0
	v_pk_fma_f32 v[4:5], v[4:5], v[88:89], v[218:219]
	s_nop 0
	v_mul_f32_e32 v8, v5, v5
	v_pk_fma_f32 v[6:7], v[6:7], v[90:91], v[220:221]
	v_fmac_f32_e32 v8, v4, v4
	v_fmac_f32_e32 v8, v6, v6
	global_store_dwordx4 v[18:19], v[4:7], off offset:128
	v_fmac_f32_e32 v8, v7, v7
	v_add_f32_e32 v28, v32, v8
	v_pk_mul_f32 v[6:7], v[6:7], v[150:151]
	v_pk_mul_f32 v[4:5], v[4:5], v[148:149]
	v_pk_add_f32 v[8:9], v[182:183], 1.0 op_sel_hi:[1,0]
	v_pk_add_f32 v[10:11], v[180:181], 1.0 op_sel_hi:[1,0]
	v_pk_mul_f32 v[6:7], v[6:7], v[8:9]
	v_pk_mul_f32 v[4:5], v[4:5], v[10:11]
	v_and_b32_sdwa v9, v4, v170 dst_sel:DWORD dst_unused:UNUSED_PAD src0_sel:WORD_1 src1_sel:DWORD
	v_add3_u32 v4, v4, v9, s56
	v_and_b32_sdwa v9, v5, v170 dst_sel:DWORD dst_unused:UNUSED_PAD src0_sel:WORD_1 src1_sel:DWORD
	v_add3_u32 v5, v5, v9, s56
	v_and_b32_e32 v8, 0xffff0000, v5
	v_cvt_pk_bf16_f32 v5, v6, v7
	v_or_b32_sdwa v4, v8, v4 dst_sel:DWORD dst_unused:UNUSED_PAD src0_sel:DWORD src1_sel:WORD_1
	global_store_dwordx2 v[16:17], v[4:5], off offset:64
	s_nop 0
	v_pk_fma_f32 v[0:1], v[0:1], v[136:137], v[222:223]
	s_nop 0
	v_mul_f32_e32 v4, v1, v1
	v_pk_fma_f32 v[2:3], v[2:3], v[138:139], v[224:225]
	v_fmac_f32_e32 v4, v0, v0
	v_fmac_f32_e32 v4, v2, v2
	global_store_dwordx4 v[18:19], v[0:3], off offset:192
	v_fmac_f32_e32 v4, v3, v3
	v_add_f32_e32 v18, v28, v4
	v_pk_mul_f32 v[2:3], v[2:3], v[154:155]
	v_pk_mul_f32 v[0:1], v[0:1], v[152:153]
	v_pk_add_f32 v[4:5], v[192:193], 1.0 op_sel_hi:[1,0]
	v_pk_add_f32 v[6:7], v[190:191], 1.0 op_sel_hi:[1,0]
	v_pk_mul_f32 v[2:3], v[2:3], v[4:5]
	v_pk_mul_f32 v[0:1], v[0:1], v[6:7]
	v_and_b32_sdwa v5, v0, v170 dst_sel:DWORD dst_unused:UNUSED_PAD src0_sel:WORD_1 src1_sel:DWORD
	v_add3_u32 v0, v0, v5, s56
	v_and_b32_sdwa v5, v1, v170 dst_sel:DWORD dst_unused:UNUSED_PAD src0_sel:WORD_1 src1_sel:DWORD
	v_add3_u32 v1, v1, v5, s56
	v_and_b32_e32 v4, 0xffff0000, v1
	v_cvt_pk_bf16_f32 v1, v2, v3
	v_or_b32_sdwa v0, v4, v0 dst_sel:DWORD dst_unused:UNUSED_PAD src0_sel:DWORD src1_sel:WORD_1
	global_store_dwordx2 v[16:17], v[0:1], off offset:96
	ds_bpermute_b32 v0, v105, v18
	s_waitcnt lgkmcnt(0)
	v_add_f32_e32 v0, v18, v0
	ds_bpermute_b32 v1, v104, v0
	s_and_saveexec_b64 s[0:1], vcc
	s_movk_i32 s89, 0xff
	s_cbranch_execz .LBB0_124
	v_readlane_b32 s2, v253, 20
	s_add_u32 s2, s26, s2
	s_addc_u32 s3, s27, 0
	v_lshl_add_u64 v[2:3], v[12:13], 2, s[2:3]
	s_waitcnt lgkmcnt(0)
	v_add_f32_e32 v0, v0, v1
	global_store_dword v[2:3], v0, off

.LBB0_143:
	s_add_i32 s29, s28, 2
	v_add_u32_e32 v117, v87, v88
	v_add_u32_e32 v116, v91, v88
	ds_read_b128 v[56:59], v117 offset:16384
	ds_read_b128 v[60:63], v116
	ds_read_b128 v[64:67], v117 offset:18432
	ds_read_b128 v[68:71], v116 offset:2048
	s_cmp_lt_u32 s28, 30
	s_cselect_b64 s[0:1], -1, 0
	s_and_b64 vcc, s[0:1], exec
	v_add_u32_e32 v118, v91, v89
	v_add_u32_e32 v119, v87, v89
	s_cselect_b32 s92, s27, 0xf80
	ds_read_b128 v[72:75], v117 offset:20480
	ds_read_b128 v[76:79], v117 offset:22528
	ds_read_b128 v[92:95], v118
	ds_read_b128 v[96:99], v118 offset:2048
	ds_read_b128 v[100:103], v119 offset:16384
	ds_read_b128 v[104:107], v119 offset:18432
	ds_read_b128 v[108:111], v119 offset:20480
	ds_read_b128 v[112:115], v119 offset:22528
	s_waitcnt vmcnt(5)
	ds_write_b128 v90, v[4:7] offset:32768
	s_waitcnt vmcnt(3)
	ds_write_b128 v90, v[32:35] offset:36864
	v_lshl_add_u64 v[32:33], v[80:81], 0, s[92:93]
	s_waitcnt lgkmcnt(12)
	v_mfma_f32_16x16x32_bf16 v[44:47], v[56:59], v[60:63], v[44:47]
	s_waitcnt vmcnt(2)
	ds_write_b128 v90, v[28:31] offset:40960
	s_waitcnt vmcnt(1)
	ds_write_b128 v90, v[24:27] offset:45056
	s_waitcnt vmcnt(1)
	ds_write_b128 v90, v[16:19] offset:49152
	v_lshl_add_u64 v[34:35], v[82:83], 0, s[92:93]
	s_waitcnt vmcnt(0)
	ds_write_b128 v90, v[20:23] offset:53248
	s_waitcnt lgkmcnt(14)
	v_mfma_f32_16x16x32_bf16 v[4:7], v[56:59], v[68:71], v[36:39]
	global_load_dwordx4 v[56:59], v[34:35], off
	s_addk_i32 s27, 0x100
	s_nop 0
	v_add_co_u32_e64 v36, s[0:1], s33, v32
	v_mfma_f32_16x16x32_bf16 v[52:55], v[64:67], v[60:63], v[52:55]
	s_nop 0
	v_addc_co_u32_e64 v37, s[0:1], 0, v33, s[0:1]
	v_add_co_u32_e64 v38, s[0:1], s7, v32
	s_waitcnt lgkmcnt(13)
	v_mfma_f32_16x16x32_bf16 v[48:51], v[72:75], v[60:63], v[48:51]
	v_addc_co_u32_e64 v39, s[0:1], 0, v33, s[0:1]
	s_waitcnt lgkmcnt(12)
	v_mfma_f32_16x16x32_bf16 v[40:43], v[76:79], v[60:63], v[40:43]
	s_waitcnt lgkmcnt(9)
	v_mfma_f32_16x16x32_bf16 v[16:19], v[100:103], v[92:95], v[44:47]
	s_nop 2
	v_add_co_u32_e64 v44, s[0:1], s90, v32
	v_mfma_f32_16x16x32_bf16 v[8:11], v[64:67], v[68:71], v[8:11]
	s_nop 0
	v_addc_co_u32_e64 v45, s[0:1], 0, v33, s[0:1]
	v_add_co_u32_e64 v34, s[0:1], s33, v34
	v_mfma_f32_16x16x32_bf16 v[0:3], v[72:75], v[68:71], v[0:3]
	s_nop 0
	v_addc_co_u32_e64 v35, s[0:1], 0, v35, s[0:1]
	global_load_dwordx4 v[64:67], v[32:33], off
	global_load_dwordx4 v[60:63], v[36:37], off
	v_mfma_f32_16x16x32_bf16 v[12:15], v[76:79], v[68:71], v[12:15]
	global_load_dwordx4 v[68:71], v[38:39], off
	global_load_dwordx4 v[72:75], v[44:45], off
	global_load_dwordx4 v[76:79], v[34:35], off
	s_waitcnt lgkmcnt(0)
	s_barrier
	v_mfma_f32_16x16x32_bf16 v[20:23], v[104:107], v[92:95], v[52:55]
	ds_read_b128 v[32:35], v117 offset:49152
	ds_read_b128 v[36:39], v117 offset:51200
	s_min_u32 s0, s28, 28
	v_mfma_f32_16x16x32_bf16 v[24:27], v[108:111], v[92:95], v[48:51]
	s_lshl_b32 s92, s0, 7
	s_mov_b32 s28, s29
	v_mfma_f32_16x16x32_bf16 v[28:31], v[112:115], v[92:95], v[40:43]
	s_nop 2
	ds_read_b128 v[40:43], v116 offset:32768
	ds_read_b128 v[44:47], v116 offset:34816
	ds_read_b128 v[48:51], v117 offset:53248
	ds_read_b128 v[52:55], v117 offset:55296
	v_mfma_f32_16x16x32_bf16 v[8:11], v[104:107], v[96:99], v[8:11]
	v_mfma_f32_16x16x32_bf16 v[4:7], v[100:103], v[96:99], v[4:7]
	v_mfma_f32_16x16x32_bf16 v[0:3], v[108:111], v[96:99], v[0:3]
	v_lshl_add_u64 v[108:109], v[80:81], 0, s[92:93]
	v_lshl_add_u64 v[110:111], v[82:83], 0, s[92:93]
	s_waitcnt lgkmcnt(3)
	v_mfma_f32_16x16x32_bf16 v[16:19], v[32:35], v[40:43], v[16:19]
	v_mfma_f32_16x16x32_bf16 v[20:23], v[36:39], v[40:43], v[20:23]
	s_waitcnt lgkmcnt(1)
	v_mfma_f32_16x16x32_bf16 v[24:27], v[48:51], v[40:43], v[24:27]
	s_waitcnt lgkmcnt(0)
	v_mfma_f32_16x16x32_bf16 v[28:31], v[52:55], v[40:43], v[28:31]
	v_mfma_f32_16x16x32_bf16 v[8:11], v[36:39], v[44:47], v[8:11]
	ds_read_b128 v[36:39], v119 offset:49152
	ds_read_b128 v[40:43], v118 offset:32768
	ds_read_b128 v[92:95], v119 offset:51200
	v_mfma_f32_16x16x32_bf16 v[12:15], v[112:115], v[96:99], v[12:15]
	v_add_co_u32_e64 v112, s[0:1], s33, v108
	v_mfma_f32_16x16x32_bf16 v[32:35], v[32:35], v[44:47], v[4:7]
	s_nop 0
	v_addc_co_u32_e64 v113, s[0:1], 0, v109, s[0:1]
	s_nop 0
	global_load_dwordx4 v[4:7], v[108:109], off offset:384
	ds_read_b128 v[96:99], v118 offset:34816
	ds_read_b128 v[100:103], v119 offset:53248
	ds_read_b128 v[104:107], v119 offset:55296
	v_mfma_f32_16x16x32_bf16 v[12:15], v[52:55], v[44:47], v[12:15]
	s_waitcnt lgkmcnt(3)
	v_mfma_f32_16x16x32_bf16 v[52:55], v[92:95], v[40:43], v[20:23]
	s_nop 2
	v_add_co_u32_e64 v20, s[0:1], s7, v108
	v_mfma_f32_16x16x32_bf16 v[0:3], v[48:51], v[44:47], v[0:3]
	s_nop 0
	v_addc_co_u32_e64 v21, s[0:1], 0, v109, s[0:1]
	v_add_co_u32_e64 v22, s[0:1], s90, v108
	v_mfma_f32_16x16x32_bf16 v[44:47], v[36:39], v[40:43], v[16:19]
	s_nop 0
	v_addc_co_u32_e64 v23, s[0:1], 0, v109, s[0:1]
	v_add_co_u32_e64 v108, s[0:1], s33, v110
	s_waitcnt lgkmcnt(1)
	v_mfma_f32_16x16x32_bf16 v[48:51], v[100:103], v[40:43], v[24:27]
	global_load_dwordx4 v[16:19], v[110:111], off offset:384
	v_addc_co_u32_e64 v109, s[0:1], 0, v111, s[0:1]
	s_waitcnt lgkmcnt(0)
	v_mfma_f32_16x16x32_bf16 v[40:43], v[104:107], v[40:43], v[28:31]
	v_mfma_f32_16x16x32_bf16 v[36:39], v[36:39], v[96:99], v[32:35]
	s_nop 2
	global_load_dwordx4 v[32:35], v[112:113], off offset:384
	global_load_dwordx4 v[28:31], v[20:21], off offset:384
	global_load_dwordx4 v[24:27], v[22:23], off offset:384
	s_nop 0
	global_load_dwordx4 v[20:23], v[108:109], off offset:384
	v_mfma_f32_16x16x32_bf16 v[8:11], v[92:95], v[96:99], v[8:11]
	s_waitcnt vmcnt(10)
	ds_write_b128 v90, v[64:67]
	ds_write_b128 v90, v[56:59] offset:16384
	s_waitcnt vmcnt(9)
	ds_write_b128 v90, v[60:63] offset:4096
	s_waitcnt vmcnt(8)
	ds_write_b128 v90, v[68:71] offset:8192
	s_waitcnt vmcnt(7)
	ds_write_b128 v90, v[72:75] offset:12288
	s_waitcnt vmcnt(6)
	ds_write_b128 v90, v[76:79] offset:20480
	s_waitcnt lgkmcnt(0)
	s_barrier
	v_mfma_f32_16x16x32_bf16 v[0:3], v[100:103], v[96:99], v[0:3]
	v_mfma_f32_16x16x32_bf16 v[12:15], v[104:107], v[96:99], v[12:15]
	s_cbranch_vccnz .LBB0_143
	s_lshl_b32 s0, s2, 10
	s_waitcnt vmcnt(5)
	v_or_b32_e32 v4, s26, v85
	s_waitcnt vmcnt(4)
	v_add3_u32 v16, v4, v86, s0
	v_add_u32_e32 v4, 0x2000, v16
	v_ashrrev_i32_e32 v5, 31, v4
	v_readlane_b32 s16, v251, 20
	v_lshlrev_b64 v[4:5], 11, v[4:5]
	v_readlane_b32 s17, v251, 21
	s_lshl_b32 s0, s3, 1
	s_nop 0
	v_lshl_add_u64 v[4:5], s[16:17], 0, v[4:5]
	v_lshl_or_b32 v128, v84, 3, s0
	v_lshl_add_u64 v[4:5], v[4:5], 0, v[128:129]
	v_cvt_pk_bf16_f32 v7, v46, v47
	v_cvt_pk_bf16_f32 v6, v44, v45
	global_store_dwordx2 v[4:5], v[6:7], off
	v_cvt_pk_bf16_f32 v7, v54, v55
	v_cvt_pk_bf16_f32 v6, v52, v53
	global_store_dwordx2 v[4:5], v[6:7], off offset:32
	v_cvt_pk_bf16_f32 v7, v50, v51
	v_cvt_pk_bf16_f32 v6, v48, v49
	global_store_dwordx2 v[4:5], v[6:7], off offset:64
	v_cvt_pk_bf16_f32 v7, v42, v43
	v_cvt_pk_bf16_f32 v6, v40, v41
	global_store_dwordx2 v[4:5], v[6:7], off offset:96
	v_add_u32_e32 v4, 0x2010, v16
	v_ashrrev_i32_e32 v5, 31, v4
	v_lshlrev_b64 v[4:5], 11, v[4:5]
	v_lshl_add_u64 v[4:5], s[16:17], 0, v[4:5]
	v_lshl_add_u64 v[4:5], v[4:5], 0, v[128:129]
	v_cvt_pk_bf16_f32 v7, v38, v39
	v_cvt_pk_bf16_f32 v6, v36, v37
	global_store_dwordx2 v[4:5], v[6:7], off
	v_and_b32_sdwa v6, v10, v170 dst_sel:DWORD dst_unused:UNUSED_PAD src0_sel:WORD_1 src1_sel:DWORD
	v_and_b32_sdwa v7, v8, v170 dst_sel:DWORD dst_unused:UNUSED_PAD src0_sel:WORD_1 src1_sel:DWORD
	v_add3_u32 v8, v8, v7, s56
	v_add3_u32 v6, v10, v6, s56
	v_and_b32_sdwa v7, v11, v170 dst_sel:DWORD dst_unused:UNUSED_PAD src0_sel:WORD_1 src1_sel:DWORD
	v_and_b32_sdwa v10, v9, v170 dst_sel:DWORD dst_unused:UNUSED_PAD src0_sel:WORD_1 src1_sel:DWORD
	v_add3_u32 v7, v11, v7, s56
	v_add3_u32 v9, v9, v10, s56
	v_and_b32_e32 v7, 0xffff0000, v7
	v_and_b32_e32 v9, 0xffff0000, v9
	v_or_b32_sdwa v7, v7, v6 dst_sel:DWORD dst_unused:UNUSED_PAD src0_sel:DWORD src1_sel:WORD_1
	v_or_b32_sdwa v6, v9, v8 dst_sel:DWORD dst_unused:UNUSED_PAD src0_sel:DWORD src1_sel:WORD_1
	global_store_dwordx2 v[4:5], v[6:7], off offset:32
	v_and_b32_sdwa v7, v0, v170 dst_sel:DWORD dst_unused:UNUSED_PAD src0_sel:WORD_1 src1_sel:DWORD
	v_add3_u32 v0, v0, v7, s56
	v_and_b32_sdwa v7, v1, v170 dst_sel:DWORD dst_unused:UNUSED_PAD src0_sel:WORD_1 src1_sel:DWORD
	v_add3_u32 v1, v1, v7, s56
	v_and_b32_e32 v6, 0xffff0000, v1
	v_cvt_pk_bf16_f32 v1, v2, v3
	v_or_b32_sdwa v0, v6, v0 dst_sel:DWORD dst_unused:UNUSED_PAD src0_sel:DWORD src1_sel:WORD_1
	global_store_dwordx2 v[4:5], v[0:1], off offset:64
	v_cvt_pk_bf16_f32 v1, v14, v15
	v_cvt_pk_bf16_f32 v0, v12, v13
	s_movk_i32 s89, 0xff
	global_store_dwordx2 v[4:5], v[0:1], off offset:96

.LBB0_163:
	s_or_b64 exec, exec, s[0:1]
	s_mov_b64 s[0:1], src_shared_base
	s_add_i32 s0, 0, 0x11fe0
	s_cmp_lg_u32 s0, -1
	s_cselect_b32 s0, s0, 0
	s_cselect_b32 s1, s1, 0
	v_mov_b32_e32 v0, s0
	v_mov_b32_e32 v1, s1
	s_waitcnt lgkmcnt(0)
	s_barrier
	flat_load_dword v8, v[0:1] sc0 sc1
	s_waitcnt vmcnt(0)
	s_movk_i32 s0, 0x880
	s_waitcnt lgkmcnt(0)
	v_cmp_gt_i32_e32 vcc, s0, v8
	s_mov_b64 s[0:1], -1
	s_and_saveexec_b64 s[26:27], vcc
	s_cbranch_execz .LBB0_158
	s_movk_i32 s0, 0x1ff
	v_cmp_lt_i32_e32 vcc, s0, v8
	s_and_saveexec_b64 s[0:1], vcc
	s_xor_b64 s[48:49], exec, s[0:1]
	s_cbranch_execz .LBB0_197
	s_movk_i32 s0, 0x5ff
	v_cmp_lt_u32_e32 vcc, s0, v8
	s_and_saveexec_b64 s[0:1], vcc
	s_xor_b64 s[2:3], exec, s[0:1]
	s_cbranch_execz .LBB0_167
	s_movk_i32 s0, 0x67f
	v_cmp_lt_u32_e32 vcc, s0, v8
	v_mov_b32_e32 v0, 0xfffffa00
	v_mov_b32_e32 v1, 0xfffff980
	v_cndmask_b32_e32 v0, v0, v1, vcc
	v_cndmask_b32_e64 v2, 4, 2, vcc
	v_cndmask_b32_e64 v1, 6, 4, vcc
	v_cndmask_b32_e64 v3, 3, 1, vcc
	v_add_u32_e32 v0, v0, v8
	v_lshrrev_b32_e32 v2, v2, v8
	v_lshrrev_b32_e32 v128, v1, v0
	v_lshrrev_b32_e32 v3, v3, v8
	v_mov_b32_e32 v0, 0x2000
	v_lshlrev_b32_e32 v2, 7, v2
	v_lshl_add_u32 v0, v128, 10, v0
	v_lshlrev_b32_e32 v1, 8, v128
	v_and_b32_e32 v130, 0x180, v2
	v_lshlrev_b32_e32 v2, 7, v3
	v_mov_b32_e32 v104, v166
	v_cndmask_b32_e64 v4, 7, 1, vcc
	v_cndmask_b32_e32 v0, v0, v1, vcc
	s_barrier
	v_mov_b32_e32 v1, v129
	v_readlane_b32 s0, v251, 32
	v_and_b32_e32 v132, 0x80, v2
	v_and_b32_e32 v4, v4, v8
	v_ashrrev_i32_e32 v6, 3, v104
	v_lshlrev_b64 v[0:1], 10, v[0:1]
	v_readlane_b32 s1, v251, 33
	v_add_u32_e32 v2, v6, v132
	v_lshlrev_b32_e32 v133, 7, v4
	v_lshl_add_u64 v[0:1], s[0:1], 0, v[0:1]
	v_ashrrev_i32_e32 v3, 31, v2
	v_readlane_b32 s0, v250, 37
	v_lshlrev_b64 v[34:35], 20, v[128:129]
	v_lshlrev_b64 v[32:33], 18, v[128:129]
	v_lshlrev_b32_e32 v128, 1, v130
	v_lshlrev_b64 v[2:3], 8, v[2:3]
	v_readlane_b32 s1, v250, 38
	v_lshlrev_b32_e32 v7, 4, v104
	v_add_u32_e32 v4, v6, v133
	v_lshl_add_u64 v[0:1], v[0:1], 0, v[128:129]
	v_lshl_add_u64 v[2:3], s[0:1], 0, v[2:3]
	v_and_b32_e32 v128, 0x70, v7
	v_ashrrev_i32_e32 v5, 31, v4
	v_lshl_add_u64 v[2:3], v[2:3], 0, v[128:129]
	v_lshlrev_b64 v[4:5], 10, v[4:5]
	s_movk_i32 s0, 0x2000
	v_lshl_add_u64 v[0:1], v[0:1], 0, v[4:5]
	v_add_co_u32_e64 v4, s[0:1], s0, v2
	global_load_dwordx4 v[12:15], v[2:3], off
	s_nop 0
	v_addc_co_u32_e64 v5, s[0:1], 0, v3, s[0:1]
	s_movk_i32 s0, 0x4000
	s_nop 0
	v_add_co_u32_e64 v8, s[0:1], s0, v2
	global_load_dwordx4 v[16:19], v[4:5], off
	s_nop 0
	v_addc_co_u32_e64 v9, s[0:1], 0, v3, s[0:1]
	global_load_dwordx4 v[20:23], v[8:9], off
	v_add_co_u32_e64 v50, s[0:1], s58, v2
	v_lshl_add_u64 v[48:49], v[0:1], 0, v[128:129]
	s_nop 0
	v_addc_co_u32_e64 v51, s[0:1], 0, v3, s[0:1]
	global_load_dwordx4 v[24:27], v[50:51], off
	global_load_dwordx4 v[28:31], v[48:49], off
	s_mov_b32 s0, 0x8000
	v_add_co_u32_e64 v52, s[0:1], s0, v48
	v_ashrrev_i32_e32 v0, 1, v104
	s_nop 0
	v_addc_co_u32_e64 v53, s[0:1], 0, v49, s[0:1]
	v_add_co_u32_e64 v54, s[0:1], s11, v48
	global_load_dwordx4 v[36:39], v[52:53], off
	s_nop 0
	v_addc_co_u32_e64 v55, s[0:1], 0, v49, s[0:1]
	global_load_dwordx4 v[40:43], v[54:55], off
	v_add_co_u32_e64 v56, s[0:1], s60, v48
	v_and_b32_e32 v134, 15, v104
	s_nop 0
	v_addc_co_u32_e64 v57, s[0:1], 0, v49, s[0:1]
	global_load_dwordx4 v[44:47], v[56:57], off
	v_and_b32_e32 v135, 0xffffffc0, v0
	v_lshlrev_b32_e32 v0, 7, v6
	v_xor_b32_e32 v1, v7, v104
	s_movk_i32 s0, 0x70
	v_bfe_u32 v128, v104, 6, 1
	v_lshlrev_b32_e32 v6, 7, v134
	v_and_or_b32 v0, v1, s0, v0
	v_lshl_or_b32 v59, v128, 13, v6
	v_add_u32_e32 v136, 0, v0
	global_load_dwordx4 v[0:3], v[2:3], off offset:128
	s_nop 0
	global_load_dwordx4 v[4:7], v[4:5], off offset:128
	s_nop 0
	global_load_dwordx4 v[8:11], v[8:9], off offset:128
	s_waitcnt vmcnt(10)
	ds_write_b128 v136, v[12:15]
	s_waitcnt vmcnt(9)
	ds_write_b128 v136, v[16:19] offset:4096
	s_waitcnt vmcnt(8)
	ds_write_b128 v136, v[20:23] offset:8192
	global_load_dwordx4 v[12:15], v[50:51], off offset:128
	global_load_dwordx4 v[16:19], v[48:49], off offset:128
	global_load_dwordx4 v[20:23], v[52:53], off offset:128
	v_lshrrev_b32_e32 v58, 4, v104
	v_bfe_u32 v105, v104, 1, 3
	v_add_u32_e32 v106, 0, v59
	s_waitcnt vmcnt(10)
	ds_write_b128 v136, v[24:27] offset:12288
	global_load_dwordx4 v[24:27], v[54:55], off offset:128
	s_waitcnt vmcnt(10)
	ds_write_b128 v136, v[28:31] offset:16384
	global_load_dwordx4 v[28:31], v[56:57], off offset:128
	v_bfe_u32 v137, v104, 4, 2
	v_bitop3_b32 v104, v137, v105, 4 bitop3:0x36
	v_lshlrev_b32_e32 v109, 4, v104
	v_add_u32_e32 v122, v106, v109
	s_mov_b64 s[0:1], 0x800000
	v_lshl_add_u64 v[34:35], v[34:35], 0, s[0:1]
	s_waitcnt vmcnt(10)
	ds_write_b128 v136, v[36:39] offset:20480
	v_bitop3_b32 v36, v58, v105, 3 bitop3:0x6c
	v_readlane_b32 s0, v251, 26
	s_waitcnt vmcnt(9)
	ds_write_b128 v136, v[40:43] offset:24576
	v_lshlrev_b32_e32 v40, 4, v36
	v_add_u32_e32 v120, v106, v40
	v_or_b32_e32 v41, v135, v134
	v_lshl_add_u32 v108, v41, 7, 0
	v_add_u32_e32 v121, v108, v40
	s_waitcnt vmcnt(8)
	ds_write_b128 v136, v[44:47] offset:28672
	s_waitcnt lgkmcnt(0)
	s_barrier
	ds_read_b128 v[36:39], v120 offset:16384
	ds_read_b128 v[48:51], v120 offset:18432
	ds_read_b128 v[56:59], v120 offset:20480
	ds_read_b128 v[64:67], v120 offset:22528
	ds_read_b128 v[40:43], v121
	ds_read_b128 v[68:71], v121 offset:2048
	ds_read_b128 v[84:87], v121 offset:4096
	ds_read_b128 v[100:103], v121 offset:6144
	ds_read_b128 v[104:107], v122 offset:16384
	v_add_u32_e32 v124, v108, v109
	ds_read_b128 v[108:111], v122 offset:18432
	ds_read_b128 v[112:115], v122 offset:20480
	ds_read_b128 v[116:119], v122 offset:22528
	s_waitcnt lgkmcnt(7)
	v_mfma_f32_16x16x32_bf16 v[44:47], v[36:39], v[40:43], 0
	v_cndmask_b32_e32 v33, v35, v33, vcc
	v_cndmask_b32_e32 v32, v34, v32, vcc
	v_readlane_b32 s1, v251, 27
	v_mfma_f32_16x16x32_bf16 v[52:55], v[48:51], v[40:43], 0
	s_nop 0
	v_lshl_add_u64 v[32:33], v[32:33], 1, s[0:1]
	s_movk_i32 s0, 0x4f
	v_mfma_f32_16x16x32_bf16 v[60:63], v[56:59], v[40:43], 0
	v_mfma_f32_16x16x32_bf16 v[40:43], v[64:67], v[40:43], 0
	s_waitcnt lgkmcnt(6)
	v_mfma_f32_16x16x32_bf16 v[72:75], v[36:39], v[68:71], 0
	v_mfma_f32_16x16x32_bf16 v[76:79], v[48:51], v[68:71], 0
	v_mfma_f32_16x16x32_bf16 v[80:83], v[56:59], v[68:71], 0
	v_mfma_f32_16x16x32_bf16 v[68:71], v[64:67], v[68:71], 0
	s_waitcnt lgkmcnt(5)
	v_mfma_f32_16x16x32_bf16 v[88:91], v[36:39], v[84:87], 0
	v_mfma_f32_16x16x32_bf16 v[92:95], v[48:51], v[84:87], 0
	v_mfma_f32_16x16x32_bf16 v[96:99], v[56:59], v[84:87], 0
	v_mfma_f32_16x16x32_bf16 v[84:87], v[64:67], v[84:87], 0
	s_waitcnt lgkmcnt(4)
	v_mfma_f32_16x16x32_bf16 v[36:39], v[36:39], v[100:103], 0
	v_mfma_f32_16x16x32_bf16 v[48:51], v[48:51], v[100:103], 0
	v_mfma_f32_16x16x32_bf16 v[56:59], v[56:59], v[100:103], 0
	v_mfma_f32_16x16x32_bf16 v[64:67], v[64:67], v[100:103], 0
	ds_read_b128 v[100:103], v124
	s_waitcnt lgkmcnt(0)
	v_mfma_f32_16x16x32_bf16 v[44:47], v[104:107], v[100:103], v[44:47]
	v_mfma_f32_16x16x32_bf16 v[52:55], v[108:111], v[100:103], v[52:55]
	v_mfma_f32_16x16x32_bf16 v[60:63], v[112:115], v[100:103], v[60:63]
	v_mfma_f32_16x16x32_bf16 v[40:43], v[116:119], v[100:103], v[40:43]
	ds_read_b128 v[100:103], v124 offset:2048
	s_waitcnt lgkmcnt(0)
	v_mfma_f32_16x16x32_bf16 v[72:75], v[104:107], v[100:103], v[72:75]
	v_mfma_f32_16x16x32_bf16 v[76:79], v[108:111], v[100:103], v[76:79]
	v_mfma_f32_16x16x32_bf16 v[80:83], v[112:115], v[100:103], v[80:83]
	v_mfma_f32_16x16x32_bf16 v[68:71], v[116:119], v[100:103], v[68:71]
	ds_read_b128 v[100:103], v124 offset:4096
	s_waitcnt lgkmcnt(0)
	v_mfma_f32_16x16x32_bf16 v[88:91], v[104:107], v[100:103], v[88:91]
	v_mfma_f32_16x16x32_bf16 v[92:95], v[108:111], v[100:103], v[92:95]
	v_mfma_f32_16x16x32_bf16 v[96:99], v[112:115], v[100:103], v[96:99]
	v_mfma_f32_16x16x32_bf16 v[84:87], v[116:119], v[100:103], v[84:87]
	ds_read_b128 v[100:103], v124 offset:6144
	s_waitcnt vmcnt(7)
	ds_write_b128 v136, v[0:3] offset:32768
	s_waitcnt vmcnt(6)
	ds_write_b128 v136, v[4:7] offset:36864
	s_waitcnt vmcnt(5)
	ds_write_b128 v136, v[8:11] offset:40960
	s_waitcnt vmcnt(4)
	ds_write_b128 v136, v[12:15] offset:45056
	s_waitcnt vmcnt(3)
	ds_write_b128 v136, v[16:19] offset:49152
	s_waitcnt vmcnt(2)
	ds_write_b128 v136, v[20:23] offset:53248
	s_waitcnt vmcnt(1)
	ds_write_b128 v136, v[24:27] offset:57344
	s_waitcnt vmcnt(0)
	ds_write_b128 v136, v[28:31] offset:61440
	s_waitcnt lgkmcnt(0)
	v_mfma_f32_16x16x32_bf16 v[36:39], v[104:107], v[100:103], v[36:39]
	s_barrier
	ds_read_b128 v[104:107], v120 offset:49152
	v_mfma_f32_16x16x32_bf16 v[48:51], v[108:111], v[100:103], v[48:51]
	ds_read_b128 v[108:111], v120 offset:51200
	v_mfma_f32_16x16x32_bf16 v[56:59], v[112:115], v[100:103], v[56:59]
	ds_read_b128 v[112:115], v120 offset:53248
	v_mfma_f32_16x16x32_bf16 v[64:67], v[116:119], v[100:103], v[64:67]
	ds_read_b128 v[116:119], v120 offset:55296
	ds_read_b128 v[100:103], v121 offset:32768
	s_waitcnt lgkmcnt(0)
	v_mfma_f32_16x16x32_bf16 v[44:47], v[104:107], v[100:103], v[44:47]
	v_mfma_f32_16x16x32_bf16 v[52:55], v[108:111], v[100:103], v[52:55]
	v_mfma_f32_16x16x32_bf16 v[60:63], v[112:115], v[100:103], v[60:63]
	v_mfma_f32_16x16x32_bf16 v[40:43], v[116:119], v[100:103], v[40:43]
	ds_read_b128 v[100:103], v121 offset:34816
	s_waitcnt lgkmcnt(0)
	v_mfma_f32_16x16x32_bf16 v[72:75], v[104:107], v[100:103], v[72:75]
	v_mfma_f32_16x16x32_bf16 v[76:79], v[108:111], v[100:103], v[76:79]
	v_mfma_f32_16x16x32_bf16 v[80:83], v[112:115], v[100:103], v[80:83]
	v_mfma_f32_16x16x32_bf16 v[68:71], v[116:119], v[100:103], v[68:71]
	ds_read_b128 v[100:103], v121 offset:36864
	s_waitcnt lgkmcnt(0)
	v_mfma_f32_16x16x32_bf16 v[88:91], v[104:107], v[100:103], v[88:91]
	v_mfma_f32_16x16x32_bf16 v[92:95], v[108:111], v[100:103], v[92:95]
	v_mfma_f32_16x16x32_bf16 v[96:99], v[112:115], v[100:103], v[96:99]
	v_mfma_f32_16x16x32_bf16 v[84:87], v[116:119], v[100:103], v[84:87]
	ds_read_b128 v[100:103], v121 offset:38912
	s_waitcnt lgkmcnt(0)
	v_mfma_f32_16x16x32_bf16 v[36:39], v[104:107], v[100:103], v[36:39]
	ds_read_b128 v[104:107], v122 offset:49152
	v_mfma_f32_16x16x32_bf16 v[48:51], v[108:111], v[100:103], v[48:51]
	ds_read_b128 v[108:111], v122 offset:51200
	v_mfma_f32_16x16x32_bf16 v[56:59], v[112:115], v[100:103], v[56:59]
	ds_read_b128 v[112:115], v122 offset:53248
	v_mfma_f32_16x16x32_bf16 v[64:67], v[116:119], v[100:103], v[64:67]
	ds_read_b128 v[116:119], v122 offset:55296
	ds_read_b128 v[100:103], v124 offset:32768
	s_waitcnt lgkmcnt(0)
	v_mfma_f32_16x16x32_bf16 v[44:47], v[104:107], v[100:103], v[44:47]
	v_mfma_f32_16x16x32_bf16 v[52:55], v[108:111], v[100:103], v[52:55]
	v_mfma_f32_16x16x32_bf16 v[60:63], v[112:115], v[100:103], v[60:63]
	v_mfma_f32_16x16x32_bf16 v[40:43], v[116:119], v[100:103], v[40:43]
	ds_read_b128 v[100:103], v124 offset:34816
	ds_read_b128 v[120:123], v124 offset:36864
	ds_read_b128 v[124:127], v124 offset:38912
	ds_write_b128 v136, v[0:3]
	v_or_b32_e32 v0, v134, v132
	v_add_u32_e32 v0, v0, v135
	ds_write_b128 v136, v[4:7] offset:4096
	ds_write_b128 v136, v[8:11] offset:8192
	ds_write_b128 v136, v[12:15] offset:12288
	ds_write_b128 v136, v[16:19] offset:16384
	ds_write_b128 v136, v[20:23] offset:20480
	ds_write_b128 v136, v[24:27] offset:24576
	s_waitcnt lgkmcnt(8)
	v_mfma_f32_16x16x32_bf16 v[20:23], v[116:119], v[120:123], v[84:87]
	v_lshlrev_b32_e32 v1, 6, v128
	v_lshlrev_b32_e32 v2, 2, v137
	ds_write_b128 v136, v[28:31] offset:28672
	v_and_or_b32 v85, v0, s0, v130
	v_cndmask_b32_e64 v86, 11, 9, vcc
	v_or3_b32 v84, v1, v2, v133
	v_lshlrev_b32_e32 v1, v86, v85
	v_lshlrev_b32_e32 v128, 1, v1
	v_ashrrev_i32_e32 v0, 7, v0
	v_cndmask_b32_e64 v1, 10, 8, vcc
	s_waitcnt lgkmcnt(8)
	v_mfma_f32_16x16x32_bf16 v[24:27], v[104:107], v[124:127], v[36:39]
	v_lshl_add_u64 v[34:35], v[32:33], 0, v[128:129]
	v_lshlrev_b32_e32 v128, 1, v84
	s_waitcnt lgkmcnt(0)
	v_lshlrev_b32_e32 v36, v1, v0
	v_and_b32_sdwa v38, v46, v170 dst_sel:DWORD dst_unused:UNUSED_PAD src0_sel:WORD_1 src1_sel:DWORD
	v_and_b32_sdwa v39, v44, v170 dst_sel:DWORD dst_unused:UNUSED_PAD src0_sel:WORD_1 src1_sel:DWORD
	v_ashrrev_i32_e32 v37, 31, v36
	v_add3_u32 v44, v44, v39, s56
	v_add3_u32 v38, v46, v38, s56
	v_and_b32_sdwa v39, v47, v170 dst_sel:DWORD dst_unused:UNUSED_PAD src0_sel:WORD_1 src1_sel:DWORD
	v_and_b32_sdwa v46, v45, v170 dst_sel:DWORD dst_unused:UNUSED_PAD src0_sel:WORD_1 src1_sel:DWORD
	v_lshlrev_b64 v[36:37], 1, v[36:37]
	v_add3_u32 v39, v47, v39, s56
	v_add3_u32 v45, v45, v46, s56
	v_lshl_add_u64 v[34:35], v[34:35], 0, v[36:37]
	v_and_b32_e32 v39, 0xffff0000, v39
	v_and_b32_e32 v45, 0xffff0000, v45
	v_lshl_add_u64 v[34:35], v[34:35], 0, v[128:129]
	v_or_b32_sdwa v39, v39, v38 dst_sel:DWORD dst_unused:UNUSED_PAD src0_sel:DWORD src1_sel:WORD_1
	v_or_b32_sdwa v38, v45, v44 dst_sel:DWORD dst_unused:UNUSED_PAD src0_sel:DWORD src1_sel:WORD_1
	s_barrier
	global_store_dwordx2 v[34:35], v[38:39], off
	v_cvt_pk_bf16_f32 v39, v54, v55
	v_cvt_pk_bf16_f32 v38, v52, v53
	global_store_dwordx2 v[34:35], v[38:39], off offset:32
	v_cvt_pk_bf16_f32 v39, v62, v63
	v_cvt_pk_bf16_f32 v38, v60, v61
	global_store_dwordx2 v[34:35], v[38:39], off offset:64
	v_and_b32_sdwa v38, v42, v170 dst_sel:DWORD dst_unused:UNUSED_PAD src0_sel:WORD_1 src1_sel:DWORD
	v_and_b32_sdwa v39, v40, v170 dst_sel:DWORD dst_unused:UNUSED_PAD src0_sel:WORD_1 src1_sel:DWORD
	v_add3_u32 v40, v40, v39, s56
	v_add3_u32 v38, v42, v38, s56
	v_and_b32_sdwa v39, v43, v170 dst_sel:DWORD dst_unused:UNUSED_PAD src0_sel:WORD_1 src1_sel:DWORD
	v_and_b32_sdwa v42, v41, v170 dst_sel:DWORD dst_unused:UNUSED_PAD src0_sel:WORD_1 src1_sel:DWORD
	v_mfma_f32_16x16x32_bf16 v[72:75], v[104:107], v[100:103], v[72:75]
	v_add3_u32 v39, v43, v39, s56
	v_add3_u32 v41, v41, v42, s56
	v_and_b32_e32 v39, 0xffff0000, v39
	v_and_b32_e32 v41, 0xffff0000, v41
	v_or_b32_sdwa v39, v39, v38 dst_sel:DWORD dst_unused:UNUSED_PAD src0_sel:DWORD src1_sel:WORD_1
	v_or_b32_sdwa v38, v41, v40 dst_sel:DWORD dst_unused:UNUSED_PAD src0_sel:DWORD src1_sel:WORD_1
	global_store_dwordx2 v[34:35], v[38:39], off offset:96
	v_or_b32_e32 v34, 16, v85
	v_lshlrev_b32_e32 v34, v86, v34
	v_mfma_f32_16x16x32_bf16 v[76:79], v[108:111], v[100:103], v[76:79]
	v_lshlrev_b32_e32 v34, 1, v34
	v_mov_b32_e32 v35, v129
	v_lshl_add_u64 v[34:35], v[32:33], 0, v[34:35]
	v_lshl_add_u64 v[34:35], v[34:35], 0, v[36:37]
	v_lshl_add_u64 v[34:35], v[34:35], 0, v[128:129]
	v_cvt_pk_bf16_f32 v39, v74, v75
	v_cvt_pk_bf16_f32 v38, v72, v73
	global_store_dwordx2 v[34:35], v[38:39], off
	v_mfma_f32_16x16x32_bf16 v[80:83], v[112:115], v[100:103], v[80:83]
	v_cvt_pk_bf16_f32 v39, v78, v79
	v_cvt_pk_bf16_f32 v38, v76, v77
	global_store_dwordx2 v[34:35], v[38:39], off offset:32
	v_mfma_f32_16x16x32_bf16 v[68:71], v[116:119], v[100:103], v[68:71]
	s_nop 3
	v_cvt_pk_bf16_f32 v39, v82, v83
	s_nop 2
	v_cvt_pk_bf16_f32 v38, v80, v81
	global_store_dwordx2 v[34:35], v[38:39], off offset:64
	v_mfma_f32_16x16x32_bf16 v[8:11], v[104:107], v[120:123], v[88:91]
	s_nop 3
	v_cvt_pk_bf16_f32 v39, v70, v71
	s_nop 2
	v_cvt_pk_bf16_f32 v38, v68, v69
	global_store_dwordx2 v[34:35], v[38:39], off offset:96
	v_or_b32_e32 v34, 32, v85
	v_lshlrev_b32_e32 v34, v86, v34
	s_nop 2
	v_and_b32_sdwa v39, v8, v170 dst_sel:DWORD dst_unused:UNUSED_PAD src0_sel:WORD_1 src1_sel:DWORD
	v_mfma_f32_16x16x32_bf16 v[12:15], v[108:111], v[120:123], v[92:95]
	v_lshlrev_b32_e32 v34, 1, v34
	v_mov_b32_e32 v35, v129
	v_add3_u32 v8, v8, v39, s56
	v_and_b32_sdwa v39, v9, v170 dst_sel:DWORD dst_unused:UNUSED_PAD src0_sel:WORD_1 src1_sel:DWORD
	v_lshl_add_u64 v[34:35], v[32:33], 0, v[34:35]
	v_add3_u32 v9, v9, v39, s56
	v_lshl_add_u64 v[34:35], v[34:35], 0, v[36:37]
	v_and_b32_e32 v38, 0xffff0000, v9
	v_lshl_add_u64 v[34:35], v[34:35], 0, v[128:129]
	v_cvt_pk_bf16_f32 v9, v10, v11
	v_or_b32_sdwa v8, v38, v8 dst_sel:DWORD dst_unused:UNUSED_PAD src0_sel:DWORD src1_sel:WORD_1
	global_store_dwordx2 v[34:35], v[8:9], off
	v_mfma_f32_16x16x32_bf16 v[16:19], v[112:115], v[120:123], v[96:99]
	v_cvt_pk_bf16_f32 v9, v14, v15
	v_cvt_pk_bf16_f32 v8, v12, v13
	global_store_dwordx2 v[34:35], v[8:9], off offset:32
	s_nop 4
	v_cvt_pk_bf16_f32 v9, v18, v19
	s_nop 3
	v_cvt_pk_bf16_f32 v8, v16, v17
	global_store_dwordx2 v[34:35], v[8:9], off offset:64
	v_cvt_pk_bf16_f32 v9, v22, v23
	v_cvt_pk_bf16_f32 v8, v20, v21
	global_store_dwordx2 v[34:35], v[8:9], off offset:96
	v_or_b32_e32 v8, 48, v85
	v_lshlrev_b32_e32 v8, v86, v8
	v_mfma_f32_16x16x32_bf16 v[28:31], v[108:111], v[124:127], v[48:51]
	v_lshlrev_b32_e32 v8, 1, v8
	v_mov_b32_e32 v9, v129
	v_lshl_add_u64 v[8:9], v[32:33], 0, v[8:9]
	v_lshl_add_u64 v[8:9], v[8:9], 0, v[36:37]
	v_lshl_add_u64 v[8:9], v[8:9], 0, v[128:129]
	v_cvt_pk_bf16_f32 v11, v26, v27
	v_cvt_pk_bf16_f32 v10, v24, v25
	global_store_dwordx2 v[8:9], v[10:11], off
	v_mfma_f32_16x16x32_bf16 v[4:7], v[112:115], v[124:127], v[56:59]
	v_cvt_pk_bf16_f32 v11, v30, v31
	v_cvt_pk_bf16_f32 v10, v28, v29
	global_store_dwordx2 v[8:9], v[10:11], off offset:32
	s_nop 4
	v_and_b32_sdwa v11, v4, v170 dst_sel:DWORD dst_unused:UNUSED_PAD src0_sel:WORD_1 src1_sel:DWORD
	v_mfma_f32_16x16x32_bf16 v[0:3], v[116:119], v[124:127], v[64:67]
	s_nop 2
	v_add3_u32 v4, v4, v11, s56
	s_nop 1
	v_and_b32_sdwa v11, v5, v170 dst_sel:DWORD dst_unused:UNUSED_PAD src0_sel:WORD_1 src1_sel:DWORD
	s_nop 0
	v_add3_u32 v5, v5, v11, s56
	v_and_b32_e32 v10, 0xffff0000, v5
	v_cvt_pk_bf16_f32 v5, v6, v7
	v_or_b32_sdwa v4, v10, v4 dst_sel:DWORD dst_unused:UNUSED_PAD src0_sel:DWORD src1_sel:WORD_1
	global_store_dwordx2 v[8:9], v[4:5], off offset:64
	s_nop 0
	v_bfe_u32 v4, v0, 16, 1
	v_add3_u32 v0, v0, v4, s56
	v_bfe_u32 v4, v1, 16, 1
	v_lshrrev_b32_e32 v0, 16, v0
	v_add3_u32 v1, v1, v4, s56
	v_and_or_b32 v4, v1, s5, v0
	v_bfe_u32 v0, v2, 16, 1
	v_add3_u32 v0, v2, v0, s56
	v_bfe_u32 v1, v3, 16, 1
	v_lshrrev_b32_e32 v0, 16, v0
	v_add3_u32 v1, v3, v1, s56
	s_mov_b64 s[0:1], 0x60
	v_and_or_b32 v2, v1, s5, v0
	v_lshl_add_u64 v[0:1], v[8:9], 0, s[0:1]
	global_store_dword v[8:9], v4, off offset:96

.Ltail236:
	s_add_i32 s24, s25, 2
	v_add_u32_e32 v111, v104, v105
	ds_read_b128 v[136:139], v111 offset:16384
	ds_read_b128 v[140:143], v111 offset:18432
	ds_read_b128 v[144:147], v111 offset:20480
	ds_read_b128 v[148:151], v111 offset:22528
	v_add_u32_e32 v110, v103, v105
	ds_read_b128 v[116:119], v110
	s_add_i32 s25, s25, 4
	ds_read_b128 v[120:123], v110 offset:2048
	s_min_u32 s25, s25, 63
	v_add_u32_e32 v113, v104, v114
	s_lshl_b32 s92, s25, 7
	ds_read_b128 v[124:127], v110 offset:4096
	v_add_u32_e32 v112, v103, v114
	ds_read_b128 v[194:197], v113 offset:16384
	ds_read_b128 v[198:201], v113 offset:18432
	ds_read_b128 v[202:205], v113 offset:20480
	ds_read_b128 v[206:209], v113 offset:22528
	v_lshl_add_u64 v[164:165], v[98:99], 0, s[92:93]
	ds_read_b128 v[132:135], v110 offset:6144
	ds_read_b128 v[152:155], v112
	ds_read_b128 v[156:159], v112 offset:2048
	ds_read_b128 v[160:163], v112 offset:4096
	ds_read_b128 v[190:193], v112 offset:6144
	s_waitcnt lgkmcnt(11)
	v_mfma_f32_16x16x32_bf16 v[92:95], v[136:139], v[116:119], v[92:95]
	v_mfma_f32_16x16x32_bf16 v[56:59], v[140:143], v[116:119], v[56:59]
	v_mfma_f32_16x16x32_bf16 v[52:55], v[144:147], v[116:119], v[52:55]
	v_mfma_f32_16x16x32_bf16 v[48:51], v[148:151], v[116:119], v[48:51]
	s_waitcnt vmcnt(7)
	ds_write_b128 v109, v[60:63] offset:32768
	v_add_co_u32_e32 v60, vcc, s7, v164
	s_waitcnt lgkmcnt(11)
	v_mfma_f32_16x16x32_bf16 v[44:47], v[136:139], v[120:123], v[44:47]
	v_addc_co_u32_e32 v61, vcc, 0, v165, vcc
	v_mfma_f32_16x16x32_bf16 v[40:43], v[140:143], v[120:123], v[40:43]
	v_mfma_f32_16x16x32_bf16 v[36:39], v[144:147], v[120:123], v[36:39]
	v_mfma_f32_16x16x32_bf16 v[32:35], v[148:151], v[120:123], v[32:35]
	v_add_co_u32_e32 v60, vcc, s52, v164
	s_waitcnt vmcnt(6)
	ds_write_b128 v109, v[64:67] offset:36864
	s_nop 0
	v_addc_co_u32_e32 v61, vcc, 0, v165, vcc
	s_waitcnt lgkmcnt(11)
	v_mfma_f32_16x16x32_bf16 v[28:31], v[136:139], v[124:127], v[28:31]
	v_lshl_add_u64 v[64:65], v[100:101], 0, s[92:93]
	v_mfma_f32_16x16x32_bf16 v[24:27], v[140:143], v[124:127], v[24:27]
	v_mfma_f32_16x16x32_bf16 v[20:23], v[144:147], v[124:127], v[20:23]
	v_mfma_f32_16x16x32_bf16 v[16:19], v[148:151], v[124:127], v[16:19]
	v_add_co_u32_e32 v60, vcc, s34, v164
	s_waitcnt vmcnt(5)
	ds_write_b128 v109, v[68:71] offset:40960
	s_nop 0
	v_addc_co_u32_e32 v61, vcc, 0, v165, vcc
	v_add_co_u32_e32 v66, vcc, s7, v64
	s_waitcnt lgkmcnt(7)
	v_mfma_f32_16x16x32_bf16 v[12:15], v[136:139], v[132:135], v[12:15]
	v_addc_co_u32_e32 v67, vcc, 0, v65, vcc
	v_mfma_f32_16x16x32_bf16 v[8:11], v[140:143], v[132:135], v[8:11]
	v_mfma_f32_16x16x32_bf16 v[4:7], v[144:147], v[132:135], v[4:7]
	v_mfma_f32_16x16x32_bf16 v[0:3], v[148:151], v[132:135], v[0:3]
	s_waitcnt vmcnt(4)
	ds_write_b128 v109, v[76:79] offset:45056
	s_waitcnt lgkmcnt(7)
	v_mfma_f32_16x16x32_bf16 v[60:63], v[194:197], v[152:155], v[92:95]
	v_mfma_f32_16x16x32_bf16 v[56:59], v[198:201], v[152:155], v[56:59]
	v_mfma_f32_16x16x32_bf16 v[52:55], v[202:205], v[152:155], v[52:55]
	v_mfma_f32_16x16x32_bf16 v[48:51], v[206:209], v[152:155], v[48:51]
	s_waitcnt vmcnt(3)
	ds_write_b128 v109, v[72:75] offset:49152
	s_waitcnt lgkmcnt(7)
	v_mfma_f32_16x16x32_bf16 v[44:47], v[194:197], v[156:159], v[44:47]
	v_mfma_f32_16x16x32_bf16 v[40:43], v[198:201], v[156:159], v[40:43]
	v_mfma_f32_16x16x32_bf16 v[36:39], v[202:205], v[156:159], v[36:39]
	v_mfma_f32_16x16x32_bf16 v[32:35], v[206:209], v[156:159], v[32:35]
	v_add_co_u32_e32 v66, vcc, s52, v64
	s_waitcnt vmcnt(2)
	ds_write_b128 v109, v[80:83] offset:53248
	v_addc_co_u32_e32 v67, vcc, 0, v65, vcc
	v_add_co_u32_e32 v64, vcc, s34, v64
	s_waitcnt lgkmcnt(7)
	v_mfma_f32_16x16x32_bf16 v[28:31], v[194:197], v[160:163], v[28:31]
	v_addc_co_u32_e32 v65, vcc, 0, v65, vcc
	v_mfma_f32_16x16x32_bf16 v[24:27], v[198:201], v[160:163], v[24:27]
	v_mfma_f32_16x16x32_bf16 v[20:23], v[202:205], v[160:163], v[20:23]
	v_mfma_f32_16x16x32_bf16 v[16:19], v[206:209], v[160:163], v[16:19]
	s_waitcnt vmcnt(1)
	ds_write_b128 v109, v[84:87] offset:57344
	s_waitcnt lgkmcnt(7)
	v_mfma_f32_16x16x32_bf16 v[12:15], v[194:197], v[190:193], v[12:15]
	v_mfma_f32_16x16x32_bf16 v[8:11], v[198:201], v[190:193], v[8:11]
	v_mfma_f32_16x16x32_bf16 v[4:7], v[202:205], v[190:193], v[4:7]
	v_mfma_f32_16x16x32_bf16 v[0:3], v[206:209], v[190:193], v[0:3]
	s_waitcnt vmcnt(0)
	ds_write_b128 v109, v[88:91] offset:61440
	s_waitcnt lgkmcnt(0)
	s_barrier
	ds_read_b128 v[80:83], v111 offset:49152
	ds_read_b128 v[84:87], v111 offset:51200
	ds_read_b128 v[88:91], v111 offset:53248
	ds_read_b128 v[92:95], v111 offset:55296
	ds_read_b128 v[64:67], v110 offset:32768
	ds_read_b128 v[68:71], v110 offset:34816
	s_min_u32 s25, s24, 60
	s_lshl_b32 s92, s25, 7
	ds_read_b128 v[72:75], v110 offset:36864
	v_lshl_add_u64 v[164:165], v[98:99], 0, s[92:93]
	ds_read_b128 v[76:79], v110 offset:38912
	ds_read_b128 v[152:155], v112 offset:32768
	ds_read_b128 v[156:159], v112 offset:34816
	ds_read_b128 v[160:163], v112 offset:36864
	ds_read_b128 v[190:193], v112 offset:38912
	ds_read_b128 v[194:197], v113 offset:49152
	ds_read_b128 v[198:201], v113 offset:51200
	ds_read_b128 v[202:205], v113 offset:53248
	ds_read_b128 v[206:209], v113 offset:55296
	s_waitcnt lgkmcnt(11)
	v_mfma_f32_16x16x32_bf16 v[210:213], v[80:83], v[64:67], v[60:63]
	v_mfma_f32_16x16x32_bf16 v[56:59], v[84:87], v[64:67], v[56:59]
	v_mfma_f32_16x16x32_bf16 v[52:55], v[88:91], v[64:67], v[52:55]
	v_mfma_f32_16x16x32_bf16 v[48:51], v[92:95], v[64:67], v[48:51]
	v_add_co_u32_e32 v64, vcc, s7, v164
	s_nop 0
	s_nop 0
	v_addc_co_u32_e32 v65, vcc, 0, v165, vcc
	s_waitcnt lgkmcnt(10)
	v_mfma_f32_16x16x32_bf16 v[44:47], v[80:83], v[68:71], v[44:47]
	v_mfma_f32_16x16x32_bf16 v[40:43], v[84:87], v[68:71], v[40:43]
	v_mfma_f32_16x16x32_bf16 v[36:39], v[88:91], v[68:71], v[36:39]
	v_mfma_f32_16x16x32_bf16 v[32:35], v[92:95], v[68:71], v[32:35]
	v_add_co_u32_e32 v68, vcc, s52, v164
	s_nop 0
	s_nop 0
	v_addc_co_u32_e32 v69, vcc, 0, v165, vcc
	s_waitcnt lgkmcnt(9)
	v_mfma_f32_16x16x32_bf16 v[28:31], v[80:83], v[72:75], v[28:31]
	v_mfma_f32_16x16x32_bf16 v[24:27], v[84:87], v[72:75], v[24:27]
	v_mfma_f32_16x16x32_bf16 v[20:23], v[88:91], v[72:75], v[20:23]
	v_mfma_f32_16x16x32_bf16 v[16:19], v[92:95], v[72:75], v[16:19]
	v_add_co_u32_e32 v72, vcc, s34, v164
	s_waitcnt lgkmcnt(8)
	v_mfma_f32_16x16x32_bf16 v[4:7], v[88:91], v[76:79], v[4:7]
	v_addc_co_u32_e32 v73, vcc, 0, v165, vcc
	v_lshl_add_u64 v[88:89], v[100:101], 0, s[92:93]
	v_mfma_f32_16x16x32_bf16 v[12:15], v[80:83], v[76:79], v[12:15]
	v_add_co_u32_e32 v80, vcc, s7, v88
	v_mfma_f32_16x16x32_bf16 v[8:11], v[84:87], v[76:79], v[8:11]
	s_nop 0
	v_addc_co_u32_e32 v81, vcc, 0, v89, vcc
	v_add_co_u32_e32 v84, vcc, s52, v88
	v_mfma_f32_16x16x32_bf16 v[0:3], v[92:95], v[76:79], v[0:3]
	s_nop 0
	v_addc_co_u32_e32 v85, vcc, 0, v89, vcc
	s_waitcnt lgkmcnt(3)
	v_mfma_f32_16x16x32_bf16 v[92:95], v[194:197], v[152:155], v[210:213]
	s_waitcnt lgkmcnt(2)
	v_mfma_f32_16x16x32_bf16 v[56:59], v[198:201], v[152:155], v[56:59]
	s_waitcnt lgkmcnt(1)
	v_mfma_f32_16x16x32_bf16 v[52:55], v[202:205], v[152:155], v[52:55]
	s_waitcnt lgkmcnt(0)
	v_mfma_f32_16x16x32_bf16 v[48:51], v[206:209], v[152:155], v[48:51]
	v_add_co_u32_e32 v88, vcc, s34, v88
	s_nop 1
	v_addc_co_u32_e32 v89, vcc, 0, v89, vcc
	v_mfma_f32_16x16x32_bf16 v[44:47], v[194:197], v[156:159], v[44:47]
	v_mfma_f32_16x16x32_bf16 v[40:43], v[198:201], v[156:159], v[40:43]
	v_mfma_f32_16x16x32_bf16 v[36:39], v[202:205], v[156:159], v[36:39]
	v_mfma_f32_16x16x32_bf16 v[32:35], v[206:209], v[156:159], v[32:35]
	v_mfma_f32_16x16x32_bf16 v[28:31], v[194:197], v[160:163], v[28:31]
	v_mfma_f32_16x16x32_bf16 v[24:27], v[198:201], v[160:163], v[24:27]
	v_mfma_f32_16x16x32_bf16 v[20:23], v[202:205], v[160:163], v[20:23]
	v_mfma_f32_16x16x32_bf16 v[16:19], v[206:209], v[160:163], v[16:19]
	v_mfma_f32_16x16x32_bf16 v[12:15], v[194:197], v[190:193], v[12:15]
	v_mfma_f32_16x16x32_bf16 v[8:11], v[198:201], v[190:193], v[8:11]
	v_mfma_f32_16x16x32_bf16 v[4:7], v[202:205], v[190:193], v[4:7]
	v_mfma_f32_16x16x32_bf16 v[0:3], v[206:209], v[190:193], v[0:3]
	s_mov_b32 s25, s24
	s_waitcnt lgkmcnt(0)
	s_barrier
	s_add_i32 s26, s69, 1
	v_readlane_b32 s16, v251, 5
	s_and_b64 s[24:25], s[8:9], exec
	s_mul_i32 s25, s69, 0x12000
	s_waitcnt vmcnt(2)
	v_add_u32_e32 v80, s16, v108
	v_readlane_b32 s28, v250, 25
	v_add_u32_e32 v60, 0xffffe000, v80
	s_cselect_b32 s24, 3, s26
	v_readlane_b32 s29, v250, 26
	s_add_u32 s25, s28, s25
	v_or_b32_e32 v70, v80, v107
	v_lshlrev_b32_e32 v114, 6, v102
	v_readlane_b32 s16, v251, 6
	v_lshrrev_b32_e32 v60, 10, v60
	s_movk_i32 s5, 0x1800
	s_addc_u32 s26, s29, 0
	v_or_b32_e32 v81, s16, v114
	v_lshlrev_b32_e32 v115, 2, v97
	v_mad_u32_u24 v60, v60, s5, s5
	v_cmp_lt_i32_e32 vcc, s13, v70
	s_add_u32 s40, s25, 0x5000
	v_or_b32_e32 v64, v81, v115
	v_cndmask_b32_e32 v76, 0, v60, vcc
	s_addc_u32 s41, s26, 0
	v_ashrrev_i32_e32 v77, 31, v76
	v_ashrrev_i32_e32 v65, 31, v64
	v_ashrrev_i32_e32 v71, 31, v70
	v_lshl_add_u64 v[60:61], v[76:77], 2, s[40:41]
	v_lshlrev_b64 v[66:67], 2, v[64:65]
	v_readlane_b32 s16, v250, 15
	v_lshl_add_u64 v[74:75], v[60:61], 0, v[66:67]
	v_lshlrev_b64 v[60:61], 12, v[70:71]
	v_readlane_b32 s17, v250, 16
	v_readlane_b32 s68, v250, 41
	s_mul_i32 s25, s24, 0x12000
	v_lshl_add_u64 v[60:61], s[16:17], 0, v[60:61]
	v_lshl_add_u64 v[72:73], v[60:61], 0, v[66:67]
	global_load_dwordx4 v[116:119], v[74:75], off
	global_load_dwordx4 v[120:123], v[74:75], off offset:64
	global_load_dwordx4 v[124:127], v[74:75], off offset:128
	global_load_dwordx4 v[132:135], v[74:75], off offset:192
	global_load_dwordx4 v[190:193], v[72:73], off
	global_load_dwordx4 v[194:197], v[72:73], off offset:64
	global_load_dwordx4 v[198:201], v[72:73], off offset:128
	global_load_dwordx4 v[202:205], v[72:73], off offset:192
	v_add_co_u32_e32 v164, vcc, 0x10000, v72
	s_nop 1
	v_addc_co_u32_e32 v165, vcc, 0, v73, vcc
	v_add_co_u32_e32 v222, vcc, 0x20000, v72
	s_nop 1
	v_addc_co_u32_e32 v223, vcc, 0, v73, vcc
	v_add_co_u32_e32 v224, vcc, 0x30000, v72
	s_nop 1
	v_addc_co_u32_e32 v225, vcc, 0, v73, vcc
	global_load_dwordx4 v[206:209], v[164:165], off
	global_load_dwordx4 v[210:213], v[164:165], off offset:64
	global_load_dwordx4 v[214:217], v[164:165], off offset:128
	global_load_dwordx4 v[218:221], v[164:165], off offset:192
	s_lshl_b32 s24, s24, 12
	v_readlane_b32 s70, v250, 43
	v_readlane_b32 s71, v250, 44
	s_add_u32 s26, s70, s24
	s_addc_u32 s27, s71, 0
	s_add_u32 s24, s28, s25
	s_addc_u32 s25, s29, 0
	s_add_u32 s42, s24, 0x1000
	v_cndmask_b32_e64 v68, 0, 1, s[2:3]
	s_addc_u32 s43, s25, 0
	s_andn2_b64 vcc, exec, s[2:3]
	v_readlane_b32 s2, v250, 21
	s_waitcnt vmcnt(3)
	v_lshlrev_b64 v[86:87], 10, v[70:71]
	v_readlane_b32 s3, v250, 22
	v_cmp_ne_u32_e64 s[36:37], 1, v68
	v_lshl_add_u64 v[68:69], s[26:27], 0, v[66:67]
	v_lshl_add_u64 v[78:79], v[76:77], 2, s[42:43]
	v_lshl_add_u64 v[76:77], v[86:87], 1, s[2:3]
	v_readlane_b32 s69, v250, 42
	v_readlane_b32 s72, v250, 45
	v_readlane_b32 s73, v250, 46
	v_readlane_b32 s74, v250, 47
	v_readlane_b32 s75, v250, 48
	v_readlane_b32 s76, v250, 49
	v_readlane_b32 s77, v250, 50
	v_readlane_b32 s78, v250, 51
	v_readlane_b32 s79, v250, 52
	v_readlane_b32 s80, v250, 53
	v_readlane_b32 s81, v250, 54
	v_readlane_b32 s82, v250, 55
	v_readlane_b32 s83, v250, 56
	s_waitcnt vmcnt(4)
	v_pk_fma_f32 v[62:63], v[94:95], v[118:119], v[192:193]
	v_pk_fma_f32 v[60:61], v[92:93], v[116:117], v[190:191]
	global_store_dwordx4 v[72:73], v[60:63], off
	s_cbranch_vccnz .LBB0_239
	v_lshl_add_u64 v[86:87], v[78:79], 0, v[66:67]
	global_load_dwordx4 v[136:139], v[68:69], off
	global_load_dwordx4 v[140:143], v[68:69], off offset:64
	global_load_dwordx4 v[144:147], v[68:69], off offset:128
	global_load_dwordx4 v[148:151], v[68:69], off offset:192
	s_waitcnt vmcnt(0)
	v_pk_mul_f32 v[84:85], v[62:63], v[138:139]
	global_load_dwordx4 v[152:155], v[86:87], off
	global_load_dwordx4 v[156:159], v[86:87], off offset:64
	global_load_dwordx4 v[160:163], v[86:87], off offset:128
	global_load_dwordx4 v[180:183], v[86:87], off offset:192
	v_pk_mul_f32 v[82:83], v[60:61], v[136:137]
	s_waitcnt vmcnt(0)
	v_pk_add_f32 v[88:89], v[154:155], 1.0 op_sel_hi:[1,0]
	v_pk_add_f32 v[86:87], v[152:153], 1.0 op_sel_hi:[1,0]
	v_pk_mul_f32 v[84:85], v[84:85], v[88:89]
	v_pk_mul_f32 v[82:83], v[82:83], v[86:87]
	v_and_b32_sdwa v89, v82, v170 dst_sel:DWORD dst_unused:UNUSED_PAD src0_sel:WORD_1 src1_sel:DWORD
	v_add3_u32 v82, v82, v89, s56
	v_and_b32_sdwa v89, v83, v170 dst_sel:DWORD dst_unused:UNUSED_PAD src0_sel:WORD_1 src1_sel:DWORD
	v_add3_u32 v83, v83, v89, s56
	v_and_b32_e32 v88, 0xffff0000, v83
	v_lshl_add_u64 v[86:87], v[64:65], 1, v[76:77]
	v_cvt_pk_bf16_f32 v83, v84, v85
	v_or_b32_sdwa v82, v88, v82 dst_sel:DWORD dst_unused:UNUSED_PAD src0_sel:DWORD src1_sel:WORD_1
	global_store_dwordx2 v[86:87], v[82:83], off

.Ltail282:
	s_add_i32 s25, s28, 2
	ds_read_b128 v[136:139], v111 offset:16384
	ds_read_b128 v[140:143], v111 offset:18432
	ds_read_b128 v[144:147], v111 offset:20480
	ds_read_b128 v[148:151], v111 offset:22528
	ds_read_b128 v[116:119], v110
	s_add_i32 s28, s28, 4
	ds_read_b128 v[120:123], v110 offset:2048
	s_min_u32 s28, s28, 63
	s_lshl_b32 s92, s28, 7
	ds_read_b128 v[124:127], v110 offset:4096
	ds_read_b128 v[194:197], v113 offset:16384
	ds_read_b128 v[198:201], v113 offset:18432
	ds_read_b128 v[202:205], v113 offset:20480
	ds_read_b128 v[206:209], v113 offset:22528
	v_lshl_add_u64 v[164:165], v[100:101], 0, s[92:93]
	ds_read_b128 v[132:135], v110 offset:6144
	ds_read_b128 v[152:155], v112
	ds_read_b128 v[156:159], v112 offset:2048
	ds_read_b128 v[160:163], v112 offset:4096
	ds_read_b128 v[190:193], v112 offset:6144
	s_waitcnt lgkmcnt(11)
	v_mfma_f32_16x16x32_bf16 v[92:95], v[136:139], v[116:119], v[92:95]
	v_mfma_f32_16x16x32_bf16 v[56:59], v[140:143], v[116:119], v[56:59]
	v_mfma_f32_16x16x32_bf16 v[52:55], v[144:147], v[116:119], v[52:55]
	v_mfma_f32_16x16x32_bf16 v[48:51], v[148:151], v[116:119], v[48:51]
	s_waitcnt vmcnt(7)
	ds_write_b128 v109, v[60:63] offset:32768
	v_add_co_u32_e32 v60, vcc, s7, v164
	s_waitcnt lgkmcnt(11)
	v_mfma_f32_16x16x32_bf16 v[44:47], v[136:139], v[120:123], v[44:47]
	v_addc_co_u32_e32 v61, vcc, 0, v165, vcc
	v_mfma_f32_16x16x32_bf16 v[40:43], v[140:143], v[120:123], v[40:43]
	v_mfma_f32_16x16x32_bf16 v[36:39], v[144:147], v[120:123], v[36:39]
	v_mfma_f32_16x16x32_bf16 v[32:35], v[148:151], v[120:123], v[32:35]
	v_add_co_u32_e32 v60, vcc, s52, v164
	s_waitcnt vmcnt(6)
	ds_write_b128 v109, v[64:67] offset:36864
	s_nop 0
	v_addc_co_u32_e32 v61, vcc, 0, v165, vcc
	s_waitcnt lgkmcnt(11)
	v_mfma_f32_16x16x32_bf16 v[28:31], v[136:139], v[124:127], v[28:31]
	v_lshl_add_u64 v[64:65], v[102:103], 0, s[92:93]
	v_mfma_f32_16x16x32_bf16 v[24:27], v[140:143], v[124:127], v[24:27]
	v_mfma_f32_16x16x32_bf16 v[20:23], v[144:147], v[124:127], v[20:23]
	v_mfma_f32_16x16x32_bf16 v[16:19], v[148:151], v[124:127], v[16:19]
	v_add_co_u32_e32 v60, vcc, s34, v164
	s_waitcnt vmcnt(5)
	ds_write_b128 v109, v[68:71] offset:40960
	s_nop 0
	v_addc_co_u32_e32 v61, vcc, 0, v165, vcc
	v_add_co_u32_e32 v66, vcc, s7, v64
	s_waitcnt lgkmcnt(7)
	v_mfma_f32_16x16x32_bf16 v[12:15], v[136:139], v[132:135], v[12:15]
	v_addc_co_u32_e32 v67, vcc, 0, v65, vcc
	v_mfma_f32_16x16x32_bf16 v[8:11], v[140:143], v[132:135], v[8:11]
	v_mfma_f32_16x16x32_bf16 v[4:7], v[144:147], v[132:135], v[4:7]
	v_mfma_f32_16x16x32_bf16 v[0:3], v[148:151], v[132:135], v[0:3]
	s_waitcnt vmcnt(4)
	ds_write_b128 v109, v[76:79] offset:45056
	s_waitcnt lgkmcnt(7)
	v_mfma_f32_16x16x32_bf16 v[60:63], v[194:197], v[152:155], v[92:95]
	v_mfma_f32_16x16x32_bf16 v[56:59], v[198:201], v[152:155], v[56:59]
	v_mfma_f32_16x16x32_bf16 v[52:55], v[202:205], v[152:155], v[52:55]
	v_mfma_f32_16x16x32_bf16 v[48:51], v[206:209], v[152:155], v[48:51]
	s_waitcnt vmcnt(3)
	ds_write_b128 v109, v[72:75] offset:49152
	s_waitcnt lgkmcnt(7)
	v_mfma_f32_16x16x32_bf16 v[44:47], v[194:197], v[156:159], v[44:47]
	v_mfma_f32_16x16x32_bf16 v[40:43], v[198:201], v[156:159], v[40:43]
	v_mfma_f32_16x16x32_bf16 v[36:39], v[202:205], v[156:159], v[36:39]
	v_mfma_f32_16x16x32_bf16 v[32:35], v[206:209], v[156:159], v[32:35]
	v_add_co_u32_e32 v66, vcc, s52, v64
	s_waitcnt vmcnt(2)
	ds_write_b128 v109, v[80:83] offset:53248
	v_addc_co_u32_e32 v67, vcc, 0, v65, vcc
	v_add_co_u32_e32 v64, vcc, s34, v64
	s_waitcnt lgkmcnt(7)
	v_mfma_f32_16x16x32_bf16 v[28:31], v[194:197], v[160:163], v[28:31]
	v_addc_co_u32_e32 v65, vcc, 0, v65, vcc
	v_mfma_f32_16x16x32_bf16 v[24:27], v[198:201], v[160:163], v[24:27]
	v_mfma_f32_16x16x32_bf16 v[20:23], v[202:205], v[160:163], v[20:23]
	v_mfma_f32_16x16x32_bf16 v[16:19], v[206:209], v[160:163], v[16:19]
	s_waitcnt vmcnt(1)
	ds_write_b128 v109, v[84:87] offset:57344
	s_waitcnt lgkmcnt(7)
	v_mfma_f32_16x16x32_bf16 v[12:15], v[194:197], v[190:193], v[12:15]
	v_mfma_f32_16x16x32_bf16 v[8:11], v[198:201], v[190:193], v[8:11]
	v_mfma_f32_16x16x32_bf16 v[4:7], v[202:205], v[190:193], v[4:7]
	v_mfma_f32_16x16x32_bf16 v[0:3], v[206:209], v[190:193], v[0:3]
	s_waitcnt vmcnt(0)
	ds_write_b128 v109, v[88:91] offset:61440
	s_waitcnt lgkmcnt(0)
	s_barrier
	ds_read_b128 v[80:83], v111 offset:49152
	ds_read_b128 v[84:87], v111 offset:51200
	ds_read_b128 v[88:91], v111 offset:53248
	ds_read_b128 v[92:95], v111 offset:55296
	ds_read_b128 v[64:67], v110 offset:32768
	ds_read_b128 v[68:71], v110 offset:34816
	s_min_u32 s28, s25, 60
	s_lshl_b32 s92, s28, 7
	ds_read_b128 v[72:75], v110 offset:36864
	v_lshl_add_u64 v[164:165], v[100:101], 0, s[92:93]
	ds_read_b128 v[76:79], v110 offset:38912
	ds_read_b128 v[152:155], v112 offset:32768
	ds_read_b128 v[156:159], v112 offset:34816
	ds_read_b128 v[160:163], v112 offset:36864
	ds_read_b128 v[190:193], v112 offset:38912
	ds_read_b128 v[194:197], v113 offset:49152
	ds_read_b128 v[198:201], v113 offset:51200
	ds_read_b128 v[202:205], v113 offset:53248
	ds_read_b128 v[206:209], v113 offset:55296
	s_waitcnt lgkmcnt(11)
	v_mfma_f32_16x16x32_bf16 v[210:213], v[80:83], v[64:67], v[60:63]
	v_mfma_f32_16x16x32_bf16 v[56:59], v[84:87], v[64:67], v[56:59]
	v_mfma_f32_16x16x32_bf16 v[52:55], v[88:91], v[64:67], v[52:55]
	v_mfma_f32_16x16x32_bf16 v[48:51], v[92:95], v[64:67], v[48:51]
	v_add_co_u32_e32 v64, vcc, s7, v164
	s_nop 0
	s_nop 0
	v_addc_co_u32_e32 v65, vcc, 0, v165, vcc
	s_waitcnt lgkmcnt(10)
	v_mfma_f32_16x16x32_bf16 v[44:47], v[80:83], v[68:71], v[44:47]
	v_mfma_f32_16x16x32_bf16 v[40:43], v[84:87], v[68:71], v[40:43]
	v_mfma_f32_16x16x32_bf16 v[36:39], v[88:91], v[68:71], v[36:39]
	v_mfma_f32_16x16x32_bf16 v[32:35], v[92:95], v[68:71], v[32:35]
	v_add_co_u32_e32 v68, vcc, s52, v164
	s_nop 0
	s_nop 0
	v_addc_co_u32_e32 v69, vcc, 0, v165, vcc
	s_waitcnt lgkmcnt(9)
	v_mfma_f32_16x16x32_bf16 v[28:31], v[80:83], v[72:75], v[28:31]
	v_mfma_f32_16x16x32_bf16 v[24:27], v[84:87], v[72:75], v[24:27]
	v_mfma_f32_16x16x32_bf16 v[20:23], v[88:91], v[72:75], v[20:23]
	v_mfma_f32_16x16x32_bf16 v[16:19], v[92:95], v[72:75], v[16:19]
	v_add_co_u32_e32 v72, vcc, s34, v164
	s_waitcnt lgkmcnt(8)
	v_mfma_f32_16x16x32_bf16 v[4:7], v[88:91], v[76:79], v[4:7]
	v_addc_co_u32_e32 v73, vcc, 0, v165, vcc
	v_lshl_add_u64 v[88:89], v[102:103], 0, s[92:93]
	v_mfma_f32_16x16x32_bf16 v[12:15], v[80:83], v[76:79], v[12:15]
	v_add_co_u32_e32 v80, vcc, s7, v88
	v_mfma_f32_16x16x32_bf16 v[8:11], v[84:87], v[76:79], v[8:11]
	s_nop 0
	v_addc_co_u32_e32 v81, vcc, 0, v89, vcc
	v_add_co_u32_e32 v84, vcc, s52, v88
	v_mfma_f32_16x16x32_bf16 v[0:3], v[92:95], v[76:79], v[0:3]
	s_nop 0
	v_addc_co_u32_e32 v85, vcc, 0, v89, vcc
	s_waitcnt lgkmcnt(3)
	v_mfma_f32_16x16x32_bf16 v[92:95], v[194:197], v[152:155], v[210:213]
	s_waitcnt lgkmcnt(2)
	v_mfma_f32_16x16x32_bf16 v[56:59], v[198:201], v[152:155], v[56:59]
	s_waitcnt lgkmcnt(1)
	v_mfma_f32_16x16x32_bf16 v[52:55], v[202:205], v[152:155], v[52:55]
	s_waitcnt lgkmcnt(0)
	v_mfma_f32_16x16x32_bf16 v[48:51], v[206:209], v[152:155], v[48:51]
	v_add_co_u32_e32 v88, vcc, s34, v88
	s_nop 1
	v_addc_co_u32_e32 v89, vcc, 0, v89, vcc
	v_mfma_f32_16x16x32_bf16 v[44:47], v[194:197], v[156:159], v[44:47]
	v_mfma_f32_16x16x32_bf16 v[40:43], v[198:201], v[156:159], v[40:43]
	v_mfma_f32_16x16x32_bf16 v[36:39], v[202:205], v[156:159], v[36:39]
	v_mfma_f32_16x16x32_bf16 v[32:35], v[206:209], v[156:159], v[32:35]
	v_mfma_f32_16x16x32_bf16 v[28:31], v[194:197], v[160:163], v[28:31]
	v_mfma_f32_16x16x32_bf16 v[24:27], v[198:201], v[160:163], v[24:27]
	v_mfma_f32_16x16x32_bf16 v[20:23], v[202:205], v[160:163], v[20:23]
	v_mfma_f32_16x16x32_bf16 v[16:19], v[206:209], v[160:163], v[16:19]
	v_mfma_f32_16x16x32_bf16 v[12:15], v[194:197], v[190:193], v[12:15]
	v_mfma_f32_16x16x32_bf16 v[8:11], v[198:201], v[190:193], v[8:11]
	v_mfma_f32_16x16x32_bf16 v[4:7], v[202:205], v[190:193], v[4:7]
	v_mfma_f32_16x16x32_bf16 v[0:3], v[206:209], v[190:193], v[0:3]
	s_mov_b32 s28, s25
	s_waitcnt lgkmcnt(0)
	s_barrier
	s_waitcnt vmcnt(2)
	v_add_u32_e32 v80, s2, v108
	v_add_u32_e32 v60, 0xffffe000, v80
	v_or_b32_e32 v70, v80, v107
	v_lshrrev_b32_e32 v60, 10, v60
	s_movk_i32 s2, 0x1800
	v_or_b32_e32 v81, s3, v114
	v_mad_u32_u24 v60, v60, s2, s2
	v_cmp_lt_i32_e32 vcc, s13, v70
	v_or_b32_e32 v64, v81, v115
	v_ashrrev_i32_e32 v71, 31, v70
	v_cndmask_b32_e32 v82, 0, v60, vcc
	v_readlane_b32 s2, v250, 15
	v_ashrrev_i32_e32 v83, 31, v82
	v_ashrrev_i32_e32 v65, 31, v64
	v_lshlrev_b64 v[68:69], 12, v[70:71]
	v_readlane_b32 s3, v250, 16
	v_lshl_add_u64 v[60:61], v[82:83], 2, s[40:41]
	v_lshlrev_b64 v[66:67], 2, v[64:65]
	v_lshl_add_u64 v[68:69], s[2:3], 0, v[68:69]
	v_lshl_add_u64 v[74:75], v[60:61], 0, v[66:67]
	v_lshl_add_u64 v[72:73], v[68:69], 0, v[66:67]
	global_load_dwordx4 v[60:63], v[74:75], off
	global_load_dwordx4 v[76:79], v[72:73], off
	v_readlane_b32 s2, v250, 21
	s_waitcnt vmcnt(3)
	v_lshlrev_b64 v[84:85], 10, v[70:71]
	v_readlane_b32 s3, v250, 22
	s_and_b64 vcc, exec, s[36:37]
	v_lshl_add_u64 v[68:69], s[26:27], 0, v[66:67]
	s_waitcnt vmcnt(0)
	v_pk_fma_f32 v[62:63], v[94:95], v[62:63], v[78:79]
	v_pk_fma_f32 v[60:61], v[92:93], v[60:61], v[76:77]
	v_lshl_add_u64 v[76:77], v[82:83], 2, s[42:43]
	v_lshl_add_u64 v[78:79], v[84:85], 1, s[2:3]
	global_store_dwordx4 v[72:73], v[60:63], off
	s_cbranch_vccnz .LBB0_285
	v_lshl_add_u64 v[86:87], v[76:77], 0, v[66:67]
	global_load_dwordx4 v[82:85], v[68:69], off
	s_waitcnt vmcnt(0)
	v_pk_mul_f32 v[84:85], v[62:63], v[84:85]
	global_load_dwordx4 v[86:89], v[86:87], off
	v_pk_mul_f32 v[82:83], v[60:61], v[82:83]
	s_waitcnt vmcnt(0)
	v_pk_add_f32 v[88:89], v[88:89], 1.0 op_sel_hi:[1,0]
	v_pk_add_f32 v[86:87], v[86:87], 1.0 op_sel_hi:[1,0]
	v_pk_mul_f32 v[84:85], v[84:85], v[88:89]
	v_pk_mul_f32 v[82:83], v[82:83], v[86:87]
	v_and_b32_sdwa v89, v82, v170 dst_sel:DWORD dst_unused:UNUSED_PAD src0_sel:WORD_1 src1_sel:DWORD
	v_add3_u32 v82, v82, v89, s56
	v_and_b32_sdwa v89, v83, v170 dst_sel:DWORD dst_unused:UNUSED_PAD src0_sel:WORD_1 src1_sel:DWORD
	v_add3_u32 v83, v83, v89, s56
	v_and_b32_e32 v88, 0xffff0000, v83
	v_lshl_add_u64 v[86:87], v[64:65], 1, v[78:79]
	v_cvt_pk_bf16_f32 v83, v84, v85
	v_or_b32_sdwa v82, v88, v82 dst_sel:DWORD dst_unused:UNUSED_PAD src0_sel:DWORD src1_sel:WORD_1
	global_store_dwordx2 v[86:87], v[82:83], off

.Ltail327:
	s_add_i32 s0, s1, 2
	v_add_u32_e32 v127, v89, v90
	ds_read_b128 v[100:103], v127 offset:16384
	ds_read_b128 v[106:109], v127 offset:18432
	ds_read_b128 v[110:113], v127 offset:20480
	ds_read_b128 v[114:117], v127 offset:22528
	v_add_u32_e32 v126, v88, v90
	ds_read_b128 v[92:95], v126
	ds_read_b128 v[96:99], v126 offset:2048
	s_add_i32 s1, s1, 4
	s_min_u32 s1, s1, 63
	v_add_u32_e32 v128, v88, v91
	v_add_u32_e32 v130, v89, v91
	s_lshl_b32 s92, s1, 7
	ds_read_b128 v[118:121], v130 offset:18432
	ds_read_b128 v[122:125], v130 offset:20480
	ds_read_b128 v[132:135], v130 offset:22528
	s_waitcnt lgkmcnt(4)
	v_mfma_f32_16x16x32_bf16 v[76:79], v[100:103], v[92:95], v[76:79]
	v_lshl_add_u64 v[48:49], v[80:81], 0, s[92:93]
	v_add_co_u32_e32 v50, vcc, s7, v48
	v_mfma_f32_16x16x32_bf16 v[56:59], v[106:109], v[92:95], v[56:59]
	s_nop 0
	v_addc_co_u32_e32 v51, vcc, 0, v49, vcc
	v_mfma_f32_16x16x32_bf16 v[44:47], v[110:113], v[92:95], v[44:47]
	v_mfma_f32_16x16x32_bf16 v[24:27], v[114:117], v[92:95], v[24:27]
	s_waitcnt lgkmcnt(3)
	v_mfma_f32_16x16x32_bf16 v[92:95], v[100:103], v[96:99], v[12:15]
	s_nop 2
	ds_read_b128 v[12:15], v128
	v_mfma_f32_16x16x32_bf16 v[100:103], v[106:109], v[96:99], v[8:11]
	v_mfma_f32_16x16x32_bf16 v[106:109], v[110:113], v[96:99], v[4:7]
	ds_read_b128 v[110:113], v128 offset:2048
	v_mfma_f32_16x16x32_bf16 v[96:99], v[114:117], v[96:99], v[0:3]
	ds_read_b128 v[114:117], v130 offset:16384
	s_waitcnt vmcnt(0)
	ds_write_b128 v87, v[16:19] offset:53248
	v_add_co_u32_e32 v50, vcc, s52, v48
	s_waitcnt vmcnt(1)
	ds_write_b128 v87, v[20:23] offset:49152
	s_nop 0
	v_addc_co_u32_e32 v51, vcc, 0, v49, vcc
	v_add_co_u32_e32 v48, vcc, s34, v48
	s_nop 0
	s_nop 0
	v_addc_co_u32_e32 v49, vcc, 0, v49, vcc
	s_waitcnt vmcnt(2)
	ds_write_b128 v87, v[28:31] offset:45056
	v_lshl_add_u64 v[48:49], v[82:83], 0, s[92:93]
	s_waitcnt vmcnt(5)
	ds_write_b128 v87, v[36:39] offset:32768
	s_waitcnt lgkmcnt(4)
	v_mfma_f32_16x16x32_bf16 v[0:3], v[114:117], v[12:15], v[76:79]
	v_mfma_f32_16x16x32_bf16 v[4:7], v[118:121], v[12:15], v[56:59]
	v_add_co_u32_e32 v48, vcc, s7, v48
	s_waitcnt vmcnt(4)
	ds_write_b128 v87, v[40:43] offset:36864
	s_nop 0
	v_addc_co_u32_e32 v49, vcc, 0, v49, vcc
	v_mfma_f32_16x16x32_bf16 v[8:11], v[122:125], v[12:15], v[44:47]
	v_mfma_f32_16x16x32_bf16 v[12:15], v[132:135], v[12:15], v[24:27]
	s_waitcnt vmcnt(3)
	ds_write_b128 v87, v[32:35] offset:40960
	v_mfma_f32_16x16x32_bf16 v[24:27], v[114:117], v[110:113], v[92:95]
	v_mfma_f32_16x16x32_bf16 v[44:47], v[118:121], v[110:113], v[100:103]
	v_mfma_f32_16x16x32_bf16 v[56:59], v[122:125], v[110:113], v[106:109]
	v_mfma_f32_16x16x32_bf16 v[76:79], v[132:135], v[110:113], v[96:99]
	s_waitcnt lgkmcnt(0)
	s_barrier
	ds_read_b128 v[100:103], v127 offset:49152
	ds_read_b128 v[106:109], v127 offset:51200
	ds_read_b128 v[110:113], v127 offset:53248
	ds_read_b128 v[114:117], v127 offset:55296
	ds_read_b128 v[92:95], v126 offset:32768
	ds_read_b128 v[96:99], v126 offset:34816
	s_min_u32 s1, s0, 60
	s_lshl_b32 s92, s1, 7
	ds_read_b128 v[118:121], v130 offset:51200
	ds_read_b128 v[122:125], v130 offset:53248
	ds_read_b128 v[132:135], v130 offset:55296
	s_waitcnt lgkmcnt(4)
	v_mfma_f32_16x16x32_bf16 v[0:3], v[100:103], v[92:95], v[0:3]
	v_lshl_add_u64 v[16:17], v[80:81], 0, s[92:93]
	v_add_co_u32_e32 v18, vcc, s7, v16
	v_mfma_f32_16x16x32_bf16 v[4:7], v[106:109], v[92:95], v[4:7]
	s_nop 0
	v_addc_co_u32_e32 v19, vcc, 0, v17, vcc
	v_mfma_f32_16x16x32_bf16 v[8:11], v[110:113], v[92:95], v[8:11]
	v_mfma_f32_16x16x32_bf16 v[12:15], v[114:117], v[92:95], v[12:15]
	s_waitcnt lgkmcnt(3)
	v_mfma_f32_16x16x32_bf16 v[92:95], v[100:103], v[96:99], v[24:27]
	s_nop 2
	ds_read_b128 v[24:27], v128 offset:32768
	v_mfma_f32_16x16x32_bf16 v[100:103], v[106:109], v[96:99], v[44:47]
	v_mfma_f32_16x16x32_bf16 v[106:109], v[110:113], v[96:99], v[56:59]
	ds_read_b128 v[110:113], v128 offset:34816
	v_mfma_f32_16x16x32_bf16 v[96:99], v[114:117], v[96:99], v[76:79]
	ds_read_b128 v[114:117], v130 offset:49152
	v_add_co_u32_e32 v18, vcc, s52, v16
	s_nop 0
	s_nop 0
	v_addc_co_u32_e32 v19, vcc, 0, v17, vcc
	v_add_co_u32_e32 v16, vcc, s34, v16
	s_nop 0
	s_nop 0
	v_addc_co_u32_e32 v17, vcc, 0, v17, vcc
	v_lshl_add_u64 v[16:17], v[82:83], 0, s[92:93]
	s_waitcnt lgkmcnt(0)
	v_mfma_f32_16x16x32_bf16 v[76:79], v[114:117], v[24:27], v[0:3]
	v_mfma_f32_16x16x32_bf16 v[56:59], v[118:121], v[24:27], v[4:7]
	v_add_co_u32_e32 v16, vcc, s7, v16
	s_nop 0
	s_nop 0
	v_addc_co_u32_e32 v17, vcc, 0, v17, vcc
	v_mfma_f32_16x16x32_bf16 v[44:47], v[122:125], v[24:27], v[8:11]
	v_mfma_f32_16x16x32_bf16 v[24:27], v[132:135], v[24:27], v[12:15]
	v_mfma_f32_16x16x32_bf16 v[12:15], v[114:117], v[110:113], v[92:95]
	v_mfma_f32_16x16x32_bf16 v[8:11], v[118:121], v[110:113], v[100:103]
	v_mfma_f32_16x16x32_bf16 v[4:7], v[122:125], v[110:113], v[106:109]
	v_mfma_f32_16x16x32_bf16 v[0:3], v[132:135], v[110:113], v[96:99]
	s_mov_b32 s1, s0
	s_waitcnt lgkmcnt(0)
	s_barrier
	v_readlane_b32 s0, v251, 18
	s_nop 1
	v_add_u32_e32 v48, s0, v86
	v_readlane_b32 s0, v251, 19
	s_waitcnt vmcnt(0)
	v_add_u32_e32 v16, 0xffffe000, v48
	v_or_b32_e32 v34, v48, v85
	v_lshl_or_b32 v32, v84, 2, s0
	v_lshrrev_b32_e32 v16, 10, v16
	s_movk_i32 s0, 0x1800
	v_mad_u32_u24 v16, v16, s0, s0
	v_cmp_lt_i32_e32 vcc, s13, v34
	v_ashrrev_i32_e32 v35, 31, v34
	v_lshlrev_b32_e32 v128, 2, v32
	v_cndmask_b32_e32 v28, 0, v16, vcc
	v_ashrrev_i32_e32 v29, 31, v28
	v_lshl_add_u64 v[16:17], v[28:29], 2, s[40:41]
	v_readlane_b32 s0, v250, 15
	v_lshl_add_u64 v[40:41], v[16:17], 0, v[128:129]
	v_lshlrev_b64 v[16:17], 12, v[34:35]
	v_readlane_b32 s1, v250, 16
	v_lshlrev_b64 v[30:31], 10, v[34:35]
	s_and_b64 vcc, exec, s[36:37]
	v_lshl_add_u64 v[16:17], s[0:1], 0, v[16:17]
	v_lshl_add_u64 v[38:39], v[16:17], 0, v[128:129]
	global_load_dwordx4 v[60:63], v[40:41], off
	global_load_dwordx4 v[72:75], v[40:41], off offset:64
	global_load_dwordx4 v[80:83], v[40:41], off offset:128
	global_load_dwordx4 v[88:91], v[40:41], off offset:192
	global_load_dwordx4 v[190:193], v[38:39], off
	global_load_dwordx4 v[194:197], v[38:39], off offset:64
	global_load_dwordx4 v[198:201], v[38:39], off offset:128
	global_load_dwordx4 v[202:205], v[38:39], off offset:192
	v_add_co_u32_e32 v54, vcc, 0x10000, v38
	s_nop 1
	v_addc_co_u32_e32 v55, vcc, 0, v39, vcc
	global_load_dwordx4 v[206:209], v[54:55], off
	global_load_dwordx4 v[210:213], v[54:55], off offset:64
	global_load_dwordx4 v[214:217], v[54:55], off offset:128
	global_load_dwordx4 v[218:221], v[54:55], off offset:192
	v_readlane_b32 s0, v250, 21
	v_readlane_b32 s1, v250, 22
	v_lshl_add_u64 v[42:43], v[28:29], 2, s[42:43]
	v_lshlrev_b32_e32 v32, 1, v32
	v_lshl_add_u64 v[36:37], v[30:31], 1, s[0:1]
	s_waitcnt vmcnt(4)
	v_pk_fma_f32 v[18:19], v[78:79], v[62:63], v[192:193]
	v_pk_fma_f32 v[16:17], v[76:77], v[60:61], v[190:191]
	global_store_dwordx4 v[38:39], v[16:19], off
	s_cbranch_vccnz .LBB0_330
	v_lshl_add_u64 v[28:29], v[42:43], 0, v[128:129]
	global_load_dwordx4 v[136:139], v128, s[26:27]
	global_load_dwordx4 v[140:143], v128, s[26:27] offset:64
	global_load_dwordx4 v[144:147], v128, s[26:27] offset:128
	global_load_dwordx4 v[148:151], v128, s[26:27] offset:192
	v_mov_b32_e32 v33, v129
	global_load_dwordx4 v[152:155], v[28:29], off
	global_load_dwordx4 v[156:159], v[28:29], off offset:64
	global_load_dwordx4 v[160:163], v[28:29], off offset:128
	global_load_dwordx4 v[180:183], v[28:29], off offset:192
	s_waitcnt vmcnt(0)
	v_pk_mul_f32 v[22:23], v[18:19], v[138:139]
	v_pk_mul_f32 v[20:21], v[16:17], v[136:137]
	s_waitcnt vmcnt(0)
	v_pk_add_f32 v[30:31], v[154:155], 1.0 op_sel_hi:[1,0]
	v_pk_add_f32 v[28:29], v[152:153], 1.0 op_sel_hi:[1,0]
	v_pk_mul_f32 v[22:23], v[22:23], v[30:31]
	v_pk_mul_f32 v[20:21], v[20:21], v[28:29]
	v_and_b32_sdwa v31, v20, v170 dst_sel:DWORD dst_unused:UNUSED_PAD src0_sel:WORD_1 src1_sel:DWORD
	v_add3_u32 v20, v20, v31, s56
	v_and_b32_sdwa v31, v21, v170 dst_sel:DWORD dst_unused:UNUSED_PAD src0_sel:WORD_1 src1_sel:DWORD
	v_add3_u32 v21, v21, v31, s56
	v_and_b32_e32 v30, 0xffff0000, v21
	v_lshl_add_u64 v[28:29], v[36:37], 0, v[32:33]
	v_cvt_pk_bf16_f32 v21, v22, v23
	v_or_b32_sdwa v20, v30, v20 dst_sel:DWORD dst_unused:UNUSED_PAD src0_sel:DWORD src1_sel:WORD_1
	global_store_dwordx2 v[28:29], v[20:21], off

.Ltail359:
	s_add_i32 s27, s28, 2
	v_add_u32_e32 v181, v144, v145
	ds_read_b128 v[80:83], v181 offset:16384
	ds_read_b128 v[84:87], v181 offset:18432
	ds_read_b128 v[88:91], v181 offset:20480
	ds_read_b128 v[92:95], v181 offset:22528
	v_add_u32_e32 v180, v143, v145
	ds_read_b128 v[64:67], v180
	s_add_i32 s28, s28, 4
	ds_read_b128 v[68:71], v180 offset:2048
	s_min_u32 s28, s28, 15
	s_lshl_b32 s92, s28, 7
	ds_read_b128 v[72:75], v180 offset:4096
	ds_read_b128 v[76:79], v180 offset:6144
	v_add_u32_e32 v182, v143, v146
	v_add_u32_e32 v186, v144, v146
	v_lshl_add_u64 v[224:225], v[138:139], 0, s[92:93]
	ds_read_b128 v[192:195], v182
	ds_read_b128 v[196:199], v182 offset:2048
	ds_read_b128 v[200:203], v182 offset:4096
	ds_read_b128 v[204:207], v182 offset:6144
	ds_read_b128 v[208:211], v186 offset:16384
	ds_read_b128 v[212:215], v186 offset:18432
	ds_read_b128 v[216:219], v186 offset:20480
	ds_read_b128 v[220:223], v186 offset:22528
	s_waitcnt lgkmcnt(11)
	v_mfma_f32_16x16x32_bf16 v[60:63], v[80:83], v[64:67], v[60:63]
	v_mfma_f32_16x16x32_bf16 v[56:59], v[84:87], v[64:67], v[56:59]
	v_mfma_f32_16x16x32_bf16 v[52:55], v[88:91], v[64:67], v[52:55]
	v_mfma_f32_16x16x32_bf16 v[48:51], v[92:95], v[64:67], v[48:51]
	s_waitcnt vmcnt(7)
	ds_write_b128 v156, v[96:99] offset:32768
	v_add_co_u32_e32 v96, vcc, s11, v224
	s_waitcnt lgkmcnt(11)
	v_mfma_f32_16x16x32_bf16 v[44:47], v[80:83], v[68:71], v[44:47]
	v_addc_co_u32_e32 v97, vcc, 0, v225, vcc
	v_mfma_f32_16x16x32_bf16 v[40:43], v[84:87], v[68:71], v[40:43]
	v_mfma_f32_16x16x32_bf16 v[36:39], v[88:91], v[68:71], v[36:39]
	v_mfma_f32_16x16x32_bf16 v[32:35], v[92:95], v[68:71], v[32:35]
	v_add_co_u32_e32 v96, vcc, s33, v224
	s_waitcnt vmcnt(6)
	ds_write_b128 v156, v[100:103] offset:36864
	s_nop 0
	v_addc_co_u32_e32 v97, vcc, 0, v225, vcc
	s_waitcnt lgkmcnt(11)
	v_mfma_f32_16x16x32_bf16 v[28:31], v[80:83], v[72:75], v[28:31]
	v_mfma_f32_16x16x32_bf16 v[24:27], v[84:87], v[72:75], v[24:27]
	v_mfma_f32_16x16x32_bf16 v[20:23], v[88:91], v[72:75], v[20:23]
	v_mfma_f32_16x16x32_bf16 v[16:19], v[92:95], v[72:75], v[16:19]
	s_waitcnt vmcnt(5)
	ds_write_b128 v156, v[104:107] offset:40960
	s_waitcnt lgkmcnt(11)
	v_mfma_f32_16x16x32_bf16 v[12:15], v[80:83], v[76:79], v[12:15]
	v_add_co_u32_e32 v80, vcc, s59, v224
	v_mfma_f32_16x16x32_bf16 v[0:3], v[92:95], v[76:79], v[0:3]
	s_nop 0
	v_addc_co_u32_e32 v81, vcc, 0, v225, vcc
	v_lshl_add_u64 v[92:93], v[140:141], 0, s[92:93]
	v_mfma_f32_16x16x32_bf16 v[8:11], v[84:87], v[76:79], v[8:11]
	v_add_co_u32_e32 v84, vcc, s11, v92
	s_nop 1
	v_addc_co_u32_e32 v85, vcc, 0, v93, vcc
	v_mfma_f32_16x16x32_bf16 v[4:7], v[88:91], v[76:79], v[4:7]
	v_add_co_u32_e32 v88, vcc, s33, v92
	s_nop 0
	s_nop 0
	v_addc_co_u32_e32 v89, vcc, 0, v93, vcc
	s_waitcnt vmcnt(4)
	ds_write_b128 v156, v[112:115] offset:45056
	s_waitcnt lgkmcnt(7)
	v_mfma_f32_16x16x32_bf16 v[60:63], v[208:211], v[192:195], v[60:63]
	s_waitcnt lgkmcnt(6)
	v_mfma_f32_16x16x32_bf16 v[56:59], v[212:215], v[192:195], v[56:59]
	s_waitcnt lgkmcnt(5)
	v_mfma_f32_16x16x32_bf16 v[52:55], v[216:219], v[192:195], v[52:55]
	s_waitcnt lgkmcnt(4)
	v_mfma_f32_16x16x32_bf16 v[48:51], v[220:223], v[192:195], v[48:51]
	v_add_co_u32_e32 v92, vcc, s59, v92
	s_waitcnt vmcnt(3)
	ds_write_b128 v156, v[108:111] offset:49152
	s_nop 0
	v_addc_co_u32_e32 v93, vcc, 0, v93, vcc
	v_mfma_f32_16x16x32_bf16 v[44:47], v[208:211], v[196:199], v[44:47]
	v_mfma_f32_16x16x32_bf16 v[40:43], v[212:215], v[196:199], v[40:43]
	v_mfma_f32_16x16x32_bf16 v[36:39], v[216:219], v[196:199], v[36:39]
	v_mfma_f32_16x16x32_bf16 v[32:35], v[220:223], v[196:199], v[32:35]
	s_waitcnt vmcnt(2)
	ds_write_b128 v156, v[116:119] offset:53248
	v_mfma_f32_16x16x32_bf16 v[28:31], v[208:211], v[200:203], v[28:31]
	v_mfma_f32_16x16x32_bf16 v[24:27], v[212:215], v[200:203], v[24:27]
	v_mfma_f32_16x16x32_bf16 v[20:23], v[216:219], v[200:203], v[20:23]
	v_mfma_f32_16x16x32_bf16 v[16:19], v[220:223], v[200:203], v[16:19]
	s_waitcnt vmcnt(1)
	ds_write_b128 v156, v[120:123] offset:57344
	v_mfma_f32_16x16x32_bf16 v[12:15], v[208:211], v[204:207], v[12:15]
	v_mfma_f32_16x16x32_bf16 v[8:11], v[212:215], v[204:207], v[8:11]
	v_mfma_f32_16x16x32_bf16 v[4:7], v[216:219], v[204:207], v[4:7]
	v_mfma_f32_16x16x32_bf16 v[0:3], v[220:223], v[204:207], v[0:3]
	s_waitcnt vmcnt(0)
	ds_write_b128 v156, v[124:127] offset:61440
	s_waitcnt lgkmcnt(0)
	s_barrier
	ds_read_b128 v[112:115], v181 offset:49152
	ds_read_b128 v[116:119], v181 offset:51200
	ds_read_b128 v[120:123], v181 offset:53248
	ds_read_b128 v[124:127], v181 offset:55296
	ds_read_b128 v[96:99], v180 offset:32768
	ds_read_b128 v[100:103], v180 offset:34816
	s_min_u32 s28, s27, 12
	s_lshl_b32 s92, s28, 7
	ds_read_b128 v[104:107], v180 offset:36864
	v_lshl_add_u64 v[224:225], v[138:139], 0, s[92:93]
	ds_read_b128 v[108:111], v180 offset:38912
	ds_read_b128 v[192:195], v182 offset:32768
	ds_read_b128 v[196:199], v182 offset:34816
	ds_read_b128 v[200:203], v182 offset:36864
	ds_read_b128 v[204:207], v182 offset:38912
	ds_read_b128 v[208:211], v186 offset:49152
	ds_read_b128 v[212:215], v186 offset:51200
	ds_read_b128 v[216:219], v186 offset:53248
	ds_read_b128 v[220:223], v186 offset:55296
	s_waitcnt lgkmcnt(11)
	v_mfma_f32_16x16x32_bf16 v[60:63], v[112:115], v[96:99], v[60:63]
	v_mfma_f32_16x16x32_bf16 v[56:59], v[116:119], v[96:99], v[56:59]
	v_mfma_f32_16x16x32_bf16 v[52:55], v[120:123], v[96:99], v[52:55]
	v_mfma_f32_16x16x32_bf16 v[48:51], v[124:127], v[96:99], v[48:51]
	v_add_co_u32_e32 v64, vcc, s11, v224
	s_waitcnt lgkmcnt(10)
	v_mfma_f32_16x16x32_bf16 v[44:47], v[112:115], v[100:103], v[44:47]
	v_addc_co_u32_e32 v65, vcc, 0, v225, vcc
	v_mfma_f32_16x16x32_bf16 v[40:43], v[116:119], v[100:103], v[40:43]
	v_mfma_f32_16x16x32_bf16 v[36:39], v[120:123], v[100:103], v[36:39]
	v_mfma_f32_16x16x32_bf16 v[32:35], v[124:127], v[100:103], v[32:35]
	v_add_co_u32_e32 v64, vcc, s33, v224
	s_nop 1
	v_addc_co_u32_e32 v65, vcc, 0, v225, vcc
	s_waitcnt lgkmcnt(9)
	v_mfma_f32_16x16x32_bf16 v[28:31], v[112:115], v[104:107], v[28:31]
	v_mfma_f32_16x16x32_bf16 v[24:27], v[116:119], v[104:107], v[24:27]
	v_mfma_f32_16x16x32_bf16 v[20:23], v[120:123], v[104:107], v[20:23]
	v_mfma_f32_16x16x32_bf16 v[16:19], v[124:127], v[104:107], v[16:19]
	v_add_co_u32_e32 v64, vcc, s59, v224
	s_nop 1
	v_addc_co_u32_e32 v65, vcc, 0, v225, vcc
	s_waitcnt lgkmcnt(8)
	v_mfma_f32_16x16x32_bf16 v[12:15], v[112:115], v[108:111], v[12:15]
	v_mfma_f32_16x16x32_bf16 v[8:11], v[116:119], v[108:111], v[8:11]
	v_mfma_f32_16x16x32_bf16 v[4:7], v[120:123], v[108:111], v[4:7]
	v_mfma_f32_16x16x32_bf16 v[0:3], v[124:127], v[108:111], v[0:3]
	v_lshl_add_u64 v[64:65], v[140:141], 0, s[92:93]
	v_add_co_u32_e32 v66, vcc, s11, v64
	s_nop 1
	v_addc_co_u32_e32 v67, vcc, 0, v65, vcc
	s_waitcnt lgkmcnt(3)
	v_mfma_f32_16x16x32_bf16 v[60:63], v[208:211], v[192:195], v[60:63]
	s_waitcnt lgkmcnt(2)
	v_mfma_f32_16x16x32_bf16 v[56:59], v[212:215], v[192:195], v[56:59]
	s_waitcnt lgkmcnt(1)
	v_mfma_f32_16x16x32_bf16 v[52:55], v[216:219], v[192:195], v[52:55]
	s_waitcnt lgkmcnt(0)
	v_mfma_f32_16x16x32_bf16 v[48:51], v[220:223], v[192:195], v[48:51]
	v_mfma_f32_16x16x32_bf16 v[44:47], v[208:211], v[196:199], v[44:47]
	v_mfma_f32_16x16x32_bf16 v[40:43], v[212:215], v[196:199], v[40:43]
	v_mfma_f32_16x16x32_bf16 v[36:39], v[216:219], v[196:199], v[36:39]
	v_mfma_f32_16x16x32_bf16 v[32:35], v[220:223], v[196:199], v[32:35]
	v_add_co_u32_e32 v66, vcc, s33, v64
	s_nop 1
	v_addc_co_u32_e32 v67, vcc, 0, v65, vcc
	v_add_co_u32_e32 v64, vcc, s59, v64
	v_mfma_f32_16x16x32_bf16 v[28:31], v[208:211], v[200:203], v[28:31]
	s_nop 0
	v_addc_co_u32_e32 v65, vcc, 0, v65, vcc
	v_mfma_f32_16x16x32_bf16 v[24:27], v[212:215], v[200:203], v[24:27]
	v_mfma_f32_16x16x32_bf16 v[20:23], v[216:219], v[200:203], v[20:23]
	v_mfma_f32_16x16x32_bf16 v[16:19], v[220:223], v[200:203], v[16:19]
	v_mfma_f32_16x16x32_bf16 v[12:15], v[208:211], v[204:207], v[12:15]
	v_mfma_f32_16x16x32_bf16 v[8:11], v[212:215], v[204:207], v[8:11]
	v_mfma_f32_16x16x32_bf16 v[4:7], v[216:219], v[204:207], v[4:7]
	v_mfma_f32_16x16x32_bf16 v[0:3], v[220:223], v[204:207], v[0:3]
	s_mov_b32 s28, s27
	s_waitcnt lgkmcnt(0)
	s_barrier
	s_and_saveexec_b64 s[28:29], s[36:37]
	s_cbranch_execz .LBB0_353
	v_add_f32_e32 v64, 0, v128
	v_add_f32_e32 v64, v64, v157
	v_add_f32_e32 v64, v64, v158
	v_add_f32_e32 v64, v64, v159
	v_add_f32_e32 v64, v64, v160
	v_add_f32_e32 v64, v64, v161
	v_add_f32_e32 v64, v64, v162
	v_add_f32_e32 v64, v64, v163
	v_add_f32_e32 v64, v64, v164
	v_add_f32_e32 v64, v64, v165
	v_add_f32_e32 v64, v64, v168
	v_add_f32_e32 v64, v64, v175
	v_add_f32_e32 v64, v64, v179
	v_add_f32_e32 v64, v64, v183
	v_add_f32_e32 v64, v64, v190
	v_add_f32_e32 v64, v64, v191
	v_fmamk_f32 v64, v64, 0x3a800000, v167
	s_mov_b32 s16, 0x800000
	v_mul_f32_e32 v65, 0x4b800000, v64
	v_cmp_gt_f32_e32 vcc, s16, v64
	s_nop 1
	v_cndmask_b32_e32 v64, v64, v65, vcc
	v_rsq_f32_e32 v64, v64
	s_nop 0
	v_mul_f32_e32 v65, 0x45800000, v64
	v_cndmask_b32_e32 v64, v64, v65, vcc
	ds_write_b32 v155, v64
	s_branch .LBB0_353

.Ltail372:
	s_add_i32 s3, s24, 2
	v_add_u32_e32 v180, v142, v144
	ds_read_b128 v[44:47], v180
	ds_read_b128 v[48:51], v180 offset:2048
	v_add_u32_e32 v181, v143, v144
	ds_read_b128 v[52:55], v180 offset:4096
	ds_read_b128 v[56:59], v180 offset:6144
	ds_read_b128 v[60:63], v181 offset:16384
	ds_read_b128 v[68:71], v181 offset:18432
	ds_read_b128 v[72:75], v181 offset:20480
	ds_read_b128 v[76:79], v181 offset:22528
	v_add_u32_e32 v182, v142, v145
	s_add_i32 s24, s24, 4
	ds_read_b128 v[192:195], v182
	s_min_u32 s24, s24, 15
	s_lshl_b32 s92, s24, 7
	v_add_u32_e32 v186, v143, v145
	v_lshl_add_u64 v[224:225], v[138:139], 0, s[92:93]
	ds_read_b128 v[196:199], v182 offset:2048
	ds_read_b128 v[200:203], v182 offset:4096
	ds_read_b128 v[204:207], v182 offset:6144
	ds_read_b128 v[208:211], v186 offset:16384
	ds_read_b128 v[212:215], v186 offset:18432
	ds_read_b128 v[216:219], v186 offset:20480
	ds_read_b128 v[220:223], v186 offset:22528
	s_waitcnt lgkmcnt(11)
	v_mfma_f32_16x16x32_bf16 v[92:95], v[44:47], v[60:63], v[92:95]
	s_waitcnt lgkmcnt(10)
	v_mfma_f32_16x16x32_bf16 v[88:91], v[44:47], v[68:71], v[88:91]
	s_waitcnt lgkmcnt(9)
	v_mfma_f32_16x16x32_bf16 v[84:87], v[44:47], v[72:75], v[84:87]
	s_waitcnt lgkmcnt(8)
	v_mfma_f32_16x16x32_bf16 v[44:47], v[44:47], v[76:79], v[80:83]
	s_nop 2
	s_waitcnt vmcnt(7)
	ds_write_b128 v156, v[96:99] offset:32768
	v_add_co_u32_e32 v96, vcc, s11, v224
	v_mfma_f32_16x16x32_bf16 v[64:67], v[48:51], v[60:63], v[64:67]
	s_nop 0
	v_addc_co_u32_e32 v97, vcc, 0, v225, vcc
	v_mfma_f32_16x16x32_bf16 v[40:43], v[48:51], v[68:71], v[40:43]
	v_mfma_f32_16x16x32_bf16 v[36:39], v[48:51], v[72:75], v[36:39]
	v_mfma_f32_16x16x32_bf16 v[32:35], v[48:51], v[76:79], v[32:35]
	v_add_co_u32_e32 v96, vcc, s33, v224
	s_waitcnt vmcnt(6)
	ds_write_b128 v156, v[100:103] offset:36864
	s_nop 0
	v_addc_co_u32_e32 v97, vcc, 0, v225, vcc
	v_mfma_f32_16x16x32_bf16 v[28:31], v[52:55], v[60:63], v[28:31]
	v_mfma_f32_16x16x32_bf16 v[24:27], v[52:55], v[68:71], v[24:27]
	v_mfma_f32_16x16x32_bf16 v[20:23], v[52:55], v[72:75], v[20:23]
	v_mfma_f32_16x16x32_bf16 v[16:19], v[52:55], v[76:79], v[16:19]
	s_waitcnt vmcnt(5)
	ds_write_b128 v156, v[104:107] offset:40960
	v_mfma_f32_16x16x32_bf16 v[12:15], v[56:59], v[60:63], v[12:15]
	v_add_co_u32_e32 v60, vcc, s59, v224
	s_nop 1
	v_addc_co_u32_e32 v61, vcc, 0, v225, vcc
	v_mfma_f32_16x16x32_bf16 v[8:11], v[56:59], v[68:71], v[8:11]
	v_mfma_f32_16x16x32_bf16 v[4:7], v[56:59], v[72:75], v[4:7]
	v_mfma_f32_16x16x32_bf16 v[0:3], v[56:59], v[76:79], v[0:3]
	s_waitcnt vmcnt(4)
	ds_write_b128 v156, v[112:115] offset:45056
	s_waitcnt lgkmcnt(5)
	v_mfma_f32_16x16x32_bf16 v[72:75], v[192:195], v[216:219], v[84:87]
	s_nop 2
	v_lshl_add_u64 v[84:85], v[140:141], 0, s[92:93]
	v_add_co_u32_e32 v86, vcc, s11, v84
	v_mfma_f32_16x16x32_bf16 v[60:63], v[192:195], v[208:211], v[92:95]
	s_nop 0
	v_addc_co_u32_e32 v87, vcc, 0, v85, vcc
	v_mfma_f32_16x16x32_bf16 v[68:71], v[192:195], v[212:215], v[88:91]
	s_waitcnt lgkmcnt(4)
	v_mfma_f32_16x16x32_bf16 v[44:47], v[192:195], v[220:223], v[44:47]
	s_waitcnt vmcnt(3)
	ds_write_b128 v156, v[108:111] offset:49152
	v_mfma_f32_16x16x32_bf16 v[64:67], v[196:199], v[208:211], v[64:67]
	v_mfma_f32_16x16x32_bf16 v[40:43], v[196:199], v[212:215], v[40:43]
	v_mfma_f32_16x16x32_bf16 v[36:39], v[196:199], v[216:219], v[36:39]
	v_mfma_f32_16x16x32_bf16 v[32:35], v[196:199], v[220:223], v[32:35]
	v_add_co_u32_e32 v86, vcc, s33, v84
	s_waitcnt vmcnt(2)
	ds_write_b128 v156, v[116:119] offset:53248
	v_addc_co_u32_e32 v87, vcc, 0, v85, vcc
	v_add_co_u32_e32 v84, vcc, s59, v84
	v_mfma_f32_16x16x32_bf16 v[28:31], v[200:203], v[208:211], v[28:31]
	s_nop 0
	v_addc_co_u32_e32 v85, vcc, 0, v85, vcc
	v_mfma_f32_16x16x32_bf16 v[24:27], v[200:203], v[212:215], v[24:27]
	v_mfma_f32_16x16x32_bf16 v[20:23], v[200:203], v[216:219], v[20:23]
	v_mfma_f32_16x16x32_bf16 v[16:19], v[200:203], v[220:223], v[16:19]
	s_waitcnt vmcnt(1)
	ds_write_b128 v156, v[120:123] offset:57344
	v_mfma_f32_16x16x32_bf16 v[12:15], v[204:207], v[208:211], v[12:15]
	v_mfma_f32_16x16x32_bf16 v[8:11], v[204:207], v[212:215], v[8:11]
	v_mfma_f32_16x16x32_bf16 v[4:7], v[204:207], v[216:219], v[4:7]
	v_mfma_f32_16x16x32_bf16 v[0:3], v[204:207], v[220:223], v[0:3]
	s_waitcnt vmcnt(0)
	ds_write_b128 v156, v[124:127] offset:61440
	s_waitcnt lgkmcnt(0)
	s_barrier
	ds_read_b128 v[84:87], v180 offset:32768
	ds_read_b128 v[88:91], v180 offset:34816
	ds_read_b128 v[112:115], v181 offset:49152
	ds_read_b128 v[116:119], v181 offset:51200
	ds_read_b128 v[120:123], v181 offset:53248
	ds_read_b128 v[124:127], v181 offset:55296
	ds_read_b128 v[92:95], v180 offset:36864
	ds_read_b128 v[108:111], v180 offset:38912
	ds_read_b128 v[204:207], v182 offset:32768
	s_min_u32 s24, s3, 12
	s_lshl_b32 s92, s24, 7
	ds_read_b128 v[208:211], v182 offset:34816
	ds_read_b128 v[212:215], v182 offset:36864
	ds_read_b128 v[216:219], v182 offset:38912
	ds_read_b128 v[220:223], v186 offset:49152
	ds_read_b128 v[224:227], v186 offset:51200
	ds_read_b128 v[228:231], v186 offset:53248
	ds_read_b128 v[232:235], v186 offset:55296
	s_waitcnt lgkmcnt(13)
	v_mfma_f32_16x16x32_bf16 v[60:63], v[84:87], v[112:115], v[60:63]
	s_waitcnt lgkmcnt(12)
	v_mfma_f32_16x16x32_bf16 v[68:71], v[84:87], v[116:119], v[68:71]
	s_waitcnt lgkmcnt(11)
	v_mfma_f32_16x16x32_bf16 v[72:75], v[84:87], v[120:123], v[72:75]
	s_waitcnt lgkmcnt(10)
	v_mfma_f32_16x16x32_bf16 v[44:47], v[84:87], v[124:127], v[44:47]
	v_lshl_add_u64 v[84:85], v[138:139], 0, s[92:93]
	v_add_co_u32_e32 v80, vcc, s11, v84
	v_mfma_f32_16x16x32_bf16 v[64:67], v[88:91], v[112:115], v[64:67]
	s_nop 0
	v_addc_co_u32_e32 v81, vcc, 0, v85, vcc
	v_mfma_f32_16x16x32_bf16 v[40:43], v[88:91], v[116:119], v[40:43]
	v_mfma_f32_16x16x32_bf16 v[36:39], v[88:91], v[120:123], v[36:39]
	v_mfma_f32_16x16x32_bf16 v[32:35], v[88:91], v[124:127], v[32:35]
	v_add_co_u32_e32 v48, vcc, s33, v84
	s_waitcnt lgkmcnt(9)
	v_mfma_f32_16x16x32_bf16 v[28:31], v[92:95], v[112:115], v[28:31]
	v_addc_co_u32_e32 v49, vcc, 0, v85, vcc
	v_mfma_f32_16x16x32_bf16 v[24:27], v[92:95], v[116:119], v[24:27]
	v_mfma_f32_16x16x32_bf16 v[20:23], v[92:95], v[120:123], v[20:23]
	v_mfma_f32_16x16x32_bf16 v[16:19], v[92:95], v[124:127], v[16:19]
	v_add_co_u32_e32 v48, vcc, s59, v84
	s_nop 1
	v_addc_co_u32_e32 v49, vcc, 0, v85, vcc
	s_waitcnt lgkmcnt(8)
	v_mfma_f32_16x16x32_bf16 v[12:15], v[108:111], v[112:115], v[12:15]
	v_mfma_f32_16x16x32_bf16 v[8:11], v[108:111], v[116:119], v[8:11]
	v_mfma_f32_16x16x32_bf16 v[4:7], v[108:111], v[120:123], v[4:7]
	v_mfma_f32_16x16x32_bf16 v[0:3], v[108:111], v[124:127], v[0:3]
	s_waitcnt lgkmcnt(0)
	v_mfma_f32_16x16x32_bf16 v[80:83], v[204:207], v[232:235], v[44:47]
	s_nop 2
	v_lshl_add_u64 v[44:45], v[140:141], 0, s[92:93]
	v_add_co_u32_e32 v46, vcc, s11, v44
	v_mfma_f32_16x16x32_bf16 v[92:95], v[204:207], v[220:223], v[60:63]
	s_nop 0
	v_addc_co_u32_e32 v47, vcc, 0, v45, vcc
	v_mfma_f32_16x16x32_bf16 v[88:91], v[204:207], v[224:227], v[68:71]
	v_mfma_f32_16x16x32_bf16 v[84:87], v[204:207], v[228:231], v[72:75]
	v_mfma_f32_16x16x32_bf16 v[64:67], v[208:211], v[220:223], v[64:67]
	v_mfma_f32_16x16x32_bf16 v[40:43], v[208:211], v[224:227], v[40:43]
	v_mfma_f32_16x16x32_bf16 v[36:39], v[208:211], v[228:231], v[36:39]
	v_mfma_f32_16x16x32_bf16 v[32:35], v[208:211], v[232:235], v[32:35]
	v_add_co_u32_e32 v46, vcc, s33, v44
	s_nop 1
	v_addc_co_u32_e32 v47, vcc, 0, v45, vcc
	v_add_co_u32_e32 v44, vcc, s59, v44
	v_mfma_f32_16x16x32_bf16 v[28:31], v[212:215], v[220:223], v[28:31]
	s_nop 0
	v_addc_co_u32_e32 v45, vcc, 0, v45, vcc
	v_mfma_f32_16x16x32_bf16 v[24:27], v[212:215], v[224:227], v[24:27]
	v_mfma_f32_16x16x32_bf16 v[20:23], v[212:215], v[228:231], v[20:23]
	v_mfma_f32_16x16x32_bf16 v[16:19], v[212:215], v[232:235], v[16:19]
	v_mfma_f32_16x16x32_bf16 v[12:15], v[216:219], v[220:223], v[12:15]
	v_mfma_f32_16x16x32_bf16 v[8:11], v[216:219], v[224:227], v[8:11]
	v_mfma_f32_16x16x32_bf16 v[4:7], v[216:219], v[228:231], v[4:7]
	v_mfma_f32_16x16x32_bf16 v[0:3], v[216:219], v[232:235], v[0:3]
	s_mov_b32 s24, s3
	s_waitcnt lgkmcnt(0)
	s_barrier
	s_and_saveexec_b64 s[24:25], s[36:37]
	s_cbranch_execz .LBB0_366
	v_add_f32_e32 v44, 0, v128
	v_add_f32_e32 v44, v44, v157
	v_add_f32_e32 v44, v44, v158
	v_add_f32_e32 v44, v44, v159
	v_add_f32_e32 v44, v44, v160
	v_add_f32_e32 v44, v44, v161
	v_add_f32_e32 v44, v44, v162
	v_add_f32_e32 v44, v44, v163
	v_add_f32_e32 v44, v44, v164
	v_add_f32_e32 v44, v44, v165
	v_add_f32_e32 v44, v44, v168
	v_add_f32_e32 v44, v44, v175
	v_add_f32_e32 v44, v44, v179
	v_add_f32_e32 v44, v44, v183
	v_add_f32_e32 v44, v44, v190
	v_add_f32_e32 v44, v44, v191
	v_fmamk_f32 v44, v44, 0x3a800000, v167
	s_mov_b32 s3, 0x800000
	v_mul_f32_e32 v45, 0x4b800000, v44
	v_cmp_gt_f32_e32 vcc, s3, v44
	s_nop 1
	v_cndmask_b32_e32 v44, v44, v45, vcc
	v_rsq_f32_e32 v44, v44
	s_nop 0
	v_mul_f32_e32 v45, 0x45800000, v44
	v_cndmask_b32_e32 v44, v44, v45, vcc
	ds_write_b32 v155, v44
	s_branch .LBB0_366

.Ltail392:
	s_add_i32 s0, s1, 2
	v_add_u32_e32 v111, v104, v105
	ds_read_b128 v[136:139], v111 offset:16384
	ds_read_b128 v[140:143], v111 offset:18432
	ds_read_b128 v[144:147], v111 offset:20480
	ds_read_b128 v[148:151], v111 offset:22528
	v_add_u32_e32 v110, v103, v105
	ds_read_b128 v[116:119], v110
	s_add_i32 s1, s1, 4
	ds_read_b128 v[120:123], v110 offset:2048
	s_min_u32 s1, s1, 15
	v_add_u32_e32 v113, v104, v114
	s_lshl_b32 s92, s1, 7
	ds_read_b128 v[124:127], v110 offset:4096
	v_add_u32_e32 v112, v103, v114
	ds_read_b128 v[194:197], v113 offset:16384
	ds_read_b128 v[198:201], v113 offset:18432
	ds_read_b128 v[202:205], v113 offset:20480
	ds_read_b128 v[206:209], v113 offset:22528
	v_lshl_add_u64 v[164:165], v[98:99], 0, s[92:93]
	ds_read_b128 v[132:135], v110 offset:6144
	ds_read_b128 v[152:155], v112
	ds_read_b128 v[156:159], v112 offset:2048
	ds_read_b128 v[160:163], v112 offset:4096
	ds_read_b128 v[190:193], v112 offset:6144
	s_waitcnt lgkmcnt(11)
	v_mfma_f32_16x16x32_bf16 v[92:95], v[136:139], v[116:119], v[92:95]
	v_mfma_f32_16x16x32_bf16 v[88:91], v[140:143], v[116:119], v[88:91]
	v_mfma_f32_16x16x32_bf16 v[52:55], v[144:147], v[116:119], v[52:55]
	v_mfma_f32_16x16x32_bf16 v[48:51], v[148:151], v[116:119], v[48:51]
	s_waitcnt vmcnt(7)
	ds_write_b128 v109, v[56:59] offset:32768
	v_add_co_u32_e32 v56, vcc, s11, v164
	s_waitcnt lgkmcnt(11)
	v_mfma_f32_16x16x32_bf16 v[44:47], v[136:139], v[120:123], v[44:47]
	v_addc_co_u32_e32 v57, vcc, 0, v165, vcc
	v_mfma_f32_16x16x32_bf16 v[40:43], v[140:143], v[120:123], v[40:43]
	v_mfma_f32_16x16x32_bf16 v[36:39], v[144:147], v[120:123], v[36:39]
	v_mfma_f32_16x16x32_bf16 v[32:35], v[148:151], v[120:123], v[32:35]
	v_add_co_u32_e32 v56, vcc, s33, v164
	s_waitcnt vmcnt(6)
	ds_write_b128 v109, v[60:63] offset:36864
	s_nop 0
	v_addc_co_u32_e32 v57, vcc, 0, v165, vcc
	s_waitcnt lgkmcnt(11)
	v_mfma_f32_16x16x32_bf16 v[28:31], v[136:139], v[124:127], v[28:31]
	v_mfma_f32_16x16x32_bf16 v[24:27], v[140:143], v[124:127], v[24:27]
	v_mfma_f32_16x16x32_bf16 v[20:23], v[144:147], v[124:127], v[20:23]
	v_mfma_f32_16x16x32_bf16 v[16:19], v[148:151], v[124:127], v[16:19]
	v_add_co_u32_e32 v56, vcc, s59, v164
	s_waitcnt vmcnt(5)
	ds_write_b128 v109, v[64:67] offset:40960
	s_nop 0
	v_addc_co_u32_e32 v57, vcc, 0, v165, vcc
	v_lshl_add_u64 v[64:65], v[100:101], 0, s[92:93]
	v_add_co_u32_e32 v66, vcc, s11, v64
	s_waitcnt lgkmcnt(7)
	v_mfma_f32_16x16x32_bf16 v[12:15], v[136:139], v[132:135], v[12:15]
	v_addc_co_u32_e32 v67, vcc, 0, v65, vcc
	v_mfma_f32_16x16x32_bf16 v[8:11], v[140:143], v[132:135], v[8:11]
	v_mfma_f32_16x16x32_bf16 v[4:7], v[144:147], v[132:135], v[4:7]
	v_mfma_f32_16x16x32_bf16 v[0:3], v[148:151], v[132:135], v[0:3]
	s_waitcnt vmcnt(4)
	ds_write_b128 v109, v[72:75] offset:45056
	s_waitcnt lgkmcnt(7)
	v_mfma_f32_16x16x32_bf16 v[56:59], v[194:197], v[152:155], v[92:95]
	v_mfma_f32_16x16x32_bf16 v[60:63], v[198:201], v[152:155], v[88:91]
	v_mfma_f32_16x16x32_bf16 v[52:55], v[202:205], v[152:155], v[52:55]
	v_mfma_f32_16x16x32_bf16 v[48:51], v[206:209], v[152:155], v[48:51]
	s_waitcnt vmcnt(3)
	ds_write_b128 v109, v[68:71] offset:49152
	s_waitcnt lgkmcnt(7)
	v_mfma_f32_16x16x32_bf16 v[44:47], v[194:197], v[156:159], v[44:47]
	v_mfma_f32_16x16x32_bf16 v[40:43], v[198:201], v[156:159], v[40:43]
	v_mfma_f32_16x16x32_bf16 v[36:39], v[202:205], v[156:159], v[36:39]
	v_mfma_f32_16x16x32_bf16 v[32:35], v[206:209], v[156:159], v[32:35]
	v_add_co_u32_e32 v66, vcc, s33, v64
	s_waitcnt vmcnt(2)
	ds_write_b128 v109, v[76:79] offset:53248
	v_addc_co_u32_e32 v67, vcc, 0, v65, vcc
	v_add_co_u32_e32 v64, vcc, s59, v64
	s_waitcnt lgkmcnt(7)
	v_mfma_f32_16x16x32_bf16 v[28:31], v[194:197], v[160:163], v[28:31]
	v_addc_co_u32_e32 v65, vcc, 0, v65, vcc
	v_mfma_f32_16x16x32_bf16 v[24:27], v[198:201], v[160:163], v[24:27]
	v_mfma_f32_16x16x32_bf16 v[20:23], v[202:205], v[160:163], v[20:23]
	v_mfma_f32_16x16x32_bf16 v[16:19], v[206:209], v[160:163], v[16:19]
	s_waitcnt vmcnt(1)
	ds_write_b128 v109, v[80:83] offset:57344
	s_waitcnt lgkmcnt(7)
	v_mfma_f32_16x16x32_bf16 v[12:15], v[194:197], v[190:193], v[12:15]
	v_mfma_f32_16x16x32_bf16 v[8:11], v[198:201], v[190:193], v[8:11]
	v_mfma_f32_16x16x32_bf16 v[4:7], v[202:205], v[190:193], v[4:7]
	v_mfma_f32_16x16x32_bf16 v[0:3], v[206:209], v[190:193], v[0:3]
	s_waitcnt vmcnt(0)
	ds_write_b128 v109, v[84:87] offset:61440
	s_waitcnt lgkmcnt(0)
	s_barrier
	ds_read_b128 v[84:87], v111 offset:51200
	ds_read_b128 v[80:83], v111 offset:49152
	ds_read_b128 v[88:91], v111 offset:53248
	ds_read_b128 v[92:95], v111 offset:55296
	ds_read_b128 v[64:67], v110 offset:32768
	s_min_u32 s1, s0, 12
	s_lshl_b32 s92, s1, 7
	ds_read_b128 v[68:71], v110 offset:34816
	v_lshl_add_u64 v[164:165], v[98:99], 0, s[92:93]
	ds_read_b128 v[72:75], v110 offset:36864
	ds_read_b128 v[76:79], v110 offset:38912
	ds_read_b128 v[152:155], v112 offset:32768
	ds_read_b128 v[156:159], v112 offset:34816
	ds_read_b128 v[160:163], v112 offset:36864
	ds_read_b128 v[190:193], v112 offset:38912
	ds_read_b128 v[194:197], v113 offset:49152
	ds_read_b128 v[198:201], v113 offset:51200
	ds_read_b128 v[202:205], v113 offset:53248
	ds_read_b128 v[206:209], v113 offset:55296
	s_waitcnt lgkmcnt(11)
	v_mfma_f32_16x16x32_bf16 v[214:217], v[84:87], v[64:67], v[60:63]
	v_mfma_f32_16x16x32_bf16 v[210:213], v[80:83], v[64:67], v[56:59]
	s_nop 1
	v_add_co_u32_e32 v60, vcc, s11, v164
	s_nop 1
	v_addc_co_u32_e32 v61, vcc, 0, v165, vcc
	v_mfma_f32_16x16x32_bf16 v[52:55], v[88:91], v[64:67], v[52:55]
	v_mfma_f32_16x16x32_bf16 v[48:51], v[92:95], v[64:67], v[48:51]
	v_add_co_u32_e32 v64, vcc, s33, v164
	s_nop 0
	s_nop 0
	v_addc_co_u32_e32 v65, vcc, 0, v165, vcc
	s_waitcnt lgkmcnt(10)
	v_mfma_f32_16x16x32_bf16 v[44:47], v[80:83], v[68:71], v[44:47]
	v_mfma_f32_16x16x32_bf16 v[40:43], v[84:87], v[68:71], v[40:43]
	v_mfma_f32_16x16x32_bf16 v[36:39], v[88:91], v[68:71], v[36:39]
	v_mfma_f32_16x16x32_bf16 v[32:35], v[92:95], v[68:71], v[32:35]
	v_add_co_u32_e32 v68, vcc, s59, v164
	s_waitcnt lgkmcnt(9)
	v_mfma_f32_16x16x32_bf16 v[28:31], v[80:83], v[72:75], v[28:31]
	v_addc_co_u32_e32 v69, vcc, 0, v165, vcc
	v_mfma_f32_16x16x32_bf16 v[24:27], v[84:87], v[72:75], v[24:27]
	v_mfma_f32_16x16x32_bf16 v[20:23], v[88:91], v[72:75], v[20:23]
	v_mfma_f32_16x16x32_bf16 v[16:19], v[92:95], v[72:75], v[16:19]
	s_waitcnt lgkmcnt(8)
	v_mfma_f32_16x16x32_bf16 v[8:11], v[84:87], v[76:79], v[8:11]
	v_lshl_add_u64 v[84:85], v[100:101], 0, s[92:93]
	v_mfma_f32_16x16x32_bf16 v[12:15], v[80:83], v[76:79], v[12:15]
	v_mfma_f32_16x16x32_bf16 v[4:7], v[88:91], v[76:79], v[4:7]
	v_mfma_f32_16x16x32_bf16 v[0:3], v[92:95], v[76:79], v[0:3]
	v_add_co_u32_e32 v76, vcc, s11, v84
	s_nop 0
	s_nop 0
	v_addc_co_u32_e32 v77, vcc, 0, v85, vcc
	v_add_co_u32_e32 v80, vcc, s33, v84
	s_nop 1
	v_addc_co_u32_e32 v81, vcc, 0, v85, vcc
	s_waitcnt lgkmcnt(3)
	v_mfma_f32_16x16x32_bf16 v[92:95], v[194:197], v[152:155], v[210:213]
	s_waitcnt lgkmcnt(2)
	v_mfma_f32_16x16x32_bf16 v[88:91], v[198:201], v[152:155], v[214:217]
	s_waitcnt lgkmcnt(1)
	v_mfma_f32_16x16x32_bf16 v[52:55], v[202:205], v[152:155], v[52:55]
	s_waitcnt lgkmcnt(0)
	v_mfma_f32_16x16x32_bf16 v[48:51], v[206:209], v[152:155], v[48:51]
	v_add_co_u32_e32 v84, vcc, s59, v84
	s_nop 1
	v_addc_co_u32_e32 v85, vcc, 0, v85, vcc
	v_mfma_f32_16x16x32_bf16 v[44:47], v[194:197], v[156:159], v[44:47]
	v_mfma_f32_16x16x32_bf16 v[40:43], v[198:201], v[156:159], v[40:43]
	v_mfma_f32_16x16x32_bf16 v[36:39], v[202:205], v[156:159], v[36:39]
	v_mfma_f32_16x16x32_bf16 v[32:35], v[206:209], v[156:159], v[32:35]
	v_mfma_f32_16x16x32_bf16 v[28:31], v[194:197], v[160:163], v[28:31]
	v_mfma_f32_16x16x32_bf16 v[24:27], v[198:201], v[160:163], v[24:27]
	v_mfma_f32_16x16x32_bf16 v[20:23], v[202:205], v[160:163], v[20:23]
	v_mfma_f32_16x16x32_bf16 v[16:19], v[206:209], v[160:163], v[16:19]
	v_mfma_f32_16x16x32_bf16 v[12:15], v[194:197], v[190:193], v[12:15]
	v_mfma_f32_16x16x32_bf16 v[8:11], v[198:201], v[190:193], v[8:11]
	v_mfma_f32_16x16x32_bf16 v[4:7], v[202:205], v[190:193], v[4:7]
	v_mfma_f32_16x16x32_bf16 v[0:3], v[206:209], v[190:193], v[0:3]
	s_mov_b32 s1, s0
	s_waitcnt lgkmcnt(0)
	s_barrier
	s_mul_i32 s0, s69, 0x12000
	v_readlane_b32 s16, v250, 25
	s_add_u32 s24, s16, s0
	v_readlane_b32 s0, v251, 5
	v_lshlrev_b32_e32 v114, 6, v102
	v_readlane_b32 s17, v250, 26
	s_waitcnt vmcnt(5)
	v_add_u32_e32 v64, s0, v108
	v_readlane_b32 s0, v251, 6
	v_add_u32_e32 v56, 0xffffe000, v64
	v_or_b32_e32 v62, v64, v107
	v_or_b32_e32 v65, s0, v114
	v_lshrrev_b32_e32 v56, 10, v56
	s_movk_i32 s0, 0x1800
	v_mad_u32_u24 v56, v56, s0, s0
	v_cmp_lt_i32_e32 vcc, s13, v62
	s_addc_u32 s25, s17, 0
	v_lshlrev_b32_e32 v115, 2, v97
	v_cndmask_b32_e32 v56, 0, v56, vcc
	s_add_u32 s40, s24, 0x2000
	v_or_b32_e32 v58, v65, v115
	v_ashrrev_i32_e32 v57, 31, v56
	s_addc_u32 s41, s25, 0
	s_waitcnt vmcnt(4)
	v_lshlrev_b64 v[74:75], 2, v[56:57]
	v_ashrrev_i32_e32 v59, 31, v58
	v_ashrrev_i32_e32 v63, 31, v62
	v_lshl_add_u64 v[56:57], s[40:41], 0, v[74:75]
	v_lshlrev_b64 v[60:61], 2, v[58:59]
	v_readlane_b32 s0, v250, 15
	s_waitcnt vmcnt(1)
	v_lshl_add_u64 v[82:83], v[56:57], 0, v[60:61]
	v_lshlrev_b64 v[56:57], 12, v[62:63]
	v_readlane_b32 s1, v250, 16
	v_readlane_b32 s16, v250, 21
	v_lshlrev_b64 v[78:79], 11, v[62:63]
	v_lshl_add_u64 v[56:57], s[0:1], 0, v[56:57]
	s_waitcnt vmcnt(0)
	v_lshl_add_u64 v[84:85], v[56:57], 0, v[60:61]
	global_load_dwordx4 v[116:119], v[82:83], off
	global_load_dwordx4 v[120:123], v[82:83], off offset:64
	global_load_dwordx4 v[124:127], v[82:83], off offset:128
	global_load_dwordx4 v[132:135], v[82:83], off offset:192
	global_load_dwordx4 v[190:193], v[84:85], off
	global_load_dwordx4 v[194:197], v[84:85], off offset:64
	global_load_dwordx4 v[198:201], v[84:85], off offset:128
	global_load_dwordx4 v[202:205], v[84:85], off offset:192
	v_add_co_u32_e32 v164, vcc, 0x10000, v84
	s_nop 1
	v_addc_co_u32_e32 v165, vcc, 0, v85, vcc
	v_add_co_u32_e32 v222, vcc, 0x20000, v84
	s_nop 1
	v_addc_co_u32_e32 v223, vcc, 0, v85, vcc
	v_add_co_u32_e32 v224, vcc, 0x30000, v84
	s_nop 1
	v_addc_co_u32_e32 v225, vcc, 0, v85, vcc
	global_load_dwordx4 v[206:209], v[164:165], off
	global_load_dwordx4 v[210:213], v[164:165], off offset:64
	global_load_dwordx4 v[214:217], v[164:165], off offset:128
	global_load_dwordx4 v[218:221], v[164:165], off offset:192
	s_lshl_b32 s0, s69, 12
	v_readlane_b32 s68, v250, 41
	v_readlane_b32 s72, v250, 45
	v_readlane_b32 s73, v250, 46
	s_add_u32 s0, s72, s0
	s_addc_u32 s1, s73, 0
	s_add_u32 s42, s24, 0x4000
	s_addc_u32 s43, s25, 0
	v_lshl_add_u64 v[74:75], s[42:43], 0, v[74:75]
	v_lshl_add_u64 v[56:57], s[0:1], 0, v[60:61]
	v_lshl_add_u64 v[86:87], v[74:75], 0, v[60:61]
	v_readlane_b32 s17, v250, 22
	v_readlane_b32 s69, v250, 42
	v_readlane_b32 s69, v254, 49
	v_lshl_add_u64 v[78:79], s[16:17], 0, v[78:79]
	s_mul_i32 s24, s69, 0x140000
	s_add_u32 s24, s86, s24
	v_lshrrev_b32_e32 v65, 6, v65
	s_mov_b32 s16, 0xa000
	s_addc_u32 s25, s87, 0
	s_add_u32 s38, s24, 0xaf1a000
	s_addc_u32 s39, s25, 0
	v_cmp_eq_u32_e64 s[36:37], 0, v97
	v_readlane_b32 s70, v250, 43
	v_readlane_b32 s71, v250, 44
	v_readlane_b32 s74, v250, 47
	v_readlane_b32 s75, v250, 48
	v_readlane_b32 s76, v250, 49
	v_readlane_b32 s77, v250, 50
	v_readlane_b32 s78, v250, 51
	v_readlane_b32 s79, v250, 52
	v_readlane_b32 s80, v250, 53
	v_readlane_b32 s81, v250, 54
	v_readlane_b32 s82, v250, 55
	v_readlane_b32 s83, v250, 56
	s_waitcnt vmcnt(4)
	v_pk_fma_f32 v[68:69], v[94:95], v[118:119], v[192:193]
	v_pk_fma_f32 v[66:67], v[92:93], v[116:117], v[190:191]
	global_store_dwordx4 v[84:85], v[66:69], off
	global_load_dwordx4 v[136:139], v[56:57], off
	global_load_dwordx4 v[140:143], v[56:57], off offset:64
	global_load_dwordx4 v[144:147], v[56:57], off offset:128
	global_load_dwordx4 v[148:151], v[56:57], off offset:192
	global_load_dwordx4 v[152:155], v[86:87], off
	global_load_dwordx4 v[156:159], v[86:87], off offset:64
	global_load_dwordx4 v[160:163], v[86:87], off offset:128
	global_load_dwordx4 v[180:183], v[86:87], off offset:192
	v_lshl_add_u64 v[92:93], v[58:59], 1, v[78:79]
	s_waitcnt vmcnt(0)
	v_pk_mul_f32 v[72:73], v[68:69], v[138:139]
	v_pk_mul_f32 v[70:71], v[66:67], v[136:137]
	s_waitcnt vmcnt(0)
	v_pk_add_f32 v[76:77], v[154:155], 1.0 op_sel_hi:[1,0]
	v_pk_add_f32 v[74:75], v[152:153], 1.0 op_sel_hi:[1,0]
	v_pk_mul_f32 v[72:73], v[72:73], v[76:77]
	v_pk_mul_f32 v[70:71], v[70:71], v[74:75]
	v_and_b32_sdwa v77, v71, v170 dst_sel:DWORD dst_unused:UNUSED_PAD src0_sel:WORD_1 src1_sel:DWORD
	v_and_b32_sdwa v75, v70, v170 dst_sel:DWORD dst_unused:UNUSED_PAD src0_sel:WORD_1 src1_sel:DWORD
	v_add3_u32 v71, v71, v77, s56
	v_add3_u32 v70, v70, v75, s56
	v_and_b32_e32 v74, 0xffff0000, v71
	v_cvt_pk_bf16_f32 v71, v72, v73
	v_or_b32_sdwa v70, v74, v70 dst_sel:DWORD dst_unused:UNUSED_PAD src0_sel:DWORD src1_sel:WORD_1
	global_store_dwordx2 v[92:93], v[70:71], off
	s_nop 0
	s_waitcnt vmcnt(0)
	v_pk_fma_f32 v[72:73], v[90:91], v[122:123], v[196:197]
	v_pk_fma_f32 v[70:71], v[88:89], v[120:121], v[194:195]
	global_store_dwordx4 v[84:85], v[70:73], off offset:64
	v_pk_mul_f32 v[76:77], v[72:73], v[142:143]
	v_pk_mul_f32 v[74:75], v[70:71], v[140:141]
	v_pk_add_f32 v[80:81], v[158:159], 1.0 op_sel_hi:[1,0]
	v_pk_add_f32 v[78:79], v[156:157], 1.0 op_sel_hi:[1,0]
	v_pk_mul_f32 v[76:77], v[76:77], v[80:81]
	v_pk_mul_f32 v[74:75], v[74:75], v[78:79]
	v_and_b32_sdwa v81, v75, v170 dst_sel:DWORD dst_unused:UNUSED_PAD src0_sel:WORD_1 src1_sel:DWORD
	v_and_b32_sdwa v79, v74, v170 dst_sel:DWORD dst_unused:UNUSED_PAD src0_sel:WORD_1 src1_sel:DWORD
	v_add3_u32 v75, v75, v81, s56
	v_add3_u32 v74, v74, v79, s56
	v_and_b32_e32 v78, 0xffff0000, v75
	v_cvt_pk_bf16_f32 v75, v76, v77
	v_or_b32_sdwa v74, v78, v74 dst_sel:DWORD dst_unused:UNUSED_PAD src0_sel:DWORD src1_sel:WORD_1
	global_store_dwordx2 v[92:93], v[74:75], off offset:32
	s_nop 0
	v_pk_fma_f32 v[54:55], v[54:55], v[126:127], v[200:201]
	v_pk_fma_f32 v[52:53], v[52:53], v[124:125], v[198:199]
	global_store_dwordx4 v[84:85], v[52:55], off offset:128
	v_pk_mul_f32 v[76:77], v[54:55], v[146:147]
	v_pk_mul_f32 v[74:75], v[52:53], v[144:145]
	v_pk_add_f32 v[80:81], v[162:163], 1.0 op_sel_hi:[1,0]
	v_pk_add_f32 v[78:79], v[160:161], 1.0 op_sel_hi:[1,0]
	v_pk_mul_f32 v[76:77], v[76:77], v[80:81]
	v_pk_mul_f32 v[74:75], v[74:75], v[78:79]
	v_and_b32_sdwa v81, v75, v170 dst_sel:DWORD dst_unused:UNUSED_PAD src0_sel:WORD_1 src1_sel:DWORD
	v_and_b32_sdwa v79, v74, v170 dst_sel:DWORD dst_unused:UNUSED_PAD src0_sel:WORD_1 src1_sel:DWORD
	v_add3_u32 v75, v75, v81, s56
	v_add3_u32 v74, v74, v79, s56
	v_and_b32_e32 v78, 0xffff0000, v75
	v_cvt_pk_bf16_f32 v75, v76, v77
	v_or_b32_sdwa v74, v78, v74 dst_sel:DWORD dst_unused:UNUSED_PAD src0_sel:DWORD src1_sel:WORD_1
	global_store_dwordx2 v[92:93], v[74:75], off offset:64
	s_nop 0
	v_pk_fma_f32 v[76:77], v[50:51], v[134:135], v[204:205]
	v_pk_fma_f32 v[74:75], v[48:49], v[132:133], v[202:203]
	global_store_dwordx4 v[84:85], v[74:77], off offset:192
	s_nop 0
	v_mbcnt_lo_u32_b32 v48, -1, 0
	v_mbcnt_hi_u32_b32 v48, -1, v48
	v_and_b32_e32 v50, 64, v48
	v_xor_b32_e32 v49, 16, v48
	v_add_u32_e32 v50, 64, v50
	v_xor_b32_e32 v51, 32, v48
	v_cmp_lt_i32_e32 vcc, v49, v50
	s_nop 1
	v_cndmask_b32_e32 v49, v48, v49, vcc
	v_cmp_lt_i32_e32 vcc, v51, v50
	v_lshlrev_b32_e32 v105, 2, v49
	s_nop 0
	v_cndmask_b32_e32 v50, v48, v51, vcc
	v_lshlrev_b32_e32 v104, 2, v50
	v_mul_f32_e32 v50, v67, v67
	v_mul_f32_e32 v51, v71, v71
	v_fmac_f32_e32 v50, v66, v66
	v_fmac_f32_e32 v51, v70, v70
	v_fmac_f32_e32 v50, v68, v68
	v_fmac_f32_e32 v51, v72, v72
	v_fmac_f32_e32 v50, v69, v69
	v_fmac_f32_e32 v51, v73, v73
	v_add_f32_e32 v50, v50, v51
	v_mul_f32_e32 v51, v53, v53
	v_fmac_f32_e32 v51, v52, v52
	v_fmac_f32_e32 v51, v54, v54
	v_fmac_f32_e32 v51, v55, v55
	v_add_f32_e32 v50, v50, v51
	v_mul_f32_e32 v51, v75, v75
	v_fmac_f32_e32 v51, v74, v74
	v_fmac_f32_e32 v51, v76, v76
	v_fmac_f32_e32 v51, v77, v77
	v_add_f32_e32 v50, v50, v51
	ds_bpermute_b32 v51, v105, v50
	v_mul_lo_u32 v48, v65, s16
	v_ashrrev_i32_e32 v49, 31, v48
	v_lshl_add_u64 v[48:49], s[38:39], 0, v[48:49]
	v_lshl_add_u64 v[48:49], v[62:63], 2, v[48:49]
	s_waitcnt lgkmcnt(0)
	v_add_f32_e32 v50, v50, v51
	ds_bpermute_b32 v51, v104, v50
	v_pk_mul_f32 v[52:53], v[76:77], v[150:151]
	v_pk_mul_f32 v[54:55], v[74:75], v[148:149]
	v_pk_add_f32 v[66:67], v[182:183], 1.0 op_sel_hi:[1,0]
	v_pk_add_f32 v[68:69], v[180:181], 1.0 op_sel_hi:[1,0]
	v_pk_mul_f32 v[52:53], v[52:53], v[66:67]
	v_pk_mul_f32 v[54:55], v[54:55], v[68:69]
	v_cvt_pk_bf16_f32 v53, v52, v53
	v_cvt_pk_bf16_f32 v52, v54, v55
	global_store_dwordx2 v[92:93], v[52:53], off offset:96
	s_and_saveexec_b64 s[24:25], s[36:37]
	s_cbranch_execz .LBB0_395
	s_waitcnt lgkmcnt(0)
	v_add_f32_e32 v50, v50, v51
	global_store_dword v[48:49], v50, off

.Ltail406:
	s_add_i32 s29, s44, 2
	ds_read_b128 v[136:139], v111 offset:16384
	ds_read_b128 v[140:143], v111 offset:18432
	ds_read_b128 v[144:147], v111 offset:20480
	ds_read_b128 v[148:151], v111 offset:22528
	ds_read_b128 v[116:119], v110
	s_add_i32 s44, s44, 4
	ds_read_b128 v[120:123], v110 offset:2048
	s_min_u32 s44, s44, 15
	s_lshl_b32 s92, s44, 7
	ds_read_b128 v[124:127], v110 offset:4096
	ds_read_b128 v[194:197], v113 offset:16384
	ds_read_b128 v[198:201], v113 offset:18432
	ds_read_b128 v[202:205], v113 offset:20480
	ds_read_b128 v[206:209], v113 offset:22528
	v_lshl_add_u64 v[164:165], v[100:101], 0, s[92:93]
	ds_read_b128 v[132:135], v110 offset:6144
	ds_read_b128 v[152:155], v112
	ds_read_b128 v[156:159], v112 offset:2048
	ds_read_b128 v[160:163], v112 offset:4096
	ds_read_b128 v[190:193], v112 offset:6144
	s_waitcnt lgkmcnt(11)
	v_mfma_f32_16x16x32_bf16 v[92:95], v[136:139], v[116:119], v[92:95]
	v_mfma_f32_16x16x32_bf16 v[88:91], v[140:143], v[116:119], v[88:91]
	v_mfma_f32_16x16x32_bf16 v[56:59], v[144:147], v[116:119], v[56:59]
	v_mfma_f32_16x16x32_bf16 v[48:51], v[148:151], v[116:119], v[48:51]
	s_waitcnt vmcnt(7)
	ds_write_b128 v109, v[52:55] offset:32768
	v_add_co_u32_e32 v52, vcc, s11, v164
	s_waitcnt lgkmcnt(11)
	v_mfma_f32_16x16x32_bf16 v[44:47], v[136:139], v[120:123], v[44:47]
	v_addc_co_u32_e32 v53, vcc, 0, v165, vcc
	v_mfma_f32_16x16x32_bf16 v[40:43], v[140:143], v[120:123], v[40:43]
	v_mfma_f32_16x16x32_bf16 v[36:39], v[144:147], v[120:123], v[36:39]
	v_mfma_f32_16x16x32_bf16 v[32:35], v[148:151], v[120:123], v[32:35]
	v_add_co_u32_e32 v52, vcc, s33, v164
	s_waitcnt vmcnt(6)
	ds_write_b128 v109, v[60:63] offset:36864
	s_nop 0
	v_addc_co_u32_e32 v53, vcc, 0, v165, vcc
	s_waitcnt lgkmcnt(11)
	v_mfma_f32_16x16x32_bf16 v[28:31], v[136:139], v[124:127], v[28:31]
	v_mfma_f32_16x16x32_bf16 v[24:27], v[140:143], v[124:127], v[24:27]
	v_mfma_f32_16x16x32_bf16 v[20:23], v[144:147], v[124:127], v[20:23]
	v_mfma_f32_16x16x32_bf16 v[16:19], v[148:151], v[124:127], v[16:19]
	v_add_co_u32_e32 v52, vcc, s59, v164
	s_waitcnt vmcnt(5)
	ds_write_b128 v109, v[64:67] offset:40960
	s_nop 0
	v_addc_co_u32_e32 v53, vcc, 0, v165, vcc
	v_lshl_add_u64 v[64:65], v[102:103], 0, s[92:93]
	v_add_co_u32_e32 v66, vcc, s11, v64
	s_waitcnt lgkmcnt(7)
	v_mfma_f32_16x16x32_bf16 v[12:15], v[136:139], v[132:135], v[12:15]
	v_addc_co_u32_e32 v67, vcc, 0, v65, vcc
	v_mfma_f32_16x16x32_bf16 v[8:11], v[140:143], v[132:135], v[8:11]
	v_mfma_f32_16x16x32_bf16 v[4:7], v[144:147], v[132:135], v[4:7]
	v_mfma_f32_16x16x32_bf16 v[0:3], v[148:151], v[132:135], v[0:3]
	s_waitcnt vmcnt(4)
	ds_write_b128 v109, v[72:75] offset:45056
	s_waitcnt lgkmcnt(7)
	v_mfma_f32_16x16x32_bf16 v[52:55], v[194:197], v[152:155], v[92:95]
	v_mfma_f32_16x16x32_bf16 v[60:63], v[198:201], v[152:155], v[88:91]
	v_mfma_f32_16x16x32_bf16 v[56:59], v[202:205], v[152:155], v[56:59]
	v_mfma_f32_16x16x32_bf16 v[48:51], v[206:209], v[152:155], v[48:51]
	s_waitcnt vmcnt(3)
	ds_write_b128 v109, v[68:71] offset:49152
	s_waitcnt lgkmcnt(7)
	v_mfma_f32_16x16x32_bf16 v[44:47], v[194:197], v[156:159], v[44:47]
	v_mfma_f32_16x16x32_bf16 v[40:43], v[198:201], v[156:159], v[40:43]
	v_mfma_f32_16x16x32_bf16 v[36:39], v[202:205], v[156:159], v[36:39]
	v_mfma_f32_16x16x32_bf16 v[32:35], v[206:209], v[156:159], v[32:35]
	v_add_co_u32_e32 v66, vcc, s33, v64
	s_waitcnt vmcnt(2)
	ds_write_b128 v109, v[76:79] offset:53248
	v_addc_co_u32_e32 v67, vcc, 0, v65, vcc
	v_add_co_u32_e32 v64, vcc, s59, v64
	s_waitcnt lgkmcnt(7)
	v_mfma_f32_16x16x32_bf16 v[28:31], v[194:197], v[160:163], v[28:31]
	v_addc_co_u32_e32 v65, vcc, 0, v65, vcc
	v_mfma_f32_16x16x32_bf16 v[24:27], v[198:201], v[160:163], v[24:27]
	v_mfma_f32_16x16x32_bf16 v[20:23], v[202:205], v[160:163], v[20:23]
	v_mfma_f32_16x16x32_bf16 v[16:19], v[206:209], v[160:163], v[16:19]
	s_waitcnt vmcnt(1)
	ds_write_b128 v109, v[80:83] offset:57344
	s_waitcnt lgkmcnt(7)
	v_mfma_f32_16x16x32_bf16 v[12:15], v[194:197], v[190:193], v[12:15]
	v_mfma_f32_16x16x32_bf16 v[8:11], v[198:201], v[190:193], v[8:11]
	v_mfma_f32_16x16x32_bf16 v[4:7], v[202:205], v[190:193], v[4:7]
	v_mfma_f32_16x16x32_bf16 v[0:3], v[206:209], v[190:193], v[0:3]
	s_waitcnt vmcnt(0)
	ds_write_b128 v109, v[84:87] offset:61440
	s_waitcnt lgkmcnt(0)
	s_barrier
	ds_read_b128 v[84:87], v111 offset:51200
	ds_read_b128 v[80:83], v111 offset:49152
	ds_read_b128 v[88:91], v111 offset:53248
	ds_read_b128 v[92:95], v111 offset:55296
	ds_read_b128 v[64:67], v110 offset:32768
	s_min_u32 s44, s29, 12
	s_lshl_b32 s92, s44, 7
	ds_read_b128 v[68:71], v110 offset:34816
	v_lshl_add_u64 v[164:165], v[100:101], 0, s[92:93]
	ds_read_b128 v[72:75], v110 offset:36864
	ds_read_b128 v[76:79], v110 offset:38912
	ds_read_b128 v[152:155], v112 offset:32768
	ds_read_b128 v[156:159], v112 offset:34816
	ds_read_b128 v[160:163], v112 offset:36864
	ds_read_b128 v[190:193], v112 offset:38912
	ds_read_b128 v[194:197], v113 offset:49152
	ds_read_b128 v[198:201], v113 offset:51200
	ds_read_b128 v[202:205], v113 offset:53248
	ds_read_b128 v[206:209], v113 offset:55296
	s_waitcnt lgkmcnt(11)
	v_mfma_f32_16x16x32_bf16 v[214:217], v[84:87], v[64:67], v[60:63]
	v_mfma_f32_16x16x32_bf16 v[210:213], v[80:83], v[64:67], v[52:55]
	s_nop 1
	v_add_co_u32_e32 v60, vcc, s11, v164
	s_nop 1
	v_addc_co_u32_e32 v61, vcc, 0, v165, vcc
	v_mfma_f32_16x16x32_bf16 v[56:59], v[88:91], v[64:67], v[56:59]
	v_mfma_f32_16x16x32_bf16 v[48:51], v[92:95], v[64:67], v[48:51]
	v_add_co_u32_e32 v64, vcc, s33, v164
	s_nop 0
	s_nop 0
	v_addc_co_u32_e32 v65, vcc, 0, v165, vcc
	s_waitcnt lgkmcnt(10)
	v_mfma_f32_16x16x32_bf16 v[44:47], v[80:83], v[68:71], v[44:47]
	v_mfma_f32_16x16x32_bf16 v[40:43], v[84:87], v[68:71], v[40:43]
	v_mfma_f32_16x16x32_bf16 v[36:39], v[88:91], v[68:71], v[36:39]
	v_mfma_f32_16x16x32_bf16 v[32:35], v[92:95], v[68:71], v[32:35]
	v_add_co_u32_e32 v68, vcc, s59, v164
	s_waitcnt lgkmcnt(9)
	v_mfma_f32_16x16x32_bf16 v[28:31], v[80:83], v[72:75], v[28:31]
	v_addc_co_u32_e32 v69, vcc, 0, v165, vcc
	v_mfma_f32_16x16x32_bf16 v[24:27], v[84:87], v[72:75], v[24:27]
	v_mfma_f32_16x16x32_bf16 v[20:23], v[88:91], v[72:75], v[20:23]
	v_mfma_f32_16x16x32_bf16 v[16:19], v[92:95], v[72:75], v[16:19]
	s_waitcnt lgkmcnt(8)
	v_mfma_f32_16x16x32_bf16 v[8:11], v[84:87], v[76:79], v[8:11]
	v_lshl_add_u64 v[84:85], v[102:103], 0, s[92:93]
	v_mfma_f32_16x16x32_bf16 v[12:15], v[80:83], v[76:79], v[12:15]
	v_mfma_f32_16x16x32_bf16 v[4:7], v[88:91], v[76:79], v[4:7]
	v_mfma_f32_16x16x32_bf16 v[0:3], v[92:95], v[76:79], v[0:3]
	v_add_co_u32_e32 v76, vcc, s11, v84
	s_nop 0
	s_nop 0
	v_addc_co_u32_e32 v77, vcc, 0, v85, vcc
	v_add_co_u32_e32 v80, vcc, s33, v84
	s_nop 1
	v_addc_co_u32_e32 v81, vcc, 0, v85, vcc
	s_waitcnt lgkmcnt(3)
	v_mfma_f32_16x16x32_bf16 v[92:95], v[194:197], v[152:155], v[210:213]
	s_waitcnt lgkmcnt(2)
	v_mfma_f32_16x16x32_bf16 v[88:91], v[198:201], v[152:155], v[214:217]
	s_waitcnt lgkmcnt(1)
	v_mfma_f32_16x16x32_bf16 v[56:59], v[202:205], v[152:155], v[56:59]
	s_waitcnt lgkmcnt(0)
	v_mfma_f32_16x16x32_bf16 v[48:51], v[206:209], v[152:155], v[48:51]
	v_add_co_u32_e32 v84, vcc, s59, v84
	s_nop 1
	v_addc_co_u32_e32 v85, vcc, 0, v85, vcc
	v_mfma_f32_16x16x32_bf16 v[44:47], v[194:197], v[156:159], v[44:47]
	v_mfma_f32_16x16x32_bf16 v[40:43], v[198:201], v[156:159], v[40:43]
	v_mfma_f32_16x16x32_bf16 v[36:39], v[202:205], v[156:159], v[36:39]
	v_mfma_f32_16x16x32_bf16 v[32:35], v[206:209], v[156:159], v[32:35]
	v_mfma_f32_16x16x32_bf16 v[28:31], v[194:197], v[160:163], v[28:31]
	v_mfma_f32_16x16x32_bf16 v[24:27], v[198:201], v[160:163], v[24:27]
	v_mfma_f32_16x16x32_bf16 v[20:23], v[202:205], v[160:163], v[20:23]
	v_mfma_f32_16x16x32_bf16 v[16:19], v[206:209], v[160:163], v[16:19]
	v_mfma_f32_16x16x32_bf16 v[12:15], v[194:197], v[190:193], v[12:15]
	v_mfma_f32_16x16x32_bf16 v[8:11], v[198:201], v[190:193], v[8:11]
	v_mfma_f32_16x16x32_bf16 v[4:7], v[202:205], v[190:193], v[4:7]
	v_mfma_f32_16x16x32_bf16 v[0:3], v[206:209], v[190:193], v[0:3]
	s_mov_b32 s44, s29
	s_waitcnt lgkmcnt(0)
	s_barrier
	s_waitcnt vmcnt(5)
	v_add_u32_e32 v64, s24, v108
	v_add_u32_e32 v52, 0xffffe000, v64
	v_or_b32_e32 v62, v64, v107
	v_lshrrev_b32_e32 v52, 10, v52
	s_movk_i32 s16, 0x1800
	v_mad_u32_u24 v52, v52, s16, s16
	v_cmp_lt_i32_e32 vcc, s13, v62
	v_or_b32_e32 v65, s25, v114
	v_or_b32_e32 v54, v65, v115
	v_cndmask_b32_e32 v52, 0, v52, vcc
	v_ashrrev_i32_e32 v53, 31, v52
	s_waitcnt vmcnt(4)
	v_lshlrev_b64 v[74:75], 2, v[52:53]
	v_ashrrev_i32_e32 v55, 31, v54
	v_ashrrev_i32_e32 v63, 31, v62
	v_lshl_add_u64 v[52:53], s[40:41], 0, v[74:75]
	v_lshlrev_b64 v[60:61], 2, v[54:55]
	v_readlane_b32 s16, v250, 15
	s_waitcnt vmcnt(1)
	v_lshl_add_u64 v[82:83], v[52:53], 0, v[60:61]
	v_lshlrev_b64 v[52:53], 12, v[62:63]
	v_readlane_b32 s17, v250, 16
	v_lshl_add_u64 v[74:75], s[42:43], 0, v[74:75]
	s_waitcnt vmcnt(0)
	v_lshl_add_u64 v[86:87], v[74:75], 0, v[60:61]
	v_lshl_add_u64 v[52:53], s[16:17], 0, v[52:53]
	v_lshl_add_u64 v[84:85], v[52:53], 0, v[60:61]
	global_load_dwordx4 v[66:69], v[82:83], off
	global_load_dwordx4 v[70:73], v[84:85], off
	v_lshl_add_u64 v[52:53], s[0:1], 0, v[60:61]
	v_readlane_b32 s16, v250, 21
	v_lshlrev_b64 v[78:79], 11, v[62:63]
	v_readlane_b32 s17, v250, 22
	s_waitcnt vmcnt(0)
	v_pk_fma_f32 v[68:69], v[94:95], v[68:69], v[72:73]
	v_pk_fma_f32 v[66:67], v[92:93], v[66:67], v[70:71]
	global_store_dwordx4 v[84:85], v[66:69], off
	global_load_dwordx4 v[70:73], v[52:53], off
	global_load_dwordx4 v[74:77], v[86:87], off
	v_lshl_add_u64 v[78:79], s[16:17], 0, v[78:79]
	v_lshl_add_u64 v[92:93], v[54:55], 1, v[78:79]
	s_mov_b32 s16, 0xa000
	s_waitcnt vmcnt(1)
	v_pk_mul_f32 v[72:73], v[68:69], v[72:73]
	v_pk_mul_f32 v[70:71], v[66:67], v[70:71]
	s_waitcnt vmcnt(0)
	v_pk_add_f32 v[76:77], v[76:77], 1.0 op_sel_hi:[1,0]
	v_pk_add_f32 v[74:75], v[74:75], 1.0 op_sel_hi:[1,0]
	v_pk_mul_f32 v[72:73], v[72:73], v[76:77]
	v_pk_mul_f32 v[70:71], v[70:71], v[74:75]
	v_and_b32_sdwa v77, v71, v170 dst_sel:DWORD dst_unused:UNUSED_PAD src0_sel:WORD_1 src1_sel:DWORD
	v_and_b32_sdwa v75, v70, v170 dst_sel:DWORD dst_unused:UNUSED_PAD src0_sel:WORD_1 src1_sel:DWORD
	v_add3_u32 v71, v71, v77, s56
	v_add3_u32 v70, v70, v75, s56
	v_and_b32_e32 v74, 0xffff0000, v71
	v_cvt_pk_bf16_f32 v71, v72, v73
	v_or_b32_sdwa v70, v74, v70 dst_sel:DWORD dst_unused:UNUSED_PAD src0_sel:DWORD src1_sel:WORD_1
	global_store_dwordx2 v[92:93], v[70:71], off
	global_load_dwordx4 v[70:73], v[82:83], off offset:64
	s_nop 0
	global_load_dwordx4 v[74:77], v[84:85], off offset:64
	s_waitcnt vmcnt(0)
	v_pk_fma_f32 v[72:73], v[90:91], v[72:73], v[76:77]
	v_pk_fma_f32 v[70:71], v[88:89], v[70:71], v[74:75]
	global_store_dwordx4 v[84:85], v[70:73], off offset:64
	global_load_dwordx4 v[74:77], v[52:53], off offset:64
	global_load_dwordx4 v[78:81], v[86:87], off offset:64
	s_waitcnt vmcnt(1)
	v_pk_mul_f32 v[76:77], v[72:73], v[76:77]
	v_pk_mul_f32 v[74:75], v[70:71], v[74:75]
	s_waitcnt vmcnt(0)
	v_pk_add_f32 v[80:81], v[80:81], 1.0 op_sel_hi:[1,0]
	v_pk_add_f32 v[78:79], v[78:79], 1.0 op_sel_hi:[1,0]
	v_pk_mul_f32 v[76:77], v[76:77], v[80:81]
	v_pk_mul_f32 v[74:75], v[74:75], v[78:79]
	v_and_b32_sdwa v81, v75, v170 dst_sel:DWORD dst_unused:UNUSED_PAD src0_sel:WORD_1 src1_sel:DWORD
	v_and_b32_sdwa v79, v74, v170 dst_sel:DWORD dst_unused:UNUSED_PAD src0_sel:WORD_1 src1_sel:DWORD
	v_add3_u32 v75, v75, v81, s56
	v_add3_u32 v74, v74, v79, s56
	v_and_b32_e32 v78, 0xffff0000, v75
	v_cvt_pk_bf16_f32 v75, v76, v77
	v_or_b32_sdwa v74, v78, v74 dst_sel:DWORD dst_unused:UNUSED_PAD src0_sel:DWORD src1_sel:WORD_1
	global_store_dwordx2 v[92:93], v[74:75], off offset:32
	global_load_dwordx4 v[74:77], v[82:83], off offset:128
	s_nop 0
	global_load_dwordx4 v[78:81], v[84:85], off offset:128
	s_waitcnt vmcnt(0)
	v_pk_fma_f32 v[58:59], v[58:59], v[76:77], v[80:81]
	v_pk_fma_f32 v[56:57], v[56:57], v[74:75], v[78:79]
	global_store_dwordx4 v[84:85], v[56:59], off offset:128
	global_load_dwordx4 v[74:77], v[52:53], off offset:128
	global_load_dwordx4 v[78:81], v[86:87], off offset:128
	s_waitcnt vmcnt(1)
	v_pk_mul_f32 v[76:77], v[58:59], v[76:77]
	v_pk_mul_f32 v[74:75], v[56:57], v[74:75]
	s_waitcnt vmcnt(0)
	v_pk_add_f32 v[80:81], v[80:81], 1.0 op_sel_hi:[1,0]
	v_pk_add_f32 v[78:79], v[78:79], 1.0 op_sel_hi:[1,0]
	v_pk_mul_f32 v[76:77], v[76:77], v[80:81]
	v_pk_mul_f32 v[74:75], v[74:75], v[78:79]
	v_and_b32_sdwa v81, v75, v170 dst_sel:DWORD dst_unused:UNUSED_PAD src0_sel:WORD_1 src1_sel:DWORD
	v_and_b32_sdwa v79, v74, v170 dst_sel:DWORD dst_unused:UNUSED_PAD src0_sel:WORD_1 src1_sel:DWORD
	v_add3_u32 v75, v75, v81, s56
	v_add3_u32 v74, v74, v79, s56
	v_and_b32_e32 v78, 0xffff0000, v75
	v_cvt_pk_bf16_f32 v75, v76, v77
	v_or_b32_sdwa v74, v78, v74 dst_sel:DWORD dst_unused:UNUSED_PAD src0_sel:DWORD src1_sel:WORD_1
	global_store_dwordx2 v[92:93], v[74:75], off offset:64
	global_load_dwordx4 v[74:77], v[82:83], off offset:192
	s_nop 0
	global_load_dwordx4 v[78:81], v[84:85], off offset:192
	s_waitcnt vmcnt(0)
	v_pk_fma_f32 v[76:77], v[50:51], v[76:77], v[80:81]
	v_pk_fma_f32 v[74:75], v[48:49], v[74:75], v[78:79]
	global_store_dwordx4 v[84:85], v[74:77], off offset:192
	global_load_dwordx4 v[78:81], v[52:53], off offset:192
	s_nop 0
	global_load_dwordx4 v[82:85], v[86:87], off offset:192
	v_mul_f32_e32 v48, v67, v67
	v_mul_f32_e32 v49, v71, v71
	v_fmac_f32_e32 v48, v66, v66
	v_fmac_f32_e32 v49, v70, v70
	v_fmac_f32_e32 v48, v68, v68
	v_fmac_f32_e32 v49, v72, v72
	v_fmac_f32_e32 v48, v69, v69
	v_fmac_f32_e32 v49, v73, v73
	v_add_f32_e32 v48, v48, v49
	v_mul_f32_e32 v49, v57, v57
	v_fmac_f32_e32 v49, v56, v56
	v_fmac_f32_e32 v49, v58, v58
	v_fmac_f32_e32 v49, v59, v59
	v_add_f32_e32 v48, v48, v49
	v_mul_f32_e32 v49, v75, v75
	v_fmac_f32_e32 v49, v74, v74
	v_fmac_f32_e32 v49, v76, v76
	v_fmac_f32_e32 v49, v77, v77
	v_add_f32_e32 v50, v48, v49
	ds_bpermute_b32 v51, v105, v50
	v_lshrrev_b32_e32 v48, 6, v65
	v_mul_lo_u32 v48, v48, s16
	v_ashrrev_i32_e32 v49, 31, v48
	v_lshl_add_u64 v[48:49], s[38:39], 0, v[48:49]
	s_waitcnt lgkmcnt(0)
	v_add_f32_e32 v50, v50, v51
	ds_bpermute_b32 v51, v104, v50
	v_lshl_add_u64 v[48:49], v[62:63], 2, v[48:49]
	s_waitcnt vmcnt(1)
	v_pk_mul_f32 v[56:57], v[76:77], v[80:81]
	v_pk_mul_f32 v[58:59], v[74:75], v[78:79]
	s_waitcnt vmcnt(0)
	v_pk_add_f32 v[66:67], v[84:85], 1.0 op_sel_hi:[1,0]
	v_pk_add_f32 v[68:69], v[82:83], 1.0 op_sel_hi:[1,0]
	v_pk_mul_f32 v[56:57], v[56:57], v[66:67]
	v_pk_mul_f32 v[58:59], v[58:59], v[68:69]
	v_cvt_pk_bf16_f32 v57, v56, v57
	v_cvt_pk_bf16_f32 v56, v58, v59
	global_store_dwordx2 v[92:93], v[56:57], off offset:96
	s_and_saveexec_b64 s[24:25], s[36:37]
	s_cbranch_execz .LBB0_409
	s_waitcnt lgkmcnt(0)
	v_add_f32_e32 v50, v50, v51
	global_store_dword v[48:49], v50, off

.Ltail419:
	s_add_i32 s2, s3, 2
	v_add_u32_e32 v127, v89, v90
	ds_read_b128 v[100:103], v127 offset:16384
	ds_read_b128 v[106:109], v127 offset:18432
	ds_read_b128 v[110:113], v127 offset:20480
	ds_read_b128 v[114:117], v127 offset:22528
	v_add_u32_e32 v126, v88, v90
	ds_read_b128 v[92:95], v126
	ds_read_b128 v[96:99], v126 offset:2048
	s_add_i32 s3, s3, 4
	s_min_u32 s3, s3, 15
	v_add_u32_e32 v128, v88, v91
	v_add_u32_e32 v130, v89, v91
	s_lshl_b32 s92, s3, 7
	ds_read_b128 v[118:121], v130 offset:18432
	ds_read_b128 v[122:125], v130 offset:20480
	ds_read_b128 v[132:135], v130 offset:22528
	s_waitcnt lgkmcnt(4)
	v_mfma_f32_16x16x32_bf16 v[76:79], v[100:103], v[92:95], v[76:79]
	v_lshl_add_u64 v[44:45], v[80:81], 0, s[92:93]
	v_add_co_u32_e32 v46, vcc, s11, v44
	v_mfma_f32_16x16x32_bf16 v[68:71], v[106:109], v[92:95], v[68:71]
	s_nop 0
	v_addc_co_u32_e32 v47, vcc, 0, v45, vcc
	v_mfma_f32_16x16x32_bf16 v[52:55], v[110:113], v[92:95], v[52:55]
	v_mfma_f32_16x16x32_bf16 v[40:43], v[114:117], v[92:95], v[40:43]
	s_waitcnt lgkmcnt(3)
	v_mfma_f32_16x16x32_bf16 v[92:95], v[100:103], v[96:99], v[36:39]
	s_nop 2
	ds_read_b128 v[36:39], v128
	v_mfma_f32_16x16x32_bf16 v[100:103], v[106:109], v[96:99], v[8:11]
	v_mfma_f32_16x16x32_bf16 v[106:109], v[110:113], v[96:99], v[4:7]
	ds_read_b128 v[110:113], v128 offset:2048
	v_mfma_f32_16x16x32_bf16 v[96:99], v[114:117], v[96:99], v[0:3]
	ds_read_b128 v[114:117], v130 offset:16384
	s_waitcnt vmcnt(0)
	ds_write_b128 v87, v[12:15] offset:53248
	v_add_co_u32_e32 v46, vcc, s33, v44
	s_waitcnt vmcnt(1)
	ds_write_b128 v87, v[16:19] offset:49152
	s_nop 0
	v_addc_co_u32_e32 v47, vcc, 0, v45, vcc
	v_add_co_u32_e32 v44, vcc, s59, v44
	s_nop 0
	s_nop 0
	v_addc_co_u32_e32 v45, vcc, 0, v45, vcc
	s_waitcnt vmcnt(2)
	ds_write_b128 v87, v[20:23] offset:45056
	v_lshl_add_u64 v[44:45], v[82:83], 0, s[92:93]
	s_waitcnt vmcnt(5)
	ds_write_b128 v87, v[28:31] offset:32768
	s_waitcnt lgkmcnt(4)
	v_mfma_f32_16x16x32_bf16 v[0:3], v[114:117], v[36:39], v[76:79]
	v_mfma_f32_16x16x32_bf16 v[4:7], v[118:121], v[36:39], v[68:71]
	v_add_co_u32_e32 v44, vcc, s11, v44
	s_waitcnt vmcnt(4)
	ds_write_b128 v87, v[32:35] offset:36864
	s_nop 0
	v_addc_co_u32_e32 v45, vcc, 0, v45, vcc
	v_mfma_f32_16x16x32_bf16 v[8:11], v[122:125], v[36:39], v[52:55]
	v_mfma_f32_16x16x32_bf16 v[36:39], v[132:135], v[36:39], v[40:43]
	s_waitcnt vmcnt(3)
	ds_write_b128 v87, v[24:27] offset:40960
	v_mfma_f32_16x16x32_bf16 v[40:43], v[114:117], v[110:113], v[92:95]
	v_mfma_f32_16x16x32_bf16 v[52:55], v[118:121], v[110:113], v[100:103]
	v_mfma_f32_16x16x32_bf16 v[68:71], v[122:125], v[110:113], v[106:109]
	v_mfma_f32_16x16x32_bf16 v[76:79], v[132:135], v[110:113], v[96:99]
	s_waitcnt lgkmcnt(0)
	s_barrier
	ds_read_b128 v[100:103], v127 offset:49152
	ds_read_b128 v[106:109], v127 offset:51200
	ds_read_b128 v[110:113], v127 offset:53248
	ds_read_b128 v[114:117], v127 offset:55296
	ds_read_b128 v[92:95], v126 offset:32768
	ds_read_b128 v[96:99], v126 offset:34816
	s_min_u32 s3, s2, 12
	s_lshl_b32 s92, s3, 7
	ds_read_b128 v[118:121], v130 offset:51200
	ds_read_b128 v[122:125], v130 offset:53248
	ds_read_b128 v[132:135], v130 offset:55296
	s_waitcnt lgkmcnt(4)
	v_mfma_f32_16x16x32_bf16 v[0:3], v[100:103], v[92:95], v[0:3]
	v_lshl_add_u64 v[12:13], v[80:81], 0, s[92:93]
	v_add_co_u32_e32 v14, vcc, s11, v12
	v_mfma_f32_16x16x32_bf16 v[4:7], v[106:109], v[92:95], v[4:7]
	s_nop 0
	v_addc_co_u32_e32 v15, vcc, 0, v13, vcc
	v_mfma_f32_16x16x32_bf16 v[8:11], v[110:113], v[92:95], v[8:11]
	v_mfma_f32_16x16x32_bf16 v[36:39], v[114:117], v[92:95], v[36:39]
	s_waitcnt lgkmcnt(3)
	v_mfma_f32_16x16x32_bf16 v[92:95], v[100:103], v[96:99], v[40:43]
	s_nop 2
	ds_read_b128 v[40:43], v128 offset:32768
	v_mfma_f32_16x16x32_bf16 v[100:103], v[106:109], v[96:99], v[52:55]
	v_mfma_f32_16x16x32_bf16 v[106:109], v[110:113], v[96:99], v[68:71]
	ds_read_b128 v[110:113], v128 offset:34816
	v_mfma_f32_16x16x32_bf16 v[96:99], v[114:117], v[96:99], v[76:79]
	ds_read_b128 v[114:117], v130 offset:49152
	v_add_co_u32_e32 v14, vcc, s33, v12
	s_nop 0
	s_nop 0
	v_addc_co_u32_e32 v15, vcc, 0, v13, vcc
	v_add_co_u32_e32 v12, vcc, s59, v12
	s_nop 0
	s_nop 0
	v_addc_co_u32_e32 v13, vcc, 0, v13, vcc
	v_lshl_add_u64 v[12:13], v[82:83], 0, s[92:93]
	s_waitcnt lgkmcnt(0)
	v_mfma_f32_16x16x32_bf16 v[76:79], v[114:117], v[40:43], v[0:3]
	v_mfma_f32_16x16x32_bf16 v[68:71], v[118:121], v[40:43], v[4:7]
	v_add_co_u32_e32 v12, vcc, s11, v12
	s_nop 0
	s_nop 0
	v_addc_co_u32_e32 v13, vcc, 0, v13, vcc
	v_mfma_f32_16x16x32_bf16 v[52:55], v[122:125], v[40:43], v[8:11]
	v_mfma_f32_16x16x32_bf16 v[40:43], v[132:135], v[40:43], v[36:39]
	v_mfma_f32_16x16x32_bf16 v[36:39], v[114:117], v[110:113], v[92:95]
	v_mfma_f32_16x16x32_bf16 v[8:11], v[118:121], v[110:113], v[100:103]
	v_mfma_f32_16x16x32_bf16 v[4:7], v[122:125], v[110:113], v[106:109]
	v_mfma_f32_16x16x32_bf16 v[0:3], v[132:135], v[110:113], v[96:99]
	s_mov_b32 s3, s2
	s_waitcnt lgkmcnt(0)
	s_barrier
	v_readlane_b32 s2, v251, 18
	s_waitcnt vmcnt(1)
	s_nop 0
	v_add_u32_e32 v18, s2, v86
	v_readlane_b32 s2, v251, 19
	s_waitcnt vmcnt(0)
	v_add_u32_e32 v13, 0xffffe000, v18
	v_or_b32_e32 v12, v18, v85
	v_lshl_or_b32 v19, v84, 2, s2
	v_lshrrev_b32_e32 v13, 10, v13
	s_movk_i32 s2, 0x1800
	v_mad_u32_u24 v13, v13, s2, s2
	v_cmp_lt_i32_e32 vcc, s13, v12
	v_lshlrev_b32_e32 v128, 2, v19
	v_readlane_b32 s2, v250, 15
	v_cndmask_b32_e32 v14, 0, v13, vcc
	v_ashrrev_i32_e32 v15, 31, v14
	v_lshlrev_b64 v[24:25], 2, v[14:15]
	v_ashrrev_i32_e32 v13, 31, v12
	v_lshl_add_u64 v[14:15], s[40:41], 0, v[24:25]
	v_lshl_add_u64 v[48:49], v[14:15], 0, v[128:129]
	v_lshlrev_b64 v[14:15], 12, v[12:13]
	v_readlane_b32 s3, v250, 16
	v_lshl_add_u64 v[28:29], s[42:43], 0, v[24:25]
	v_lshlrev_b64 v[32:33], 11, v[12:13]
	v_lshl_add_u64 v[14:15], s[2:3], 0, v[14:15]
	v_lshl_add_u64 v[50:51], v[14:15], 0, v[128:129]
	global_load_dwordx4 v[72:75], v[48:49], off
	global_load_dwordx4 v[80:83], v[48:49], off offset:64
	global_load_dwordx4 v[88:91], v[48:49], off offset:128
	global_load_dwordx4 v[136:139], v[48:49], off offset:192
	global_load_dwordx4 v[194:197], v[50:51], off
	global_load_dwordx4 v[198:201], v[50:51], off offset:64
	global_load_dwordx4 v[202:205], v[50:51], off offset:128
	global_load_dwordx4 v[206:209], v[50:51], off offset:192
	v_add_co_u32_e32 v58, vcc, 0x10000, v50
	s_nop 1
	v_addc_co_u32_e32 v59, vcc, 0, v51, vcc
	global_load_dwordx4 v[210:213], v[58:59], off
	global_load_dwordx4 v[214:217], v[58:59], off offset:64
	global_load_dwordx4 v[218:221], v[58:59], off offset:128
	global_load_dwordx4 v[222:225], v[58:59], off offset:192
	v_readlane_b32 s2, v250, 21
	v_readlane_b32 s3, v250, 22
	v_cmp_eq_u32_e32 vcc, 0, v84
	s_waitcnt vmcnt(4)
	v_pk_fma_f32 v[22:23], v[78:79], v[74:75], v[196:197]
	v_pk_fma_f32 v[20:21], v[76:77], v[72:73], v[194:195]
	global_store_dwordx4 v[50:51], v[20:23], off
	v_lshl_add_u64 v[14:15], v[28:29], 0, v[128:129]
	global_load_dwordx4 v[140:143], v128, s[0:1]
	global_load_dwordx4 v[144:147], v128, s[0:1] offset:64
	global_load_dwordx4 v[148:151], v128, s[0:1] offset:128
	global_load_dwordx4 v[152:155], v128, s[0:1] offset:192
	global_load_dwordx4 v[156:159], v[14:15], off
	global_load_dwordx4 v[160:163], v[14:15], off offset:64
	global_load_dwordx4 v[180:183], v[14:15], off offset:128
	global_load_dwordx4 v[190:193], v[14:15], off offset:192
	v_lshlrev_b32_e32 v16, 1, v19
	v_mov_b32_e32 v17, v129
	v_lshl_add_u64 v[32:33], s[2:3], 0, v[32:33]
	v_lshl_add_u64 v[56:57], v[32:33], 0, v[16:17]
	s_waitcnt vmcnt(0)
	v_pk_mul_f32 v[26:27], v[22:23], v[142:143]
	v_pk_mul_f32 v[24:25], v[20:21], v[140:141]
	s_waitcnt vmcnt(0)
	v_pk_add_f32 v[30:31], v[158:159], 1.0 op_sel_hi:[1,0]
	v_pk_add_f32 v[28:29], v[156:157], 1.0 op_sel_hi:[1,0]
	v_pk_mul_f32 v[26:27], v[26:27], v[30:31]
	v_pk_mul_f32 v[24:25], v[24:25], v[28:29]
	v_and_b32_sdwa v19, v26, v170 dst_sel:DWORD dst_unused:UNUSED_PAD src0_sel:WORD_1 src1_sel:DWORD
	v_and_b32_sdwa v29, v27, v170 dst_sel:DWORD dst_unused:UNUSED_PAD src0_sel:WORD_1 src1_sel:DWORD
	v_and_b32_sdwa v30, v25, v170 dst_sel:DWORD dst_unused:UNUSED_PAD src0_sel:WORD_1 src1_sel:DWORD
	v_and_b32_sdwa v28, v24, v170 dst_sel:DWORD dst_unused:UNUSED_PAD src0_sel:WORD_1 src1_sel:DWORD
	v_add3_u32 v19, v26, v19, s56
	v_add3_u32 v26, v27, v29, s56
	v_add3_u32 v25, v25, v30, s56
	v_add3_u32 v24, v24, v28, s56
	v_and_b32_e32 v26, 0xffff0000, v26
	v_and_b32_e32 v27, 0xffff0000, v25
	v_or_b32_sdwa v25, v26, v19 dst_sel:DWORD dst_unused:UNUSED_PAD src0_sel:DWORD src1_sel:WORD_1
	v_or_b32_sdwa v24, v27, v24 dst_sel:DWORD dst_unused:UNUSED_PAD src0_sel:DWORD src1_sel:WORD_1
	global_store_dwordx2 v[56:57], v[24:25], off
	s_nop 0
	s_waitcnt vmcnt(0)
	v_pk_fma_f32 v[26:27], v[70:71], v[82:83], v[200:201]
	v_pk_fma_f32 v[24:25], v[68:69], v[80:81], v[198:199]
	global_store_dwordx4 v[50:51], v[24:27], off offset:64
	v_pk_mul_f32 v[30:31], v[26:27], v[146:147]
	v_pk_mul_f32 v[28:29], v[24:25], v[144:145]
	v_pk_add_f32 v[34:35], v[162:163], 1.0 op_sel_hi:[1,0]
	v_pk_add_f32 v[32:33], v[160:161], 1.0 op_sel_hi:[1,0]
	v_pk_mul_f32 v[30:31], v[30:31], v[34:35]
	v_pk_mul_f32 v[28:29], v[28:29], v[32:33]
	v_and_b32_sdwa v19, v30, v170 dst_sel:DWORD dst_unused:UNUSED_PAD src0_sel:WORD_1 src1_sel:DWORD
	v_and_b32_sdwa v33, v31, v170 dst_sel:DWORD dst_unused:UNUSED_PAD src0_sel:WORD_1 src1_sel:DWORD
	v_and_b32_sdwa v34, v29, v170 dst_sel:DWORD dst_unused:UNUSED_PAD src0_sel:WORD_1 src1_sel:DWORD
	v_and_b32_sdwa v32, v28, v170 dst_sel:DWORD dst_unused:UNUSED_PAD src0_sel:WORD_1 src1_sel:DWORD
	v_add3_u32 v19, v30, v19, s56
	v_add3_u32 v30, v31, v33, s56
	v_add3_u32 v29, v29, v34, s56
	v_add3_u32 v28, v28, v32, s56
	v_and_b32_e32 v30, 0xffff0000, v30
	v_and_b32_e32 v31, 0xffff0000, v29
	v_or_b32_sdwa v29, v30, v19 dst_sel:DWORD dst_unused:UNUSED_PAD src0_sel:DWORD src1_sel:WORD_1
	v_or_b32_sdwa v28, v31, v28 dst_sel:DWORD dst_unused:UNUSED_PAD src0_sel:DWORD src1_sel:WORD_1
	global_store_dwordx2 v[56:57], v[28:29], off offset:32
	s_nop 0
	v_pk_fma_f32 v[30:31], v[54:55], v[90:91], v[204:205]
	v_pk_fma_f32 v[28:29], v[52:53], v[88:89], v[202:203]
	global_store_dwordx4 v[50:51], v[28:31], off offset:128
	v_pk_mul_f32 v[34:35], v[30:31], v[150:151]
	v_pk_mul_f32 v[32:33], v[28:29], v[148:149]
	v_pk_add_f32 v[46:47], v[182:183], 1.0 op_sel_hi:[1,0]
	v_pk_add_f32 v[44:45], v[180:181], 1.0 op_sel_hi:[1,0]
	v_pk_mul_f32 v[34:35], v[34:35], v[46:47]
	v_pk_mul_f32 v[32:33], v[32:33], v[44:45]
	v_and_b32_sdwa v19, v34, v170 dst_sel:DWORD dst_unused:UNUSED_PAD src0_sel:WORD_1 src1_sel:DWORD
	v_and_b32_sdwa v45, v35, v170 dst_sel:DWORD dst_unused:UNUSED_PAD src0_sel:WORD_1 src1_sel:DWORD
	v_and_b32_sdwa v46, v33, v170 dst_sel:DWORD dst_unused:UNUSED_PAD src0_sel:WORD_1 src1_sel:DWORD
	v_and_b32_sdwa v44, v32, v170 dst_sel:DWORD dst_unused:UNUSED_PAD src0_sel:WORD_1 src1_sel:DWORD
	v_add3_u32 v19, v34, v19, s56
	v_add3_u32 v34, v35, v45, s56
	v_add3_u32 v33, v33, v46, s56
	v_add3_u32 v32, v32, v44, s56
	v_and_b32_e32 v34, 0xffff0000, v34
	v_and_b32_e32 v35, 0xffff0000, v33
	v_or_b32_sdwa v33, v34, v19 dst_sel:DWORD dst_unused:UNUSED_PAD src0_sel:DWORD src1_sel:WORD_1
	v_or_b32_sdwa v32, v35, v32 dst_sel:DWORD dst_unused:UNUSED_PAD src0_sel:DWORD src1_sel:WORD_1
	global_store_dwordx2 v[56:57], v[32:33], off offset:64
	s_nop 0
	v_pk_fma_f32 v[34:35], v[42:43], v[138:139], v[208:209]
	v_pk_fma_f32 v[32:33], v[40:41], v[136:137], v[206:207]
	global_store_dwordx4 v[50:51], v[32:35], off offset:192
	v_mul_f32_e32 v14, v21, v21
	v_mul_f32_e32 v15, v25, v25
	v_fmac_f32_e32 v14, v20, v20
	v_fmac_f32_e32 v15, v24, v24
	v_fmac_f32_e32 v14, v22, v22
	v_fmac_f32_e32 v15, v26, v26
	v_fmac_f32_e32 v14, v23, v23
	v_fmac_f32_e32 v15, v27, v27
	v_add_f32_e32 v14, v14, v15
	v_mul_f32_e32 v15, v29, v29
	v_fmac_f32_e32 v15, v28, v28
	v_fmac_f32_e32 v15, v30, v30
	v_fmac_f32_e32 v15, v31, v31
	v_add_f32_e32 v14, v14, v15
	v_mul_f32_e32 v15, v33, v33
	v_fmac_f32_e32 v15, v32, v32
	v_fmac_f32_e32 v15, v34, v34
	v_fmac_f32_e32 v15, v35, v35
	v_add_f32_e32 v14, v14, v15
	ds_bpermute_b32 v15, v105, v14
	s_waitcnt lgkmcnt(0)
	v_add_f32_e32 v14, v14, v15
	ds_bpermute_b32 v15, v104, v14
	v_pk_mul_f32 v[20:21], v[34:35], v[154:155]
	v_pk_mul_f32 v[22:23], v[32:33], v[152:153]
	v_pk_add_f32 v[24:25], v[192:193], 1.0 op_sel_hi:[1,0]
	v_pk_add_f32 v[26:27], v[190:191], 1.0 op_sel_hi:[1,0]
	v_pk_mul_f32 v[20:21], v[20:21], v[24:25]
	v_pk_mul_f32 v[22:23], v[22:23], v[26:27]
	v_and_b32_sdwa v19, v20, v170 dst_sel:DWORD dst_unused:UNUSED_PAD src0_sel:WORD_1 src1_sel:DWORD
	v_and_b32_sdwa v25, v21, v170 dst_sel:DWORD dst_unused:UNUSED_PAD src0_sel:WORD_1 src1_sel:DWORD
	v_and_b32_sdwa v26, v23, v170 dst_sel:DWORD dst_unused:UNUSED_PAD src0_sel:WORD_1 src1_sel:DWORD
	v_and_b32_sdwa v24, v22, v170 dst_sel:DWORD dst_unused:UNUSED_PAD src0_sel:WORD_1 src1_sel:DWORD
	v_add3_u32 v19, v20, v19, s56
	v_add3_u32 v20, v21, v25, s56
	v_add3_u32 v21, v23, v26, s56
	v_add3_u32 v22, v22, v24, s56
	v_and_b32_e32 v20, 0xffff0000, v20
	v_and_b32_e32 v23, 0xffff0000, v21
	v_or_b32_sdwa v21, v20, v19 dst_sel:DWORD dst_unused:UNUSED_PAD src0_sel:DWORD src1_sel:WORD_1
	v_or_b32_sdwa v20, v23, v22 dst_sel:DWORD dst_unused:UNUSED_PAD src0_sel:DWORD src1_sel:WORD_1
	global_store_dwordx2 v[56:57], v[20:21], off offset:96
	s_and_saveexec_b64 s[2:3], vcc
	s_cbranch_execz .LBB0_422
	v_readlane_b32 s16, v253, 20
	s_add_u32 s24, s38, s16
	s_addc_u32 s25, s39, 0
	v_lshl_add_u64 v[20:21], v[12:13], 2, s[24:25]
	s_waitcnt lgkmcnt(0)
	v_add_f32_e32 v13, v14, v15
	global_store_dword v[20:21], v13, off
.LBB0_422:
	s_or_b64 exec, exec, s[2:3]
	v_add_u32_e32 v13, 0xffffe010, v18
	s_waitcnt lgkmcnt(0)
	v_lshl_add_u64 v[14:15], s[0:1], 0, v[128:129]
	v_or_b32_e32 v12, 16, v12
	v_lshrrev_b32_e32 v13, 10, v13
	s_movk_i32 s0, 0x1800
	v_mad_u32_u24 v13, v13, s0, s0
	v_cmp_lt_i32_e64 s[0:1], s13, v12
	s_nop 1
	v_cndmask_b32_e64 v18, 0, v13, s[0:1]
	v_ashrrev_i32_e32 v19, 31, v18
	v_lshlrev_b64 v[34:35], 2, v[18:19]
	v_ashrrev_i32_e32 v13, 31, v12
	v_lshl_add_u64 v[18:19], s[40:41], 0, v[34:35]
	v_readlane_b32 s0, v250, 15
	v_lshl_add_u64 v[20:21], v[18:19], 0, v[128:129]
	v_lshlrev_b64 v[18:19], 12, v[12:13]
	v_readlane_b32 s1, v250, 16
	s_nop 0
	s_nop 0
	v_lshl_add_u64 v[18:19], s[0:1], 0, v[18:19]
	v_lshl_add_u64 v[18:19], v[18:19], 0, v[128:129]
	v_readlane_b32 s0, v250, 21
	v_readlane_b32 s1, v250, 22
	s_waitcnt vmcnt(16)
	v_pk_fma_f32 v[28:29], v[38:39], v[74:75], v[212:213]
	v_pk_fma_f32 v[26:27], v[36:37], v[72:73], v[210:211]
	v_lshl_add_u64 v[22:23], s[42:43], 0, v[34:35]
	global_store_dwordx4 v[18:19], v[26:29], off
	v_lshl_add_u64 v[22:23], v[22:23], 0, v[128:129]
	v_mul_f32_e32 v38, v27, v27
	v_fmac_f32_e32 v38, v26, v26
	v_fmac_f32_e32 v38, v28, v28
	v_fmac_f32_e32 v38, v29, v29
	v_pk_mul_f32 v[24:25], v[28:29], v[142:143]
	v_pk_add_f32 v[28:29], v[158:159], 1.0 op_sel_hi:[1,0]
	v_pk_mul_f32 v[26:27], v[26:27], v[140:141]
	v_pk_add_f32 v[30:31], v[156:157], 1.0 op_sel_hi:[1,0]
	v_pk_mul_f32 v[24:25], v[24:25], v[28:29]
	v_lshlrev_b64 v[28:29], 11, v[12:13]
	v_pk_mul_f32 v[26:27], v[26:27], v[30:31]
	v_lshl_add_u64 v[28:29], s[0:1], 0, v[28:29]
	v_lshl_add_u64 v[16:17], v[28:29], 0, v[16:17]
	v_cvt_pk_bf16_f32 v25, v24, v25
	v_cvt_pk_bf16_f32 v24, v26, v27
	global_store_dwordx2 v[16:17], v[24:25], off
	s_nop 0
	v_pk_fma_f32 v[8:9], v[8:9], v[80:81], v[214:215]
	s_nop 0
	v_mul_f32_e32 v24, v9, v9
	v_pk_fma_f32 v[10:11], v[10:11], v[82:83], v[216:217]
	v_fmac_f32_e32 v24, v8, v8
	v_fmac_f32_e32 v24, v10, v10
	global_store_dwordx4 v[18:19], v[8:11], off offset:64
	v_fmac_f32_e32 v24, v11, v11
	v_add_f32_e32 v32, v38, v24
	v_pk_mul_f32 v[10:11], v[10:11], v[146:147]
	v_pk_mul_f32 v[8:9], v[8:9], v[144:145]
	v_pk_add_f32 v[24:25], v[162:163], 1.0 op_sel_hi:[1,0]
	v_pk_add_f32 v[26:27], v[160:161], 1.0 op_sel_hi:[1,0]
	v_pk_mul_f32 v[10:11], v[10:11], v[24:25]
	v_pk_mul_f32 v[8:9], v[8:9], v[26:27]
	v_and_b32_sdwa v25, v8, v170 dst_sel:DWORD dst_unused:UNUSED_PAD src0_sel:WORD_1 src1_sel:DWORD
	v_add3_u32 v8, v8, v25, s56
	v_and_b32_sdwa v25, v9, v170 dst_sel:DWORD dst_unused:UNUSED_PAD src0_sel:WORD_1 src1_sel:DWORD
	v_add3_u32 v9, v9, v25, s56
	v_and_b32_e32 v24, 0xffff0000, v9
	v_cvt_pk_bf16_f32 v9, v10, v11
	v_or_b32_sdwa v8, v24, v8 dst_sel:DWORD dst_unused:UNUSED_PAD src0_sel:DWORD src1_sel:WORD_1
	global_store_dwordx2 v[16:17], v[8:9], off offset:32
	s_nop 0
	v_pk_fma_f32 v[4:5], v[4:5], v[88:89], v[218:219]
	s_nop 0
	v_mul_f32_e32 v8, v5, v5
	v_pk_fma_f32 v[6:7], v[6:7], v[90:91], v[220:221]
	v_fmac_f32_e32 v8, v4, v4
	v_fmac_f32_e32 v8, v6, v6
	global_store_dwordx4 v[18:19], v[4:7], off offset:128
	v_fmac_f32_e32 v8, v7, v7
	v_add_f32_e32 v28, v32, v8
	v_pk_mul_f32 v[6:7], v[6:7], v[150:151]
	v_pk_mul_f32 v[4:5], v[4:5], v[148:149]
	v_pk_add_f32 v[8:9], v[182:183], 1.0 op_sel_hi:[1,0]
	v_pk_add_f32 v[10:11], v[180:181], 1.0 op_sel_hi:[1,0]
	v_pk_mul_f32 v[6:7], v[6:7], v[8:9]
	v_pk_mul_f32 v[4:5], v[4:5], v[10:11]
	v_and_b32_sdwa v9, v4, v170 dst_sel:DWORD dst_unused:UNUSED_PAD src0_sel:WORD_1 src1_sel:DWORD
	v_add3_u32 v4, v4, v9, s56
	v_and_b32_sdwa v9, v5, v170 dst_sel:DWORD dst_unused:UNUSED_PAD src0_sel:WORD_1 src1_sel:DWORD
	v_add3_u32 v5, v5, v9, s56
	v_and_b32_e32 v8, 0xffff0000, v5
	v_cvt_pk_bf16_f32 v5, v6, v7
	v_or_b32_sdwa v4, v8, v4 dst_sel:DWORD dst_unused:UNUSED_PAD src0_sel:DWORD src1_sel:WORD_1
	global_store_dwordx2 v[16:17], v[4:5], off offset:64
	s_nop 0
	v_pk_fma_f32 v[0:1], v[0:1], v[136:137], v[222:223]
	s_nop 0
	v_mul_f32_e32 v4, v1, v1
	v_pk_fma_f32 v[2:3], v[2:3], v[138:139], v[224:225]
	v_fmac_f32_e32 v4, v0, v0
	v_fmac_f32_e32 v4, v2, v2
	global_store_dwordx4 v[18:19], v[0:3], off offset:192
	v_fmac_f32_e32 v4, v3, v3
	v_add_f32_e32 v18, v28, v4
	v_pk_mul_f32 v[2:3], v[2:3], v[154:155]
	v_pk_mul_f32 v[0:1], v[0:1], v[152:153]
	v_pk_add_f32 v[4:5], v[192:193], 1.0 op_sel_hi:[1,0]
	v_pk_add_f32 v[6:7], v[190:191], 1.0 op_sel_hi:[1,0]
	v_pk_mul_f32 v[2:3], v[2:3], v[4:5]
	v_pk_mul_f32 v[0:1], v[0:1], v[6:7]
	v_and_b32_sdwa v5, v0, v170 dst_sel:DWORD dst_unused:UNUSED_PAD src0_sel:WORD_1 src1_sel:DWORD
	v_add3_u32 v0, v0, v5, s56
	v_and_b32_sdwa v5, v1, v170 dst_sel:DWORD dst_unused:UNUSED_PAD src0_sel:WORD_1 src1_sel:DWORD
	v_add3_u32 v1, v1, v5, s56
	v_and_b32_e32 v4, 0xffff0000, v1
	v_cvt_pk_bf16_f32 v1, v2, v3
	v_or_b32_sdwa v0, v4, v0 dst_sel:DWORD dst_unused:UNUSED_PAD src0_sel:DWORD src1_sel:WORD_1
	global_store_dwordx2 v[16:17], v[0:1], off offset:96
	ds_bpermute_b32 v0, v105, v18
	s_waitcnt lgkmcnt(0)
	v_add_f32_e32 v0, v18, v0
	ds_bpermute_b32 v1, v104, v0
	s_and_saveexec_b64 s[0:1], vcc
	s_movk_i32 s89, 0xff
	s_cbranch_execz .LBB0_424
	v_readlane_b32 s2, v253, 20
	s_add_u32 s2, s38, s2
	s_addc_u32 s3, s39, 0
	v_lshl_add_u64 v[2:3], v[12:13], 2, s[2:3]
	s_waitcnt lgkmcnt(0)
	v_add_f32_e32 v0, v0, v1
	global_store_dword v[2:3], v0, off

.Ltail582:
	s_add_i32 s0, s1, 2
	v_add_u32_e32 v111, v104, v105
	ds_read_b128 v[136:139], v111 offset:16384
	ds_read_b128 v[140:143], v111 offset:18432
	ds_read_b128 v[144:147], v111 offset:20480
	ds_read_b128 v[148:151], v111 offset:22528
	v_add_u32_e32 v110, v103, v105
	ds_read_b128 v[116:119], v110
	s_add_i32 s1, s1, 4
	ds_read_b128 v[120:123], v110 offset:2048
	s_min_u32 s1, s1, 63
	v_add_u32_e32 v113, v104, v114
	s_lshl_b32 s92, s1, 7
	ds_read_b128 v[124:127], v110 offset:4096
	v_add_u32_e32 v112, v103, v114
	ds_read_b128 v[194:197], v113 offset:16384
	ds_read_b128 v[198:201], v113 offset:18432
	ds_read_b128 v[202:205], v113 offset:20480
	ds_read_b128 v[206:209], v113 offset:22528
	v_lshl_add_u64 v[164:165], v[98:99], 0, s[92:93]
	ds_read_b128 v[132:135], v110 offset:6144
	ds_read_b128 v[152:155], v112
	ds_read_b128 v[156:159], v112 offset:2048
	ds_read_b128 v[160:163], v112 offset:4096
	ds_read_b128 v[190:193], v112 offset:6144
	s_waitcnt lgkmcnt(11)
	v_mfma_f32_16x16x32_bf16 v[92:95], v[136:139], v[116:119], v[92:95]
	v_mfma_f32_16x16x32_bf16 v[88:91], v[140:143], v[116:119], v[88:91]
	v_mfma_f32_16x16x32_bf16 v[52:55], v[144:147], v[116:119], v[52:55]
	v_mfma_f32_16x16x32_bf16 v[48:51], v[148:151], v[116:119], v[48:51]
	s_waitcnt vmcnt(7)
	ds_write_b128 v109, v[56:59] offset:32768
	v_add_co_u32_e32 v56, vcc, s7, v164
	s_waitcnt lgkmcnt(11)
	v_mfma_f32_16x16x32_bf16 v[44:47], v[136:139], v[120:123], v[44:47]
	v_addc_co_u32_e32 v57, vcc, 0, v165, vcc
	v_mfma_f32_16x16x32_bf16 v[40:43], v[140:143], v[120:123], v[40:43]
	v_mfma_f32_16x16x32_bf16 v[36:39], v[144:147], v[120:123], v[36:39]
	v_mfma_f32_16x16x32_bf16 v[32:35], v[148:151], v[120:123], v[32:35]
	v_add_co_u32_e32 v56, vcc, s52, v164
	s_waitcnt vmcnt(6)
	ds_write_b128 v109, v[60:63] offset:36864
	s_nop 0
	v_addc_co_u32_e32 v57, vcc, 0, v165, vcc
	s_waitcnt lgkmcnt(11)
	v_mfma_f32_16x16x32_bf16 v[28:31], v[136:139], v[124:127], v[28:31]
	v_mfma_f32_16x16x32_bf16 v[24:27], v[140:143], v[124:127], v[24:27]
	v_mfma_f32_16x16x32_bf16 v[20:23], v[144:147], v[124:127], v[20:23]
	v_mfma_f32_16x16x32_bf16 v[16:19], v[148:151], v[124:127], v[16:19]
	v_add_co_u32_e32 v56, vcc, s34, v164
	s_waitcnt vmcnt(5)
	ds_write_b128 v109, v[64:67] offset:40960
	s_nop 0
	v_addc_co_u32_e32 v57, vcc, 0, v165, vcc
	v_lshl_add_u64 v[64:65], v[100:101], 0, s[92:93]
	v_add_co_u32_e32 v66, vcc, s7, v64
	s_waitcnt lgkmcnt(7)
	v_mfma_f32_16x16x32_bf16 v[12:15], v[136:139], v[132:135], v[12:15]
	v_addc_co_u32_e32 v67, vcc, 0, v65, vcc
	v_mfma_f32_16x16x32_bf16 v[8:11], v[140:143], v[132:135], v[8:11]
	v_mfma_f32_16x16x32_bf16 v[4:7], v[144:147], v[132:135], v[4:7]
	v_mfma_f32_16x16x32_bf16 v[0:3], v[148:151], v[132:135], v[0:3]
	s_waitcnt vmcnt(4)
	ds_write_b128 v109, v[72:75] offset:45056
	s_waitcnt lgkmcnt(7)
	v_mfma_f32_16x16x32_bf16 v[56:59], v[194:197], v[152:155], v[92:95]
	v_mfma_f32_16x16x32_bf16 v[60:63], v[198:201], v[152:155], v[88:91]
	v_mfma_f32_16x16x32_bf16 v[52:55], v[202:205], v[152:155], v[52:55]
	v_mfma_f32_16x16x32_bf16 v[48:51], v[206:209], v[152:155], v[48:51]
	s_waitcnt vmcnt(3)
	ds_write_b128 v109, v[68:71] offset:49152
	s_waitcnt lgkmcnt(7)
	v_mfma_f32_16x16x32_bf16 v[44:47], v[194:197], v[156:159], v[44:47]
	v_mfma_f32_16x16x32_bf16 v[40:43], v[198:201], v[156:159], v[40:43]
	v_mfma_f32_16x16x32_bf16 v[36:39], v[202:205], v[156:159], v[36:39]
	v_mfma_f32_16x16x32_bf16 v[32:35], v[206:209], v[156:159], v[32:35]
	v_add_co_u32_e32 v66, vcc, s52, v64
	s_waitcnt vmcnt(2)
	ds_write_b128 v109, v[76:79] offset:53248
	v_addc_co_u32_e32 v67, vcc, 0, v65, vcc
	v_add_co_u32_e32 v64, vcc, s34, v64
	s_waitcnt lgkmcnt(7)
	v_mfma_f32_16x16x32_bf16 v[28:31], v[194:197], v[160:163], v[28:31]
	v_addc_co_u32_e32 v65, vcc, 0, v65, vcc
	v_mfma_f32_16x16x32_bf16 v[24:27], v[198:201], v[160:163], v[24:27]
	v_mfma_f32_16x16x32_bf16 v[20:23], v[202:205], v[160:163], v[20:23]
	v_mfma_f32_16x16x32_bf16 v[16:19], v[206:209], v[160:163], v[16:19]
	s_waitcnt vmcnt(1)
	ds_write_b128 v109, v[80:83] offset:57344
	s_waitcnt lgkmcnt(7)
	v_mfma_f32_16x16x32_bf16 v[12:15], v[194:197], v[190:193], v[12:15]
	v_mfma_f32_16x16x32_bf16 v[8:11], v[198:201], v[190:193], v[8:11]
	v_mfma_f32_16x16x32_bf16 v[4:7], v[202:205], v[190:193], v[4:7]
	v_mfma_f32_16x16x32_bf16 v[0:3], v[206:209], v[190:193], v[0:3]
	s_waitcnt vmcnt(0)
	ds_write_b128 v109, v[84:87] offset:61440
	s_waitcnt lgkmcnt(0)
	s_barrier
	ds_read_b128 v[84:87], v111 offset:51200
	ds_read_b128 v[80:83], v111 offset:49152
	ds_read_b128 v[88:91], v111 offset:53248
	ds_read_b128 v[92:95], v111 offset:55296
	ds_read_b128 v[64:67], v110 offset:32768
	s_min_u32 s1, s0, 60
	s_lshl_b32 s92, s1, 7
	ds_read_b128 v[68:71], v110 offset:34816
	v_lshl_add_u64 v[164:165], v[98:99], 0, s[92:93]
	ds_read_b128 v[72:75], v110 offset:36864
	ds_read_b128 v[76:79], v110 offset:38912
	ds_read_b128 v[152:155], v112 offset:32768
	ds_read_b128 v[156:159], v112 offset:34816
	ds_read_b128 v[160:163], v112 offset:36864
	ds_read_b128 v[190:193], v112 offset:38912
	ds_read_b128 v[194:197], v113 offset:49152
	ds_read_b128 v[198:201], v113 offset:51200
	ds_read_b128 v[202:205], v113 offset:53248
	ds_read_b128 v[206:209], v113 offset:55296
	s_waitcnt lgkmcnt(11)
	v_mfma_f32_16x16x32_bf16 v[214:217], v[84:87], v[64:67], v[60:63]
	v_mfma_f32_16x16x32_bf16 v[210:213], v[80:83], v[64:67], v[56:59]
	s_nop 1
	v_add_co_u32_e32 v60, vcc, s7, v164
	s_nop 1
	v_addc_co_u32_e32 v61, vcc, 0, v165, vcc
	v_mfma_f32_16x16x32_bf16 v[52:55], v[88:91], v[64:67], v[52:55]
	v_mfma_f32_16x16x32_bf16 v[48:51], v[92:95], v[64:67], v[48:51]
	v_add_co_u32_e32 v64, vcc, s52, v164
	s_nop 0
	s_nop 0
	v_addc_co_u32_e32 v65, vcc, 0, v165, vcc
	s_waitcnt lgkmcnt(10)
	v_mfma_f32_16x16x32_bf16 v[44:47], v[80:83], v[68:71], v[44:47]
	v_mfma_f32_16x16x32_bf16 v[40:43], v[84:87], v[68:71], v[40:43]
	v_mfma_f32_16x16x32_bf16 v[36:39], v[88:91], v[68:71], v[36:39]
	v_mfma_f32_16x16x32_bf16 v[32:35], v[92:95], v[68:71], v[32:35]
	v_add_co_u32_e32 v68, vcc, s34, v164
	s_waitcnt lgkmcnt(9)
	v_mfma_f32_16x16x32_bf16 v[28:31], v[80:83], v[72:75], v[28:31]
	v_addc_co_u32_e32 v69, vcc, 0, v165, vcc
	v_mfma_f32_16x16x32_bf16 v[24:27], v[84:87], v[72:75], v[24:27]
	v_mfma_f32_16x16x32_bf16 v[20:23], v[88:91], v[72:75], v[20:23]
	v_mfma_f32_16x16x32_bf16 v[16:19], v[92:95], v[72:75], v[16:19]
	s_waitcnt lgkmcnt(8)
	v_mfma_f32_16x16x32_bf16 v[8:11], v[84:87], v[76:79], v[8:11]
	v_lshl_add_u64 v[84:85], v[100:101], 0, s[92:93]
	v_mfma_f32_16x16x32_bf16 v[12:15], v[80:83], v[76:79], v[12:15]
	v_mfma_f32_16x16x32_bf16 v[4:7], v[88:91], v[76:79], v[4:7]
	v_mfma_f32_16x16x32_bf16 v[0:3], v[92:95], v[76:79], v[0:3]
	v_add_co_u32_e32 v76, vcc, s7, v84
	s_nop 0
	s_nop 0
	v_addc_co_u32_e32 v77, vcc, 0, v85, vcc
	v_add_co_u32_e32 v80, vcc, s52, v84
	s_nop 1
	v_addc_co_u32_e32 v81, vcc, 0, v85, vcc
	s_waitcnt lgkmcnt(3)
	v_mfma_f32_16x16x32_bf16 v[92:95], v[194:197], v[152:155], v[210:213]
	s_waitcnt lgkmcnt(2)
	v_mfma_f32_16x16x32_bf16 v[88:91], v[198:201], v[152:155], v[214:217]
	s_waitcnt lgkmcnt(1)
	v_mfma_f32_16x16x32_bf16 v[52:55], v[202:205], v[152:155], v[52:55]
	s_waitcnt lgkmcnt(0)
	v_mfma_f32_16x16x32_bf16 v[48:51], v[206:209], v[152:155], v[48:51]
	v_add_co_u32_e32 v84, vcc, s34, v84
	s_nop 1
	v_addc_co_u32_e32 v85, vcc, 0, v85, vcc
	v_mfma_f32_16x16x32_bf16 v[44:47], v[194:197], v[156:159], v[44:47]
	v_mfma_f32_16x16x32_bf16 v[40:43], v[198:201], v[156:159], v[40:43]
	v_mfma_f32_16x16x32_bf16 v[36:39], v[202:205], v[156:159], v[36:39]
	v_mfma_f32_16x16x32_bf16 v[32:35], v[206:209], v[156:159], v[32:35]
	v_mfma_f32_16x16x32_bf16 v[28:31], v[194:197], v[160:163], v[28:31]
	v_mfma_f32_16x16x32_bf16 v[24:27], v[198:201], v[160:163], v[24:27]
	v_mfma_f32_16x16x32_bf16 v[20:23], v[202:205], v[160:163], v[20:23]
	v_mfma_f32_16x16x32_bf16 v[16:19], v[206:209], v[160:163], v[16:19]
	v_mfma_f32_16x16x32_bf16 v[12:15], v[194:197], v[190:193], v[12:15]
	v_mfma_f32_16x16x32_bf16 v[8:11], v[198:201], v[190:193], v[8:11]
	v_mfma_f32_16x16x32_bf16 v[4:7], v[202:205], v[190:193], v[4:7]
	v_mfma_f32_16x16x32_bf16 v[0:3], v[206:209], v[190:193], v[0:3]
	s_mov_b32 s1, s0
	s_waitcnt lgkmcnt(0)
	s_barrier
	s_or_b32 s0, s69, 1
	s_mul_i32 s1, s69, 0x12000
	v_readlane_b32 s26, v250, 25
	v_readlane_b32 s27, v250, 26
	s_add_u32 s1, s26, s1
	s_addc_u32 s24, s27, 0
	s_add_u32 s38, s1, 0x5000
	v_readlane_b32 s1, v251, 5
	v_lshlrev_b32_e32 v114, 6, v102
	v_lshlrev_b32_e32 v115, 2, v97
	s_waitcnt vmcnt(5)
	v_add_u32_e32 v64, s1, v108
	v_readlane_b32 s1, v251, 6
	v_add_u32_e32 v56, 0xffffe000, v64
	v_or_b32_e32 v62, v64, v107
	v_or_b32_e32 v65, s1, v114
	v_lshrrev_b32_e32 v56, 10, v56
	s_movk_i32 s1, 0x1800
	v_mad_u32_u24 v56, v56, s1, s1
	v_cmp_lt_i32_e32 vcc, s13, v62
	v_or_b32_e32 v58, v65, v115
	s_addc_u32 s39, s24, 0
	v_cndmask_b32_e32 v56, 0, v56, vcc
	v_ashrrev_i32_e32 v57, 31, v56
	s_waitcnt vmcnt(4)
	v_lshlrev_b64 v[74:75], 2, v[56:57]
	v_ashrrev_i32_e32 v59, 31, v58
	v_ashrrev_i32_e32 v63, 31, v62
	v_lshl_add_u64 v[56:57], s[38:39], 0, v[74:75]
	v_lshlrev_b64 v[60:61], 2, v[58:59]
	v_readlane_b32 s16, v250, 15
	s_waitcnt vmcnt(1)
	v_lshl_add_u64 v[82:83], v[56:57], 0, v[60:61]
	v_lshlrev_b64 v[56:57], 12, v[62:63]
	v_readlane_b32 s17, v250, 16
	v_readlane_b32 s68, v250, 41
	s_mul_i32 s24, s0, 0x12000
	v_lshl_add_u64 v[56:57], s[16:17], 0, v[56:57]
	s_waitcnt vmcnt(0)
	v_lshl_add_u64 v[84:85], v[56:57], 0, v[60:61]
	global_load_dwordx4 v[116:119], v[82:83], off
	global_load_dwordx4 v[120:123], v[82:83], off offset:64
	global_load_dwordx4 v[124:127], v[82:83], off offset:128
	global_load_dwordx4 v[132:135], v[82:83], off offset:192
	global_load_dwordx4 v[190:193], v[84:85], off
	global_load_dwordx4 v[194:197], v[84:85], off offset:64
	global_load_dwordx4 v[198:201], v[84:85], off offset:128
	global_load_dwordx4 v[202:205], v[84:85], off offset:192
	v_add_co_u32_e32 v164, vcc, 0x10000, v84
	s_nop 1
	v_addc_co_u32_e32 v165, vcc, 0, v85, vcc
	v_add_co_u32_e32 v222, vcc, 0x20000, v84
	s_nop 1
	v_addc_co_u32_e32 v223, vcc, 0, v85, vcc
	v_add_co_u32_e32 v224, vcc, 0x30000, v84
	s_nop 1
	v_addc_co_u32_e32 v225, vcc, 0, v85, vcc
	global_load_dwordx4 v[206:209], v[164:165], off
	global_load_dwordx4 v[210:213], v[164:165], off offset:64
	global_load_dwordx4 v[214:217], v[164:165], off offset:128
	global_load_dwordx4 v[218:221], v[164:165], off offset:192
	s_lshl_b32 s0, s0, 12
	v_readlane_b32 s70, v250, 43
	v_readlane_b32 s71, v250, 44
	s_add_u32 s0, s70, s0
	s_addc_u32 s1, s71, 0
	s_add_u32 s24, s26, s24
	s_addc_u32 s25, s27, 0
	s_add_u32 s40, s24, 0x1000
	s_addc_u32 s41, s25, 0
	v_lshl_add_u64 v[74:75], s[40:41], 0, v[74:75]
	v_lshl_add_u64 v[56:57], s[0:1], 0, v[60:61]
	v_lshl_add_u64 v[86:87], v[74:75], 0, v[60:61]
	v_readlane_b32 s16, v250, 21
	v_lshlrev_b64 v[78:79], 11, v[62:63]
	v_readlane_b32 s17, v250, 22
	v_readlane_b32 s69, v250, 42
	v_readlane_b32 s69, v254, 49
	v_lshl_add_u64 v[78:79], s[16:17], 0, v[78:79]
	s_mul_i32 s24, s69, 0x140000
	s_add_u32 s24, s86, s24
	s_mov_b32 s16, 0xa000
	s_addc_u32 s25, s87, 0
	s_add_u32 s26, s24, 0xafba000
	s_addc_u32 s27, s25, 0
	v_cmp_eq_u32_e64 s[36:37], 0, v97
	v_readlane_b32 s72, v250, 45
	v_readlane_b32 s73, v250, 46
	v_readlane_b32 s74, v250, 47
	v_readlane_b32 s75, v250, 48
	v_readlane_b32 s76, v250, 49
	v_readlane_b32 s77, v250, 50
	v_readlane_b32 s78, v250, 51
	v_readlane_b32 s79, v250, 52
	v_readlane_b32 s80, v250, 53
	v_readlane_b32 s81, v250, 54
	v_readlane_b32 s82, v250, 55
	v_readlane_b32 s83, v250, 56
	s_waitcnt vmcnt(4)
	v_pk_fma_f32 v[68:69], v[94:95], v[118:119], v[192:193]
	v_pk_fma_f32 v[66:67], v[92:93], v[116:117], v[190:191]
	global_store_dwordx4 v[84:85], v[66:69], off
	global_load_dwordx4 v[136:139], v[56:57], off
	global_load_dwordx4 v[140:143], v[56:57], off offset:64
	global_load_dwordx4 v[144:147], v[56:57], off offset:128
	global_load_dwordx4 v[148:151], v[56:57], off offset:192
	global_load_dwordx4 v[152:155], v[86:87], off
	global_load_dwordx4 v[156:159], v[86:87], off offset:64
	global_load_dwordx4 v[160:163], v[86:87], off offset:128
	global_load_dwordx4 v[180:183], v[86:87], off offset:192
	v_lshl_add_u64 v[92:93], v[58:59], 1, v[78:79]
	s_waitcnt vmcnt(0)
	v_pk_mul_f32 v[72:73], v[68:69], v[138:139]
	v_pk_mul_f32 v[70:71], v[66:67], v[136:137]
	s_waitcnt vmcnt(0)
	v_pk_add_f32 v[76:77], v[154:155], 1.0 op_sel_hi:[1,0]
	v_pk_add_f32 v[74:75], v[152:153], 1.0 op_sel_hi:[1,0]
	v_pk_mul_f32 v[72:73], v[72:73], v[76:77]
	v_pk_mul_f32 v[70:71], v[70:71], v[74:75]
	v_and_b32_sdwa v77, v71, v170 dst_sel:DWORD dst_unused:UNUSED_PAD src0_sel:WORD_1 src1_sel:DWORD
	v_and_b32_sdwa v75, v70, v170 dst_sel:DWORD dst_unused:UNUSED_PAD src0_sel:WORD_1 src1_sel:DWORD
	v_add3_u32 v71, v71, v77, s56
	v_add3_u32 v70, v70, v75, s56
	v_and_b32_e32 v74, 0xffff0000, v71
	v_cvt_pk_bf16_f32 v71, v72, v73
	v_or_b32_sdwa v70, v74, v70 dst_sel:DWORD dst_unused:UNUSED_PAD src0_sel:DWORD src1_sel:WORD_1
	global_store_dwordx2 v[92:93], v[70:71], off
	s_nop 0
	s_waitcnt vmcnt(0)
	v_pk_fma_f32 v[72:73], v[90:91], v[122:123], v[196:197]
	v_pk_fma_f32 v[70:71], v[88:89], v[120:121], v[194:195]
	global_store_dwordx4 v[84:85], v[70:73], off offset:64
	v_pk_mul_f32 v[76:77], v[72:73], v[142:143]
	v_pk_mul_f32 v[74:75], v[70:71], v[140:141]
	v_pk_add_f32 v[80:81], v[158:159], 1.0 op_sel_hi:[1,0]
	v_pk_add_f32 v[78:79], v[156:157], 1.0 op_sel_hi:[1,0]
	v_pk_mul_f32 v[76:77], v[76:77], v[80:81]
	v_pk_mul_f32 v[74:75], v[74:75], v[78:79]
	v_and_b32_sdwa v81, v75, v170 dst_sel:DWORD dst_unused:UNUSED_PAD src0_sel:WORD_1 src1_sel:DWORD
	v_and_b32_sdwa v79, v74, v170 dst_sel:DWORD dst_unused:UNUSED_PAD src0_sel:WORD_1 src1_sel:DWORD
	v_add3_u32 v75, v75, v81, s56
	v_add3_u32 v74, v74, v79, s56
	v_and_b32_e32 v78, 0xffff0000, v75
	v_cvt_pk_bf16_f32 v75, v76, v77
	v_or_b32_sdwa v74, v78, v74 dst_sel:DWORD dst_unused:UNUSED_PAD src0_sel:DWORD src1_sel:WORD_1
	global_store_dwordx2 v[92:93], v[74:75], off offset:32
	s_nop 0
	v_pk_fma_f32 v[54:55], v[54:55], v[126:127], v[200:201]
	v_pk_fma_f32 v[52:53], v[52:53], v[124:125], v[198:199]
	global_store_dwordx4 v[84:85], v[52:55], off offset:128
	v_pk_mul_f32 v[76:77], v[54:55], v[146:147]
	v_pk_mul_f32 v[74:75], v[52:53], v[144:145]
	v_pk_add_f32 v[80:81], v[162:163], 1.0 op_sel_hi:[1,0]
	v_pk_add_f32 v[78:79], v[160:161], 1.0 op_sel_hi:[1,0]
	v_pk_mul_f32 v[76:77], v[76:77], v[80:81]
	v_pk_mul_f32 v[74:75], v[74:75], v[78:79]
	v_and_b32_sdwa v81, v75, v170 dst_sel:DWORD dst_unused:UNUSED_PAD src0_sel:WORD_1 src1_sel:DWORD
	v_and_b32_sdwa v79, v74, v170 dst_sel:DWORD dst_unused:UNUSED_PAD src0_sel:WORD_1 src1_sel:DWORD
	v_add3_u32 v75, v75, v81, s56
	v_add3_u32 v74, v74, v79, s56
	v_and_b32_e32 v78, 0xffff0000, v75
	v_cvt_pk_bf16_f32 v75, v76, v77
	v_or_b32_sdwa v74, v78, v74 dst_sel:DWORD dst_unused:UNUSED_PAD src0_sel:DWORD src1_sel:WORD_1
	global_store_dwordx2 v[92:93], v[74:75], off offset:64
	s_nop 0
	v_pk_fma_f32 v[76:77], v[50:51], v[134:135], v[204:205]
	v_pk_fma_f32 v[74:75], v[48:49], v[132:133], v[202:203]
	global_store_dwordx4 v[84:85], v[74:77], off offset:192
	s_nop 0
	v_mul_f32_e32 v50, v67, v67
	v_mul_f32_e32 v51, v71, v71
	v_fmac_f32_e32 v50, v66, v66
	v_fmac_f32_e32 v51, v70, v70
	v_fmac_f32_e32 v50, v68, v68
	v_fmac_f32_e32 v51, v72, v72
	v_fmac_f32_e32 v50, v69, v69
	v_fmac_f32_e32 v51, v73, v73
	v_add_f32_e32 v50, v50, v51
	v_mul_f32_e32 v51, v53, v53
	v_fmac_f32_e32 v51, v52, v52
	v_fmac_f32_e32 v51, v54, v54
	v_fmac_f32_e32 v51, v55, v55
	v_add_f32_e32 v50, v50, v51
	v_mul_f32_e32 v51, v75, v75
	v_xor_b32_e32 v48, 16, v176
	v_fmac_f32_e32 v51, v74, v74
	v_cmp_lt_i32_e32 vcc, v48, v177
	v_fmac_f32_e32 v51, v76, v76
	v_fmac_f32_e32 v51, v77, v77
	v_cndmask_b32_e32 v48, v176, v48, vcc
	v_lshlrev_b32_e32 v105, 2, v48
	v_add_f32_e32 v50, v50, v51
	ds_bpermute_b32 v51, v105, v50
	v_xor_b32_e32 v49, 32, v176
	v_cmp_lt_i32_e32 vcc, v49, v177
	v_lshrrev_b32_e32 v48, 6, v65
	v_mul_lo_u32 v48, v48, s16
	v_cndmask_b32_e32 v49, v176, v49, vcc
	v_lshlrev_b32_e32 v104, 2, v49
	s_waitcnt lgkmcnt(0)
	v_add_f32_e32 v50, v50, v51
	ds_bpermute_b32 v51, v104, v50
	v_ashrrev_i32_e32 v49, 31, v48
	v_lshl_add_u64 v[48:49], s[26:27], 0, v[48:49]
	v_lshl_add_u64 v[48:49], v[62:63], 2, v[48:49]
	v_pk_mul_f32 v[52:53], v[76:77], v[150:151]
	v_pk_mul_f32 v[54:55], v[74:75], v[148:149]
	v_pk_add_f32 v[66:67], v[182:183], 1.0 op_sel_hi:[1,0]
	v_pk_add_f32 v[68:69], v[180:181], 1.0 op_sel_hi:[1,0]
	v_pk_mul_f32 v[52:53], v[52:53], v[66:67]
	v_pk_mul_f32 v[54:55], v[54:55], v[68:69]
	v_cvt_pk_bf16_f32 v53, v52, v53
	v_cvt_pk_bf16_f32 v52, v54, v55
	global_store_dwordx2 v[92:93], v[52:53], off offset:96
	s_and_saveexec_b64 s[24:25], s[36:37]
	s_cbranch_execz .LBB0_585
	s_waitcnt lgkmcnt(0)
	v_add_f32_e32 v50, v50, v51
	global_store_dword v[48:49], v50, off

.Ltail596:
	s_add_i32 s29, s42, 2
	ds_read_b128 v[136:139], v111 offset:16384
	ds_read_b128 v[140:143], v111 offset:18432
	ds_read_b128 v[144:147], v111 offset:20480
	ds_read_b128 v[148:151], v111 offset:22528
	ds_read_b128 v[116:119], v110
	s_add_i32 s42, s42, 4
	ds_read_b128 v[120:123], v110 offset:2048
	s_min_u32 s42, s42, 63
	s_lshl_b32 s92, s42, 7
	ds_read_b128 v[124:127], v110 offset:4096
	ds_read_b128 v[194:197], v113 offset:16384
	ds_read_b128 v[198:201], v113 offset:18432
	ds_read_b128 v[202:205], v113 offset:20480
	ds_read_b128 v[206:209], v113 offset:22528
	v_lshl_add_u64 v[164:165], v[100:101], 0, s[92:93]
	ds_read_b128 v[132:135], v110 offset:6144
	ds_read_b128 v[152:155], v112
	ds_read_b128 v[156:159], v112 offset:2048
	ds_read_b128 v[160:163], v112 offset:4096
	ds_read_b128 v[190:193], v112 offset:6144
	s_waitcnt lgkmcnt(11)
	v_mfma_f32_16x16x32_bf16 v[92:95], v[136:139], v[116:119], v[92:95]
	v_mfma_f32_16x16x32_bf16 v[88:91], v[140:143], v[116:119], v[88:91]
	v_mfma_f32_16x16x32_bf16 v[56:59], v[144:147], v[116:119], v[56:59]
	v_mfma_f32_16x16x32_bf16 v[48:51], v[148:151], v[116:119], v[48:51]
	s_waitcnt vmcnt(7)
	ds_write_b128 v109, v[52:55] offset:32768
	v_add_co_u32_e32 v52, vcc, s7, v164
	s_waitcnt lgkmcnt(11)
	v_mfma_f32_16x16x32_bf16 v[44:47], v[136:139], v[120:123], v[44:47]
	v_addc_co_u32_e32 v53, vcc, 0, v165, vcc
	v_mfma_f32_16x16x32_bf16 v[40:43], v[140:143], v[120:123], v[40:43]
	v_mfma_f32_16x16x32_bf16 v[36:39], v[144:147], v[120:123], v[36:39]
	v_mfma_f32_16x16x32_bf16 v[32:35], v[148:151], v[120:123], v[32:35]
	v_add_co_u32_e32 v52, vcc, s52, v164
	s_waitcnt vmcnt(6)
	ds_write_b128 v109, v[60:63] offset:36864
	s_nop 0
	v_addc_co_u32_e32 v53, vcc, 0, v165, vcc
	s_waitcnt lgkmcnt(11)
	v_mfma_f32_16x16x32_bf16 v[28:31], v[136:139], v[124:127], v[28:31]
	v_mfma_f32_16x16x32_bf16 v[24:27], v[140:143], v[124:127], v[24:27]
	v_mfma_f32_16x16x32_bf16 v[20:23], v[144:147], v[124:127], v[20:23]
	v_mfma_f32_16x16x32_bf16 v[16:19], v[148:151], v[124:127], v[16:19]
	v_add_co_u32_e32 v52, vcc, s34, v164
	s_waitcnt vmcnt(5)
	ds_write_b128 v109, v[64:67] offset:40960
	s_nop 0
	v_addc_co_u32_e32 v53, vcc, 0, v165, vcc
	v_lshl_add_u64 v[64:65], v[102:103], 0, s[92:93]
	v_add_co_u32_e32 v66, vcc, s7, v64
	s_waitcnt lgkmcnt(7)
	v_mfma_f32_16x16x32_bf16 v[12:15], v[136:139], v[132:135], v[12:15]
	v_addc_co_u32_e32 v67, vcc, 0, v65, vcc
	v_mfma_f32_16x16x32_bf16 v[8:11], v[140:143], v[132:135], v[8:11]
	v_mfma_f32_16x16x32_bf16 v[4:7], v[144:147], v[132:135], v[4:7]
	v_mfma_f32_16x16x32_bf16 v[0:3], v[148:151], v[132:135], v[0:3]
	s_waitcnt vmcnt(4)
	ds_write_b128 v109, v[72:75] offset:45056
	s_waitcnt lgkmcnt(7)
	v_mfma_f32_16x16x32_bf16 v[52:55], v[194:197], v[152:155], v[92:95]
	v_mfma_f32_16x16x32_bf16 v[60:63], v[198:201], v[152:155], v[88:91]
	v_mfma_f32_16x16x32_bf16 v[56:59], v[202:205], v[152:155], v[56:59]
	v_mfma_f32_16x16x32_bf16 v[48:51], v[206:209], v[152:155], v[48:51]
	s_waitcnt vmcnt(3)
	ds_write_b128 v109, v[68:71] offset:49152
	s_waitcnt lgkmcnt(7)
	v_mfma_f32_16x16x32_bf16 v[44:47], v[194:197], v[156:159], v[44:47]
	v_mfma_f32_16x16x32_bf16 v[40:43], v[198:201], v[156:159], v[40:43]
	v_mfma_f32_16x16x32_bf16 v[36:39], v[202:205], v[156:159], v[36:39]
	v_mfma_f32_16x16x32_bf16 v[32:35], v[206:209], v[156:159], v[32:35]
	v_add_co_u32_e32 v66, vcc, s52, v64
	s_waitcnt vmcnt(2)
	ds_write_b128 v109, v[76:79] offset:53248
	v_addc_co_u32_e32 v67, vcc, 0, v65, vcc
	v_add_co_u32_e32 v64, vcc, s34, v64
	s_waitcnt lgkmcnt(7)
	v_mfma_f32_16x16x32_bf16 v[28:31], v[194:197], v[160:163], v[28:31]
	v_addc_co_u32_e32 v65, vcc, 0, v65, vcc
	v_mfma_f32_16x16x32_bf16 v[24:27], v[198:201], v[160:163], v[24:27]
	v_mfma_f32_16x16x32_bf16 v[20:23], v[202:205], v[160:163], v[20:23]
	v_mfma_f32_16x16x32_bf16 v[16:19], v[206:209], v[160:163], v[16:19]
	s_waitcnt vmcnt(1)
	ds_write_b128 v109, v[80:83] offset:57344
	s_waitcnt lgkmcnt(7)
	v_mfma_f32_16x16x32_bf16 v[12:15], v[194:197], v[190:193], v[12:15]
	v_mfma_f32_16x16x32_bf16 v[8:11], v[198:201], v[190:193], v[8:11]
	v_mfma_f32_16x16x32_bf16 v[4:7], v[202:205], v[190:193], v[4:7]
	v_mfma_f32_16x16x32_bf16 v[0:3], v[206:209], v[190:193], v[0:3]
	s_waitcnt vmcnt(0)
	ds_write_b128 v109, v[84:87] offset:61440
	s_waitcnt lgkmcnt(0)
	s_barrier
	ds_read_b128 v[84:87], v111 offset:51200
	ds_read_b128 v[80:83], v111 offset:49152
	ds_read_b128 v[88:91], v111 offset:53248
	ds_read_b128 v[92:95], v111 offset:55296
	ds_read_b128 v[64:67], v110 offset:32768
	s_min_u32 s42, s29, 60
	s_lshl_b32 s92, s42, 7
	ds_read_b128 v[68:71], v110 offset:34816
	v_lshl_add_u64 v[164:165], v[100:101], 0, s[92:93]
	ds_read_b128 v[72:75], v110 offset:36864
	ds_read_b128 v[76:79], v110 offset:38912
	ds_read_b128 v[152:155], v112 offset:32768
	ds_read_b128 v[156:159], v112 offset:34816
	ds_read_b128 v[160:163], v112 offset:36864
	ds_read_b128 v[190:193], v112 offset:38912
	ds_read_b128 v[194:197], v113 offset:49152
	ds_read_b128 v[198:201], v113 offset:51200
	ds_read_b128 v[202:205], v113 offset:53248
	ds_read_b128 v[206:209], v113 offset:55296
	s_waitcnt lgkmcnt(11)
	v_mfma_f32_16x16x32_bf16 v[214:217], v[84:87], v[64:67], v[60:63]
	v_mfma_f32_16x16x32_bf16 v[210:213], v[80:83], v[64:67], v[52:55]
	s_nop 1
	v_add_co_u32_e32 v60, vcc, s7, v164
	s_nop 1
	v_addc_co_u32_e32 v61, vcc, 0, v165, vcc
	v_mfma_f32_16x16x32_bf16 v[56:59], v[88:91], v[64:67], v[56:59]
	v_mfma_f32_16x16x32_bf16 v[48:51], v[92:95], v[64:67], v[48:51]
	v_add_co_u32_e32 v64, vcc, s52, v164
	s_nop 0
	s_nop 0
	v_addc_co_u32_e32 v65, vcc, 0, v165, vcc
	s_waitcnt lgkmcnt(10)
	v_mfma_f32_16x16x32_bf16 v[44:47], v[80:83], v[68:71], v[44:47]
	v_mfma_f32_16x16x32_bf16 v[40:43], v[84:87], v[68:71], v[40:43]
	v_mfma_f32_16x16x32_bf16 v[36:39], v[88:91], v[68:71], v[36:39]
	v_mfma_f32_16x16x32_bf16 v[32:35], v[92:95], v[68:71], v[32:35]
	v_add_co_u32_e32 v68, vcc, s34, v164
	s_waitcnt lgkmcnt(9)
	v_mfma_f32_16x16x32_bf16 v[28:31], v[80:83], v[72:75], v[28:31]
	v_addc_co_u32_e32 v69, vcc, 0, v165, vcc
	v_mfma_f32_16x16x32_bf16 v[24:27], v[84:87], v[72:75], v[24:27]
	v_mfma_f32_16x16x32_bf16 v[20:23], v[88:91], v[72:75], v[20:23]
	v_mfma_f32_16x16x32_bf16 v[16:19], v[92:95], v[72:75], v[16:19]
	s_waitcnt lgkmcnt(8)
	v_mfma_f32_16x16x32_bf16 v[8:11], v[84:87], v[76:79], v[8:11]
	v_lshl_add_u64 v[84:85], v[102:103], 0, s[92:93]
	v_mfma_f32_16x16x32_bf16 v[12:15], v[80:83], v[76:79], v[12:15]
	v_mfma_f32_16x16x32_bf16 v[4:7], v[88:91], v[76:79], v[4:7]
	v_mfma_f32_16x16x32_bf16 v[0:3], v[92:95], v[76:79], v[0:3]
	v_add_co_u32_e32 v76, vcc, s7, v84
	s_nop 0
	s_nop 0
	v_addc_co_u32_e32 v77, vcc, 0, v85, vcc
	v_add_co_u32_e32 v80, vcc, s52, v84
	s_nop 1
	v_addc_co_u32_e32 v81, vcc, 0, v85, vcc
	s_waitcnt lgkmcnt(3)
	v_mfma_f32_16x16x32_bf16 v[92:95], v[194:197], v[152:155], v[210:213]
	s_waitcnt lgkmcnt(2)
	v_mfma_f32_16x16x32_bf16 v[88:91], v[198:201], v[152:155], v[214:217]
	s_waitcnt lgkmcnt(1)
	v_mfma_f32_16x16x32_bf16 v[56:59], v[202:205], v[152:155], v[56:59]
	s_waitcnt lgkmcnt(0)
	v_mfma_f32_16x16x32_bf16 v[48:51], v[206:209], v[152:155], v[48:51]
	v_add_co_u32_e32 v84, vcc, s34, v84
	s_nop 1
	v_addc_co_u32_e32 v85, vcc, 0, v85, vcc
	v_mfma_f32_16x16x32_bf16 v[44:47], v[194:197], v[156:159], v[44:47]
	v_mfma_f32_16x16x32_bf16 v[40:43], v[198:201], v[156:159], v[40:43]
	v_mfma_f32_16x16x32_bf16 v[36:39], v[202:205], v[156:159], v[36:39]
	v_mfma_f32_16x16x32_bf16 v[32:35], v[206:209], v[156:159], v[32:35]
	v_mfma_f32_16x16x32_bf16 v[28:31], v[194:197], v[160:163], v[28:31]
	v_mfma_f32_16x16x32_bf16 v[24:27], v[198:201], v[160:163], v[24:27]
	v_mfma_f32_16x16x32_bf16 v[20:23], v[202:205], v[160:163], v[20:23]
	v_mfma_f32_16x16x32_bf16 v[16:19], v[206:209], v[160:163], v[16:19]
	v_mfma_f32_16x16x32_bf16 v[12:15], v[194:197], v[190:193], v[12:15]
	v_mfma_f32_16x16x32_bf16 v[8:11], v[198:201], v[190:193], v[8:11]
	v_mfma_f32_16x16x32_bf16 v[4:7], v[202:205], v[190:193], v[4:7]
	v_mfma_f32_16x16x32_bf16 v[0:3], v[206:209], v[190:193], v[0:3]
	s_mov_b32 s42, s29
	s_waitcnt lgkmcnt(0)
	s_barrier
	s_waitcnt vmcnt(5)
	v_add_u32_e32 v64, s24, v108
	v_add_u32_e32 v52, 0xffffe000, v64
	v_or_b32_e32 v62, v64, v107
	v_lshrrev_b32_e32 v52, 10, v52
	s_movk_i32 s16, 0x1800
	v_mad_u32_u24 v52, v52, s16, s16
	v_cmp_lt_i32_e32 vcc, s13, v62
	v_or_b32_e32 v65, s25, v114
	v_or_b32_e32 v54, v65, v115
	v_cndmask_b32_e32 v52, 0, v52, vcc
	v_ashrrev_i32_e32 v53, 31, v52
	s_waitcnt vmcnt(4)
	v_lshlrev_b64 v[74:75], 2, v[52:53]
	v_ashrrev_i32_e32 v55, 31, v54
	v_ashrrev_i32_e32 v63, 31, v62
	v_lshl_add_u64 v[52:53], s[38:39], 0, v[74:75]
	v_lshlrev_b64 v[60:61], 2, v[54:55]
	v_readlane_b32 s16, v250, 15
	s_waitcnt vmcnt(1)
	v_lshl_add_u64 v[82:83], v[52:53], 0, v[60:61]
	v_lshlrev_b64 v[52:53], 12, v[62:63]
	v_readlane_b32 s17, v250, 16
	v_lshl_add_u64 v[74:75], s[40:41], 0, v[74:75]
	s_waitcnt vmcnt(0)
	v_lshl_add_u64 v[86:87], v[74:75], 0, v[60:61]
	v_lshl_add_u64 v[52:53], s[16:17], 0, v[52:53]
	v_lshl_add_u64 v[84:85], v[52:53], 0, v[60:61]
	global_load_dwordx4 v[66:69], v[82:83], off
	global_load_dwordx4 v[70:73], v[84:85], off
	v_lshl_add_u64 v[52:53], s[0:1], 0, v[60:61]
	v_readlane_b32 s16, v250, 21
	v_lshlrev_b64 v[78:79], 11, v[62:63]
	v_readlane_b32 s17, v250, 22
	s_waitcnt vmcnt(0)
	v_pk_fma_f32 v[68:69], v[94:95], v[68:69], v[72:73]
	v_pk_fma_f32 v[66:67], v[92:93], v[66:67], v[70:71]
	global_store_dwordx4 v[84:85], v[66:69], off
	global_load_dwordx4 v[70:73], v[52:53], off
	global_load_dwordx4 v[74:77], v[86:87], off
	v_lshl_add_u64 v[78:79], s[16:17], 0, v[78:79]
	v_lshl_add_u64 v[92:93], v[54:55], 1, v[78:79]
	s_mov_b32 s16, 0xa000
	s_waitcnt vmcnt(1)
	v_pk_mul_f32 v[72:73], v[68:69], v[72:73]
	v_pk_mul_f32 v[70:71], v[66:67], v[70:71]
	s_waitcnt vmcnt(0)
	v_pk_add_f32 v[76:77], v[76:77], 1.0 op_sel_hi:[1,0]
	v_pk_add_f32 v[74:75], v[74:75], 1.0 op_sel_hi:[1,0]
	v_pk_mul_f32 v[72:73], v[72:73], v[76:77]
	v_pk_mul_f32 v[70:71], v[70:71], v[74:75]
	v_and_b32_sdwa v77, v71, v170 dst_sel:DWORD dst_unused:UNUSED_PAD src0_sel:WORD_1 src1_sel:DWORD
	v_and_b32_sdwa v75, v70, v170 dst_sel:DWORD dst_unused:UNUSED_PAD src0_sel:WORD_1 src1_sel:DWORD
	v_add3_u32 v71, v71, v77, s56
	v_add3_u32 v70, v70, v75, s56
	v_and_b32_e32 v74, 0xffff0000, v71
	v_cvt_pk_bf16_f32 v71, v72, v73
	v_or_b32_sdwa v70, v74, v70 dst_sel:DWORD dst_unused:UNUSED_PAD src0_sel:DWORD src1_sel:WORD_1
	global_store_dwordx2 v[92:93], v[70:71], off
	global_load_dwordx4 v[70:73], v[82:83], off offset:64
	s_nop 0
	global_load_dwordx4 v[74:77], v[84:85], off offset:64
	s_waitcnt vmcnt(0)
	v_pk_fma_f32 v[72:73], v[90:91], v[72:73], v[76:77]
	v_pk_fma_f32 v[70:71], v[88:89], v[70:71], v[74:75]
	global_store_dwordx4 v[84:85], v[70:73], off offset:64
	global_load_dwordx4 v[74:77], v[52:53], off offset:64
	global_load_dwordx4 v[78:81], v[86:87], off offset:64
	s_waitcnt vmcnt(1)
	v_pk_mul_f32 v[76:77], v[72:73], v[76:77]
	v_pk_mul_f32 v[74:75], v[70:71], v[74:75]
	s_waitcnt vmcnt(0)
	v_pk_add_f32 v[80:81], v[80:81], 1.0 op_sel_hi:[1,0]
	v_pk_add_f32 v[78:79], v[78:79], 1.0 op_sel_hi:[1,0]
	v_pk_mul_f32 v[76:77], v[76:77], v[80:81]
	v_pk_mul_f32 v[74:75], v[74:75], v[78:79]
	v_and_b32_sdwa v81, v75, v170 dst_sel:DWORD dst_unused:UNUSED_PAD src0_sel:WORD_1 src1_sel:DWORD
	v_and_b32_sdwa v79, v74, v170 dst_sel:DWORD dst_unused:UNUSED_PAD src0_sel:WORD_1 src1_sel:DWORD
	v_add3_u32 v75, v75, v81, s56
	v_add3_u32 v74, v74, v79, s56
	v_and_b32_e32 v78, 0xffff0000, v75
	v_cvt_pk_bf16_f32 v75, v76, v77
	v_or_b32_sdwa v74, v78, v74 dst_sel:DWORD dst_unused:UNUSED_PAD src0_sel:DWORD src1_sel:WORD_1
	global_store_dwordx2 v[92:93], v[74:75], off offset:32
	global_load_dwordx4 v[74:77], v[82:83], off offset:128
	s_nop 0
	global_load_dwordx4 v[78:81], v[84:85], off offset:128
	s_waitcnt vmcnt(0)
	v_pk_fma_f32 v[58:59], v[58:59], v[76:77], v[80:81]
	v_pk_fma_f32 v[56:57], v[56:57], v[74:75], v[78:79]
	global_store_dwordx4 v[84:85], v[56:59], off offset:128
	global_load_dwordx4 v[74:77], v[52:53], off offset:128
	global_load_dwordx4 v[78:81], v[86:87], off offset:128
	s_waitcnt vmcnt(1)
	v_pk_mul_f32 v[76:77], v[58:59], v[76:77]
	v_pk_mul_f32 v[74:75], v[56:57], v[74:75]
	s_waitcnt vmcnt(0)
	v_pk_add_f32 v[80:81], v[80:81], 1.0 op_sel_hi:[1,0]
	v_pk_add_f32 v[78:79], v[78:79], 1.0 op_sel_hi:[1,0]
	v_pk_mul_f32 v[76:77], v[76:77], v[80:81]
	v_pk_mul_f32 v[74:75], v[74:75], v[78:79]
	v_and_b32_sdwa v81, v75, v170 dst_sel:DWORD dst_unused:UNUSED_PAD src0_sel:WORD_1 src1_sel:DWORD
	v_and_b32_sdwa v79, v74, v170 dst_sel:DWORD dst_unused:UNUSED_PAD src0_sel:WORD_1 src1_sel:DWORD
	v_add3_u32 v75, v75, v81, s56
	v_add3_u32 v74, v74, v79, s56
	v_and_b32_e32 v78, 0xffff0000, v75
	v_cvt_pk_bf16_f32 v75, v76, v77
	v_or_b32_sdwa v74, v78, v74 dst_sel:DWORD dst_unused:UNUSED_PAD src0_sel:DWORD src1_sel:WORD_1
	global_store_dwordx2 v[92:93], v[74:75], off offset:64
	global_load_dwordx4 v[74:77], v[82:83], off offset:192
	s_nop 0
	global_load_dwordx4 v[78:81], v[84:85], off offset:192
	s_waitcnt vmcnt(0)
	v_pk_fma_f32 v[76:77], v[50:51], v[76:77], v[80:81]
	v_pk_fma_f32 v[74:75], v[48:49], v[74:75], v[78:79]
	global_store_dwordx4 v[84:85], v[74:77], off offset:192
	global_load_dwordx4 v[78:81], v[52:53], off offset:192
	s_nop 0
	global_load_dwordx4 v[82:85], v[86:87], off offset:192
	v_mul_f32_e32 v48, v67, v67
	v_mul_f32_e32 v49, v71, v71
	v_fmac_f32_e32 v48, v66, v66
	v_fmac_f32_e32 v49, v70, v70
	v_fmac_f32_e32 v48, v68, v68
	v_fmac_f32_e32 v49, v72, v72
	v_fmac_f32_e32 v48, v69, v69
	v_fmac_f32_e32 v49, v73, v73
	v_add_f32_e32 v48, v48, v49
	v_mul_f32_e32 v49, v57, v57
	v_fmac_f32_e32 v49, v56, v56
	v_fmac_f32_e32 v49, v58, v58
	v_fmac_f32_e32 v49, v59, v59
	v_add_f32_e32 v48, v48, v49
	v_mul_f32_e32 v49, v75, v75
	v_fmac_f32_e32 v49, v74, v74
	v_fmac_f32_e32 v49, v76, v76
	v_fmac_f32_e32 v49, v77, v77
	v_add_f32_e32 v50, v48, v49
	ds_bpermute_b32 v51, v105, v50
	v_lshrrev_b32_e32 v48, 6, v65
	v_mul_lo_u32 v48, v48, s16
	v_ashrrev_i32_e32 v49, 31, v48
	v_lshl_add_u64 v[48:49], s[26:27], 0, v[48:49]
	s_waitcnt lgkmcnt(0)
	v_add_f32_e32 v50, v50, v51
	ds_bpermute_b32 v51, v104, v50
	v_lshl_add_u64 v[48:49], v[62:63], 2, v[48:49]
	s_waitcnt vmcnt(1)
	v_pk_mul_f32 v[56:57], v[76:77], v[80:81]
	v_pk_mul_f32 v[58:59], v[74:75], v[78:79]
	s_waitcnt vmcnt(0)
	v_pk_add_f32 v[66:67], v[84:85], 1.0 op_sel_hi:[1,0]
	v_pk_add_f32 v[68:69], v[82:83], 1.0 op_sel_hi:[1,0]
	v_pk_mul_f32 v[56:57], v[56:57], v[66:67]
	v_pk_mul_f32 v[58:59], v[58:59], v[68:69]
	v_cvt_pk_bf16_f32 v57, v56, v57
	v_cvt_pk_bf16_f32 v56, v58, v59
	global_store_dwordx2 v[92:93], v[56:57], off offset:96
	s_and_saveexec_b64 s[24:25], s[36:37]
	s_cbranch_execz .LBB0_599
	s_waitcnt lgkmcnt(0)
	v_add_f32_e32 v50, v50, v51
	global_store_dword v[48:49], v50, off

.Ltail609:
	s_add_i32 s2, s3, 2
	v_add_u32_e32 v127, v89, v90
	ds_read_b128 v[100:103], v127 offset:16384
	ds_read_b128 v[106:109], v127 offset:18432
	ds_read_b128 v[110:113], v127 offset:20480
	ds_read_b128 v[114:117], v127 offset:22528
	v_add_u32_e32 v126, v88, v90
	ds_read_b128 v[92:95], v126
	ds_read_b128 v[96:99], v126 offset:2048
	s_add_i32 s3, s3, 4
	s_min_u32 s3, s3, 63
	v_add_u32_e32 v128, v88, v91
	v_add_u32_e32 v130, v89, v91
	s_lshl_b32 s92, s3, 7
	ds_read_b128 v[118:121], v130 offset:18432
	ds_read_b128 v[122:125], v130 offset:20480
	ds_read_b128 v[132:135], v130 offset:22528
	s_waitcnt lgkmcnt(4)
	v_mfma_f32_16x16x32_bf16 v[76:79], v[100:103], v[92:95], v[76:79]
	v_lshl_add_u64 v[44:45], v[80:81], 0, s[92:93]
	v_add_co_u32_e32 v46, vcc, s7, v44
	v_mfma_f32_16x16x32_bf16 v[68:71], v[106:109], v[92:95], v[68:71]
	s_nop 0
	v_addc_co_u32_e32 v47, vcc, 0, v45, vcc
	v_mfma_f32_16x16x32_bf16 v[52:55], v[110:113], v[92:95], v[52:55]
	v_mfma_f32_16x16x32_bf16 v[40:43], v[114:117], v[92:95], v[40:43]
	s_waitcnt lgkmcnt(3)
	v_mfma_f32_16x16x32_bf16 v[92:95], v[100:103], v[96:99], v[36:39]
	s_nop 2
	ds_read_b128 v[36:39], v128
	v_mfma_f32_16x16x32_bf16 v[100:103], v[106:109], v[96:99], v[8:11]
	v_mfma_f32_16x16x32_bf16 v[106:109], v[110:113], v[96:99], v[4:7]
	ds_read_b128 v[110:113], v128 offset:2048
	v_mfma_f32_16x16x32_bf16 v[96:99], v[114:117], v[96:99], v[0:3]
	ds_read_b128 v[114:117], v130 offset:16384
	s_waitcnt vmcnt(0)
	ds_write_b128 v87, v[12:15] offset:53248
	v_add_co_u32_e32 v46, vcc, s52, v44
	s_waitcnt vmcnt(1)
	ds_write_b128 v87, v[16:19] offset:49152
	s_nop 0
	v_addc_co_u32_e32 v47, vcc, 0, v45, vcc
	v_add_co_u32_e32 v44, vcc, s34, v44
	s_nop 0
	s_nop 0
	v_addc_co_u32_e32 v45, vcc, 0, v45, vcc
	s_waitcnt vmcnt(2)
	ds_write_b128 v87, v[20:23] offset:45056
	v_lshl_add_u64 v[44:45], v[82:83], 0, s[92:93]
	s_waitcnt vmcnt(5)
	ds_write_b128 v87, v[28:31] offset:32768
	s_waitcnt lgkmcnt(4)
	v_mfma_f32_16x16x32_bf16 v[0:3], v[114:117], v[36:39], v[76:79]
	v_mfma_f32_16x16x32_bf16 v[4:7], v[118:121], v[36:39], v[68:71]
	v_add_co_u32_e32 v44, vcc, s7, v44
	s_waitcnt vmcnt(4)
	ds_write_b128 v87, v[32:35] offset:36864
	s_nop 0
	v_addc_co_u32_e32 v45, vcc, 0, v45, vcc
	v_mfma_f32_16x16x32_bf16 v[8:11], v[122:125], v[36:39], v[52:55]
	v_mfma_f32_16x16x32_bf16 v[36:39], v[132:135], v[36:39], v[40:43]
	s_waitcnt vmcnt(3)
	ds_write_b128 v87, v[24:27] offset:40960
	v_mfma_f32_16x16x32_bf16 v[40:43], v[114:117], v[110:113], v[92:95]
	v_mfma_f32_16x16x32_bf16 v[52:55], v[118:121], v[110:113], v[100:103]
	v_mfma_f32_16x16x32_bf16 v[68:71], v[122:125], v[110:113], v[106:109]
	v_mfma_f32_16x16x32_bf16 v[76:79], v[132:135], v[110:113], v[96:99]
	s_waitcnt lgkmcnt(0)
	s_barrier
	ds_read_b128 v[100:103], v127 offset:49152
	ds_read_b128 v[106:109], v127 offset:51200
	ds_read_b128 v[110:113], v127 offset:53248
	ds_read_b128 v[114:117], v127 offset:55296
	ds_read_b128 v[92:95], v126 offset:32768
	ds_read_b128 v[96:99], v126 offset:34816
	s_min_u32 s3, s2, 60
	s_lshl_b32 s92, s3, 7
	ds_read_b128 v[118:121], v130 offset:51200
	ds_read_b128 v[122:125], v130 offset:53248
	ds_read_b128 v[132:135], v130 offset:55296
	s_waitcnt lgkmcnt(4)
	v_mfma_f32_16x16x32_bf16 v[0:3], v[100:103], v[92:95], v[0:3]
	v_lshl_add_u64 v[12:13], v[80:81], 0, s[92:93]
	v_add_co_u32_e32 v14, vcc, s7, v12
	v_mfma_f32_16x16x32_bf16 v[4:7], v[106:109], v[92:95], v[4:7]
	s_nop 0
	v_addc_co_u32_e32 v15, vcc, 0, v13, vcc
	v_mfma_f32_16x16x32_bf16 v[8:11], v[110:113], v[92:95], v[8:11]
	v_mfma_f32_16x16x32_bf16 v[36:39], v[114:117], v[92:95], v[36:39]
	s_waitcnt lgkmcnt(3)
	v_mfma_f32_16x16x32_bf16 v[92:95], v[100:103], v[96:99], v[40:43]
	s_nop 2
	ds_read_b128 v[40:43], v128 offset:32768
	v_mfma_f32_16x16x32_bf16 v[100:103], v[106:109], v[96:99], v[52:55]
	v_mfma_f32_16x16x32_bf16 v[106:109], v[110:113], v[96:99], v[68:71]
	ds_read_b128 v[110:113], v128 offset:34816
	v_mfma_f32_16x16x32_bf16 v[96:99], v[114:117], v[96:99], v[76:79]
	ds_read_b128 v[114:117], v130 offset:49152
	v_add_co_u32_e32 v14, vcc, s52, v12
	s_nop 0
	s_nop 0
	v_addc_co_u32_e32 v15, vcc, 0, v13, vcc
	v_add_co_u32_e32 v12, vcc, s34, v12
	s_nop 0
	s_nop 0
	v_addc_co_u32_e32 v13, vcc, 0, v13, vcc
	v_lshl_add_u64 v[12:13], v[82:83], 0, s[92:93]
	s_waitcnt lgkmcnt(0)
	v_mfma_f32_16x16x32_bf16 v[76:79], v[114:117], v[40:43], v[0:3]
	v_mfma_f32_16x16x32_bf16 v[68:71], v[118:121], v[40:43], v[4:7]
	v_add_co_u32_e32 v12, vcc, s7, v12
	s_nop 0
	s_nop 0
	v_addc_co_u32_e32 v13, vcc, 0, v13, vcc
	v_mfma_f32_16x16x32_bf16 v[52:55], v[122:125], v[40:43], v[8:11]
	v_mfma_f32_16x16x32_bf16 v[40:43], v[132:135], v[40:43], v[36:39]
	v_mfma_f32_16x16x32_bf16 v[36:39], v[114:117], v[110:113], v[92:95]
	v_mfma_f32_16x16x32_bf16 v[8:11], v[118:121], v[110:113], v[100:103]
	v_mfma_f32_16x16x32_bf16 v[4:7], v[122:125], v[110:113], v[106:109]
	v_mfma_f32_16x16x32_bf16 v[0:3], v[132:135], v[110:113], v[96:99]
	s_mov_b32 s3, s2
	s_waitcnt lgkmcnt(0)
	s_barrier
	v_readlane_b32 s2, v251, 18
	s_waitcnt vmcnt(1)
	s_nop 0
	v_add_u32_e32 v18, s2, v86
	v_readlane_b32 s2, v251, 19
	s_waitcnt vmcnt(0)
	v_add_u32_e32 v13, 0xffffe000, v18
	v_or_b32_e32 v12, v18, v85
	v_lshl_or_b32 v19, v84, 2, s2
	v_lshrrev_b32_e32 v13, 10, v13
	s_movk_i32 s2, 0x1800
	v_mad_u32_u24 v13, v13, s2, s2
	v_cmp_lt_i32_e32 vcc, s13, v12
	v_lshlrev_b32_e32 v128, 2, v19
	v_readlane_b32 s2, v250, 15
	v_cndmask_b32_e32 v14, 0, v13, vcc
	v_ashrrev_i32_e32 v15, 31, v14
	v_lshlrev_b64 v[24:25], 2, v[14:15]
	v_ashrrev_i32_e32 v13, 31, v12
	v_lshl_add_u64 v[14:15], s[38:39], 0, v[24:25]
	v_lshl_add_u64 v[48:49], v[14:15], 0, v[128:129]
	v_lshlrev_b64 v[14:15], 12, v[12:13]
	v_readlane_b32 s3, v250, 16
	v_lshl_add_u64 v[28:29], s[40:41], 0, v[24:25]
	v_lshlrev_b64 v[32:33], 11, v[12:13]
	v_lshl_add_u64 v[14:15], s[2:3], 0, v[14:15]
	v_lshl_add_u64 v[50:51], v[14:15], 0, v[128:129]
	global_load_dwordx4 v[72:75], v[48:49], off
	global_load_dwordx4 v[80:83], v[48:49], off offset:64
	global_load_dwordx4 v[88:91], v[48:49], off offset:128
	global_load_dwordx4 v[136:139], v[48:49], off offset:192
	global_load_dwordx4 v[194:197], v[50:51], off
	global_load_dwordx4 v[198:201], v[50:51], off offset:64
	global_load_dwordx4 v[202:205], v[50:51], off offset:128
	global_load_dwordx4 v[206:209], v[50:51], off offset:192
	v_add_co_u32_e32 v58, vcc, 0x10000, v50
	s_nop 1
	v_addc_co_u32_e32 v59, vcc, 0, v51, vcc
	global_load_dwordx4 v[210:213], v[58:59], off
	global_load_dwordx4 v[214:217], v[58:59], off offset:64
	global_load_dwordx4 v[218:221], v[58:59], off offset:128
	global_load_dwordx4 v[222:225], v[58:59], off offset:192
	v_readlane_b32 s2, v250, 21
	v_readlane_b32 s3, v250, 22
	v_cmp_eq_u32_e32 vcc, 0, v84
	s_waitcnt vmcnt(4)
	v_pk_fma_f32 v[22:23], v[78:79], v[74:75], v[196:197]
	v_pk_fma_f32 v[20:21], v[76:77], v[72:73], v[194:195]
	global_store_dwordx4 v[50:51], v[20:23], off
	v_lshl_add_u64 v[14:15], v[28:29], 0, v[128:129]
	global_load_dwordx4 v[140:143], v128, s[0:1]
	global_load_dwordx4 v[144:147], v128, s[0:1] offset:64
	global_load_dwordx4 v[148:151], v128, s[0:1] offset:128
	global_load_dwordx4 v[152:155], v128, s[0:1] offset:192
	global_load_dwordx4 v[156:159], v[14:15], off
	global_load_dwordx4 v[160:163], v[14:15], off offset:64
	global_load_dwordx4 v[180:183], v[14:15], off offset:128
	global_load_dwordx4 v[190:193], v[14:15], off offset:192
	v_lshlrev_b32_e32 v16, 1, v19
	v_mov_b32_e32 v17, v129
	v_lshl_add_u64 v[32:33], s[2:3], 0, v[32:33]
	v_lshl_add_u64 v[56:57], v[32:33], 0, v[16:17]
	s_waitcnt vmcnt(0)
	v_pk_mul_f32 v[26:27], v[22:23], v[142:143]
	v_pk_mul_f32 v[24:25], v[20:21], v[140:141]
	s_waitcnt vmcnt(0)
	v_pk_add_f32 v[30:31], v[158:159], 1.0 op_sel_hi:[1,0]
	v_pk_add_f32 v[28:29], v[156:157], 1.0 op_sel_hi:[1,0]
	v_pk_mul_f32 v[26:27], v[26:27], v[30:31]
	v_pk_mul_f32 v[24:25], v[24:25], v[28:29]
	v_and_b32_sdwa v19, v26, v170 dst_sel:DWORD dst_unused:UNUSED_PAD src0_sel:WORD_1 src1_sel:DWORD
	v_and_b32_sdwa v29, v27, v170 dst_sel:DWORD dst_unused:UNUSED_PAD src0_sel:WORD_1 src1_sel:DWORD
	v_and_b32_sdwa v30, v25, v170 dst_sel:DWORD dst_unused:UNUSED_PAD src0_sel:WORD_1 src1_sel:DWORD
	v_and_b32_sdwa v28, v24, v170 dst_sel:DWORD dst_unused:UNUSED_PAD src0_sel:WORD_1 src1_sel:DWORD
	v_add3_u32 v19, v26, v19, s56
	v_add3_u32 v26, v27, v29, s56
	v_add3_u32 v25, v25, v30, s56
	v_add3_u32 v24, v24, v28, s56
	v_and_b32_e32 v26, 0xffff0000, v26
	v_and_b32_e32 v27, 0xffff0000, v25
	v_or_b32_sdwa v25, v26, v19 dst_sel:DWORD dst_unused:UNUSED_PAD src0_sel:DWORD src1_sel:WORD_1
	v_or_b32_sdwa v24, v27, v24 dst_sel:DWORD dst_unused:UNUSED_PAD src0_sel:DWORD src1_sel:WORD_1
	global_store_dwordx2 v[56:57], v[24:25], off
	s_nop 0
	s_waitcnt vmcnt(0)
	v_pk_fma_f32 v[26:27], v[70:71], v[82:83], v[200:201]
	v_pk_fma_f32 v[24:25], v[68:69], v[80:81], v[198:199]
	global_store_dwordx4 v[50:51], v[24:27], off offset:64
	v_pk_mul_f32 v[30:31], v[26:27], v[146:147]
	v_pk_mul_f32 v[28:29], v[24:25], v[144:145]
	v_pk_add_f32 v[34:35], v[162:163], 1.0 op_sel_hi:[1,0]
	v_pk_add_f32 v[32:33], v[160:161], 1.0 op_sel_hi:[1,0]
	v_pk_mul_f32 v[30:31], v[30:31], v[34:35]
	v_pk_mul_f32 v[28:29], v[28:29], v[32:33]
	v_and_b32_sdwa v19, v30, v170 dst_sel:DWORD dst_unused:UNUSED_PAD src0_sel:WORD_1 src1_sel:DWORD
	v_and_b32_sdwa v33, v31, v170 dst_sel:DWORD dst_unused:UNUSED_PAD src0_sel:WORD_1 src1_sel:DWORD
	v_and_b32_sdwa v34, v29, v170 dst_sel:DWORD dst_unused:UNUSED_PAD src0_sel:WORD_1 src1_sel:DWORD
	v_and_b32_sdwa v32, v28, v170 dst_sel:DWORD dst_unused:UNUSED_PAD src0_sel:WORD_1 src1_sel:DWORD
	v_add3_u32 v19, v30, v19, s56
	v_add3_u32 v30, v31, v33, s56
	v_add3_u32 v29, v29, v34, s56
	v_add3_u32 v28, v28, v32, s56
	v_and_b32_e32 v30, 0xffff0000, v30
	v_and_b32_e32 v31, 0xffff0000, v29
	v_or_b32_sdwa v29, v30, v19 dst_sel:DWORD dst_unused:UNUSED_PAD src0_sel:DWORD src1_sel:WORD_1
	v_or_b32_sdwa v28, v31, v28 dst_sel:DWORD dst_unused:UNUSED_PAD src0_sel:DWORD src1_sel:WORD_1
	global_store_dwordx2 v[56:57], v[28:29], off offset:32
	s_nop 0
	v_pk_fma_f32 v[30:31], v[54:55], v[90:91], v[204:205]
	v_pk_fma_f32 v[28:29], v[52:53], v[88:89], v[202:203]
	global_store_dwordx4 v[50:51], v[28:31], off offset:128
	v_pk_mul_f32 v[34:35], v[30:31], v[150:151]
	v_pk_mul_f32 v[32:33], v[28:29], v[148:149]
	v_pk_add_f32 v[46:47], v[182:183], 1.0 op_sel_hi:[1,0]
	v_pk_add_f32 v[44:45], v[180:181], 1.0 op_sel_hi:[1,0]
	v_pk_mul_f32 v[34:35], v[34:35], v[46:47]
	v_pk_mul_f32 v[32:33], v[32:33], v[44:45]
	v_and_b32_sdwa v19, v34, v170 dst_sel:DWORD dst_unused:UNUSED_PAD src0_sel:WORD_1 src1_sel:DWORD
	v_and_b32_sdwa v45, v35, v170 dst_sel:DWORD dst_unused:UNUSED_PAD src0_sel:WORD_1 src1_sel:DWORD
	v_and_b32_sdwa v46, v33, v170 dst_sel:DWORD dst_unused:UNUSED_PAD src0_sel:WORD_1 src1_sel:DWORD
	v_and_b32_sdwa v44, v32, v170 dst_sel:DWORD dst_unused:UNUSED_PAD src0_sel:WORD_1 src1_sel:DWORD
	v_add3_u32 v19, v34, v19, s56
	v_add3_u32 v34, v35, v45, s56
	v_add3_u32 v33, v33, v46, s56
	v_add3_u32 v32, v32, v44, s56
	v_and_b32_e32 v34, 0xffff0000, v34
	v_and_b32_e32 v35, 0xffff0000, v33
	v_or_b32_sdwa v33, v34, v19 dst_sel:DWORD dst_unused:UNUSED_PAD src0_sel:DWORD src1_sel:WORD_1
	v_or_b32_sdwa v32, v35, v32 dst_sel:DWORD dst_unused:UNUSED_PAD src0_sel:DWORD src1_sel:WORD_1
	global_store_dwordx2 v[56:57], v[32:33], off offset:64
	s_nop 0
	v_pk_fma_f32 v[34:35], v[42:43], v[138:139], v[208:209]
	v_pk_fma_f32 v[32:33], v[40:41], v[136:137], v[206:207]
	global_store_dwordx4 v[50:51], v[32:35], off offset:192
	v_mul_f32_e32 v14, v21, v21
	v_mul_f32_e32 v15, v25, v25
	v_fmac_f32_e32 v14, v20, v20
	v_fmac_f32_e32 v15, v24, v24
	v_fmac_f32_e32 v14, v22, v22
	v_fmac_f32_e32 v15, v26, v26
	v_fmac_f32_e32 v14, v23, v23
	v_fmac_f32_e32 v15, v27, v27
	v_add_f32_e32 v14, v14, v15
	v_mul_f32_e32 v15, v29, v29
	v_fmac_f32_e32 v15, v28, v28
	v_fmac_f32_e32 v15, v30, v30
	v_fmac_f32_e32 v15, v31, v31
	v_add_f32_e32 v14, v14, v15
	v_mul_f32_e32 v15, v33, v33
	v_fmac_f32_e32 v15, v32, v32
	v_fmac_f32_e32 v15, v34, v34
	v_fmac_f32_e32 v15, v35, v35
	v_add_f32_e32 v14, v14, v15
	ds_bpermute_b32 v15, v105, v14
	s_waitcnt lgkmcnt(0)
	v_add_f32_e32 v14, v14, v15
	ds_bpermute_b32 v15, v104, v14
	v_pk_mul_f32 v[20:21], v[34:35], v[154:155]
	v_pk_mul_f32 v[22:23], v[32:33], v[152:153]
	v_pk_add_f32 v[24:25], v[192:193], 1.0 op_sel_hi:[1,0]
	v_pk_add_f32 v[26:27], v[190:191], 1.0 op_sel_hi:[1,0]
	v_pk_mul_f32 v[20:21], v[20:21], v[24:25]
	v_pk_mul_f32 v[22:23], v[22:23], v[26:27]
	v_and_b32_sdwa v19, v20, v170 dst_sel:DWORD dst_unused:UNUSED_PAD src0_sel:WORD_1 src1_sel:DWORD
	v_and_b32_sdwa v25, v21, v170 dst_sel:DWORD dst_unused:UNUSED_PAD src0_sel:WORD_1 src1_sel:DWORD
	v_and_b32_sdwa v26, v23, v170 dst_sel:DWORD dst_unused:UNUSED_PAD src0_sel:WORD_1 src1_sel:DWORD
	v_and_b32_sdwa v24, v22, v170 dst_sel:DWORD dst_unused:UNUSED_PAD src0_sel:WORD_1 src1_sel:DWORD
	v_add3_u32 v19, v20, v19, s56
	v_add3_u32 v20, v21, v25, s56
	v_add3_u32 v21, v23, v26, s56
	v_add3_u32 v22, v22, v24, s56
	v_and_b32_e32 v20, 0xffff0000, v20
	v_and_b32_e32 v23, 0xffff0000, v21
	v_or_b32_sdwa v21, v20, v19 dst_sel:DWORD dst_unused:UNUSED_PAD src0_sel:DWORD src1_sel:WORD_1
	v_or_b32_sdwa v20, v23, v22 dst_sel:DWORD dst_unused:UNUSED_PAD src0_sel:DWORD src1_sel:WORD_1
	global_store_dwordx2 v[56:57], v[20:21], off offset:96
	s_and_saveexec_b64 s[2:3], vcc
	s_cbranch_execz .LBB0_612
	v_readlane_b32 s16, v253, 20
	s_add_u32 s24, s26, s16
	s_addc_u32 s25, s27, 0
	v_lshl_add_u64 v[20:21], v[12:13], 2, s[24:25]
	s_waitcnt lgkmcnt(0)
	v_add_f32_e32 v13, v14, v15
	global_store_dword v[20:21], v13, off
.LBB0_612:
	s_or_b64 exec, exec, s[2:3]
	v_add_u32_e32 v13, 0xffffe010, v18
	s_waitcnt lgkmcnt(0)
	v_lshl_add_u64 v[14:15], s[0:1], 0, v[128:129]
	v_or_b32_e32 v12, 16, v12
	v_lshrrev_b32_e32 v13, 10, v13
	s_movk_i32 s0, 0x1800
	v_mad_u32_u24 v13, v13, s0, s0
	v_cmp_lt_i32_e64 s[0:1], s13, v12
	s_nop 1
	v_cndmask_b32_e64 v18, 0, v13, s[0:1]
	v_ashrrev_i32_e32 v19, 31, v18
	v_lshlrev_b64 v[34:35], 2, v[18:19]
	v_ashrrev_i32_e32 v13, 31, v12
	v_lshl_add_u64 v[18:19], s[38:39], 0, v[34:35]
	v_readlane_b32 s0, v250, 15
	v_lshl_add_u64 v[20:21], v[18:19], 0, v[128:129]
	v_lshlrev_b64 v[18:19], 12, v[12:13]
	v_readlane_b32 s1, v250, 16
	s_nop 0
	s_nop 0
	v_lshl_add_u64 v[18:19], s[0:1], 0, v[18:19]
	v_lshl_add_u64 v[18:19], v[18:19], 0, v[128:129]
	v_readlane_b32 s0, v250, 21
	v_readlane_b32 s1, v250, 22
	s_waitcnt vmcnt(16)
	v_pk_fma_f32 v[28:29], v[38:39], v[74:75], v[212:213]
	v_pk_fma_f32 v[26:27], v[36:37], v[72:73], v[210:211]
	v_lshl_add_u64 v[22:23], s[40:41], 0, v[34:35]
	global_store_dwordx4 v[18:19], v[26:29], off
	v_lshl_add_u64 v[22:23], v[22:23], 0, v[128:129]
	v_mul_f32_e32 v38, v27, v27
	v_fmac_f32_e32 v38, v26, v26
	v_fmac_f32_e32 v38, v28, v28
	v_fmac_f32_e32 v38, v29, v29
	v_pk_mul_f32 v[24:25], v[28:29], v[142:143]
	v_pk_add_f32 v[28:29], v[158:159], 1.0 op_sel_hi:[1,0]
	v_pk_mul_f32 v[26:27], v[26:27], v[140:141]
	v_pk_add_f32 v[30:31], v[156:157], 1.0 op_sel_hi:[1,0]
	v_pk_mul_f32 v[24:25], v[24:25], v[28:29]
	v_lshlrev_b64 v[28:29], 11, v[12:13]
	v_pk_mul_f32 v[26:27], v[26:27], v[30:31]
	v_lshl_add_u64 v[28:29], s[0:1], 0, v[28:29]
	v_lshl_add_u64 v[16:17], v[28:29], 0, v[16:17]
	v_cvt_pk_bf16_f32 v25, v24, v25
	v_cvt_pk_bf16_f32 v24, v26, v27
	global_store_dwordx2 v[16:17], v[24:25], off
	s_nop 0
	v_pk_fma_f32 v[8:9], v[8:9], v[80:81], v[214:215]
	s_nop 0
	v_mul_f32_e32 v24, v9, v9
	v_pk_fma_f32 v[10:11], v[10:11], v[82:83], v[216:217]
	v_fmac_f32_e32 v24, v8, v8
	v_fmac_f32_e32 v24, v10, v10
	global_store_dwordx4 v[18:19], v[8:11], off offset:64
	v_fmac_f32_e32 v24, v11, v11
	v_add_f32_e32 v32, v38, v24
	v_pk_mul_f32 v[10:11], v[10:11], v[146:147]
	v_pk_mul_f32 v[8:9], v[8:9], v[144:145]
	v_pk_add_f32 v[24:25], v[162:163], 1.0 op_sel_hi:[1,0]
	v_pk_add_f32 v[26:27], v[160:161], 1.0 op_sel_hi:[1,0]
	v_pk_mul_f32 v[10:11], v[10:11], v[24:25]
	v_pk_mul_f32 v[8:9], v[8:9], v[26:27]
	v_and_b32_sdwa v25, v8, v170 dst_sel:DWORD dst_unused:UNUSED_PAD src0_sel:WORD_1 src1_sel:DWORD
	v_add3_u32 v8, v8, v25, s56
	v_and_b32_sdwa v25, v9, v170 dst_sel:DWORD dst_unused:UNUSED_PAD src0_sel:WORD_1 src1_sel:DWORD
	v_add3_u32 v9, v9, v25, s56
	v_and_b32_e32 v24, 0xffff0000, v9
	v_cvt_pk_bf16_f32 v9, v10, v11
	v_or_b32_sdwa v8, v24, v8 dst_sel:DWORD dst_unused:UNUSED_PAD src0_sel:DWORD src1_sel:WORD_1
	global_store_dwordx2 v[16:17], v[8:9], off offset:32
	s_nop 0
	v_pk_fma_f32 v[4:5], v[4:5], v[88:89], v[218:219]
	s_nop 0
	v_mul_f32_e32 v8, v5, v5
	v_pk_fma_f32 v[6:7], v[6:7], v[90:91], v[220:221]
	v_fmac_f32_e32 v8, v4, v4
	v_fmac_f32_e32 v8, v6, v6
	global_store_dwordx4 v[18:19], v[4:7], off offset:128
	v_fmac_f32_e32 v8, v7, v7
	v_add_f32_e32 v28, v32, v8
	v_pk_mul_f32 v[6:7], v[6:7], v[150:151]
	v_pk_mul_f32 v[4:5], v[4:5], v[148:149]
	v_pk_add_f32 v[8:9], v[182:183], 1.0 op_sel_hi:[1,0]
	v_pk_add_f32 v[10:11], v[180:181], 1.0 op_sel_hi:[1,0]
	v_pk_mul_f32 v[6:7], v[6:7], v[8:9]
	v_pk_mul_f32 v[4:5], v[4:5], v[10:11]
	v_and_b32_sdwa v9, v4, v170 dst_sel:DWORD dst_unused:UNUSED_PAD src0_sel:WORD_1 src1_sel:DWORD
	v_add3_u32 v4, v4, v9, s56
	v_and_b32_sdwa v9, v5, v170 dst_sel:DWORD dst_unused:UNUSED_PAD src0_sel:WORD_1 src1_sel:DWORD
	v_add3_u32 v5, v5, v9, s56
	v_and_b32_e32 v8, 0xffff0000, v5
	v_cvt_pk_bf16_f32 v5, v6, v7
	v_or_b32_sdwa v4, v8, v4 dst_sel:DWORD dst_unused:UNUSED_PAD src0_sel:DWORD src1_sel:WORD_1
	global_store_dwordx2 v[16:17], v[4:5], off offset:64
	s_nop 0
	v_pk_fma_f32 v[0:1], v[0:1], v[136:137], v[222:223]
	s_nop 0
	v_mul_f32_e32 v4, v1, v1
	v_pk_fma_f32 v[2:3], v[2:3], v[138:139], v[224:225]
	v_fmac_f32_e32 v4, v0, v0
	v_fmac_f32_e32 v4, v2, v2
	global_store_dwordx4 v[18:19], v[0:3], off offset:192
	v_fmac_f32_e32 v4, v3, v3
	v_add_f32_e32 v18, v28, v4
	v_pk_mul_f32 v[2:3], v[2:3], v[154:155]
	v_pk_mul_f32 v[0:1], v[0:1], v[152:153]
	v_pk_add_f32 v[4:5], v[192:193], 1.0 op_sel_hi:[1,0]
	v_pk_add_f32 v[6:7], v[190:191], 1.0 op_sel_hi:[1,0]
	v_pk_mul_f32 v[2:3], v[2:3], v[4:5]
	v_pk_mul_f32 v[0:1], v[0:1], v[6:7]
	v_and_b32_sdwa v5, v0, v170 dst_sel:DWORD dst_unused:UNUSED_PAD src0_sel:WORD_1 src1_sel:DWORD
	v_add3_u32 v0, v0, v5, s56
	v_and_b32_sdwa v5, v1, v170 dst_sel:DWORD dst_unused:UNUSED_PAD src0_sel:WORD_1 src1_sel:DWORD
	v_add3_u32 v1, v1, v5, s56
	v_and_b32_e32 v4, 0xffff0000, v1
	v_cvt_pk_bf16_f32 v1, v2, v3
	v_or_b32_sdwa v0, v4, v0 dst_sel:DWORD dst_unused:UNUSED_PAD src0_sel:DWORD src1_sel:WORD_1
	global_store_dwordx2 v[16:17], v[0:1], off offset:96
	ds_bpermute_b32 v0, v105, v18
	s_waitcnt lgkmcnt(0)
	v_add_f32_e32 v0, v18, v0
	ds_bpermute_b32 v1, v104, v0
	s_and_saveexec_b64 s[0:1], vcc
	s_movk_i32 s89, 0xff
	s_cbranch_execz .LBB0_614
	v_readlane_b32 s2, v253, 20
	s_add_u32 s2, s26, s2
	s_addc_u32 s3, s27, 0
	v_lshl_add_u64 v[2:3], v[12:13], 2, s[2:3]
	s_waitcnt lgkmcnt(0)
	v_add_f32_e32 v0, v0, v1
	global_store_dword v[2:3], v0, off

.Ltail628:
	s_add_i32 s3, s24, 2
	v_add_u32_e32 v227, v144, v145
	ds_read_b128 v[36:39], v227 offset:16384
	ds_read_b128 v[40:43], v227 offset:18432
	ds_read_b128 v[44:47], v227 offset:20480
	ds_read_b128 v[48:51], v227 offset:22528
	v_add_u32_e32 v226, v143, v145
	ds_read_b128 v[16:19], v226
	v_add_u32_e32 v232, v144, v146
	s_add_i32 s24, s24, 4
	ds_read_b128 v[20:23], v226 offset:2048
	ds_read_b128 v[216:219], v232 offset:20480
	s_min_u32 s24, s24, 15
	s_lshl_b32 s92, s24, 7
	ds_read_b128 v[28:31], v226 offset:4096
	ds_read_b128 v[32:35], v226 offset:6144
	v_add_u32_e32 v228, v143, v146
	v_lshl_add_u64 v[224:225], v[138:139], 0, s[92:93]
	ds_read_b128 v[192:195], v228
	ds_read_b128 v[196:199], v228 offset:2048
	ds_read_b128 v[200:203], v228 offset:4096
	ds_read_b128 v[204:207], v228 offset:6144
	ds_read_b128 v[208:211], v232 offset:16384
	ds_read_b128 v[212:215], v232 offset:18432
	ds_read_b128 v[220:223], v232 offset:22528
	s_waitcnt lgkmcnt(11)
	v_mfma_f32_16x16x32_bf16 v[92:95], v[36:39], v[16:19], v[92:95]
	v_mfma_f32_16x16x32_bf16 v[88:91], v[40:43], v[16:19], v[88:91]
	v_mfma_f32_16x16x32_bf16 v[84:87], v[44:47], v[16:19], v[84:87]
	v_mfma_f32_16x16x32_bf16 v[16:19], v[48:51], v[16:19], v[80:83]
	s_nop 2
	s_waitcnt vmcnt(7)
	ds_write_b128 v156, v[96:99] offset:32768
	v_add_co_u32_e32 v96, vcc, s11, v224
	s_waitcnt lgkmcnt(11)
	v_mfma_f32_16x16x32_bf16 v[76:79], v[36:39], v[20:23], v[76:79]
	v_addc_co_u32_e32 v97, vcc, 0, v225, vcc
	v_mfma_f32_16x16x32_bf16 v[72:75], v[40:43], v[20:23], v[72:75]
	v_mfma_f32_16x16x32_bf16 v[68:71], v[44:47], v[20:23], v[68:71]
	v_mfma_f32_16x16x32_bf16 v[20:23], v[48:51], v[20:23], v[64:67]
	s_nop 2
	v_add_co_u32_e32 v96, vcc, s33, v224
	s_waitcnt vmcnt(6)
	ds_write_b128 v156, v[100:103] offset:36864
	s_nop 0
	v_addc_co_u32_e32 v97, vcc, 0, v225, vcc
	s_waitcnt lgkmcnt(10)
	v_mfma_f32_16x16x32_bf16 v[60:63], v[36:39], v[28:31], v[60:63]
	v_mfma_f32_16x16x32_bf16 v[56:59], v[40:43], v[28:31], v[56:59]
	v_mfma_f32_16x16x32_bf16 v[52:55], v[44:47], v[28:31], v[52:55]
	v_mfma_f32_16x16x32_bf16 v[24:27], v[48:51], v[28:31], v[24:27]
	s_waitcnt vmcnt(5)
	ds_write_b128 v156, v[104:107] offset:40960
	s_waitcnt lgkmcnt(10)
	v_mfma_f32_16x16x32_bf16 v[12:15], v[36:39], v[32:35], v[12:15]
	v_add_co_u32_e32 v36, vcc, s59, v224
	s_nop 1
	v_addc_co_u32_e32 v37, vcc, 0, v225, vcc
	v_mfma_f32_16x16x32_bf16 v[8:11], v[40:43], v[32:35], v[8:11]
	v_mfma_f32_16x16x32_bf16 v[4:7], v[44:47], v[32:35], v[4:7]
	v_mfma_f32_16x16x32_bf16 v[0:3], v[48:51], v[32:35], v[0:3]
	s_waitcnt vmcnt(4)
	ds_write_b128 v156, v[112:115] offset:45056
	s_waitcnt lgkmcnt(10)
	v_mfma_f32_16x16x32_bf16 v[44:47], v[216:219], v[192:195], v[84:87]
	s_nop 2
	v_lshl_add_u64 v[84:85], v[140:141], 0, s[92:93]
	v_add_co_u32_e32 v86, vcc, s11, v84
	s_waitcnt lgkmcnt(6)
	v_mfma_f32_16x16x32_bf16 v[36:39], v[208:211], v[192:195], v[92:95]
	v_addc_co_u32_e32 v87, vcc, 0, v85, vcc
	s_waitcnt lgkmcnt(5)
	v_mfma_f32_16x16x32_bf16 v[40:43], v[212:215], v[192:195], v[88:91]
	s_waitcnt lgkmcnt(4)
	v_mfma_f32_16x16x32_bf16 v[16:19], v[220:223], v[192:195], v[16:19]
	s_waitcnt vmcnt(3)
	ds_write_b128 v156, v[108:111] offset:49152
	v_mfma_f32_16x16x32_bf16 v[76:79], v[208:211], v[196:199], v[76:79]
	v_mfma_f32_16x16x32_bf16 v[72:75], v[212:215], v[196:199], v[72:75]
	v_mfma_f32_16x16x32_bf16 v[68:71], v[216:219], v[196:199], v[68:71]
	v_mfma_f32_16x16x32_bf16 v[20:23], v[220:223], v[196:199], v[20:23]
	v_add_co_u32_e32 v86, vcc, s33, v84
	s_waitcnt vmcnt(2)
	ds_write_b128 v156, v[116:119] offset:53248
	v_addc_co_u32_e32 v87, vcc, 0, v85, vcc
	v_add_co_u32_e32 v84, vcc, s59, v84
	v_mfma_f32_16x16x32_bf16 v[60:63], v[208:211], v[200:203], v[60:63]
	s_nop 0
	v_addc_co_u32_e32 v85, vcc, 0, v85, vcc
	v_mfma_f32_16x16x32_bf16 v[56:59], v[212:215], v[200:203], v[56:59]
	v_mfma_f32_16x16x32_bf16 v[52:55], v[216:219], v[200:203], v[52:55]
	v_mfma_f32_16x16x32_bf16 v[24:27], v[220:223], v[200:203], v[24:27]
	s_waitcnt vmcnt(1)
	ds_write_b128 v156, v[120:123] offset:57344
	v_mfma_f32_16x16x32_bf16 v[12:15], v[208:211], v[204:207], v[12:15]
	v_mfma_f32_16x16x32_bf16 v[8:11], v[212:215], v[204:207], v[8:11]
	v_mfma_f32_16x16x32_bf16 v[4:7], v[216:219], v[204:207], v[4:7]
	v_mfma_f32_16x16x32_bf16 v[0:3], v[220:223], v[204:207], v[0:3]
	s_waitcnt vmcnt(0)
	ds_write_b128 v156, v[124:127] offset:61440
	s_waitcnt lgkmcnt(0)
	s_barrier
	ds_read_b128 v[112:115], v227 offset:49152
	ds_read_b128 v[116:119], v227 offset:51200
	ds_read_b128 v[120:123], v227 offset:53248
	ds_read_b128 v[124:127], v227 offset:55296
	ds_read_b128 v[84:87], v226 offset:32768
	ds_read_b128 v[88:91], v226 offset:34816
	ds_read_b128 v[92:95], v226 offset:36864
	ds_read_b128 v[108:111], v226 offset:38912
	ds_read_b128 v[204:207], v228 offset:32768
	ds_read_b128 v[208:211], v228 offset:34816
	ds_read_b128 v[212:215], v228 offset:36864
	ds_read_b128 v[216:219], v228 offset:38912
	ds_read_b128 v[220:223], v232 offset:49152
	ds_read_b128 v[224:227], v232 offset:51200
	ds_read_b128 v[228:231], v232 offset:53248
	ds_read_b128 v[232:235], v232 offset:55296
	s_min_u32 s24, s3, 12
	s_lshl_b32 s92, s24, 7
	s_waitcnt lgkmcnt(11)
	v_mfma_f32_16x16x32_bf16 v[36:39], v[112:115], v[84:87], v[36:39]
	v_mfma_f32_16x16x32_bf16 v[40:43], v[116:119], v[84:87], v[40:43]
	v_mfma_f32_16x16x32_bf16 v[44:47], v[120:123], v[84:87], v[44:47]
	v_mfma_f32_16x16x32_bf16 v[16:19], v[124:127], v[84:87], v[16:19]
	v_lshl_add_u64 v[84:85], v[138:139], 0, s[92:93]
	v_add_co_u32_e32 v80, vcc, s11, v84
	s_waitcnt lgkmcnt(10)
	v_mfma_f32_16x16x32_bf16 v[76:79], v[112:115], v[88:91], v[76:79]
	v_addc_co_u32_e32 v81, vcc, 0, v85, vcc
	v_mfma_f32_16x16x32_bf16 v[72:75], v[116:119], v[88:91], v[72:75]
	v_mfma_f32_16x16x32_bf16 v[68:71], v[120:123], v[88:91], v[68:71]
	v_mfma_f32_16x16x32_bf16 v[20:23], v[124:127], v[88:91], v[20:23]
	v_add_co_u32_e32 v64, vcc, s33, v84
	s_waitcnt lgkmcnt(9)
	v_mfma_f32_16x16x32_bf16 v[60:63], v[112:115], v[92:95], v[60:63]
	v_addc_co_u32_e32 v65, vcc, 0, v85, vcc
	v_mfma_f32_16x16x32_bf16 v[56:59], v[116:119], v[92:95], v[56:59]
	v_mfma_f32_16x16x32_bf16 v[52:55], v[120:123], v[92:95], v[52:55]
	v_mfma_f32_16x16x32_bf16 v[24:27], v[124:127], v[92:95], v[24:27]
	v_add_co_u32_e32 v28, vcc, s59, v84
	s_waitcnt lgkmcnt(8)
	v_mfma_f32_16x16x32_bf16 v[12:15], v[112:115], v[108:111], v[12:15]
	v_addc_co_u32_e32 v29, vcc, 0, v85, vcc
	v_mfma_f32_16x16x32_bf16 v[8:11], v[116:119], v[108:111], v[8:11]
	v_mfma_f32_16x16x32_bf16 v[4:7], v[120:123], v[108:111], v[4:7]
	v_mfma_f32_16x16x32_bf16 v[0:3], v[124:127], v[108:111], v[0:3]
	s_waitcnt lgkmcnt(0)
	v_mfma_f32_16x16x32_bf16 v[80:83], v[232:235], v[204:207], v[16:19]
	s_nop 2
	v_lshl_add_u64 v[16:17], v[140:141], 0, s[92:93]
	v_add_co_u32_e32 v18, vcc, s11, v16
	v_mfma_f32_16x16x32_bf16 v[92:95], v[220:223], v[204:207], v[36:39]
	s_nop 0
	v_addc_co_u32_e32 v19, vcc, 0, v17, vcc
	v_mfma_f32_16x16x32_bf16 v[88:91], v[224:227], v[204:207], v[40:43]
	v_mfma_f32_16x16x32_bf16 v[84:87], v[228:231], v[204:207], v[44:47]
	v_mfma_f32_16x16x32_bf16 v[76:79], v[220:223], v[208:211], v[76:79]
	v_mfma_f32_16x16x32_bf16 v[72:75], v[224:227], v[208:211], v[72:75]
	v_mfma_f32_16x16x32_bf16 v[68:71], v[228:231], v[208:211], v[68:71]
	v_mfma_f32_16x16x32_bf16 v[64:67], v[232:235], v[208:211], v[20:23]
	v_add_co_u32_e32 v18, vcc, s33, v16
	s_nop 1
	v_addc_co_u32_e32 v19, vcc, 0, v17, vcc
	v_add_co_u32_e32 v16, vcc, s59, v16
	v_mfma_f32_16x16x32_bf16 v[60:63], v[220:223], v[212:215], v[60:63]
	s_nop 0
	v_addc_co_u32_e32 v17, vcc, 0, v17, vcc
	v_mfma_f32_16x16x32_bf16 v[56:59], v[224:227], v[212:215], v[56:59]
	v_mfma_f32_16x16x32_bf16 v[52:55], v[228:231], v[212:215], v[52:55]
	v_mfma_f32_16x16x32_bf16 v[24:27], v[232:235], v[212:215], v[24:27]
	v_mfma_f32_16x16x32_bf16 v[12:15], v[220:223], v[216:219], v[12:15]
	v_mfma_f32_16x16x32_bf16 v[8:11], v[224:227], v[216:219], v[8:11]
	v_mfma_f32_16x16x32_bf16 v[4:7], v[228:231], v[216:219], v[4:7]
	v_mfma_f32_16x16x32_bf16 v[0:3], v[232:235], v[216:219], v[0:3]
	s_mov_b32 s24, s3
	s_waitcnt lgkmcnt(0)
	s_barrier
	s_and_saveexec_b64 s[24:25], s[36:37]
	s_cbranch_execz .LBB0_631
	v_add_f32_e32 v16, 0, v128
	v_add_f32_e32 v16, v16, v157
	v_add_f32_e32 v16, v16, v158
	v_add_f32_e32 v16, v16, v159
	v_add_f32_e32 v16, v16, v160
	v_add_f32_e32 v16, v16, v161
	v_add_f32_e32 v16, v16, v162
	v_add_f32_e32 v16, v16, v163
	v_add_f32_e32 v16, v16, v164
	v_add_f32_e32 v16, v16, v165
	v_add_f32_e32 v16, v16, v168
	v_add_f32_e32 v16, v16, v175
	v_add_f32_e32 v16, v16, v179
	v_add_f32_e32 v16, v16, v183
	v_add_f32_e32 v16, v16, v190
	v_add_f32_e32 v16, v16, v191
	v_fmamk_f32 v16, v16, 0x3a800000, v167
	s_mov_b32 s3, 0x800000
	v_mul_f32_e32 v17, 0x4b800000, v16
	v_cmp_gt_f32_e32 vcc, s3, v16
	s_nop 1
	v_cndmask_b32_e32 v16, v16, v17, vcc
	v_rsq_f32_e32 v16, v16
	s_nop 0
	v_mul_f32_e32 v17, 0x45800000, v16
	v_cndmask_b32_e32 v16, v16, v17, vcc
	ds_write_b32 v155, v16

.Ltail666:
	s_add_i32 s2, s3, 2
	v_add_u32_e32 v123, v111, v126
	ds_read_b128 v[154:157], v123 offset:16384
	ds_read_b128 v[158:161], v123 offset:18432
	ds_read_b128 v[162:165], v123 offset:20480
	ds_read_b128 v[190:193], v123 offset:22528
	v_add_u32_e32 v122, v110, v126
	ds_read_b128 v[138:141], v122
	ds_read_b128 v[142:145], v122 offset:2048
	v_add_u32_e32 v125, v111, v137
	s_add_i32 s3, s3, 4
	ds_read_b128 v[146:149], v122 offset:4096
	ds_read_b128 v[214:217], v125 offset:18432
	s_min_u32 s3, s3, 15
	ds_read_b128 v[210:213], v125 offset:16384
	ds_read_b128 v[218:221], v125 offset:20480
	ds_read_b128 v[222:225], v125 offset:22528
	s_lshl_b32 s92, s3, 7
	v_add_u32_e32 v124, v110, v137
	v_lshl_add_u64 v[226:227], v[102:103], 0, s[92:93]
	ds_read_b128 v[150:153], v122 offset:6144
	ds_read_b128 v[194:197], v124
	ds_read_b128 v[198:201], v124 offset:2048
	ds_read_b128 v[202:205], v124 offset:4096
	ds_read_b128 v[206:209], v124 offset:6144
	s_waitcnt lgkmcnt(11)
	v_mfma_f32_16x16x32_bf16 v[92:95], v[154:157], v[138:141], v[92:95]
	v_mfma_f32_16x16x32_bf16 v[88:91], v[158:161], v[138:141], v[88:91]
	v_mfma_f32_16x16x32_bf16 v[84:87], v[162:165], v[138:141], v[84:87]
	v_mfma_f32_16x16x32_bf16 v[80:83], v[190:193], v[138:141], v[80:83]
	s_waitcnt vmcnt(7)
	ds_write_b128 v121, v[28:31] offset:32768
	s_waitcnt lgkmcnt(11)
	v_mfma_f32_16x16x32_bf16 v[28:31], v[154:157], v[142:145], v[76:79]
	s_nop 2
	v_add_co_u32_e32 v76, vcc, s11, v226
	v_mfma_f32_16x16x32_bf16 v[72:75], v[158:161], v[142:145], v[72:75]
	s_nop 0
	v_addc_co_u32_e32 v77, vcc, 0, v227, vcc
	v_mfma_f32_16x16x32_bf16 v[68:71], v[162:165], v[142:145], v[68:71]
	v_mfma_f32_16x16x32_bf16 v[64:67], v[190:193], v[142:145], v[64:67]
	s_waitcnt vmcnt(6)
	ds_write_b128 v121, v[32:35] offset:36864
	s_waitcnt lgkmcnt(11)
	v_mfma_f32_16x16x32_bf16 v[32:35], v[154:157], v[146:149], v[48:51]
	s_nop 2
	v_add_co_u32_e32 v48, vcc, s33, v226
	v_mfma_f32_16x16x32_bf16 v[24:27], v[158:161], v[146:149], v[24:27]
	s_nop 0
	v_addc_co_u32_e32 v49, vcc, 0, v227, vcc
	v_mfma_f32_16x16x32_bf16 v[20:23], v[162:165], v[146:149], v[20:23]
	v_mfma_f32_16x16x32_bf16 v[16:19], v[190:193], v[146:149], v[16:19]
	s_waitcnt vmcnt(5)
	ds_write_b128 v121, v[36:39] offset:40960
	v_add_co_u32_e32 v36, vcc, s59, v226
	s_waitcnt lgkmcnt(7)
	v_mfma_f32_16x16x32_bf16 v[12:15], v[154:157], v[150:153], v[12:15]
	v_addc_co_u32_e32 v37, vcc, 0, v227, vcc
	v_mfma_f32_16x16x32_bf16 v[8:11], v[158:161], v[150:153], v[8:11]
	v_mfma_f32_16x16x32_bf16 v[4:7], v[162:165], v[150:153], v[4:7]
	v_mfma_f32_16x16x32_bf16 v[0:3], v[190:193], v[150:153], v[0:3]
	s_waitcnt vmcnt(4)
	ds_write_b128 v121, v[44:47] offset:45056
	s_waitcnt lgkmcnt(7)
	v_mfma_f32_16x16x32_bf16 v[44:47], v[214:217], v[194:197], v[88:91]
	s_nop 2
	v_lshl_add_u64 v[88:89], v[104:105], 0, s[92:93]
	v_mfma_f32_16x16x32_bf16 v[36:39], v[210:213], v[194:197], v[92:95]
	v_mfma_f32_16x16x32_bf16 v[84:87], v[218:221], v[194:197], v[84:87]
	v_mfma_f32_16x16x32_bf16 v[80:83], v[222:225], v[194:197], v[80:83]
	s_waitcnt vmcnt(3)
	ds_write_b128 v121, v[40:43] offset:49152
	s_waitcnt lgkmcnt(7)
	v_mfma_f32_16x16x32_bf16 v[40:43], v[210:213], v[198:201], v[28:31]
	s_nop 2
	v_add_co_u32_e32 v28, vcc, s11, v88
	v_mfma_f32_16x16x32_bf16 v[72:75], v[214:217], v[198:201], v[72:75]
	s_nop 0
	v_addc_co_u32_e32 v29, vcc, 0, v89, vcc
	v_mfma_f32_16x16x32_bf16 v[68:71], v[218:221], v[198:201], v[68:71]
	v_mfma_f32_16x16x32_bf16 v[64:67], v[222:225], v[198:201], v[64:67]
	v_add_co_u32_e32 v28, vcc, s33, v88
	s_waitcnt vmcnt(2)
	ds_write_b128 v121, v[52:55] offset:53248
	v_addc_co_u32_e32 v29, vcc, 0, v89, vcc
	s_waitcnt lgkmcnt(7)
	v_mfma_f32_16x16x32_bf16 v[52:55], v[210:213], v[202:205], v[32:35]
	v_mfma_f32_16x16x32_bf16 v[24:27], v[214:217], v[202:205], v[24:27]
	v_mfma_f32_16x16x32_bf16 v[20:23], v[218:221], v[202:205], v[20:23]
	v_mfma_f32_16x16x32_bf16 v[16:19], v[222:225], v[202:205], v[16:19]
	v_add_co_u32_e32 v28, vcc, s59, v88
	s_waitcnt vmcnt(1)
	ds_write_b128 v121, v[56:59] offset:57344
	v_addc_co_u32_e32 v29, vcc, 0, v89, vcc
	s_waitcnt lgkmcnt(7)
	v_mfma_f32_16x16x32_bf16 v[12:15], v[210:213], v[206:209], v[12:15]
	v_mfma_f32_16x16x32_bf16 v[8:11], v[214:217], v[206:209], v[8:11]
	v_mfma_f32_16x16x32_bf16 v[4:7], v[218:221], v[206:209], v[4:7]
	v_mfma_f32_16x16x32_bf16 v[0:3], v[222:225], v[206:209], v[0:3]
	s_waitcnt vmcnt(0)
	ds_write_b128 v121, v[60:63] offset:61440
	s_waitcnt lgkmcnt(0)
	s_barrier
	ds_read_b128 v[92:95], v123 offset:51200
	ds_read_b128 v[88:91], v123 offset:49152
	ds_read_b128 v[162:165], v123 offset:53248
	ds_read_b128 v[190:193], v123 offset:55296
	ds_read_b128 v[28:31], v122 offset:32768
	ds_read_b128 v[32:35], v122 offset:34816
	s_min_u32 s3, s2, 12
	s_lshl_b32 s92, s3, 7
	ds_read_b128 v[56:59], v122 offset:36864
	ds_read_b128 v[60:63], v122 offset:38912
	ds_read_b128 v[194:197], v124 offset:32768
	ds_read_b128 v[198:201], v124 offset:34816
	ds_read_b128 v[202:205], v124 offset:36864
	ds_read_b128 v[206:209], v124 offset:38912
	ds_read_b128 v[210:213], v125 offset:49152
	ds_read_b128 v[214:217], v125 offset:51200
	ds_read_b128 v[218:221], v125 offset:53248
	ds_read_b128 v[222:225], v125 offset:55296
	s_waitcnt lgkmcnt(11)
	v_mfma_f32_16x16x32_bf16 v[230:233], v[92:95], v[28:31], v[44:47]
	v_mfma_f32_16x16x32_bf16 v[226:229], v[88:91], v[28:31], v[36:39]
	s_nop 1
	v_lshl_add_u64 v[44:45], v[102:103], 0, s[92:93]
	v_add_co_u32_e32 v36, vcc, s11, v44
	v_mfma_f32_16x16x32_bf16 v[84:87], v[162:165], v[28:31], v[84:87]
	s_nop 0
	v_addc_co_u32_e32 v37, vcc, 0, v45, vcc
	v_mfma_f32_16x16x32_bf16 v[80:83], v[190:193], v[28:31], v[80:83]
	s_waitcnt lgkmcnt(10)
	v_mfma_f32_16x16x32_bf16 v[138:141], v[88:91], v[32:35], v[40:43]
	v_mfma_f32_16x16x32_bf16 v[72:75], v[92:95], v[32:35], v[72:75]
	v_mfma_f32_16x16x32_bf16 v[68:71], v[162:165], v[32:35], v[68:71]
	v_mfma_f32_16x16x32_bf16 v[64:67], v[190:193], v[32:35], v[64:67]
	v_add_co_u32_e32 v36, vcc, s33, v44
	s_nop 1
	v_addc_co_u32_e32 v37, vcc, 0, v45, vcc
	v_add_co_u32_e32 v40, vcc, s59, v44
	s_waitcnt lgkmcnt(9)
	v_mfma_f32_16x16x32_bf16 v[234:237], v[88:91], v[56:59], v[52:55]
	v_addc_co_u32_e32 v41, vcc, 0, v45, vcc
	v_mfma_f32_16x16x32_bf16 v[24:27], v[92:95], v[56:59], v[24:27]
	v_mfma_f32_16x16x32_bf16 v[20:23], v[162:165], v[56:59], v[20:23]
	v_mfma_f32_16x16x32_bf16 v[16:19], v[190:193], v[56:59], v[16:19]
	s_waitcnt lgkmcnt(8)
	v_mfma_f32_16x16x32_bf16 v[12:15], v[88:91], v[60:63], v[12:15]
	v_mfma_f32_16x16x32_bf16 v[8:11], v[92:95], v[60:63], v[8:11]
	v_mfma_f32_16x16x32_bf16 v[4:7], v[162:165], v[60:63], v[4:7]
	v_mfma_f32_16x16x32_bf16 v[0:3], v[190:193], v[60:63], v[0:3]
	v_lshl_add_u64 v[60:61], v[104:105], 0, s[92:93]
	v_add_co_u32_e32 v48, vcc, s11, v60
	s_nop 0
	s_nop 0
	v_addc_co_u32_e32 v49, vcc, 0, v61, vcc
	v_add_co_u32_e32 v56, vcc, s33, v60
	s_nop 1
	v_addc_co_u32_e32 v57, vcc, 0, v61, vcc
	s_waitcnt lgkmcnt(3)
	v_mfma_f32_16x16x32_bf16 v[92:95], v[210:213], v[194:197], v[226:229]
	s_waitcnt lgkmcnt(2)
	v_mfma_f32_16x16x32_bf16 v[88:91], v[214:217], v[194:197], v[230:233]
	s_waitcnt lgkmcnt(1)
	v_mfma_f32_16x16x32_bf16 v[84:87], v[218:221], v[194:197], v[84:87]
	s_waitcnt lgkmcnt(0)
	v_mfma_f32_16x16x32_bf16 v[80:83], v[222:225], v[194:197], v[80:83]
	v_add_co_u32_e32 v60, vcc, s59, v60
	s_nop 1
	v_addc_co_u32_e32 v61, vcc, 0, v61, vcc
	v_mfma_f32_16x16x32_bf16 v[76:79], v[210:213], v[198:201], v[138:141]
	v_mfma_f32_16x16x32_bf16 v[72:75], v[214:217], v[198:201], v[72:75]
	v_mfma_f32_16x16x32_bf16 v[68:71], v[218:221], v[198:201], v[68:71]
	v_mfma_f32_16x16x32_bf16 v[64:67], v[222:225], v[198:201], v[64:67]
	v_mfma_f32_16x16x32_bf16 v[48:51], v[210:213], v[202:205], v[234:237]
	v_mfma_f32_16x16x32_bf16 v[24:27], v[214:217], v[202:205], v[24:27]
	v_mfma_f32_16x16x32_bf16 v[20:23], v[218:221], v[202:205], v[20:23]
	v_mfma_f32_16x16x32_bf16 v[16:19], v[222:225], v[202:205], v[16:19]
	v_mfma_f32_16x16x32_bf16 v[12:15], v[210:213], v[206:209], v[12:15]
	v_mfma_f32_16x16x32_bf16 v[8:11], v[214:217], v[206:209], v[8:11]
	v_mfma_f32_16x16x32_bf16 v[4:7], v[218:221], v[206:209], v[4:7]
	v_mfma_f32_16x16x32_bf16 v[0:3], v[222:225], v[206:209], v[0:3]
	s_mov_b32 s3, s2
	s_waitcnt lgkmcnt(0)
	s_barrier
	s_movk_i32 s2, 0x80
	v_cmp_gt_i32_e64 s[36:37], s2, v109
	s_add_i32 s2, 0, 0x10000
	v_lshl_add_u32 v126, v109, 2, s2
	s_and_saveexec_b64 s[2:3], s[36:37]
	v_readlane_b32 s16, v251, 44
	v_readlane_b32 s17, v251, 45
	s_cbranch_execz .LBB0_669
	s_waitcnt vmcnt(7)
	v_add_f32_e32 v28, 0, v112
	v_add_f32_e32 v28, v28, v113
	v_add_f32_e32 v28, v28, v114
	v_add_f32_e32 v28, v28, v115
	v_add_f32_e32 v28, v28, v116
	v_add_f32_e32 v28, v28, v117
	v_add_f32_e32 v28, v28, v118
	v_add_f32_e32 v28, v28, v119
	v_add_f32_e32 v28, v28, v127
	v_add_f32_e32 v28, v28, v128
	v_add_f32_e32 v28, v28, v130
	v_add_f32_e32 v28, v28, v132
	v_add_f32_e32 v28, v28, v133
	v_add_f32_e32 v28, v28, v134
	v_add_f32_e32 v28, v28, v135
	v_add_f32_e32 v28, v28, v136
	v_fmamk_f32 v28, v28, 0x3a800000, v167
	s_mov_b32 s21, 0x800000
	v_mul_f32_e32 v29, 0x4b800000, v28
	v_cmp_gt_f32_e32 vcc, s21, v28
	s_nop 1
	v_cndmask_b32_e32 v28, v28, v29, vcc
	v_rsq_f32_e32 v28, v28
	s_nop 0
	v_mul_f32_e32 v29, 0x45800000, v28
	v_cndmask_b32_e32 v28, v28, v29, vcc
	ds_write_b32 v126, v28

.Ltail702:
	s_add_i32 s2, s3, 2
	ds_read_b128 v[152:155], v123 offset:16384
	ds_read_b128 v[156:159], v123 offset:18432
	ds_read_b128 v[160:163], v123 offset:20480
	ds_read_b128 v[190:193], v123 offset:22528
	ds_read_b128 v[102:105], v122
	s_add_i32 s3, s3, 4
	ds_read_b128 v[140:143], v122 offset:2048
	s_min_u32 s3, s3, 15
	s_lshl_b32 s92, s3, 7
	ds_read_b128 v[144:147], v122 offset:4096
	v_lshl_add_u64 v[106:107], v[98:99], 0, s[92:93]
	ds_read_b128 v[148:151], v122 offset:6144
	ds_read_b128 v[194:197], v124
	ds_read_b128 v[198:201], v124 offset:2048
	ds_read_b128 v[202:205], v124 offset:4096
	ds_read_b128 v[206:209], v124 offset:6144
	ds_read_b128 v[210:213], v125 offset:16384
	ds_read_b128 v[214:217], v125 offset:18432
	ds_read_b128 v[218:221], v125 offset:20480
	ds_read_b128 v[222:225], v125 offset:22528
	s_waitcnt lgkmcnt(11)
	v_mfma_f32_16x16x32_bf16 v[60:63], v[152:155], v[102:105], v[60:63]
	v_mfma_f32_16x16x32_bf16 v[56:59], v[156:159], v[102:105], v[56:59]
	v_mfma_f32_16x16x32_bf16 v[52:55], v[160:163], v[102:105], v[52:55]
	v_mfma_f32_16x16x32_bf16 v[48:51], v[190:193], v[102:105], v[48:51]
	s_waitcnt vmcnt(7)
	ds_write_b128 v121, v[64:67] offset:32768
	v_add_co_u32_e32 v64, vcc, s11, v106
	s_waitcnt lgkmcnt(11)
	v_mfma_f32_16x16x32_bf16 v[44:47], v[152:155], v[140:143], v[44:47]
	v_addc_co_u32_e32 v65, vcc, 0, v107, vcc
	v_mfma_f32_16x16x32_bf16 v[40:43], v[156:159], v[140:143], v[40:43]
	v_mfma_f32_16x16x32_bf16 v[36:39], v[160:163], v[140:143], v[36:39]
	v_mfma_f32_16x16x32_bf16 v[32:35], v[190:193], v[140:143], v[32:35]
	v_add_co_u32_e32 v64, vcc, s33, v106
	s_waitcnt vmcnt(6)
	ds_write_b128 v121, v[68:71] offset:36864
	s_nop 0
	v_addc_co_u32_e32 v65, vcc, 0, v107, vcc
	s_waitcnt lgkmcnt(11)
	v_mfma_f32_16x16x32_bf16 v[28:31], v[152:155], v[144:147], v[28:31]
	v_mfma_f32_16x16x32_bf16 v[24:27], v[156:159], v[144:147], v[24:27]
	v_mfma_f32_16x16x32_bf16 v[20:23], v[160:163], v[144:147], v[20:23]
	v_mfma_f32_16x16x32_bf16 v[16:19], v[190:193], v[144:147], v[16:19]
	v_add_co_u32_e32 v64, vcc, s59, v106
	s_waitcnt vmcnt(5)
	ds_write_b128 v121, v[72:75] offset:40960
	s_nop 0
	v_addc_co_u32_e32 v65, vcc, 0, v107, vcc
	s_waitcnt lgkmcnt(11)
	v_mfma_f32_16x16x32_bf16 v[12:15], v[152:155], v[148:151], v[12:15]
	v_mfma_f32_16x16x32_bf16 v[8:11], v[156:159], v[148:151], v[8:11]
	v_mfma_f32_16x16x32_bf16 v[4:7], v[160:163], v[148:151], v[4:7]
	v_mfma_f32_16x16x32_bf16 v[0:3], v[190:193], v[148:151], v[0:3]
	v_lshl_add_u64 v[64:65], v[100:101], 0, s[92:93]
	v_add_co_u32_e32 v66, vcc, s11, v64
	s_waitcnt vmcnt(4)
	ds_write_b128 v121, v[80:83] offset:45056
	v_addc_co_u32_e32 v67, vcc, 0, v65, vcc
	s_waitcnt lgkmcnt(7)
	v_mfma_f32_16x16x32_bf16 v[60:63], v[210:213], v[194:197], v[60:63]
	s_waitcnt lgkmcnt(6)
	v_mfma_f32_16x16x32_bf16 v[56:59], v[214:217], v[194:197], v[56:59]
	s_waitcnt lgkmcnt(5)
	v_mfma_f32_16x16x32_bf16 v[52:55], v[218:221], v[194:197], v[52:55]
	s_waitcnt lgkmcnt(4)
	v_mfma_f32_16x16x32_bf16 v[48:51], v[222:225], v[194:197], v[48:51]
	s_waitcnt vmcnt(3)
	ds_write_b128 v121, v[76:79] offset:49152
	v_mfma_f32_16x16x32_bf16 v[44:47], v[210:213], v[198:201], v[44:47]
	v_mfma_f32_16x16x32_bf16 v[40:43], v[214:217], v[198:201], v[40:43]
	v_mfma_f32_16x16x32_bf16 v[36:39], v[218:221], v[198:201], v[36:39]
	v_mfma_f32_16x16x32_bf16 v[32:35], v[222:225], v[198:201], v[32:35]
	v_add_co_u32_e32 v66, vcc, s33, v64
	s_waitcnt vmcnt(2)
	ds_write_b128 v121, v[84:87] offset:53248
	v_addc_co_u32_e32 v67, vcc, 0, v65, vcc
	v_add_co_u32_e32 v64, vcc, s59, v64
	v_mfma_f32_16x16x32_bf16 v[28:31], v[210:213], v[202:205], v[28:31]
	s_nop 0
	v_addc_co_u32_e32 v65, vcc, 0, v65, vcc
	v_mfma_f32_16x16x32_bf16 v[24:27], v[214:217], v[202:205], v[24:27]
	v_mfma_f32_16x16x32_bf16 v[20:23], v[218:221], v[202:205], v[20:23]
	v_mfma_f32_16x16x32_bf16 v[16:19], v[222:225], v[202:205], v[16:19]
	s_waitcnt vmcnt(1)
	ds_write_b128 v121, v[88:91] offset:57344
	v_mfma_f32_16x16x32_bf16 v[12:15], v[210:213], v[206:209], v[12:15]
	v_mfma_f32_16x16x32_bf16 v[8:11], v[214:217], v[206:209], v[8:11]
	v_mfma_f32_16x16x32_bf16 v[4:7], v[218:221], v[206:209], v[4:7]
	v_mfma_f32_16x16x32_bf16 v[0:3], v[222:225], v[206:209], v[0:3]
	s_waitcnt vmcnt(0)
	ds_write_b128 v121, v[92:95] offset:61440
	s_waitcnt lgkmcnt(0)
	s_barrier
	ds_read_b128 v[80:83], v123 offset:49152
	ds_read_b128 v[84:87], v123 offset:51200
	ds_read_b128 v[88:91], v123 offset:53248
	ds_read_b128 v[92:95], v123 offset:55296
	ds_read_b128 v[64:67], v122 offset:32768
	ds_read_b128 v[68:71], v122 offset:34816
	s_min_u32 s3, s2, 12
	s_lshl_b32 s92, s3, 7
	ds_read_b128 v[72:75], v122 offset:36864
	ds_read_b128 v[76:79], v122 offset:38912
	v_lshl_add_u64 v[106:107], v[98:99], 0, s[92:93]
	ds_read_b128 v[194:197], v124 offset:32768
	ds_read_b128 v[198:201], v124 offset:34816
	ds_read_b128 v[202:205], v124 offset:36864
	ds_read_b128 v[206:209], v124 offset:38912
	ds_read_b128 v[210:213], v125 offset:49152
	ds_read_b128 v[214:217], v125 offset:51200
	ds_read_b128 v[218:221], v125 offset:53248
	ds_read_b128 v[222:225], v125 offset:55296
	s_waitcnt lgkmcnt(11)
	v_mfma_f32_16x16x32_bf16 v[60:63], v[80:83], v[64:67], v[60:63]
	v_mfma_f32_16x16x32_bf16 v[56:59], v[84:87], v[64:67], v[56:59]
	v_mfma_f32_16x16x32_bf16 v[52:55], v[88:91], v[64:67], v[52:55]
	v_mfma_f32_16x16x32_bf16 v[48:51], v[92:95], v[64:67], v[48:51]
	v_add_co_u32_e32 v102, vcc, s11, v106
	s_waitcnt lgkmcnt(10)
	v_mfma_f32_16x16x32_bf16 v[44:47], v[80:83], v[68:71], v[44:47]
	v_addc_co_u32_e32 v103, vcc, 0, v107, vcc
	v_mfma_f32_16x16x32_bf16 v[40:43], v[84:87], v[68:71], v[40:43]
	v_mfma_f32_16x16x32_bf16 v[36:39], v[88:91], v[68:71], v[36:39]
	v_mfma_f32_16x16x32_bf16 v[32:35], v[92:95], v[68:71], v[32:35]
	v_add_co_u32_e32 v102, vcc, s33, v106
	s_nop 1
	v_addc_co_u32_e32 v103, vcc, 0, v107, vcc
	s_waitcnt lgkmcnt(9)
	v_mfma_f32_16x16x32_bf16 v[28:31], v[80:83], v[72:75], v[28:31]
	v_mfma_f32_16x16x32_bf16 v[24:27], v[84:87], v[72:75], v[24:27]
	v_mfma_f32_16x16x32_bf16 v[20:23], v[88:91], v[72:75], v[20:23]
	v_mfma_f32_16x16x32_bf16 v[16:19], v[92:95], v[72:75], v[16:19]
	s_waitcnt lgkmcnt(8)
	v_mfma_f32_16x16x32_bf16 v[12:15], v[80:83], v[76:79], v[12:15]
	v_add_co_u32_e32 v80, vcc, s59, v106
	v_mfma_f32_16x16x32_bf16 v[0:3], v[92:95], v[76:79], v[0:3]
	s_nop 0
	v_addc_co_u32_e32 v81, vcc, 0, v107, vcc
	v_lshl_add_u64 v[92:93], v[100:101], 0, s[92:93]
	v_mfma_f32_16x16x32_bf16 v[8:11], v[84:87], v[76:79], v[8:11]
	v_add_co_u32_e32 v84, vcc, s11, v92
	s_nop 1
	v_addc_co_u32_e32 v85, vcc, 0, v93, vcc
	v_mfma_f32_16x16x32_bf16 v[4:7], v[88:91], v[76:79], v[4:7]
	v_add_co_u32_e32 v88, vcc, s33, v92
	s_nop 0
	s_nop 0
	v_addc_co_u32_e32 v89, vcc, 0, v93, vcc
	s_waitcnt lgkmcnt(3)
	v_mfma_f32_16x16x32_bf16 v[60:63], v[210:213], v[194:197], v[60:63]
	s_waitcnt lgkmcnt(2)
	v_mfma_f32_16x16x32_bf16 v[56:59], v[214:217], v[194:197], v[56:59]
	s_waitcnt lgkmcnt(1)
	v_mfma_f32_16x16x32_bf16 v[52:55], v[218:221], v[194:197], v[52:55]
	s_waitcnt lgkmcnt(0)
	v_mfma_f32_16x16x32_bf16 v[48:51], v[222:225], v[194:197], v[48:51]
	v_add_co_u32_e32 v92, vcc, s59, v92
	s_nop 1
	v_addc_co_u32_e32 v93, vcc, 0, v93, vcc
	v_mfma_f32_16x16x32_bf16 v[44:47], v[210:213], v[198:201], v[44:47]
	v_mfma_f32_16x16x32_bf16 v[40:43], v[214:217], v[198:201], v[40:43]
	v_mfma_f32_16x16x32_bf16 v[36:39], v[218:221], v[198:201], v[36:39]
	v_mfma_f32_16x16x32_bf16 v[32:35], v[222:225], v[198:201], v[32:35]
	v_mfma_f32_16x16x32_bf16 v[28:31], v[210:213], v[202:205], v[28:31]
	v_mfma_f32_16x16x32_bf16 v[24:27], v[214:217], v[202:205], v[24:27]
	v_mfma_f32_16x16x32_bf16 v[20:23], v[218:221], v[202:205], v[20:23]
	v_mfma_f32_16x16x32_bf16 v[16:19], v[222:225], v[202:205], v[16:19]
	v_mfma_f32_16x16x32_bf16 v[12:15], v[210:213], v[206:209], v[12:15]
	v_mfma_f32_16x16x32_bf16 v[8:11], v[214:217], v[206:209], v[8:11]
	v_mfma_f32_16x16x32_bf16 v[4:7], v[218:221], v[206:209], v[4:7]
	v_mfma_f32_16x16x32_bf16 v[0:3], v[222:225], v[206:209], v[0:3]
	s_mov_b32 s3, s2
	s_waitcnt lgkmcnt(0)
	s_barrier
	s_and_saveexec_b64 s[2:3], s[36:37]
	s_cbranch_execz .LBB0_705
	s_waitcnt vmcnt(7)
	v_add_f32_e32 v64, 0, v96
	v_add_f32_e32 v64, v64, v97
	v_add_f32_e32 v64, v64, v108
	v_add_f32_e32 v64, v64, v109
	v_add_f32_e32 v64, v64, v110
	v_add_f32_e32 v64, v64, v111
	v_add_f32_e32 v64, v64, v118
	v_add_f32_e32 v64, v64, v119
	v_add_f32_e32 v64, v64, v128
	v_add_f32_e32 v64, v64, v132
	v_add_f32_e32 v64, v64, v133
	v_add_f32_e32 v64, v64, v134
	v_add_f32_e32 v64, v64, v135
	v_add_f32_e32 v64, v64, v136
	v_add_f32_e32 v64, v64, v137
	v_add_f32_e32 v64, v64, v138
	v_fmamk_f32 v64, v64, 0x3a800000, v167
	s_mov_b32 s17, 0x800000
	v_mul_f32_e32 v65, 0x4b800000, v64
	v_cmp_gt_f32_e32 vcc, s17, v64
	s_nop 1
	v_cndmask_b32_e32 v64, v64, v65, vcc
	v_rsq_f32_e32 v64, v64
	s_nop 0
	v_mul_f32_e32 v65, 0x45800000, v64
	v_cndmask_b32_e32 v64, v64, v65, vcc
	ds_write_b32 v126, v64

.Ltail739:
	s_add_i32 s2, s3, 2
	v_add_u32_e32 v130, v105, v106
	ds_read_b128 v[116:119], v130 offset:16384
	ds_read_b128 v[120:123], v130 offset:18432
	ds_read_b128 v[124:127], v130 offset:20480
	ds_read_b128 v[132:135], v130 offset:22528
	v_add_u32_e32 v128, v104, v106
	ds_read_b128 v[108:111], v128
	ds_read_b128 v[112:115], v128 offset:2048
	s_add_i32 s3, s3, 4
	s_min_u32 s3, s3, 15
	v_add_u32_e32 v148, v104, v107
	v_add_u32_e32 v149, v105, v107
	s_lshl_b32 s92, s3, 7
	ds_read_b128 v[136:139], v149 offset:18432
	ds_read_b128 v[140:143], v149 offset:20480
	ds_read_b128 v[144:147], v149 offset:22528
	s_waitcnt lgkmcnt(4)
	v_mfma_f32_16x16x32_bf16 v[72:75], v[116:119], v[108:111], v[72:75]
	v_lshl_add_u64 v[52:53], v[80:81], 0, s[92:93]
	v_add_co_u32_e32 v54, vcc, s11, v52
	v_mfma_f32_16x16x32_bf16 v[48:51], v[120:123], v[108:111], v[48:51]
	s_nop 0
	v_addc_co_u32_e32 v55, vcc, 0, v53, vcc
	v_mfma_f32_16x16x32_bf16 v[44:47], v[124:127], v[108:111], v[44:47]
	v_mfma_f32_16x16x32_bf16 v[40:43], v[132:135], v[108:111], v[40:43]
	s_waitcnt lgkmcnt(3)
	v_mfma_f32_16x16x32_bf16 v[108:111], v[116:119], v[112:115], v[16:19]
	s_nop 2
	ds_read_b128 v[16:19], v148
	v_mfma_f32_16x16x32_bf16 v[116:119], v[120:123], v[112:115], v[8:11]
	v_mfma_f32_16x16x32_bf16 v[120:123], v[124:127], v[112:115], v[4:7]
	ds_read_b128 v[124:127], v148 offset:2048
	v_mfma_f32_16x16x32_bf16 v[112:115], v[132:135], v[112:115], v[0:3]
	ds_read_b128 v[132:135], v149 offset:16384
	s_waitcnt vmcnt(0)
	ds_write_b128 v103, v[12:15] offset:53248
	v_add_co_u32_e32 v54, vcc, s33, v52
	s_waitcnt vmcnt(1)
	ds_write_b128 v103, v[20:23] offset:49152
	s_nop 0
	v_addc_co_u32_e32 v55, vcc, 0, v53, vcc
	v_add_co_u32_e32 v52, vcc, s59, v52
	s_nop 0
	s_nop 0
	v_addc_co_u32_e32 v53, vcc, 0, v53, vcc
	s_waitcnt vmcnt(2)
	ds_write_b128 v103, v[24:27] offset:45056
	v_lshl_add_u64 v[52:53], v[82:83], 0, s[92:93]
	s_waitcnt vmcnt(5)
	ds_write_b128 v103, v[36:39] offset:32768
	s_waitcnt lgkmcnt(4)
	v_mfma_f32_16x16x32_bf16 v[0:3], v[132:135], v[16:19], v[72:75]
	v_mfma_f32_16x16x32_bf16 v[4:7], v[136:139], v[16:19], v[48:51]
	v_add_co_u32_e32 v52, vcc, s11, v52
	s_waitcnt vmcnt(4)
	ds_write_b128 v103, v[32:35] offset:36864
	s_nop 0
	v_addc_co_u32_e32 v53, vcc, 0, v53, vcc
	v_mfma_f32_16x16x32_bf16 v[8:11], v[140:143], v[16:19], v[44:47]
	v_mfma_f32_16x16x32_bf16 v[16:19], v[144:147], v[16:19], v[40:43]
	s_waitcnt vmcnt(3)
	ds_write_b128 v103, v[28:31] offset:40960
	v_mfma_f32_16x16x32_bf16 v[40:43], v[132:135], v[124:127], v[108:111]
	v_mfma_f32_16x16x32_bf16 v[44:47], v[136:139], v[124:127], v[116:119]
	v_mfma_f32_16x16x32_bf16 v[48:51], v[140:143], v[124:127], v[120:123]
	v_mfma_f32_16x16x32_bf16 v[72:75], v[144:147], v[124:127], v[112:115]
	s_waitcnt lgkmcnt(0)
	s_barrier
	ds_read_b128 v[116:119], v130 offset:49152
	ds_read_b128 v[120:123], v130 offset:51200
	ds_read_b128 v[124:127], v130 offset:53248
	ds_read_b128 v[132:135], v130 offset:55296
	ds_read_b128 v[108:111], v128 offset:32768
	ds_read_b128 v[112:115], v128 offset:34816
	s_min_u32 s3, s2, 12
	s_lshl_b32 s92, s3, 7
	ds_read_b128 v[136:139], v149 offset:51200
	ds_read_b128 v[140:143], v149 offset:53248
	ds_read_b128 v[144:147], v149 offset:55296
	s_waitcnt lgkmcnt(4)
	v_mfma_f32_16x16x32_bf16 v[0:3], v[116:119], v[108:111], v[0:3]
	v_lshl_add_u64 v[12:13], v[80:81], 0, s[92:93]
	v_add_co_u32_e32 v14, vcc, s11, v12
	v_mfma_f32_16x16x32_bf16 v[4:7], v[120:123], v[108:111], v[4:7]
	s_nop 0
	v_addc_co_u32_e32 v15, vcc, 0, v13, vcc
	v_mfma_f32_16x16x32_bf16 v[8:11], v[124:127], v[108:111], v[8:11]
	v_mfma_f32_16x16x32_bf16 v[16:19], v[132:135], v[108:111], v[16:19]
	s_waitcnt lgkmcnt(3)
	v_mfma_f32_16x16x32_bf16 v[108:111], v[116:119], v[112:115], v[40:43]
	s_nop 2
	ds_read_b128 v[40:43], v148 offset:32768
	v_mfma_f32_16x16x32_bf16 v[116:119], v[120:123], v[112:115], v[44:47]
	v_mfma_f32_16x16x32_bf16 v[120:123], v[124:127], v[112:115], v[48:51]
	ds_read_b128 v[124:127], v148 offset:34816
	v_mfma_f32_16x16x32_bf16 v[112:115], v[132:135], v[112:115], v[72:75]
	ds_read_b128 v[132:135], v149 offset:49152
	v_add_co_u32_e32 v14, vcc, s33, v12
	s_nop 0
	s_nop 0
	v_addc_co_u32_e32 v15, vcc, 0, v13, vcc
	v_add_co_u32_e32 v12, vcc, s59, v12
	s_nop 0
	s_nop 0
	v_addc_co_u32_e32 v13, vcc, 0, v13, vcc
	v_lshl_add_u64 v[12:13], v[82:83], 0, s[92:93]
	s_waitcnt lgkmcnt(0)
	v_mfma_f32_16x16x32_bf16 v[72:75], v[132:135], v[40:43], v[0:3]
	v_mfma_f32_16x16x32_bf16 v[48:51], v[136:139], v[40:43], v[4:7]
	v_add_co_u32_e32 v12, vcc, s11, v12
	s_nop 0
	s_nop 0
	v_addc_co_u32_e32 v13, vcc, 0, v13, vcc
	v_mfma_f32_16x16x32_bf16 v[44:47], v[140:143], v[40:43], v[8:11]
	v_mfma_f32_16x16x32_bf16 v[40:43], v[144:147], v[40:43], v[16:19]
	v_mfma_f32_16x16x32_bf16 v[16:19], v[132:135], v[124:127], v[108:111]
	v_mfma_f32_16x16x32_bf16 v[8:11], v[136:139], v[124:127], v[116:119]
	v_mfma_f32_16x16x32_bf16 v[4:7], v[140:143], v[124:127], v[120:123]
	v_mfma_f32_16x16x32_bf16 v[0:3], v[144:147], v[124:127], v[112:115]
	s_mov_b32 s3, s2
	s_waitcnt lgkmcnt(0)
	s_barrier
	s_movk_i32 s2, 0x80
	v_cmp_gt_i32_e32 vcc, s2, v85
	s_and_saveexec_b64 s[2:3], vcc
	s_cbranch_execz .LBB0_742
	s_waitcnt vmcnt(0)
	v_add_f32_e32 v12, 0, v102
	v_add_f32_e32 v12, v12, v86
	v_add_f32_e32 v12, v12, v87
	v_add_f32_e32 v12, v12, v88
	v_add_f32_e32 v12, v12, v89
	v_add_f32_e32 v12, v12, v90
	v_add_f32_e32 v12, v12, v91
	v_add_f32_e32 v12, v12, v92
	v_add_f32_e32 v12, v12, v93
	v_add_f32_e32 v12, v12, v95
	v_add_f32_e32 v12, v12, v96
	v_add_f32_e32 v12, v12, v97
	v_add_f32_e32 v12, v12, v98
	v_add_f32_e32 v12, v12, v99
	v_add_f32_e32 v12, v12, v100
	v_add_f32_e32 v12, v12, v101
	v_fmamk_f32 v12, v12, 0x3a800000, v167
	s_mov_b32 s16, 0x800000
	v_mul_f32_e32 v13, 0x4b800000, v12
	v_cmp_gt_f32_e32 vcc, s16, v12
	s_nop 1
	v_cndmask_b32_e32 v12, v12, v13, vcc
	v_rsq_f32_e32 v12, v12
	v_lshl_add_u32 v13, v85, 2, 0
	v_add_u32_e32 v13, 0x10000, v13
	v_mul_f32_e32 v14, 0x45800000, v12
	v_cndmask_b32_e32 v12, v12, v14, vcc
	ds_write_b32 v13, v12
